# speedup vs baseline: 1.0127x; 1.0127x over previous
; #define STAGE(P, BASE, br, kt) do { const char* _gb = (const char*)(BASE) + ((size_t)(br) * K + (size_t)(kt) * BK) * 2; \
;     __builtin_amdgcn_global_load_lds((const unsigned*)(_gb + loff0), (unsigned*)((char*)(P) + tid * 16), 16, 0, 0); \
;     __builtin_amdgcn_global_load_lds((const unsigned*)(_gb + (size_t)K * 128 + loff0), (unsigned*)((char*)(P) + tid * 16 + 8192), 16, 0, 0); } while (0)
; #define LDA(dst, b, h) for (int m = 0; m < 4; ++m) { \
;     dst[m][0] = *reinterpret_cast<const bf16x8*>((char*)SA(b, h) + aoff0 + m * 2048); \
;     dst[m][1] = *reinterpret_cast<const bf16x8*>((char*)SA(b, h) + aoff1 + m * 2048); }
; #define LDB(dst, b, h) for (int n = 0; n < 2; ++n) { \
;     dst[n][0] = *reinterpret_cast<const bf16x8*>((char*)SB(b, h) + boff0 + n * 256); \
;     dst[n][1] = *reinterpret_cast<const bf16x8*>((char*)SB(b, h) + boff1 + n * 256); }
; #define MMA(ai, bj, At, Btf) do { __builtin_amdgcn_s_setprio(1); \
;     for (int m = 0; m < 4; ++m) for (int n = 0; n < 2; ++n) for (int k = 0; k < 2; ++k) \
;       acc[ai][bj][m][n] = __builtin_amdgcn_mfma_f32_16x16x32_bf16(Btf[n][k], At[m][k], acc[ai][bj][m][n], 0, 0, 0); \
;     __builtin_amdgcn_s_setprio(0); } while (0)
; #define WAIT_L(n) asm volatile("s_waitcnt lgkmcnt(" #n ")" ::: "memory")
; #define BAR __builtin_amdgcn_s_barrier()
; #define SCHED __builtin_amdgcn_sched_barrier(0)
; template <int EPI> ...
;     ...
;     LDB(B0, 0, 0); SCHED; LDA(At, 0, 0); STAGE(SA(1, 1), A, brow + HALF, t + 1);
;     WAIT_L(8); BAR; WAIT_L(0); MMA(0, 0, At, B0); BAR; SCHED;
;     LDB(B1, 0, 1); STAGE(SB(0, 0), Bt, bcol, t + 2);
;     BAR; WAIT_L(0); MMA(0, 1, At, B1); BAR;
;     LDA(At, 0, 1); STAGE(SA(0, 0), A, brow, t + 2);
;     BAR; WAIT_L(0); MMA(1, 0, At, B0); BAR; SCHED;
.LBB0_277:
	ds_read_b128 v[162:165], v153
	ds_read_b128 v[166:169], v153 offset:256
	ds_read_b128 v[170:173], v154
	ds_read_b128 v[174:177], v154 offset:256
	v_lshl_add_u64 v[226:227], s[70:71], 0, v[130:131]
	v_readfirstlane_b32 s72, v151
	v_lshl_add_u64 v[210:211], v[226:227], 0, s[18:19]
	s_mov_b32 m0, s72
	v_readfirstlane_b32 s72, v152
	ds_read_b128 v[178:181], v150
	ds_read_b128 v[182:185], v150 offset:1024
	ds_read_b128 v[186:189], v150 offset:2048
	ds_read_b128 v[190:193], v150 offset:3072
	ds_read_b128 v[194:197], v150 offset:4096
	ds_read_b128 v[198:201], v150 offset:5120
	ds_read_b128 v[202:205], v150 offset:6144
	ds_read_b128 v[206:209], v150 offset:7168
	global_load_lds_dwordx4 v[210:211], off
	v_lshl_add_u64 v[210:211], v[226:227], 0, s[20:21]
	s_mov_b32 m0, s72
	s_nop 0
	global_load_lds_dwordx4 v[210:211], off
	s_waitcnt lgkmcnt(8)
	v_readfirstlane_b32 s72, v149
	v_lshl_add_u64 v[246:247], v[228:229], 0, s[60:61]
	s_mov_b32 m0, s72
	s_nop 0
	global_load_lds_dwordx4 v[246:247], off
	ds_read_b128 v[210:213], v155
	ds_read_b128 v[214:217], v155 offset:256
	ds_read_b128 v[218:221], v156
	ds_read_b128 v[222:225], v156 offset:256
	s_waitcnt lgkmcnt(0)
	s_setprio 1
	s_barrier
	v_mfma_f32_16x16x32_bf16 v[124:127], v[162:165], v[178:181], v[124:127]
	v_mfma_f32_16x16x32_bf16 v[120:123], v[166:169], v[178:181], v[120:123]
	v_mfma_f32_16x16x32_bf16 v[116:119], v[162:165], v[186:189], v[116:119]
	v_mfma_f32_16x16x32_bf16 v[112:115], v[166:169], v[186:189], v[112:115]
	v_mfma_f32_16x16x32_bf16 v[108:111], v[162:165], v[194:197], v[108:111]
	v_mfma_f32_16x16x32_bf16 v[104:107], v[166:169], v[194:197], v[104:107]
	v_mfma_f32_16x16x32_bf16 v[100:103], v[162:165], v[202:205], v[100:103]
	v_mfma_f32_16x16x32_bf16 v[96:99], v[166:169], v[202:205], v[96:99]
	v_mfma_f32_16x16x32_bf16 v[124:127], v[170:173], v[182:185], v[124:127]
	v_mfma_f32_16x16x32_bf16 v[120:123], v[174:177], v[182:185], v[120:123]
	v_mfma_f32_16x16x32_bf16 v[116:119], v[170:173], v[190:193], v[116:119]
	v_mfma_f32_16x16x32_bf16 v[112:115], v[174:177], v[190:193], v[112:115]
	v_mfma_f32_16x16x32_bf16 v[108:111], v[170:173], v[198:201], v[108:111]
	v_mfma_f32_16x16x32_bf16 v[104:107], v[174:177], v[198:201], v[104:107]
	v_mfma_f32_16x16x32_bf16 v[100:103], v[170:173], v[206:209], v[100:103]
	v_mfma_f32_16x16x32_bf16 v[96:99], v[174:177], v[206:209], v[96:99]
	v_mfma_f32_16x16x32_bf16 v[92:95], v[210:213], v[178:181], v[92:95]
	v_mfma_f32_16x16x32_bf16 v[88:91], v[214:217], v[178:181], v[88:91]
	v_mfma_f32_16x16x32_bf16 v[84:87], v[210:213], v[186:189], v[84:87]
	v_mfma_f32_16x16x32_bf16 v[80:83], v[214:217], v[186:189], v[80:83]
	v_mfma_f32_16x16x32_bf16 v[76:79], v[210:213], v[194:197], v[76:79]
	v_mfma_f32_16x16x32_bf16 v[72:75], v[214:217], v[194:197], v[72:75]
	v_mfma_f32_16x16x32_bf16 v[68:71], v[210:213], v[202:205], v[68:71]
	v_mfma_f32_16x16x32_bf16 v[64:67], v[214:217], v[202:205], v[64:67]
	v_mfma_f32_16x16x32_bf16 v[92:95], v[218:221], v[182:185], v[92:95]
	v_mfma_f32_16x16x32_bf16 v[88:91], v[222:225], v[182:185], v[88:91]
	v_mfma_f32_16x16x32_bf16 v[84:87], v[218:221], v[190:193], v[84:87]
	v_mfma_f32_16x16x32_bf16 v[80:83], v[222:225], v[190:193], v[80:83]
	v_mfma_f32_16x16x32_bf16 v[76:79], v[218:221], v[198:201], v[76:79]
	v_mfma_f32_16x16x32_bf16 v[72:75], v[222:225], v[198:201], v[72:75]
	v_mfma_f32_16x16x32_bf16 v[68:71], v[218:221], v[206:209], v[68:71]
	v_mfma_f32_16x16x32_bf16 v[64:67], v[222:225], v[206:209], v[64:67]
	s_barrier
	s_setprio 0
	v_lshl_add_u64 v[228:229], s[68:69], 0, v[130:131]
	v_readfirstlane_b32 s72, v136
	v_lshl_add_u64 v[230:231], v[228:229], 0, s[22:23]
	s_mov_b32 m0, s72
	v_readfirstlane_b32 s72, v137
	global_load_lds_dwordx4 v[230:231], off
	v_lshl_add_u64 v[230:231], v[228:229], 0, s[26:27]
	s_mov_b32 m0, s72
	s_nop 0
	global_load_lds_dwordx4 v[230:231], off
	v_readfirstlane_b32 s72, v138
	v_lshl_add_u64 v[230:231], v[226:227], 0, s[28:29]
	s_mov_b32 m0, s72
	v_readfirstlane_b32 s72, v139
	ds_read_b128 v[178:181], v150 offset:16384
	ds_read_b128 v[182:185], v150 offset:17408
	ds_read_b128 v[186:189], v150 offset:18432
	ds_read_b128 v[190:193], v150 offset:19456
	ds_read_b128 v[194:197], v150 offset:20480
	ds_read_b128 v[198:201], v150 offset:21504
	ds_read_b128 v[202:205], v150 offset:22528
	ds_read_b128 v[206:209], v150 offset:23552
	global_load_lds_dwordx4 v[230:231], off
	v_lshl_add_u64 v[230:231], v[226:227], 0, s[30:31]
	s_mov_b32 m0, s72
	s_nop 0
	global_load_lds_dwordx4 v[230:231], off
	v_readfirstlane_b32 s72, v140
	v_lshl_add_u64 v[246:247], v[228:229], 0, s[36:37]
	s_mov_b32 m0, s72
	v_readfirstlane_b32 s72, v141
	global_load_lds_dwordx4 v[246:247], off
	s_waitcnt vmcnt(5)
	s_waitcnt lgkmcnt(0)
	s_setprio 1
	s_barrier
; #define STAGE(P, BASE, br, kt) do { const char* _gb = (const char*)(BASE) + ((size_t)(br) * K + (size_t)(kt) * BK) * 2; \
;     __builtin_amdgcn_global_load_lds((const unsigned*)(_gb + loff0), (unsigned*)((char*)(P) + tid * 16), 16, 0, 0); \
;     __builtin_amdgcn_global_load_lds((const unsigned*)(_gb + (size_t)K * 128 + loff0), (unsigned*)((char*)(P) + tid * 16 + 8192), 16, 0, 0); } while (0)
; #define LDA(dst, b, h) for (int m = 0; m < 4; ++m) { \
;     dst[m][0] = *reinterpret_cast<const bf16x8*>((char*)SA(b, h) + aoff0 + m * 2048); \
;     dst[m][1] = *reinterpret_cast<const bf16x8*>((char*)SA(b, h) + aoff1 + m * 2048); }
; #define LDB(dst, b, h) for (int n = 0; n < 2; ++n) { \
;     dst[n][0] = *reinterpret_cast<const bf16x8*>((char*)SB(b, h) + boff0 + n * 256); \
;     dst[n][1] = *reinterpret_cast<const bf16x8*>((char*)SB(b, h) + boff1 + n * 256); }
; #define MMA(ai, bj, At, Btf) do { __builtin_amdgcn_s_setprio(1); \
;     for (int m = 0; m < 4; ++m) for (int n = 0; n < 2; ++n) for (int k = 0; k < 2; ++k) \
;       acc[ai][bj][m][n] = __builtin_amdgcn_mfma_f32_16x16x32_bf16(Btf[n][k], At[m][k], acc[ai][bj][m][n], 0, 0, 0); \
;     __builtin_amdgcn_s_setprio(0); } while (0)
; #define WAIT_V(n) asm volatile("s_waitcnt vmcnt(" #n ")" ::: "memory")
; #define WAIT_L(n) asm volatile("s_waitcnt lgkmcnt(" #n ")" ::: "memory")
; #define BAR __builtin_amdgcn_s_barrier()
; #define SCHED __builtin_amdgcn_sched_barrier(0)
; template <int EPI> ...
;     ...
;     BAR; WAIT_L(0); MMA(1, 0, At, B0); BAR; SCHED;
;     STAGE(SB(0, 1), Bt, bcol + HALF, t + 2);
;     WAIT_V(6); BAR; MMA(1, 1, At, B1); BAR;
;     LDB(B0, 1, 0); SCHED; LDA(At, 1, 0); STAGE(SA(0, 1), A, brow + HALF, t + 2);
;     WAIT_L(8); BAR; WAIT_L(0); MMA(0, 0, At, B0); BAR; SCHED;
;     LDB(B1, 1, 1); STAGE(SB(1, 0), Bt, bcol, t + 3);
;     BAR; WAIT_L(0); MMA(0, 1, At, B1); BAR;
	v_mfma_f32_16x16x32_bf16 v[60:63], v[162:165], v[178:181], v[60:63]
	v_mfma_f32_16x16x32_bf16 v[56:59], v[166:169], v[178:181], v[56:59]
	v_mfma_f32_16x16x32_bf16 v[52:55], v[162:165], v[186:189], v[52:55]
	v_mfma_f32_16x16x32_bf16 v[48:51], v[166:169], v[186:189], v[48:51]
	v_mfma_f32_16x16x32_bf16 v[44:47], v[162:165], v[194:197], v[44:47]
	v_mfma_f32_16x16x32_bf16 v[40:43], v[166:169], v[194:197], v[40:43]
	v_mfma_f32_16x16x32_bf16 v[36:39], v[162:165], v[202:205], v[36:39]
	v_mfma_f32_16x16x32_bf16 v[32:35], v[166:169], v[202:205], v[32:35]
	v_mfma_f32_16x16x32_bf16 v[60:63], v[170:173], v[182:185], v[60:63]
	v_mfma_f32_16x16x32_bf16 v[56:59], v[174:177], v[182:185], v[56:59]
	v_mfma_f32_16x16x32_bf16 v[52:55], v[170:173], v[190:193], v[52:55]
	v_mfma_f32_16x16x32_bf16 v[48:51], v[174:177], v[190:193], v[48:51]
	v_mfma_f32_16x16x32_bf16 v[44:47], v[170:173], v[198:201], v[44:47]
	v_mfma_f32_16x16x32_bf16 v[40:43], v[174:177], v[198:201], v[40:43]
	v_mfma_f32_16x16x32_bf16 v[36:39], v[170:173], v[206:209], v[36:39]
	v_mfma_f32_16x16x32_bf16 v[32:35], v[174:177], v[206:209], v[32:35]
	v_mfma_f32_16x16x32_bf16 v[28:31], v[210:213], v[178:181], v[28:31]
	v_mfma_f32_16x16x32_bf16 v[24:27], v[214:217], v[178:181], v[24:27]
	v_mfma_f32_16x16x32_bf16 v[20:23], v[210:213], v[186:189], v[20:23]
	v_mfma_f32_16x16x32_bf16 v[16:19], v[214:217], v[186:189], v[16:19]
	v_mfma_f32_16x16x32_bf16 v[12:15], v[210:213], v[194:197], v[12:15]
	v_mfma_f32_16x16x32_bf16 v[8:11], v[214:217], v[194:197], v[8:11]
	v_mfma_f32_16x16x32_bf16 v[4:7], v[210:213], v[202:205], v[4:7]
	v_mfma_f32_16x16x32_bf16 v[0:3], v[214:217], v[202:205], v[0:3]
	v_mfma_f32_16x16x32_bf16 v[28:31], v[218:221], v[182:185], v[28:31]
	v_mfma_f32_16x16x32_bf16 v[24:27], v[222:225], v[182:185], v[24:27]
	v_mfma_f32_16x16x32_bf16 v[20:23], v[218:221], v[190:193], v[20:23]
	v_mfma_f32_16x16x32_bf16 v[16:19], v[222:225], v[190:193], v[16:19]
	v_mfma_f32_16x16x32_bf16 v[12:15], v[218:221], v[198:201], v[12:15]
	v_mfma_f32_16x16x32_bf16 v[8:11], v[222:225], v[198:201], v[8:11]
	v_mfma_f32_16x16x32_bf16 v[4:7], v[218:221], v[206:209], v[4:7]
	v_mfma_f32_16x16x32_bf16 v[0:3], v[222:225], v[206:209], v[0:3]
	s_barrier
	s_setprio 0
	ds_read_b128 v[162:165], v157
	ds_read_b128 v[166:169], v157 offset:256
	ds_read_b128 v[170:173], v158
	ds_read_b128 v[174:177], v158 offset:256
	v_readfirstlane_b32 s72, v142
	v_lshl_add_u64 v[210:211], v[226:227], 0, s[46:47]
	s_mov_b32 m0, s72
	v_readfirstlane_b32 s72, v143
	ds_read_b128 v[178:181], v150 offset:32768
	ds_read_b128 v[182:185], v150 offset:33792
	ds_read_b128 v[186:189], v150 offset:34816
	ds_read_b128 v[190:193], v150 offset:35840
	ds_read_b128 v[194:197], v150 offset:36864
	ds_read_b128 v[198:201], v150 offset:37888
	ds_read_b128 v[202:205], v150 offset:38912
	ds_read_b128 v[206:209], v150 offset:39936
	global_load_lds_dwordx4 v[210:211], off
	v_lshl_add_u64 v[210:211], v[226:227], 0, s[48:49]
	s_mov_b32 m0, s72
	s_nop 0
	global_load_lds_dwordx4 v[210:211], off
	s_waitcnt lgkmcnt(8)
	v_readfirstlane_b32 s72, v141
	v_lshl_add_u64 v[246:247], v[228:229], 0, s[38:39]
	s_mov_b32 m0, s72
	s_nop 0
	global_load_lds_dwordx4 v[246:247], off
	ds_read_b128 v[210:213], v159
	ds_read_b128 v[214:217], v159 offset:256
	ds_read_b128 v[218:221], v160
	ds_read_b128 v[222:225], v160 offset:256
	s_waitcnt lgkmcnt(0)
	s_setprio 1
	s_barrier
	v_mfma_f32_16x16x32_bf16 v[124:127], v[162:165], v[178:181], v[124:127]
	v_mfma_f32_16x16x32_bf16 v[120:123], v[166:169], v[178:181], v[120:123]
	v_mfma_f32_16x16x32_bf16 v[116:119], v[162:165], v[186:189], v[116:119]
	v_mfma_f32_16x16x32_bf16 v[112:115], v[166:169], v[186:189], v[112:115]
	v_mfma_f32_16x16x32_bf16 v[108:111], v[162:165], v[194:197], v[108:111]
	v_mfma_f32_16x16x32_bf16 v[104:107], v[166:169], v[194:197], v[104:107]
	v_mfma_f32_16x16x32_bf16 v[100:103], v[162:165], v[202:205], v[100:103]
	v_mfma_f32_16x16x32_bf16 v[96:99], v[166:169], v[202:205], v[96:99]
	v_mfma_f32_16x16x32_bf16 v[124:127], v[170:173], v[182:185], v[124:127]
	v_mfma_f32_16x16x32_bf16 v[120:123], v[174:177], v[182:185], v[120:123]
	v_mfma_f32_16x16x32_bf16 v[116:119], v[170:173], v[190:193], v[116:119]
	v_mfma_f32_16x16x32_bf16 v[112:115], v[174:177], v[190:193], v[112:115]
	v_mfma_f32_16x16x32_bf16 v[108:111], v[170:173], v[198:201], v[108:111]
	v_mfma_f32_16x16x32_bf16 v[104:107], v[174:177], v[198:201], v[104:107]
	v_mfma_f32_16x16x32_bf16 v[100:103], v[170:173], v[206:209], v[100:103]
	v_mfma_f32_16x16x32_bf16 v[96:99], v[174:177], v[206:209], v[96:99]
	v_mfma_f32_16x16x32_bf16 v[92:95], v[210:213], v[178:181], v[92:95]
	v_mfma_f32_16x16x32_bf16 v[88:91], v[214:217], v[178:181], v[88:91]
	v_mfma_f32_16x16x32_bf16 v[84:87], v[210:213], v[186:189], v[84:87]
	v_mfma_f32_16x16x32_bf16 v[80:83], v[214:217], v[186:189], v[80:83]
	v_mfma_f32_16x16x32_bf16 v[76:79], v[210:213], v[194:197], v[76:79]
	v_mfma_f32_16x16x32_bf16 v[72:75], v[214:217], v[194:197], v[72:75]
	v_mfma_f32_16x16x32_bf16 v[68:71], v[210:213], v[202:205], v[68:71]
	v_mfma_f32_16x16x32_bf16 v[64:67], v[214:217], v[202:205], v[64:67]
	v_mfma_f32_16x16x32_bf16 v[92:95], v[218:221], v[182:185], v[92:95]
	v_mfma_f32_16x16x32_bf16 v[88:91], v[222:225], v[182:185], v[88:91]
	v_mfma_f32_16x16x32_bf16 v[84:87], v[218:221], v[190:193], v[84:87]
	v_mfma_f32_16x16x32_bf16 v[80:83], v[222:225], v[190:193], v[80:83]
	v_mfma_f32_16x16x32_bf16 v[76:79], v[218:221], v[198:201], v[76:79]
	v_mfma_f32_16x16x32_bf16 v[72:75], v[222:225], v[198:201], v[72:75]
	v_mfma_f32_16x16x32_bf16 v[68:71], v[218:221], v[206:209], v[68:71]
	v_mfma_f32_16x16x32_bf16 v[64:67], v[222:225], v[206:209], v[64:67]
	s_barrier
; #define STAGE(P, BASE, br, kt) do { const char* _gb = (const char*)(BASE) + ((size_t)(br) * K + (size_t)(kt) * BK) * 2; \
;     __builtin_amdgcn_global_load_lds((const unsigned*)(_gb + loff0), (unsigned*)((char*)(P) + tid * 16), 16, 0, 0); \
;     __builtin_amdgcn_global_load_lds((const unsigned*)(_gb + (size_t)K * 128 + loff0), (unsigned*)((char*)(P) + tid * 16 + 8192), 16, 0, 0); } while (0)
; #define LDA(dst, b, h) for (int m = 0; m < 4; ++m) { \
;     dst[m][0] = *reinterpret_cast<const bf16x8*>((char*)SA(b, h) + aoff0 + m * 2048); \
;     dst[m][1] = *reinterpret_cast<const bf16x8*>((char*)SA(b, h) + aoff1 + m * 2048); }
; #define LDB(dst, b, h) for (int n = 0; n < 2; ++n) { \
;     dst[n][0] = *reinterpret_cast<const bf16x8*>((char*)SB(b, h) + boff0 + n * 256); \
;     dst[n][1] = *reinterpret_cast<const bf16x8*>((char*)SB(b, h) + boff1 + n * 256); }
; #define MMA(ai, bj, At, Btf) do { __builtin_amdgcn_s_setprio(1); \
;     for (int m = 0; m < 4; ++m) for (int n = 0; n < 2; ++n) for (int k = 0; k < 2; ++k) \
;       acc[ai][bj][m][n] = __builtin_amdgcn_mfma_f32_16x16x32_bf16(Btf[n][k], At[m][k], acc[ai][bj][m][n], 0, 0, 0); \
;     __builtin_amdgcn_s_setprio(0); } while (0)
; #define WAIT_V(n) asm volatile("s_waitcnt vmcnt(" #n ")" ::: "memory")
; #define WAIT_L(n) asm volatile("s_waitcnt lgkmcnt(" #n ")" ::: "memory")
; #define BAR __builtin_amdgcn_s_barrier()
; #define SCHED __builtin_amdgcn_sched_barrier(0)
; template <int EPI> ...
;     ...
;     LDA(At, 1, 1); STAGE(SA(1, 0), A, brow, t + 3);
;     BAR; WAIT_L(0); MMA(1, 0, At, B0); BAR; SCHED;
;     STAGE(SB(1, 1), Bt, bcol + HALF, t + 3);
;     WAIT_V(6); BAR; MMA(1, 1, At, B1); BAR;
;   }
;   { LDB(B0, 0, 0); LDA(At, 0, 0); STAGE(SA(1, 1), A, brow + HALF, nt - 1);
;     BAR; WAIT_L(0); MMA(0, 0, At, B0); BAR;
	s_setprio 0
	v_readfirstlane_b32 s72, v144
	v_lshl_add_u64 v[230:231], v[228:229], 0, s[50:51]
	s_mov_b32 m0, s72
	v_readfirstlane_b32 s72, v145
	global_load_lds_dwordx4 v[230:231], off
	v_lshl_add_u64 v[230:231], v[228:229], 0, s[52:53]
	s_mov_b32 m0, s72
	s_nop 0
	global_load_lds_dwordx4 v[230:231], off
	v_readfirstlane_b32 s72, v146
	v_lshl_add_u64 v[230:231], v[226:227], 0, s[54:55]
	s_mov_b32 m0, s72
	v_readfirstlane_b32 s72, v147
	ds_read_b128 v[178:181], v150 offset:49152
	ds_read_b128 v[182:185], v150 offset:50176
	ds_read_b128 v[186:189], v150 offset:51200
	ds_read_b128 v[190:193], v150 offset:52224
	ds_read_b128 v[194:197], v150 offset:53248
	ds_read_b128 v[198:201], v150 offset:54272
	ds_read_b128 v[202:205], v150 offset:55296
	ds_read_b128 v[206:209], v150 offset:56320
	global_load_lds_dwordx4 v[230:231], off
	v_lshl_add_u64 v[226:227], v[226:227], 0, s[56:57]
	s_mov_b32 m0, s72
	s_nop 0
	global_load_lds_dwordx4 v[226:227], off
	v_readfirstlane_b32 s72, v148
	v_lshl_add_u64 v[246:247], v[228:229], 0, s[58:59]
	s_mov_b32 m0, s72
	v_readfirstlane_b32 s72, v149
	global_load_lds_dwordx4 v[246:247], off
	s_waitcnt vmcnt(5)
	s_barrier
	s_waitcnt lgkmcnt(0)
	s_setprio 1
	s_waitcnt lgkmcnt(0)
	v_mfma_f32_16x16x32_bf16 v[60:63], v[162:165], v[178:181], v[60:63]
	v_mfma_f32_16x16x32_bf16 v[56:59], v[166:169], v[178:181], v[56:59]
	v_mfma_f32_16x16x32_bf16 v[52:55], v[162:165], v[186:189], v[52:55]
	v_mfma_f32_16x16x32_bf16 v[48:51], v[166:169], v[186:189], v[48:51]
	v_mfma_f32_16x16x32_bf16 v[44:47], v[162:165], v[194:197], v[44:47]
	v_mfma_f32_16x16x32_bf16 v[40:43], v[166:169], v[194:197], v[40:43]
	v_mfma_f32_16x16x32_bf16 v[36:39], v[162:165], v[202:205], v[36:39]
	v_mfma_f32_16x16x32_bf16 v[32:35], v[166:169], v[202:205], v[32:35]
	v_mfma_f32_16x16x32_bf16 v[60:63], v[170:173], v[182:185], v[60:63]
	v_mfma_f32_16x16x32_bf16 v[56:59], v[174:177], v[182:185], v[56:59]
	v_mfma_f32_16x16x32_bf16 v[52:55], v[170:173], v[190:193], v[52:55]
	v_mfma_f32_16x16x32_bf16 v[48:51], v[174:177], v[190:193], v[48:51]
	v_mfma_f32_16x16x32_bf16 v[44:47], v[170:173], v[198:201], v[44:47]
	v_mfma_f32_16x16x32_bf16 v[40:43], v[174:177], v[198:201], v[40:43]
	v_mfma_f32_16x16x32_bf16 v[36:39], v[170:173], v[206:209], v[36:39]
	v_mfma_f32_16x16x32_bf16 v[32:35], v[174:177], v[206:209], v[32:35]
	s_setprio 0
	s_setprio 1
	v_mfma_f32_16x16x32_bf16 v[28:31], v[210:213], v[178:181], v[28:31]
	v_mfma_f32_16x16x32_bf16 v[24:27], v[214:217], v[178:181], v[24:27]
	v_mfma_f32_16x16x32_bf16 v[20:23], v[210:213], v[186:189], v[20:23]
	v_mfma_f32_16x16x32_bf16 v[16:19], v[214:217], v[186:189], v[16:19]
	v_mfma_f32_16x16x32_bf16 v[12:15], v[210:213], v[194:197], v[12:15]
	v_mfma_f32_16x16x32_bf16 v[8:11], v[214:217], v[194:197], v[8:11]
	v_mfma_f32_16x16x32_bf16 v[4:7], v[210:213], v[202:205], v[4:7]
	v_mfma_f32_16x16x32_bf16 v[0:3], v[214:217], v[202:205], v[0:3]
	v_mfma_f32_16x16x32_bf16 v[28:31], v[218:221], v[182:185], v[28:31]
	v_mfma_f32_16x16x32_bf16 v[24:27], v[222:225], v[182:185], v[24:27]
	v_mfma_f32_16x16x32_bf16 v[20:23], v[218:221], v[190:193], v[20:23]
	v_mfma_f32_16x16x32_bf16 v[16:19], v[222:225], v[190:193], v[16:19]
	v_mfma_f32_16x16x32_bf16 v[12:15], v[218:221], v[198:201], v[12:15]
	v_mfma_f32_16x16x32_bf16 v[8:11], v[222:225], v[198:201], v[8:11]
	v_mfma_f32_16x16x32_bf16 v[4:7], v[218:221], v[206:209], v[4:7]
	v_mfma_f32_16x16x32_bf16 v[0:3], v[222:225], v[206:209], v[0:3]
	s_setprio 0
	s_add_i32 s67, s67, 2
	s_add_u32 s70, s70, 0x100
	s_addc_u32 s71, s71, 0
	s_add_u32 s68, s68, 0x100
	s_addc_u32 s69, s69, 0
	s_cmp_lt_u32 s67, 28
	s_barrier
	s_cbranch_scc1 .LBB0_277
	v_readfirstlane_b32 s72, v149
	v_lshl_add_u64 v[246:247], v[228:229], 0, s[60:61]
	s_mov_b32 m0, s72
	s_nop 0
	global_load_lds_dwordx4 v[246:247], off
	v_readfirstlane_b32 s67, v151
	v_lshl_add_u64 v[210:211], v[132:133], 0, s[62:63]
	s_mov_b32 m0, s67
	v_readfirstlane_b32 s67, v152
	ds_read_b128 v[162:165], v153
	ds_read_b128 v[166:169], v153 offset:256
	ds_read_b128 v[170:173], v154
	ds_read_b128 v[174:177], v154 offset:256
	ds_read_b128 v[178:181], v150
	ds_read_b128 v[182:185], v150 offset:1024
	ds_read_b128 v[186:189], v150 offset:2048
	ds_read_b128 v[190:193], v150 offset:3072
	ds_read_b128 v[194:197], v150 offset:4096
	ds_read_b128 v[198:201], v150 offset:5120
	ds_read_b128 v[202:205], v150 offset:6144
	ds_read_b128 v[206:209], v150 offset:7168
	global_load_lds_dwordx4 v[210:211], off
	v_lshl_add_u64 v[132:133], v[132:133], 0, s[64:65]
	s_mov_b32 m0, s67
	s_nop 0
	global_load_lds_dwordx4 v[132:133], off
	s_waitcnt lgkmcnt(0)
	s_setprio 1
	s_barrier
	v_mfma_f32_16x16x32_bf16 v[124:127], v[162:165], v[178:181], v[124:127]
	v_mfma_f32_16x16x32_bf16 v[116:119], v[162:165], v[186:189], v[116:119]
	v_mfma_f32_16x16x32_bf16 v[108:111], v[162:165], v[194:197], v[108:111]
	v_mfma_f32_16x16x32_bf16 v[100:103], v[162:165], v[202:205], v[100:103]
	v_mfma_f32_16x16x32_bf16 v[124:127], v[170:173], v[182:185], v[124:127]
	v_mfma_f32_16x16x32_bf16 v[120:123], v[166:169], v[178:181], v[120:123]
	v_mfma_f32_16x16x32_bf16 v[116:119], v[170:173], v[190:193], v[116:119]
	v_mfma_f32_16x16x32_bf16 v[112:115], v[166:169], v[186:189], v[112:115]
	v_mfma_f32_16x16x32_bf16 v[108:111], v[170:173], v[198:201], v[108:111]
	v_mfma_f32_16x16x32_bf16 v[104:107], v[166:169], v[194:197], v[104:107]
	v_mfma_f32_16x16x32_bf16 v[100:103], v[170:173], v[206:209], v[100:103]
	v_mfma_f32_16x16x32_bf16 v[96:99], v[166:169], v[202:205], v[96:99]
	v_mfma_f32_16x16x32_bf16 v[210:213], v[174:177], v[182:185], v[120:123]
	v_mfma_f32_16x16x32_bf16 v[214:217], v[174:177], v[190:193], v[112:115]
	v_mfma_f32_16x16x32_bf16 v[218:221], v[174:177], v[198:201], v[104:107]
	v_mfma_f32_16x16x32_bf16 v[222:225], v[174:177], v[206:209], v[96:99]
	s_barrier
; #define STAGE(P, BASE, br, kt) do { const char* _gb = (const char*)(BASE) + ((size_t)(br) * K + (size_t)(kt) * BK) * 2; \
;     __builtin_amdgcn_global_load_lds((const unsigned*)(_gb + loff0), (unsigned*)((char*)(P) + tid * 16), 16, 0, 0); \
;     __builtin_amdgcn_global_load_lds((const unsigned*)(_gb + (size_t)K * 128 + loff0), (unsigned*)((char*)(P) + tid * 16 + 8192), 16, 0, 0); } while (0)
; #define LDA(dst, b, h) for (int m = 0; m < 4; ++m) { \
;     dst[m][0] = *reinterpret_cast<const bf16x8*>((char*)SA(b, h) + aoff0 + m * 2048); \
;     dst[m][1] = *reinterpret_cast<const bf16x8*>((char*)SA(b, h) + aoff1 + m * 2048); }
; #define LDB(dst, b, h) for (int n = 0; n < 2; ++n) { \
;     dst[n][0] = *reinterpret_cast<const bf16x8*>((char*)SB(b, h) + boff0 + n * 256); \
;     dst[n][1] = *reinterpret_cast<const bf16x8*>((char*)SB(b, h) + boff1 + n * 256); }
; #define MMA(ai, bj, At, Btf) do { __builtin_amdgcn_s_setprio(1); \
;     for (int m = 0; m < 4; ++m) for (int n = 0; n < 2; ++n) for (int k = 0; k < 2; ++k) \
;       acc[ai][bj][m][n] = __builtin_amdgcn_mfma_f32_16x16x32_bf16(Btf[n][k], At[m][k], acc[ai][bj][m][n], 0, 0, 0); \
;     __builtin_amdgcn_s_setprio(0); } while (0)
; #define WAIT_V(n) asm volatile("s_waitcnt vmcnt(" #n ")" ::: "memory")
; #define WAIT_L(n) asm volatile("s_waitcnt lgkmcnt(" #n ")" ::: "memory")
; #define BAR __builtin_amdgcn_s_barrier()
; template <int EPI> ...
;     ...
;   { LDB(B0, 0, 0); LDA(At, 0, 0); STAGE(SA(1, 1), A, brow + HALF, nt - 1);
;     BAR; WAIT_L(0); MMA(0, 0, At, B0); BAR;
;     LDB(B1, 0, 1); BAR; WAIT_L(0); MMA(0, 1, At, B1); BAR;
;     LDA(At, 0, 1); WAIT_V(4); BAR; WAIT_L(0); MMA(1, 0, At, B0); MMA(1, 1, At, B1); BAR; }
;   { LDB(B0, 1, 0); LDA(At, 1, 0); WAIT_V(2); BAR; WAIT_L(0); MMA(0, 0, At, B0); BAR;
;     LDB(B1, 1, 1); WAIT_V(0); BAR; WAIT_L(0); MMA(0, 1, At, B1); BAR;
	s_setprio 0
	s_nop 1
	ds_read_b128 v[96:99], v155
	ds_read_b128 v[104:107], v155 offset:256
	ds_read_b128 v[112:115], v156
	ds_read_b128 v[120:123], v156 offset:256
	s_waitcnt lgkmcnt(0)
	s_setprio 1
	s_barrier
	v_mfma_f32_16x16x32_bf16 v[92:95], v[96:99], v[178:181], v[92:95]
	v_mfma_f32_16x16x32_bf16 v[84:87], v[96:99], v[186:189], v[84:87]
	v_mfma_f32_16x16x32_bf16 v[76:79], v[96:99], v[194:197], v[76:79]
	v_mfma_f32_16x16x32_bf16 v[68:71], v[96:99], v[202:205], v[68:71]
	v_mfma_f32_16x16x32_bf16 v[92:95], v[112:115], v[182:185], v[92:95]
	v_mfma_f32_16x16x32_bf16 v[88:91], v[104:107], v[178:181], v[88:91]
	v_mfma_f32_16x16x32_bf16 v[84:87], v[112:115], v[190:193], v[84:87]
	v_mfma_f32_16x16x32_bf16 v[80:83], v[104:107], v[186:189], v[80:83]
	v_mfma_f32_16x16x32_bf16 v[76:79], v[112:115], v[198:201], v[76:79]
	v_mfma_f32_16x16x32_bf16 v[72:75], v[104:107], v[194:197], v[72:75]
	v_mfma_f32_16x16x32_bf16 v[68:71], v[112:115], v[206:209], v[68:71]
	v_mfma_f32_16x16x32_bf16 v[64:67], v[104:107], v[202:205], v[64:67]
	v_mfma_f32_16x16x32_bf16 v[178:181], v[120:123], v[182:185], v[88:91]
	v_mfma_f32_16x16x32_bf16 v[182:185], v[120:123], v[190:193], v[80:83]
	v_mfma_f32_16x16x32_bf16 v[186:189], v[120:123], v[198:201], v[72:75]
	v_mfma_f32_16x16x32_bf16 v[190:193], v[120:123], v[206:209], v[64:67]
	s_barrier
	s_setprio 0
	s_nop 1
	ds_read_b128 v[64:67], v150 offset:16384
	ds_read_b128 v[72:75], v150 offset:17408
	ds_read_b128 v[80:83], v150 offset:18432
	ds_read_b128 v[88:91], v150 offset:19456
	ds_read_b128 v[194:197], v150 offset:20480
	ds_read_b128 v[198:201], v150 offset:21504
	ds_read_b128 v[202:205], v150 offset:22528
	ds_read_b128 v[206:209], v150 offset:23552
	s_waitcnt vmcnt(4)
	s_waitcnt lgkmcnt(0)
	s_setprio 1
	s_barrier
	v_mfma_f32_16x16x32_bf16 v[60:63], v[162:165], v[64:67], v[60:63]
	v_mfma_f32_16x16x32_bf16 v[56:59], v[166:169], v[64:67], v[56:59]
	v_mfma_f32_16x16x32_bf16 v[52:55], v[162:165], v[80:83], v[52:55]
	v_mfma_f32_16x16x32_bf16 v[40:43], v[166:169], v[194:197], v[40:43]
	v_mfma_f32_16x16x32_bf16 v[36:39], v[162:165], v[202:205], v[36:39]
	v_mfma_f32_16x16x32_bf16 v[60:63], v[170:173], v[72:75], v[60:63]
	v_mfma_f32_16x16x32_bf16 v[56:59], v[174:177], v[72:75], v[56:59]
	v_mfma_f32_16x16x32_bf16 v[52:55], v[170:173], v[88:91], v[52:55]
	v_mfma_f32_16x16x32_bf16 v[48:51], v[166:169], v[80:83], v[48:51]
	v_mfma_f32_16x16x32_bf16 v[44:47], v[162:165], v[194:197], v[44:47]
	v_mfma_f32_16x16x32_bf16 v[40:43], v[174:177], v[198:201], v[40:43]
	v_mfma_f32_16x16x32_bf16 v[36:39], v[170:173], v[206:209], v[36:39]
	v_mfma_f32_16x16x32_bf16 v[32:35], v[166:169], v[202:205], v[32:35]
	v_mfma_f32_16x16x32_bf16 v[226:229], v[174:177], v[88:91], v[48:51]
	v_mfma_f32_16x16x32_bf16 v[230:233], v[170:173], v[198:201], v[44:47]
	v_mfma_f32_16x16x32_bf16 v[162:165], v[174:177], v[206:209], v[32:35]
	v_mfma_f32_16x16x32_bf16 v[24:27], v[104:107], v[64:67], v[24:27]
	v_mfma_f32_16x16x32_bf16 v[20:23], v[96:99], v[80:83], v[20:23]
	v_mfma_f32_16x16x32_bf16 v[8:11], v[104:107], v[194:197], v[8:11]
	v_mfma_f32_16x16x32_bf16 v[4:7], v[96:99], v[202:205], v[4:7]
	v_mfma_f32_16x16x32_bf16 v[28:31], v[96:99], v[64:67], v[28:31]
	v_mfma_f32_16x16x32_bf16 v[24:27], v[120:123], v[72:75], v[24:27]
	v_mfma_f32_16x16x32_bf16 v[20:23], v[112:115], v[88:91], v[20:23]
	v_mfma_f32_16x16x32_bf16 v[16:19], v[104:107], v[80:83], v[16:19]
	v_mfma_f32_16x16x32_bf16 v[12:15], v[96:99], v[194:197], v[12:15]
	v_mfma_f32_16x16x32_bf16 v[8:11], v[120:123], v[198:201], v[8:11]
	v_mfma_f32_16x16x32_bf16 v[4:7], v[112:115], v[206:209], v[4:7]
	v_mfma_f32_16x16x32_bf16 v[0:3], v[104:107], v[202:205], v[0:3]
	v_mfma_f32_16x16x32_bf16 v[166:169], v[112:115], v[72:75], v[28:31]
	v_mfma_f32_16x16x32_bf16 v[170:173], v[120:123], v[88:91], v[16:19]
	v_mfma_f32_16x16x32_bf16 v[174:177], v[112:115], v[198:201], v[12:15]
	v_mfma_f32_16x16x32_bf16 v[194:197], v[120:123], v[206:209], v[0:3]
	s_barrier
	s_setprio 0
	s_nop 1
	ds_read_b128 v[0:3], v157
	ds_read_b128 v[198:201], v157 offset:256
	ds_read_b128 v[12:15], v158
	ds_read_b128 v[202:205], v158 offset:256
	ds_read_b128 v[16:19], v150 offset:32768
	ds_read_b128 v[28:31], v150 offset:33792
	ds_read_b128 v[32:35], v150 offset:34816
	ds_read_b128 v[44:47], v150 offset:35840
	ds_read_b128 v[48:51], v150 offset:36864
	ds_read_b128 v[206:209], v150 offset:37888
	ds_read_b128 v[234:237], v150 offset:38912
	ds_read_b128 v[238:241], v150 offset:39936
	s_waitcnt vmcnt(2)
	s_waitcnt lgkmcnt(0)
	s_setprio 1
	s_barrier
; #define LDA(dst, b, h) for (int m = 0; m < 4; ++m) { \
;     dst[m][0] = *reinterpret_cast<const bf16x8*>((char*)SA(b, h) + aoff0 + m * 2048); \
;     dst[m][1] = *reinterpret_cast<const bf16x8*>((char*)SA(b, h) + aoff1 + m * 2048); }
; #define LDB(dst, b, h) for (int n = 0; n < 2; ++n) { \
;     dst[n][0] = *reinterpret_cast<const bf16x8*>((char*)SB(b, h) + boff0 + n * 256); \
;     dst[n][1] = *reinterpret_cast<const bf16x8*>((char*)SB(b, h) + boff1 + n * 256); }
; #define MMA(ai, bj, At, Btf) do { __builtin_amdgcn_s_setprio(1); \
;     for (int m = 0; m < 4; ++m) for (int n = 0; n < 2; ++n) for (int k = 0; k < 2; ++k) \
;       acc[ai][bj][m][n] = __builtin_amdgcn_mfma_f32_16x16x32_bf16(Btf[n][k], At[m][k], acc[ai][bj][m][n], 0, 0, 0); \
;     __builtin_amdgcn_s_setprio(0); } while (0)
; #define WAIT_V(n) asm volatile("s_waitcnt vmcnt(" #n ")" ::: "memory")
; #define WAIT_L(n) asm volatile("s_waitcnt lgkmcnt(" #n ")" ::: "memory")
; #define BAR __builtin_amdgcn_s_barrier()
; template <int EPI> ...
;     ...
;     LDA(At, 0, 1); WAIT_V(4); BAR; WAIT_L(0); MMA(1, 0, At, B0); MMA(1, 1, At, B1); BAR; }
;   { LDB(B0, 1, 0); LDA(At, 1, 0); WAIT_V(2); BAR; WAIT_L(0); MMA(0, 0, At, B0); BAR;
;     LDB(B1, 1, 1); WAIT_V(0); BAR; WAIT_L(0); MMA(0, 1, At, B1); BAR;
;     LDA(At, 1, 1); BAR; WAIT_L(0); MMA(1, 0, At, B0); MMA(1, 1, At, B1); BAR; }
;   if (wr == 0) BAR;
	v_mfma_f32_16x16x32_bf16 v[64:67], v[0:3], v[16:19], v[124:127]
	v_mfma_f32_16x16x32_bf16 v[120:123], v[12:15], v[28:31], v[64:67]
	v_mfma_f32_16x16x32_bf16 v[64:67], v[198:201], v[16:19], v[210:213]
	v_mfma_f32_16x16x32_bf16 v[112:115], v[202:205], v[28:31], v[64:67]
	v_mfma_f32_16x16x32_bf16 v[64:67], v[0:3], v[32:35], v[116:119]
	v_mfma_f32_16x16x32_bf16 v[104:107], v[12:15], v[44:47], v[64:67]
	v_mfma_f32_16x16x32_bf16 v[64:67], v[198:201], v[32:35], v[214:217]
	v_mfma_f32_16x16x32_bf16 v[96:99], v[202:205], v[44:47], v[64:67]
	v_mfma_f32_16x16x32_bf16 v[64:67], v[0:3], v[48:51], v[108:111]
	v_mfma_f32_16x16x32_bf16 v[88:91], v[12:15], v[206:209], v[64:67]
	v_mfma_f32_16x16x32_bf16 v[64:67], v[198:201], v[48:51], v[218:221]
	v_mfma_f32_16x16x32_bf16 v[80:83], v[202:205], v[206:209], v[64:67]
	v_mfma_f32_16x16x32_bf16 v[64:67], v[0:3], v[234:237], v[100:103]
	v_mfma_f32_16x16x32_bf16 v[72:75], v[12:15], v[238:241], v[64:67]
	v_mfma_f32_16x16x32_bf16 v[64:67], v[198:201], v[234:237], v[222:225]
	v_mfma_f32_16x16x32_bf16 v[64:67], v[202:205], v[238:241], v[64:67]
	s_barrier
	s_setprio 0
	ds_read_b128 v[210:213], v159
	ds_read_b128 v[214:217], v159 offset:256
	ds_read_b128 v[218:221], v160
	ds_read_b128 v[222:225], v160 offset:256
	s_waitcnt vmcnt(0)
	s_waitcnt lgkmcnt(0)
	s_setprio 1
	s_barrier
	v_mfma_f32_16x16x32_bf16 v[92:95], v[210:213], v[16:19], v[92:95]
	v_mfma_f32_16x16x32_bf16 v[16:19], v[214:217], v[16:19], v[178:181]
	v_mfma_f32_16x16x32_bf16 v[116:119], v[222:225], v[28:31], v[16:19]
	v_mfma_f32_16x16x32_bf16 v[16:19], v[210:213], v[32:35], v[84:87]
	v_mfma_f32_16x16x32_bf16 v[108:111], v[218:221], v[44:47], v[16:19]
	v_mfma_f32_16x16x32_bf16 v[16:19], v[214:217], v[32:35], v[182:185]
	v_mfma_f32_16x16x32_bf16 v[100:103], v[222:225], v[44:47], v[16:19]
	v_mfma_f32_16x16x32_bf16 v[16:19], v[210:213], v[48:51], v[76:79]
	v_mfma_f32_16x16x32_bf16 v[124:127], v[218:221], v[28:31], v[92:95]
	v_mfma_f32_16x16x32_bf16 v[92:95], v[218:221], v[206:209], v[16:19]
	v_mfma_f32_16x16x32_bf16 v[16:19], v[214:217], v[48:51], v[186:189]
	v_mfma_f32_16x16x32_bf16 v[84:87], v[222:225], v[206:209], v[16:19]
	v_mfma_f32_16x16x32_bf16 v[16:19], v[210:213], v[234:237], v[68:71]
	v_mfma_f32_16x16x32_bf16 v[76:79], v[218:221], v[238:241], v[16:19]
	v_mfma_f32_16x16x32_bf16 v[16:19], v[214:217], v[234:237], v[190:193]
	v_mfma_f32_16x16x32_bf16 v[68:71], v[222:225], v[238:241], v[16:19]
	s_barrier
	s_setprio 0
	ds_read_b128 v[178:181], v150 offset:49152
	ds_read_b128 v[182:185], v150 offset:50176
	ds_read_b128 v[186:189], v150 offset:51200
	ds_read_b128 v[190:193], v150 offset:52224
	ds_read_b128 v[206:209], v150 offset:53248
	ds_read_b128 v[234:237], v150 offset:54272
	ds_read_b128 v[238:241], v150 offset:55296
	ds_read_b128 v[242:245], v150 offset:56320
	s_waitcnt lgkmcnt(0)
	s_setprio 1
	s_barrier
	v_mfma_f32_16x16x32_bf16 v[16:19], v[0:3], v[178:181], v[60:63]
	v_mfma_f32_16x16x32_bf16 v[60:63], v[12:15], v[182:185], v[16:19]
	v_mfma_f32_16x16x32_bf16 v[16:19], v[198:201], v[178:181], v[56:59]
	v_mfma_f32_16x16x32_bf16 v[48:51], v[202:205], v[182:185], v[16:19]
	v_mfma_f32_16x16x32_bf16 v[16:19], v[0:3], v[186:189], v[52:55]
	v_mfma_f32_16x16x32_bf16 v[44:47], v[12:15], v[190:193], v[16:19]
	v_mfma_f32_16x16x32_bf16 v[16:19], v[198:201], v[186:189], v[226:229]
	v_mfma_f32_16x16x32_bf16 v[32:35], v[202:205], v[190:193], v[16:19]
	v_mfma_f32_16x16x32_bf16 v[16:19], v[0:3], v[206:209], v[230:233]
	v_mfma_f32_16x16x32_bf16 v[0:3], v[0:3], v[238:241], v[36:39]
	v_mfma_f32_16x16x32_bf16 v[28:31], v[12:15], v[234:237], v[16:19]
	v_mfma_f32_16x16x32_bf16 v[16:19], v[198:201], v[206:209], v[40:43]
	v_mfma_f32_16x16x32_bf16 v[12:15], v[12:15], v[242:245], v[0:3]
	v_mfma_f32_16x16x32_bf16 v[0:3], v[198:201], v[238:241], v[162:165]
	v_mfma_f32_16x16x32_bf16 v[16:19], v[202:205], v[234:237], v[16:19]
	v_mfma_f32_16x16x32_bf16 v[0:3], v[202:205], v[242:245], v[0:3]
	v_mfma_f32_16x16x32_bf16 v[20:23], v[210:213], v[186:189], v[20:23]
	v_mfma_f32_16x16x32_bf16 v[36:39], v[210:213], v[178:181], v[166:169]
	v_mfma_f32_16x16x32_bf16 v[40:43], v[218:221], v[190:193], v[20:23]
	v_mfma_f32_16x16x32_bf16 v[20:23], v[214:217], v[186:189], v[170:173]
	v_mfma_f32_16x16x32_bf16 v[56:59], v[218:221], v[182:185], v[36:39]
	v_mfma_f32_16x16x32_bf16 v[24:27], v[214:217], v[178:181], v[24:27]
	v_mfma_f32_16x16x32_bf16 v[36:39], v[222:225], v[190:193], v[20:23]
	v_mfma_f32_16x16x32_bf16 v[20:23], v[210:213], v[206:209], v[174:177]
	v_mfma_f32_16x16x32_bf16 v[8:11], v[214:217], v[206:209], v[8:11]
	v_mfma_f32_16x16x32_bf16 v[4:7], v[210:213], v[238:241], v[4:7]
	v_mfma_f32_16x16x32_bf16 v[52:55], v[222:225], v[182:185], v[24:27]
	v_mfma_f32_16x16x32_bf16 v[24:27], v[218:221], v[234:237], v[20:23]
	v_mfma_f32_16x16x32_bf16 v[20:23], v[222:225], v[234:237], v[8:11]
	v_mfma_f32_16x16x32_bf16 v[8:11], v[218:221], v[242:245], v[4:7]
	v_mfma_f32_16x16x32_bf16 v[4:7], v[214:217], v[238:241], v[194:197]
	v_mfma_f32_16x16x32_bf16 v[4:7], v[222:225], v[242:245], v[4:7]
	s_barrier
	s_setprio 0
	s_and_saveexec_b64 s[68:69], s[2:3]
	s_cbranch_execz .LBB0_271
	s_barrier
	s_branch .LBB0_271

; #define STAGE(P, BASE, br, kt) do { const char* _gb = (const char*)(BASE) + ((size_t)(br) * K + (size_t)(kt) * BK) * 2; \
;     __builtin_amdgcn_global_load_lds((const unsigned*)(_gb + loff0), (unsigned*)((char*)(P) + tid * 16), 16, 0, 0); \
;     __builtin_amdgcn_global_load_lds((const unsigned*)(_gb + (size_t)K * 128 + loff0), (unsigned*)((char*)(P) + tid * 16 + 8192), 16, 0, 0); } while (0)
; #define LDA(dst, b, h) for (int m = 0; m < 4; ++m) { \
;     dst[m][0] = *reinterpret_cast<const bf16x8*>((char*)SA(b, h) + aoff0 + m * 2048); \
;     dst[m][1] = *reinterpret_cast<const bf16x8*>((char*)SA(b, h) + aoff1 + m * 2048); }
; #define LDB(dst, b, h) for (int n = 0; n < 2; ++n) { \
;     dst[n][0] = *reinterpret_cast<const bf16x8*>((char*)SB(b, h) + boff0 + n * 256); \
;     dst[n][1] = *reinterpret_cast<const bf16x8*>((char*)SB(b, h) + boff1 + n * 256); }
; #define MMA(ai, bj, At, Btf) do { __builtin_amdgcn_s_setprio(1); \
;     for (int m = 0; m < 4; ++m) for (int n = 0; n < 2; ++n) for (int k = 0; k < 2; ++k) \
;       acc[ai][bj][m][n] = __builtin_amdgcn_mfma_f32_16x16x32_bf16(Btf[n][k], At[m][k], acc[ai][bj][m][n], 0, 0, 0); \
;     __builtin_amdgcn_s_setprio(0); } while (0)
; #define WAIT_L(n) asm volatile("s_waitcnt lgkmcnt(" #n ")" ::: "memory")
; #define BAR __builtin_amdgcn_s_barrier()
; #define SCHED __builtin_amdgcn_sched_barrier(0)
; template <int EPI> ...
;     ...
;     LDB(B0, 0, 0); SCHED; LDA(At, 0, 0); STAGE(SA(1, 1), A, brow + HALF, t + 1);
;     WAIT_L(8); BAR; WAIT_L(0); MMA(0, 0, At, B0); BAR; SCHED;
;     LDB(B1, 0, 1); STAGE(SB(0, 0), Bt, bcol, t + 2);
;     BAR; WAIT_L(0); MMA(0, 1, At, B1); BAR;
;     LDA(At, 0, 1); STAGE(SA(0, 0), A, brow, t + 2);
;     BAR; WAIT_L(0); MMA(1, 0, At, B0); BAR; SCHED;
.LBB0_324:
	ds_read_b128 v[160:163], v152
	ds_read_b128 v[164:167], v152 offset:256
	ds_read_b128 v[168:171], v153
	ds_read_b128 v[172:175], v153 offset:256
	v_lshl_add_u64 v[224:225], s[64:65], 0, v[132:133]
	v_readfirstlane_b32 s77, v150
	v_lshl_add_u64 v[208:209], v[224:225], 0, s[16:17]
	s_mov_b32 m0, s77
	v_readfirstlane_b32 s77, v151
	ds_read_b128 v[176:179], v149
	ds_read_b128 v[180:183], v149 offset:1024
	ds_read_b128 v[184:187], v149 offset:2048
	ds_read_b128 v[188:191], v149 offset:3072
	ds_read_b128 v[192:195], v149 offset:4096
	ds_read_b128 v[196:199], v149 offset:5120
	ds_read_b128 v[200:203], v149 offset:6144
	ds_read_b128 v[204:207], v149 offset:7168
	global_load_lds_dwordx4 v[208:209], off
	v_lshl_add_u64 v[208:209], v[224:225], 0, s[18:19]
	s_mov_b32 m0, s77
	s_nop 0
	global_load_lds_dwordx4 v[208:209], off
	s_waitcnt lgkmcnt(8)
	v_readfirstlane_b32 s77, v148
	v_lshl_add_u64 v[246:247], v[228:229], 0, s[58:59]
	s_mov_b32 m0, s77
	s_nop 0
	global_load_lds_dwordx4 v[246:247], off
	ds_read_b128 v[208:211], v154
	ds_read_b128 v[212:215], v154 offset:256
	ds_read_b128 v[216:219], v155
	ds_read_b128 v[220:223], v155 offset:256
	s_waitcnt lgkmcnt(0)
	s_setprio 1
	s_barrier
	v_mfma_f32_16x16x32_bf16 v[124:127], v[160:163], v[176:179], v[124:127]
	v_mfma_f32_16x16x32_bf16 v[120:123], v[164:167], v[176:179], v[120:123]
	v_mfma_f32_16x16x32_bf16 v[116:119], v[160:163], v[184:187], v[116:119]
	v_mfma_f32_16x16x32_bf16 v[112:115], v[164:167], v[184:187], v[112:115]
	v_mfma_f32_16x16x32_bf16 v[108:111], v[160:163], v[192:195], v[108:111]
	v_mfma_f32_16x16x32_bf16 v[104:107], v[164:167], v[192:195], v[104:107]
	v_mfma_f32_16x16x32_bf16 v[100:103], v[160:163], v[200:203], v[100:103]
	v_mfma_f32_16x16x32_bf16 v[96:99], v[164:167], v[200:203], v[96:99]
	v_mfma_f32_16x16x32_bf16 v[124:127], v[168:171], v[180:183], v[124:127]
	v_mfma_f32_16x16x32_bf16 v[120:123], v[172:175], v[180:183], v[120:123]
	v_mfma_f32_16x16x32_bf16 v[116:119], v[168:171], v[188:191], v[116:119]
	v_mfma_f32_16x16x32_bf16 v[112:115], v[172:175], v[188:191], v[112:115]
	v_mfma_f32_16x16x32_bf16 v[108:111], v[168:171], v[196:199], v[108:111]
	v_mfma_f32_16x16x32_bf16 v[104:107], v[172:175], v[196:199], v[104:107]
	v_mfma_f32_16x16x32_bf16 v[100:103], v[168:171], v[204:207], v[100:103]
	v_mfma_f32_16x16x32_bf16 v[96:99], v[172:175], v[204:207], v[96:99]
	v_mfma_f32_16x16x32_bf16 v[92:95], v[208:211], v[176:179], v[92:95]
	v_mfma_f32_16x16x32_bf16 v[88:91], v[212:215], v[176:179], v[88:91]
	v_mfma_f32_16x16x32_bf16 v[84:87], v[208:211], v[184:187], v[84:87]
	v_mfma_f32_16x16x32_bf16 v[80:83], v[212:215], v[184:187], v[80:83]
	v_mfma_f32_16x16x32_bf16 v[76:79], v[208:211], v[192:195], v[76:79]
	v_mfma_f32_16x16x32_bf16 v[72:75], v[212:215], v[192:195], v[72:75]
	v_mfma_f32_16x16x32_bf16 v[68:71], v[208:211], v[200:203], v[68:71]
	v_mfma_f32_16x16x32_bf16 v[64:67], v[212:215], v[200:203], v[64:67]
	v_mfma_f32_16x16x32_bf16 v[92:95], v[216:219], v[180:183], v[92:95]
	v_mfma_f32_16x16x32_bf16 v[88:91], v[220:223], v[180:183], v[88:91]
	v_mfma_f32_16x16x32_bf16 v[84:87], v[216:219], v[188:191], v[84:87]
	v_mfma_f32_16x16x32_bf16 v[80:83], v[220:223], v[188:191], v[80:83]
	v_mfma_f32_16x16x32_bf16 v[76:79], v[216:219], v[196:199], v[76:79]
	v_mfma_f32_16x16x32_bf16 v[72:75], v[220:223], v[196:199], v[72:75]
	v_mfma_f32_16x16x32_bf16 v[68:71], v[216:219], v[204:207], v[68:71]
	v_mfma_f32_16x16x32_bf16 v[64:67], v[220:223], v[204:207], v[64:67]
	s_barrier
	s_setprio 0
	v_lshl_add_u64 v[226:227], s[66:67], 0, v[132:133]
	v_readfirstlane_b32 s77, v135
	v_lshl_add_u64 v[228:229], v[226:227], 0, s[20:21]
	s_mov_b32 m0, s77
	v_readfirstlane_b32 s77, v136
	global_load_lds_dwordx4 v[228:229], off
	v_lshl_add_u64 v[228:229], v[226:227], 0, s[22:23]
	s_mov_b32 m0, s77
	s_nop 0
	global_load_lds_dwordx4 v[228:229], off
	v_readfirstlane_b32 s77, v137
	v_lshl_add_u64 v[228:229], v[224:225], 0, s[26:27]
	s_mov_b32 m0, s77
	v_readfirstlane_b32 s77, v138
	ds_read_b128 v[176:179], v149 offset:16384
	ds_read_b128 v[180:183], v149 offset:17408
	ds_read_b128 v[184:187], v149 offset:18432
	ds_read_b128 v[188:191], v149 offset:19456
	ds_read_b128 v[192:195], v149 offset:20480
	ds_read_b128 v[196:199], v149 offset:21504
	ds_read_b128 v[200:203], v149 offset:22528
	ds_read_b128 v[204:207], v149 offset:23552
	global_load_lds_dwordx4 v[228:229], off
	v_lshl_add_u64 v[228:229], v[224:225], 0, s[28:29]
	s_mov_b32 m0, s77
	s_nop 0
	global_load_lds_dwordx4 v[228:229], off
	v_lshl_add_u64 v[228:229], s[62:63], 0, v[132:133]
	v_readfirstlane_b32 s77, v139
	v_lshl_add_u64 v[246:247], v[228:229], 0, s[30:31]
	s_mov_b32 m0, s77
	v_readfirstlane_b32 s77, v140
	global_load_lds_dwordx4 v[246:247], off
	s_waitcnt vmcnt(5)
	s_waitcnt lgkmcnt(0)
	s_setprio 1
	s_barrier
; #define STAGE(P, BASE, br, kt) do { const char* _gb = (const char*)(BASE) + ((size_t)(br) * K + (size_t)(kt) * BK) * 2; \
;     __builtin_amdgcn_global_load_lds((const unsigned*)(_gb + loff0), (unsigned*)((char*)(P) + tid * 16), 16, 0, 0); \
;     __builtin_amdgcn_global_load_lds((const unsigned*)(_gb + (size_t)K * 128 + loff0), (unsigned*)((char*)(P) + tid * 16 + 8192), 16, 0, 0); } while (0)
; #define LDA(dst, b, h) for (int m = 0; m < 4; ++m) { \
;     dst[m][0] = *reinterpret_cast<const bf16x8*>((char*)SA(b, h) + aoff0 + m * 2048); \
;     dst[m][1] = *reinterpret_cast<const bf16x8*>((char*)SA(b, h) + aoff1 + m * 2048); }
; #define LDB(dst, b, h) for (int n = 0; n < 2; ++n) { \
;     dst[n][0] = *reinterpret_cast<const bf16x8*>((char*)SB(b, h) + boff0 + n * 256); \
;     dst[n][1] = *reinterpret_cast<const bf16x8*>((char*)SB(b, h) + boff1 + n * 256); }
; #define MMA(ai, bj, At, Btf) do { __builtin_amdgcn_s_setprio(1); \
;     for (int m = 0; m < 4; ++m) for (int n = 0; n < 2; ++n) for (int k = 0; k < 2; ++k) \
;       acc[ai][bj][m][n] = __builtin_amdgcn_mfma_f32_16x16x32_bf16(Btf[n][k], At[m][k], acc[ai][bj][m][n], 0, 0, 0); \
;     __builtin_amdgcn_s_setprio(0); } while (0)
; #define WAIT_V(n) asm volatile("s_waitcnt vmcnt(" #n ")" ::: "memory")
; #define WAIT_L(n) asm volatile("s_waitcnt lgkmcnt(" #n ")" ::: "memory")
; #define BAR __builtin_amdgcn_s_barrier()
; #define SCHED __builtin_amdgcn_sched_barrier(0)
; template <int EPI> ...
;     ...
;     BAR; WAIT_L(0); MMA(1, 0, At, B0); BAR; SCHED;
;     STAGE(SB(0, 1), Bt, bcol + HALF, t + 2);
;     WAIT_V(6); BAR; MMA(1, 1, At, B1); BAR;
;     LDB(B0, 1, 0); SCHED; LDA(At, 1, 0); STAGE(SA(0, 1), A, brow + HALF, t + 2);
;     WAIT_L(8); BAR; WAIT_L(0); MMA(0, 0, At, B0); BAR; SCHED;
;     LDB(B1, 1, 1); STAGE(SB(1, 0), Bt, bcol, t + 3);
;     BAR; WAIT_L(0); MMA(0, 1, At, B1); BAR;
	v_mfma_f32_16x16x32_bf16 v[60:63], v[160:163], v[176:179], v[60:63]
	v_mfma_f32_16x16x32_bf16 v[56:59], v[164:167], v[176:179], v[56:59]
	v_mfma_f32_16x16x32_bf16 v[52:55], v[160:163], v[184:187], v[52:55]
	v_mfma_f32_16x16x32_bf16 v[48:51], v[164:167], v[184:187], v[48:51]
	v_mfma_f32_16x16x32_bf16 v[44:47], v[160:163], v[192:195], v[44:47]
	v_mfma_f32_16x16x32_bf16 v[40:43], v[164:167], v[192:195], v[40:43]
	v_mfma_f32_16x16x32_bf16 v[36:39], v[160:163], v[200:203], v[36:39]
	v_mfma_f32_16x16x32_bf16 v[32:35], v[164:167], v[200:203], v[32:35]
	v_mfma_f32_16x16x32_bf16 v[60:63], v[168:171], v[180:183], v[60:63]
	v_mfma_f32_16x16x32_bf16 v[56:59], v[172:175], v[180:183], v[56:59]
	v_mfma_f32_16x16x32_bf16 v[52:55], v[168:171], v[188:191], v[52:55]
	v_mfma_f32_16x16x32_bf16 v[48:51], v[172:175], v[188:191], v[48:51]
	v_mfma_f32_16x16x32_bf16 v[44:47], v[168:171], v[196:199], v[44:47]
	v_mfma_f32_16x16x32_bf16 v[40:43], v[172:175], v[196:199], v[40:43]
	v_mfma_f32_16x16x32_bf16 v[36:39], v[168:171], v[204:207], v[36:39]
	v_mfma_f32_16x16x32_bf16 v[32:35], v[172:175], v[204:207], v[32:35]
	v_mfma_f32_16x16x32_bf16 v[28:31], v[208:211], v[176:179], v[28:31]
	v_mfma_f32_16x16x32_bf16 v[24:27], v[212:215], v[176:179], v[24:27]
	v_mfma_f32_16x16x32_bf16 v[20:23], v[208:211], v[184:187], v[20:23]
	v_mfma_f32_16x16x32_bf16 v[16:19], v[212:215], v[184:187], v[16:19]
	v_mfma_f32_16x16x32_bf16 v[12:15], v[208:211], v[192:195], v[12:15]
	v_mfma_f32_16x16x32_bf16 v[8:11], v[212:215], v[192:195], v[8:11]
	v_mfma_f32_16x16x32_bf16 v[4:7], v[208:211], v[200:203], v[4:7]
	v_mfma_f32_16x16x32_bf16 v[0:3], v[212:215], v[200:203], v[0:3]
	v_mfma_f32_16x16x32_bf16 v[28:31], v[216:219], v[180:183], v[28:31]
	v_mfma_f32_16x16x32_bf16 v[24:27], v[220:223], v[180:183], v[24:27]
	v_mfma_f32_16x16x32_bf16 v[20:23], v[216:219], v[188:191], v[20:23]
	v_mfma_f32_16x16x32_bf16 v[16:19], v[220:223], v[188:191], v[16:19]
	v_mfma_f32_16x16x32_bf16 v[12:15], v[216:219], v[196:199], v[12:15]
	v_mfma_f32_16x16x32_bf16 v[8:11], v[220:223], v[196:199], v[8:11]
	v_mfma_f32_16x16x32_bf16 v[4:7], v[216:219], v[204:207], v[4:7]
	v_mfma_f32_16x16x32_bf16 v[0:3], v[220:223], v[204:207], v[0:3]
	s_barrier
	s_setprio 0
	ds_read_b128 v[160:163], v156
	ds_read_b128 v[164:167], v156 offset:256
	ds_read_b128 v[168:171], v157
	ds_read_b128 v[172:175], v157 offset:256
	v_readfirstlane_b32 s77, v141
	v_lshl_add_u64 v[208:209], v[224:225], 0, s[38:39]
	s_mov_b32 m0, s77
	v_readfirstlane_b32 s77, v142
	ds_read_b128 v[176:179], v149 offset:32768
	ds_read_b128 v[180:183], v149 offset:33792
	ds_read_b128 v[184:187], v149 offset:34816
	ds_read_b128 v[188:191], v149 offset:35840
	ds_read_b128 v[192:195], v149 offset:36864
	ds_read_b128 v[196:199], v149 offset:37888
	ds_read_b128 v[200:203], v149 offset:38912
	ds_read_b128 v[204:207], v149 offset:39936
	global_load_lds_dwordx4 v[208:209], off
	v_lshl_add_u64 v[208:209], v[224:225], 0, s[46:47]
	s_mov_b32 m0, s77
	s_nop 0
	global_load_lds_dwordx4 v[208:209], off
	s_waitcnt lgkmcnt(8)
	v_readfirstlane_b32 s77, v140
	v_lshl_add_u64 v[246:247], v[228:229], 0, s[36:37]
	s_mov_b32 m0, s77
	s_nop 0
	global_load_lds_dwordx4 v[246:247], off
	ds_read_b128 v[208:211], v158
	ds_read_b128 v[212:215], v158 offset:256
	ds_read_b128 v[216:219], v159
	ds_read_b128 v[220:223], v159 offset:256
	s_waitcnt lgkmcnt(0)
	s_setprio 1
	s_barrier
	v_mfma_f32_16x16x32_bf16 v[124:127], v[160:163], v[176:179], v[124:127]
	v_mfma_f32_16x16x32_bf16 v[120:123], v[164:167], v[176:179], v[120:123]
	v_mfma_f32_16x16x32_bf16 v[116:119], v[160:163], v[184:187], v[116:119]
	v_mfma_f32_16x16x32_bf16 v[112:115], v[164:167], v[184:187], v[112:115]
	v_mfma_f32_16x16x32_bf16 v[108:111], v[160:163], v[192:195], v[108:111]
	v_mfma_f32_16x16x32_bf16 v[104:107], v[164:167], v[192:195], v[104:107]
	v_mfma_f32_16x16x32_bf16 v[100:103], v[160:163], v[200:203], v[100:103]
	v_mfma_f32_16x16x32_bf16 v[96:99], v[164:167], v[200:203], v[96:99]
	v_mfma_f32_16x16x32_bf16 v[124:127], v[168:171], v[180:183], v[124:127]
	v_mfma_f32_16x16x32_bf16 v[120:123], v[172:175], v[180:183], v[120:123]
	v_mfma_f32_16x16x32_bf16 v[116:119], v[168:171], v[188:191], v[116:119]
	v_mfma_f32_16x16x32_bf16 v[112:115], v[172:175], v[188:191], v[112:115]
	v_mfma_f32_16x16x32_bf16 v[108:111], v[168:171], v[196:199], v[108:111]
	v_mfma_f32_16x16x32_bf16 v[104:107], v[172:175], v[196:199], v[104:107]
	v_mfma_f32_16x16x32_bf16 v[100:103], v[168:171], v[204:207], v[100:103]
	v_mfma_f32_16x16x32_bf16 v[96:99], v[172:175], v[204:207], v[96:99]
	v_mfma_f32_16x16x32_bf16 v[92:95], v[208:211], v[176:179], v[92:95]
	v_mfma_f32_16x16x32_bf16 v[88:91], v[212:215], v[176:179], v[88:91]
	v_mfma_f32_16x16x32_bf16 v[84:87], v[208:211], v[184:187], v[84:87]
	v_mfma_f32_16x16x32_bf16 v[80:83], v[212:215], v[184:187], v[80:83]
	v_mfma_f32_16x16x32_bf16 v[76:79], v[208:211], v[192:195], v[76:79]
	v_mfma_f32_16x16x32_bf16 v[72:75], v[212:215], v[192:195], v[72:75]
	v_mfma_f32_16x16x32_bf16 v[68:71], v[208:211], v[200:203], v[68:71]
	v_mfma_f32_16x16x32_bf16 v[64:67], v[212:215], v[200:203], v[64:67]
	v_mfma_f32_16x16x32_bf16 v[92:95], v[216:219], v[180:183], v[92:95]
	v_mfma_f32_16x16x32_bf16 v[88:91], v[220:223], v[180:183], v[88:91]
	v_mfma_f32_16x16x32_bf16 v[84:87], v[216:219], v[188:191], v[84:87]
	v_mfma_f32_16x16x32_bf16 v[80:83], v[220:223], v[188:191], v[80:83]
	v_mfma_f32_16x16x32_bf16 v[76:79], v[216:219], v[196:199], v[76:79]
	v_mfma_f32_16x16x32_bf16 v[72:75], v[220:223], v[196:199], v[72:75]
	v_mfma_f32_16x16x32_bf16 v[68:71], v[216:219], v[204:207], v[68:71]
	v_mfma_f32_16x16x32_bf16 v[64:67], v[220:223], v[204:207], v[64:67]
	s_barrier
; #define STAGE(P, BASE, br, kt) do { const char* _gb = (const char*)(BASE) + ((size_t)(br) * K + (size_t)(kt) * BK) * 2; \
;     __builtin_amdgcn_global_load_lds((const unsigned*)(_gb + loff0), (unsigned*)((char*)(P) + tid * 16), 16, 0, 0); \
;     __builtin_amdgcn_global_load_lds((const unsigned*)(_gb + (size_t)K * 128 + loff0), (unsigned*)((char*)(P) + tid * 16 + 8192), 16, 0, 0); } while (0)
; #define LDA(dst, b, h) for (int m = 0; m < 4; ++m) { \
;     dst[m][0] = *reinterpret_cast<const bf16x8*>((char*)SA(b, h) + aoff0 + m * 2048); \
;     dst[m][1] = *reinterpret_cast<const bf16x8*>((char*)SA(b, h) + aoff1 + m * 2048); }
; #define LDB(dst, b, h) for (int n = 0; n < 2; ++n) { \
;     dst[n][0] = *reinterpret_cast<const bf16x8*>((char*)SB(b, h) + boff0 + n * 256); \
;     dst[n][1] = *reinterpret_cast<const bf16x8*>((char*)SB(b, h) + boff1 + n * 256); }
; #define MMA(ai, bj, At, Btf) do { __builtin_amdgcn_s_setprio(1); \
;     for (int m = 0; m < 4; ++m) for (int n = 0; n < 2; ++n) for (int k = 0; k < 2; ++k) \
;       acc[ai][bj][m][n] = __builtin_amdgcn_mfma_f32_16x16x32_bf16(Btf[n][k], At[m][k], acc[ai][bj][m][n], 0, 0, 0); \
;     __builtin_amdgcn_s_setprio(0); } while (0)
; #define WAIT_V(n) asm volatile("s_waitcnt vmcnt(" #n ")" ::: "memory")
; #define WAIT_L(n) asm volatile("s_waitcnt lgkmcnt(" #n ")" ::: "memory")
; #define BAR __builtin_amdgcn_s_barrier()
; #define SCHED __builtin_amdgcn_sched_barrier(0)
; template <int EPI> ...
;     ...
;     LDA(At, 1, 1); STAGE(SA(1, 0), A, brow, t + 3);
;     BAR; WAIT_L(0); MMA(1, 0, At, B0); BAR; SCHED;
;     STAGE(SB(1, 1), Bt, bcol + HALF, t + 3);
;     WAIT_V(6); BAR; MMA(1, 1, At, B1); BAR;
;   }
;   { LDB(B0, 0, 0); LDA(At, 0, 0); STAGE(SA(1, 1), A, brow + HALF, nt - 1);
;     BAR; WAIT_L(0); MMA(0, 0, At, B0); BAR;
	s_setprio 0
	v_readfirstlane_b32 s77, v143
	v_lshl_add_u64 v[230:231], v[226:227], 0, s[48:49]
	s_mov_b32 m0, s77
	v_readfirstlane_b32 s77, v144
	global_load_lds_dwordx4 v[230:231], off
	v_lshl_add_u64 v[226:227], v[226:227], 0, s[50:51]
	s_mov_b32 m0, s77
	s_nop 0
	global_load_lds_dwordx4 v[226:227], off
	v_readfirstlane_b32 s77, v145
	v_lshl_add_u64 v[226:227], v[224:225], 0, s[52:53]
	s_mov_b32 m0, s77
	v_readfirstlane_b32 s77, v146
	ds_read_b128 v[176:179], v149 offset:49152
	ds_read_b128 v[180:183], v149 offset:50176
	ds_read_b128 v[184:187], v149 offset:51200
	ds_read_b128 v[188:191], v149 offset:52224
	ds_read_b128 v[192:195], v149 offset:53248
	ds_read_b128 v[196:199], v149 offset:54272
	ds_read_b128 v[200:203], v149 offset:55296
	ds_read_b128 v[204:207], v149 offset:56320
	global_load_lds_dwordx4 v[226:227], off
	v_lshl_add_u64 v[224:225], v[224:225], 0, s[54:55]
	s_mov_b32 m0, s77
	s_nop 0
	global_load_lds_dwordx4 v[224:225], off
	v_readfirstlane_b32 s77, v147
	v_lshl_add_u64 v[246:247], v[228:229], 0, s[56:57]
	s_mov_b32 m0, s77
	v_readfirstlane_b32 s77, v148
	global_load_lds_dwordx4 v[246:247], off
	s_waitcnt vmcnt(5)
	s_barrier
	s_waitcnt lgkmcnt(0)
	s_setprio 1
	s_waitcnt lgkmcnt(0)
	v_mfma_f32_16x16x32_bf16 v[60:63], v[160:163], v[176:179], v[60:63]
	v_mfma_f32_16x16x32_bf16 v[56:59], v[164:167], v[176:179], v[56:59]
	v_mfma_f32_16x16x32_bf16 v[52:55], v[160:163], v[184:187], v[52:55]
	v_mfma_f32_16x16x32_bf16 v[48:51], v[164:167], v[184:187], v[48:51]
	v_mfma_f32_16x16x32_bf16 v[44:47], v[160:163], v[192:195], v[44:47]
	v_mfma_f32_16x16x32_bf16 v[40:43], v[164:167], v[192:195], v[40:43]
	v_mfma_f32_16x16x32_bf16 v[36:39], v[160:163], v[200:203], v[36:39]
	v_mfma_f32_16x16x32_bf16 v[32:35], v[164:167], v[200:203], v[32:35]
	v_mfma_f32_16x16x32_bf16 v[60:63], v[168:171], v[180:183], v[60:63]
	v_mfma_f32_16x16x32_bf16 v[56:59], v[172:175], v[180:183], v[56:59]
	v_mfma_f32_16x16x32_bf16 v[52:55], v[168:171], v[188:191], v[52:55]
	v_mfma_f32_16x16x32_bf16 v[48:51], v[172:175], v[188:191], v[48:51]
	v_mfma_f32_16x16x32_bf16 v[44:47], v[168:171], v[196:199], v[44:47]
	v_mfma_f32_16x16x32_bf16 v[40:43], v[172:175], v[196:199], v[40:43]
	v_mfma_f32_16x16x32_bf16 v[36:39], v[168:171], v[204:207], v[36:39]
	v_mfma_f32_16x16x32_bf16 v[32:35], v[172:175], v[204:207], v[32:35]
	s_setprio 0
	s_setprio 1
	v_mfma_f32_16x16x32_bf16 v[28:31], v[208:211], v[176:179], v[28:31]
	v_mfma_f32_16x16x32_bf16 v[24:27], v[212:215], v[176:179], v[24:27]
	v_mfma_f32_16x16x32_bf16 v[20:23], v[208:211], v[184:187], v[20:23]
	v_mfma_f32_16x16x32_bf16 v[16:19], v[212:215], v[184:187], v[16:19]
	v_mfma_f32_16x16x32_bf16 v[12:15], v[208:211], v[192:195], v[12:15]
	v_mfma_f32_16x16x32_bf16 v[8:11], v[212:215], v[192:195], v[8:11]
	v_mfma_f32_16x16x32_bf16 v[4:7], v[208:211], v[200:203], v[4:7]
	v_mfma_f32_16x16x32_bf16 v[0:3], v[212:215], v[200:203], v[0:3]
	v_mfma_f32_16x16x32_bf16 v[28:31], v[216:219], v[180:183], v[28:31]
	v_mfma_f32_16x16x32_bf16 v[24:27], v[220:223], v[180:183], v[24:27]
	v_mfma_f32_16x16x32_bf16 v[20:23], v[216:219], v[188:191], v[20:23]
	v_mfma_f32_16x16x32_bf16 v[16:19], v[220:223], v[188:191], v[16:19]
	v_mfma_f32_16x16x32_bf16 v[12:15], v[216:219], v[196:199], v[12:15]
	v_mfma_f32_16x16x32_bf16 v[8:11], v[220:223], v[196:199], v[8:11]
	v_mfma_f32_16x16x32_bf16 v[4:7], v[216:219], v[204:207], v[4:7]
	v_mfma_f32_16x16x32_bf16 v[0:3], v[220:223], v[204:207], v[0:3]
	s_setprio 0
	s_add_i32 s76, s76, 2
	s_add_u32 s62, s62, 0x100
	s_addc_u32 s63, s63, 0
	s_add_u32 s64, s64, 0x100
	s_addc_u32 s65, s65, 0
	s_add_u32 s66, s66, 0x100
	s_addc_u32 s67, s67, 0
	s_cmpk_lt_u32 s76, 0x54
	s_barrier
	s_cbranch_scc1 .LBB0_324
	v_readfirstlane_b32 s77, v148
	v_lshl_add_u64 v[246:247], v[228:229], 0, s[58:59]
	s_mov_b32 m0, s77
	s_nop 0
	global_load_lds_dwordx4 v[246:247], off
	s_add_u32 s62, s70, s75
	s_addc_u32 s63, s71, s74
	v_lshl_add_u64 v[208:209], s[62:63], 0, v[128:129]
	v_readfirstlane_b32 s62, v150
	s_mov_b32 m0, s62
	v_readfirstlane_b32 s62, v151
	ds_read_b128 v[160:163], v152
	ds_read_b128 v[164:167], v152 offset:256
	ds_read_b128 v[168:171], v153
	ds_read_b128 v[172:175], v153 offset:256
	ds_read_b128 v[176:179], v149
	ds_read_b128 v[180:183], v149 offset:1024
	ds_read_b128 v[184:187], v149 offset:2048
	ds_read_b128 v[188:191], v149 offset:3072
	ds_read_b128 v[192:195], v149 offset:4096
	ds_read_b128 v[196:199], v149 offset:5120
	ds_read_b128 v[200:203], v149 offset:6144
	ds_read_b128 v[204:207], v149 offset:7168
	global_load_lds_dwordx4 v[208:209], off
	v_lshl_add_u64 v[208:209], v[208:209], 0, s[8:9]
	s_mov_b32 m0, s62
	s_nop 0
	global_load_lds_dwordx4 v[208:209], off
	s_waitcnt lgkmcnt(0)
	s_setprio 1
	s_barrier
	v_mfma_f32_16x16x32_bf16 v[124:127], v[160:163], v[176:179], v[124:127]
	v_mfma_f32_16x16x32_bf16 v[116:119], v[160:163], v[184:187], v[116:119]
	v_mfma_f32_16x16x32_bf16 v[108:111], v[160:163], v[192:195], v[108:111]
	v_mfma_f32_16x16x32_bf16 v[100:103], v[160:163], v[200:203], v[100:103]
	v_mfma_f32_16x16x32_bf16 v[96:99], v[164:167], v[200:203], v[96:99]
	v_mfma_f32_16x16x32_bf16 v[124:127], v[168:171], v[180:183], v[124:127]
	v_mfma_f32_16x16x32_bf16 v[120:123], v[164:167], v[176:179], v[120:123]
	v_mfma_f32_16x16x32_bf16 v[116:119], v[168:171], v[188:191], v[116:119]
	v_mfma_f32_16x16x32_bf16 v[112:115], v[164:167], v[184:187], v[112:115]
	v_mfma_f32_16x16x32_bf16 v[108:111], v[168:171], v[196:199], v[108:111]
	v_mfma_f32_16x16x32_bf16 v[104:107], v[164:167], v[192:195], v[104:107]
	v_mfma_f32_16x16x32_bf16 v[100:103], v[168:171], v[204:207], v[100:103]
	v_mfma_f32_16x16x32_bf16 v[96:99], v[172:175], v[204:207], v[96:99]
	v_mfma_f32_16x16x32_bf16 v[208:211], v[172:175], v[180:183], v[120:123]
	v_mfma_f32_16x16x32_bf16 v[212:215], v[172:175], v[188:191], v[112:115]
	v_mfma_f32_16x16x32_bf16 v[216:219], v[172:175], v[196:199], v[104:107]
	s_barrier
; #define STAGE(P, BASE, br, kt) do { const char* _gb = (const char*)(BASE) + ((size_t)(br) * K + (size_t)(kt) * BK) * 2; \
;     __builtin_amdgcn_global_load_lds((const unsigned*)(_gb + loff0), (unsigned*)((char*)(P) + tid * 16), 16, 0, 0); \
;     __builtin_amdgcn_global_load_lds((const unsigned*)(_gb + (size_t)K * 128 + loff0), (unsigned*)((char*)(P) + tid * 16 + 8192), 16, 0, 0); } while (0)
; #define LDA(dst, b, h) for (int m = 0; m < 4; ++m) { \
;     dst[m][0] = *reinterpret_cast<const bf16x8*>((char*)SA(b, h) + aoff0 + m * 2048); \
;     dst[m][1] = *reinterpret_cast<const bf16x8*>((char*)SA(b, h) + aoff1 + m * 2048); }
; #define LDB(dst, b, h) for (int n = 0; n < 2; ++n) { \
;     dst[n][0] = *reinterpret_cast<const bf16x8*>((char*)SB(b, h) + boff0 + n * 256); \
;     dst[n][1] = *reinterpret_cast<const bf16x8*>((char*)SB(b, h) + boff1 + n * 256); }
; #define MMA(ai, bj, At, Btf) do { __builtin_amdgcn_s_setprio(1); \
;     for (int m = 0; m < 4; ++m) for (int n = 0; n < 2; ++n) for (int k = 0; k < 2; ++k) \
;       acc[ai][bj][m][n] = __builtin_amdgcn_mfma_f32_16x16x32_bf16(Btf[n][k], At[m][k], acc[ai][bj][m][n], 0, 0, 0); \
;     __builtin_amdgcn_s_setprio(0); } while (0)
; #define WAIT_V(n) asm volatile("s_waitcnt vmcnt(" #n ")" ::: "memory")
; #define WAIT_L(n) asm volatile("s_waitcnt lgkmcnt(" #n ")" ::: "memory")
; #define BAR __builtin_amdgcn_s_barrier()
; template <int EPI> ...
;     ...
;   { LDB(B0, 0, 0); LDA(At, 0, 0); STAGE(SA(1, 1), A, brow + HALF, nt - 1);
;     BAR; WAIT_L(0); MMA(0, 0, At, B0); BAR;
;     LDB(B1, 0, 1); BAR; WAIT_L(0); MMA(0, 1, At, B1); BAR;
;     LDA(At, 0, 1); WAIT_V(4); BAR; WAIT_L(0); MMA(1, 0, At, B0); MMA(1, 1, At, B1); BAR; }
;   { LDB(B0, 1, 0); LDA(At, 1, 0); WAIT_V(2); BAR; WAIT_L(0); MMA(0, 0, At, B0); BAR;
;     LDB(B1, 1, 1); WAIT_V(0); BAR; WAIT_L(0); MMA(0, 1, At, B1); BAR;
	s_setprio 0
	s_nop 0
	ds_read_b128 v[104:107], v154
	ds_read_b128 v[112:115], v154 offset:256
	ds_read_b128 v[120:123], v155
	ds_read_b128 v[220:223], v155 offset:256
	s_waitcnt lgkmcnt(0)
	s_setprio 1
	s_barrier
	v_mfma_f32_16x16x32_bf16 v[84:87], v[104:107], v[184:187], v[84:87]
	v_mfma_f32_16x16x32_bf16 v[76:79], v[104:107], v[192:195], v[76:79]
	v_mfma_f32_16x16x32_bf16 v[72:75], v[112:115], v[192:195], v[72:75]
	v_mfma_f32_16x16x32_bf16 v[92:95], v[104:107], v[176:179], v[92:95]
	v_mfma_f32_16x16x32_bf16 v[88:91], v[112:115], v[176:179], v[88:91]
	v_mfma_f32_16x16x32_bf16 v[84:87], v[120:123], v[188:191], v[84:87]
	v_mfma_f32_16x16x32_bf16 v[80:83], v[112:115], v[184:187], v[80:83]
	v_mfma_f32_16x16x32_bf16 v[76:79], v[120:123], v[196:199], v[76:79]
	v_mfma_f32_16x16x32_bf16 v[72:75], v[220:223], v[196:199], v[72:75]
	v_mfma_f32_16x16x32_bf16 v[68:71], v[104:107], v[200:203], v[68:71]
	v_mfma_f32_16x16x32_bf16 v[64:67], v[112:115], v[200:203], v[64:67]
	v_mfma_f32_16x16x32_bf16 v[224:227], v[120:123], v[180:183], v[92:95]
	v_mfma_f32_16x16x32_bf16 v[176:179], v[220:223], v[180:183], v[88:91]
	v_mfma_f32_16x16x32_bf16 v[180:183], v[220:223], v[188:191], v[80:83]
	v_mfma_f32_16x16x32_bf16 v[184:187], v[120:123], v[204:207], v[68:71]
	v_mfma_f32_16x16x32_bf16 v[188:191], v[220:223], v[204:207], v[64:67]
	s_barrier
	s_setprio 0
	s_nop 0
	ds_read_b128 v[64:67], v149 offset:16384
	ds_read_b128 v[68:71], v149 offset:17408
	ds_read_b128 v[80:83], v149 offset:18432
	ds_read_b128 v[88:91], v149 offset:19456
	ds_read_b128 v[92:95], v149 offset:20480
	ds_read_b128 v[192:195], v149 offset:21504
	ds_read_b128 v[196:199], v149 offset:22528
	ds_read_b128 v[200:203], v149 offset:23552
	s_waitcnt vmcnt(4)
	s_waitcnt lgkmcnt(0)
	s_setprio 1
	s_barrier
	v_mfma_f32_16x16x32_bf16 v[52:55], v[160:163], v[80:83], v[52:55]
	v_mfma_f32_16x16x32_bf16 v[44:47], v[160:163], v[92:95], v[44:47]
	v_mfma_f32_16x16x32_bf16 v[36:39], v[160:163], v[196:199], v[36:39]
	v_mfma_f32_16x16x32_bf16 v[60:63], v[160:163], v[64:67], v[60:63]
	v_mfma_f32_16x16x32_bf16 v[56:59], v[164:167], v[64:67], v[56:59]
	v_mfma_f32_16x16x32_bf16 v[52:55], v[168:171], v[88:91], v[52:55]
	v_mfma_f32_16x16x32_bf16 v[48:51], v[164:167], v[80:83], v[48:51]
	v_mfma_f32_16x16x32_bf16 v[44:47], v[168:171], v[192:195], v[44:47]
	v_mfma_f32_16x16x32_bf16 v[40:43], v[164:167], v[92:95], v[40:43]
	v_mfma_f32_16x16x32_bf16 v[36:39], v[168:171], v[200:203], v[36:39]
	v_mfma_f32_16x16x32_bf16 v[32:35], v[164:167], v[196:199], v[32:35]
	v_mfma_f32_16x16x32_bf16 v[204:207], v[168:171], v[68:71], v[60:63]
	v_mfma_f32_16x16x32_bf16 v[228:231], v[172:175], v[68:71], v[56:59]
	v_mfma_f32_16x16x32_bf16 v[232:235], v[172:175], v[88:91], v[48:51]
	v_mfma_f32_16x16x32_bf16 v[236:239], v[172:175], v[192:195], v[40:43]
	v_mfma_f32_16x16x32_bf16 v[160:163], v[172:175], v[200:203], v[32:35]
	v_mfma_f32_16x16x32_bf16 v[28:31], v[104:107], v[64:67], v[28:31]
	v_mfma_f32_16x16x32_bf16 v[20:23], v[104:107], v[80:83], v[20:23]
	v_mfma_f32_16x16x32_bf16 v[12:15], v[104:107], v[92:95], v[12:15]
	v_mfma_f32_16x16x32_bf16 v[4:7], v[104:107], v[196:199], v[4:7]
	v_mfma_f32_16x16x32_bf16 v[28:31], v[120:123], v[68:71], v[28:31]
	v_mfma_f32_16x16x32_bf16 v[24:27], v[112:115], v[64:67], v[24:27]
	v_mfma_f32_16x16x32_bf16 v[20:23], v[120:123], v[88:91], v[20:23]
	v_mfma_f32_16x16x32_bf16 v[16:19], v[112:115], v[80:83], v[16:19]
	v_mfma_f32_16x16x32_bf16 v[12:15], v[120:123], v[192:195], v[12:15]
	v_mfma_f32_16x16x32_bf16 v[8:11], v[112:115], v[92:95], v[8:11]
	v_mfma_f32_16x16x32_bf16 v[4:7], v[120:123], v[200:203], v[4:7]
	v_mfma_f32_16x16x32_bf16 v[0:3], v[112:115], v[196:199], v[0:3]
	v_mfma_f32_16x16x32_bf16 v[164:167], v[220:223], v[68:71], v[24:27]
	v_mfma_f32_16x16x32_bf16 v[168:171], v[220:223], v[88:91], v[16:19]
	v_mfma_f32_16x16x32_bf16 v[172:175], v[220:223], v[192:195], v[8:11]
	v_mfma_f32_16x16x32_bf16 v[192:195], v[220:223], v[200:203], v[0:3]
	s_barrier
	s_setprio 0
	s_nop 1
	ds_read_b128 v[0:3], v156
	ds_read_b128 v[8:11], v156 offset:256
	ds_read_b128 v[16:19], v157
	ds_read_b128 v[24:27], v157 offset:256
	ds_read_b128 v[32:35], v149 offset:32768
	ds_read_b128 v[40:43], v149 offset:33792
	ds_read_b128 v[48:51], v149 offset:34816
	ds_read_b128 v[56:59], v149 offset:35840
	ds_read_b128 v[60:63], v149 offset:36864
	ds_read_b128 v[68:71], v149 offset:37888
	ds_read_b128 v[196:199], v149 offset:38912
	ds_read_b128 v[200:203], v149 offset:39936
	s_waitcnt vmcnt(2)
	s_waitcnt lgkmcnt(0)
	s_setprio 1
	s_barrier
; #define LDA(dst, b, h) for (int m = 0; m < 4; ++m) { \
;     dst[m][0] = *reinterpret_cast<const bf16x8*>((char*)SA(b, h) + aoff0 + m * 2048); \
;     dst[m][1] = *reinterpret_cast<const bf16x8*>((char*)SA(b, h) + aoff1 + m * 2048); }
; #define LDB(dst, b, h) for (int n = 0; n < 2; ++n) { \
;     dst[n][0] = *reinterpret_cast<const bf16x8*>((char*)SB(b, h) + boff0 + n * 256); \
;     dst[n][1] = *reinterpret_cast<const bf16x8*>((char*)SB(b, h) + boff1 + n * 256); }
; #define MMA(ai, bj, At, Btf) do { __builtin_amdgcn_s_setprio(1); \
;     for (int m = 0; m < 4; ++m) for (int n = 0; n < 2; ++n) for (int k = 0; k < 2; ++k) \
;       acc[ai][bj][m][n] = __builtin_amdgcn_mfma_f32_16x16x32_bf16(Btf[n][k], At[m][k], acc[ai][bj][m][n], 0, 0, 0); \
;     __builtin_amdgcn_s_setprio(0); } while (0)
; #define WAIT_V(n) asm volatile("s_waitcnt vmcnt(" #n ")" ::: "memory")
; #define WAIT_L(n) asm volatile("s_waitcnt lgkmcnt(" #n ")" ::: "memory")
; #define BAR __builtin_amdgcn_s_barrier()
; template <int EPI> ...
;     ...
;     LDA(At, 0, 1); WAIT_V(4); BAR; WAIT_L(0); MMA(1, 0, At, B0); MMA(1, 1, At, B1); BAR; }
;   { LDB(B0, 1, 0); LDA(At, 1, 0); WAIT_V(2); BAR; WAIT_L(0); MMA(0, 0, At, B0); BAR;
;     LDB(B1, 1, 1); WAIT_V(0); BAR; WAIT_L(0); MMA(0, 1, At, B1); BAR;
;     LDA(At, 1, 1); BAR; WAIT_L(0); MMA(1, 0, At, B0); MMA(1, 1, At, B1); BAR; }
;   if (wr == 0) BAR;
	v_mfma_f32_16x16x32_bf16 v[64:67], v[0:3], v[32:35], v[124:127]
	v_mfma_f32_16x16x32_bf16 v[120:123], v[16:19], v[40:43], v[64:67]
	v_mfma_f32_16x16x32_bf16 v[64:67], v[8:11], v[32:35], v[208:211]
	v_mfma_f32_16x16x32_bf16 v[124:127], v[24:27], v[40:43], v[64:67]
	v_mfma_f32_16x16x32_bf16 v[64:67], v[0:3], v[48:51], v[116:119]
	v_mfma_f32_16x16x32_bf16 v[112:115], v[16:19], v[56:59], v[64:67]
	v_mfma_f32_16x16x32_bf16 v[64:67], v[8:11], v[48:51], v[212:215]
	v_mfma_f32_16x16x32_bf16 v[116:119], v[24:27], v[56:59], v[64:67]
	v_mfma_f32_16x16x32_bf16 v[64:67], v[0:3], v[60:63], v[108:111]
	v_mfma_f32_16x16x32_bf16 v[104:107], v[16:19], v[68:71], v[64:67]
	v_mfma_f32_16x16x32_bf16 v[64:67], v[8:11], v[60:63], v[216:219]
	v_mfma_f32_16x16x32_bf16 v[108:111], v[24:27], v[68:71], v[64:67]
	v_mfma_f32_16x16x32_bf16 v[64:67], v[0:3], v[196:199], v[100:103]
	v_mfma_f32_16x16x32_bf16 v[88:91], v[16:19], v[200:203], v[64:67]
	v_mfma_f32_16x16x32_bf16 v[64:67], v[8:11], v[196:199], v[96:99]
	v_mfma_f32_16x16x32_bf16 v[92:95], v[24:27], v[200:203], v[64:67]
	s_barrier
	s_setprio 0
	ds_read_b128 v[208:211], v158
	ds_read_b128 v[212:215], v158 offset:256
	ds_read_b128 v[216:219], v159
	ds_read_b128 v[220:223], v159 offset:256
	s_waitcnt vmcnt(0)
	s_waitcnt lgkmcnt(0)
	s_setprio 1
	s_barrier
	v_mfma_f32_16x16x32_bf16 v[64:67], v[208:211], v[32:35], v[224:227]
	v_mfma_f32_16x16x32_bf16 v[32:35], v[212:215], v[32:35], v[176:179]
	v_mfma_f32_16x16x32_bf16 v[100:103], v[220:223], v[40:43], v[32:35]
	v_mfma_f32_16x16x32_bf16 v[32:35], v[208:211], v[48:51], v[84:87]
	v_mfma_f32_16x16x32_bf16 v[80:83], v[216:219], v[56:59], v[32:35]
	v_mfma_f32_16x16x32_bf16 v[32:35], v[212:215], v[48:51], v[180:183]
	v_mfma_f32_16x16x32_bf16 v[84:87], v[220:223], v[56:59], v[32:35]
	v_mfma_f32_16x16x32_bf16 v[32:35], v[208:211], v[60:63], v[76:79]
	v_mfma_f32_16x16x32_bf16 v[96:99], v[216:219], v[40:43], v[64:67]
	v_mfma_f32_16x16x32_bf16 v[64:67], v[216:219], v[68:71], v[32:35]
	v_mfma_f32_16x16x32_bf16 v[32:35], v[212:215], v[60:63], v[72:75]
	v_mfma_f32_16x16x32_bf16 v[68:71], v[220:223], v[68:71], v[32:35]
	v_mfma_f32_16x16x32_bf16 v[32:35], v[208:211], v[196:199], v[184:187]
	v_mfma_f32_16x16x32_bf16 v[56:59], v[216:219], v[200:203], v[32:35]
	v_mfma_f32_16x16x32_bf16 v[32:35], v[212:215], v[196:199], v[188:191]
	v_mfma_f32_16x16x32_bf16 v[60:63], v[220:223], v[200:203], v[32:35]
	s_barrier
	s_setprio 0
	ds_read_b128 v[176:179], v149 offset:49152
	ds_read_b128 v[180:183], v149 offset:50176
	ds_read_b128 v[184:187], v149 offset:51200
	ds_read_b128 v[188:191], v149 offset:52224
	ds_read_b128 v[196:199], v149 offset:53248
	ds_read_b128 v[200:203], v149 offset:54272
	ds_read_b128 v[224:227], v149 offset:55296
	ds_read_b128 v[240:243], v149 offset:56320
	s_waitcnt lgkmcnt(0)
	s_setprio 1
	s_barrier
	v_mfma_f32_16x16x32_bf16 v[32:35], v[0:3], v[176:179], v[204:207]
	v_mfma_f32_16x16x32_bf16 v[72:75], v[16:19], v[180:183], v[32:35]
	v_mfma_f32_16x16x32_bf16 v[32:35], v[8:11], v[176:179], v[228:231]
	v_mfma_f32_16x16x32_bf16 v[76:79], v[24:27], v[180:183], v[32:35]
	v_mfma_f32_16x16x32_bf16 v[32:35], v[0:3], v[184:187], v[52:55]
	v_mfma_f32_16x16x32_bf16 v[48:51], v[16:19], v[188:191], v[32:35]
	v_mfma_f32_16x16x32_bf16 v[32:35], v[8:11], v[184:187], v[232:235]
	v_mfma_f32_16x16x32_bf16 v[52:55], v[24:27], v[188:191], v[32:35]
	v_mfma_f32_16x16x32_bf16 v[32:35], v[0:3], v[196:199], v[44:47]
	v_mfma_f32_16x16x32_bf16 v[40:43], v[16:19], v[200:203], v[32:35]
	v_mfma_f32_16x16x32_bf16 v[32:35], v[8:11], v[196:199], v[236:239]
	v_mfma_f32_16x16x32_bf16 v[0:3], v[0:3], v[224:227], v[36:39]
	v_mfma_f32_16x16x32_bf16 v[44:47], v[24:27], v[200:203], v[32:35]
	v_mfma_f32_16x16x32_bf16 v[32:35], v[16:19], v[240:243], v[0:3]
	v_mfma_f32_16x16x32_bf16 v[0:3], v[8:11], v[224:227], v[160:163]
	v_mfma_f32_16x16x32_bf16 v[36:39], v[24:27], v[240:243], v[0:3]
	v_mfma_f32_16x16x32_bf16 v[0:3], v[208:211], v[176:179], v[28:31]
	v_mfma_f32_16x16x32_bf16 v[24:27], v[216:219], v[180:183], v[0:3]
	v_mfma_f32_16x16x32_bf16 v[0:3], v[212:215], v[176:179], v[164:167]
	v_mfma_f32_16x16x32_bf16 v[28:31], v[220:223], v[180:183], v[0:3]
	v_mfma_f32_16x16x32_bf16 v[0:3], v[208:211], v[184:187], v[20:23]
	v_mfma_f32_16x16x32_bf16 v[16:19], v[216:219], v[188:191], v[0:3]
	v_mfma_f32_16x16x32_bf16 v[0:3], v[212:215], v[184:187], v[168:171]
	v_mfma_f32_16x16x32_bf16 v[20:23], v[220:223], v[188:191], v[0:3]
	v_mfma_f32_16x16x32_bf16 v[0:3], v[208:211], v[196:199], v[12:15]
	v_mfma_f32_16x16x32_bf16 v[8:11], v[216:219], v[200:203], v[0:3]
	v_mfma_f32_16x16x32_bf16 v[0:3], v[212:215], v[196:199], v[172:175]
	v_mfma_f32_16x16x32_bf16 v[12:15], v[220:223], v[200:203], v[0:3]
	v_mfma_f32_16x16x32_bf16 v[0:3], v[208:211], v[224:227], v[4:7]
	v_mfma_f32_16x16x32_bf16 v[4:7], v[212:215], v[224:227], v[192:195]
	v_mfma_f32_16x16x32_bf16 v[0:3], v[216:219], v[240:243], v[0:3]
	v_mfma_f32_16x16x32_bf16 v[4:7], v[220:223], v[240:243], v[4:7]
	s_barrier
	s_setprio 0
	s_and_saveexec_b64 s[62:63], s[2:3]
	s_cbranch_execz .LBB0_318
	s_barrier
	s_branch .LBB0_318

; #define STAGE(P, BASE, br, kt) do { const char* _gb = (const char*)(BASE) + ((size_t)(br) * K + (size_t)(kt) * BK) * 2; \
;     __builtin_amdgcn_global_load_lds((const unsigned*)(_gb + loff0), (unsigned*)((char*)(P) + tid * 16), 16, 0, 0); \
;     __builtin_amdgcn_global_load_lds((const unsigned*)(_gb + (size_t)K * 128 + loff0), (unsigned*)((char*)(P) + tid * 16 + 8192), 16, 0, 0); } while (0)
; #define LDA(dst, b, h) for (int m = 0; m < 4; ++m) { \
;     dst[m][0] = *reinterpret_cast<const bf16x8*>((char*)SA(b, h) + aoff0 + m * 2048); \
;     dst[m][1] = *reinterpret_cast<const bf16x8*>((char*)SA(b, h) + aoff1 + m * 2048); }
; #define LDB(dst, b, h) for (int n = 0; n < 2; ++n) { \
;     dst[n][0] = *reinterpret_cast<const bf16x8*>((char*)SB(b, h) + boff0 + n * 256); \
;     dst[n][1] = *reinterpret_cast<const bf16x8*>((char*)SB(b, h) + boff1 + n * 256); }
; #define MMA(ai, bj, At, Btf) do { __builtin_amdgcn_s_setprio(1); \
;     for (int m = 0; m < 4; ++m) for (int n = 0; n < 2; ++n) for (int k = 0; k < 2; ++k) \
;       acc[ai][bj][m][n] = __builtin_amdgcn_mfma_f32_16x16x32_bf16(Btf[n][k], At[m][k], acc[ai][bj][m][n], 0, 0, 0); \
;     __builtin_amdgcn_s_setprio(0); } while (0)
; #define WAIT_L(n) asm volatile("s_waitcnt lgkmcnt(" #n ")" ::: "memory")
; #define BAR __builtin_amdgcn_s_barrier()
; #define SCHED __builtin_amdgcn_sched_barrier(0)
; template <int EPI> ...
;     ...
;     LDB(B0, 0, 0); SCHED; LDA(At, 0, 0); STAGE(SA(1, 1), A, brow + HALF, t + 1);
;     WAIT_L(8); BAR; WAIT_L(0); MMA(0, 0, At, B0); BAR; SCHED;
;     LDB(B1, 0, 1); STAGE(SB(0, 0), Bt, bcol, t + 2);
;     BAR; WAIT_L(0); MMA(0, 1, At, B1); BAR;
;     LDA(At, 0, 1); STAGE(SA(0, 0), A, brow, t + 2);
;     BAR; WAIT_L(0); MMA(1, 0, At, B0); BAR; SCHED;
.LBB0_411:
	ds_read_b128 v[160:163], v152
	ds_read_b128 v[164:167], v152 offset:256
	ds_read_b128 v[168:171], v153
	ds_read_b128 v[172:175], v153 offset:256
	v_lshl_add_u64 v[224:225], s[68:69], 0, v[132:133]
	v_readfirstlane_b32 s70, v150
	v_lshl_add_u64 v[208:209], v[224:225], 0, s[16:17]
	s_mov_b32 m0, s70
	v_readfirstlane_b32 s70, v151
	ds_read_b128 v[176:179], v149
	ds_read_b128 v[180:183], v149 offset:1024
	ds_read_b128 v[184:187], v149 offset:2048
	ds_read_b128 v[188:191], v149 offset:3072
	ds_read_b128 v[192:195], v149 offset:4096
	ds_read_b128 v[196:199], v149 offset:5120
	ds_read_b128 v[200:203], v149 offset:6144
	ds_read_b128 v[204:207], v149 offset:7168
	global_load_lds_dwordx4 v[208:209], off
	v_lshl_add_u64 v[208:209], v[224:225], 0, s[18:19]
	s_mov_b32 m0, s70
	s_nop 0
	global_load_lds_dwordx4 v[208:209], off
	s_waitcnt lgkmcnt(8)
	v_readfirstlane_b32 s70, v148
	v_lshl_add_u64 v[246:247], v[226:227], 0, s[58:59]
	s_mov_b32 m0, s70
	s_nop 0
	global_load_lds_dwordx4 v[246:247], off
	ds_read_b128 v[208:211], v154
	ds_read_b128 v[212:215], v154 offset:256
	ds_read_b128 v[216:219], v155
	ds_read_b128 v[220:223], v155 offset:256
	s_waitcnt lgkmcnt(0)
	s_setprio 1
	s_barrier
	v_mfma_f32_16x16x32_bf16 v[124:127], v[160:163], v[176:179], v[124:127]
	v_mfma_f32_16x16x32_bf16 v[120:123], v[164:167], v[176:179], v[120:123]
	v_mfma_f32_16x16x32_bf16 v[116:119], v[160:163], v[184:187], v[116:119]
	v_mfma_f32_16x16x32_bf16 v[112:115], v[164:167], v[184:187], v[112:115]
	v_mfma_f32_16x16x32_bf16 v[108:111], v[160:163], v[192:195], v[108:111]
	v_mfma_f32_16x16x32_bf16 v[104:107], v[164:167], v[192:195], v[104:107]
	v_mfma_f32_16x16x32_bf16 v[100:103], v[160:163], v[200:203], v[100:103]
	v_mfma_f32_16x16x32_bf16 v[96:99], v[164:167], v[200:203], v[96:99]
	v_mfma_f32_16x16x32_bf16 v[124:127], v[168:171], v[180:183], v[124:127]
	v_mfma_f32_16x16x32_bf16 v[120:123], v[172:175], v[180:183], v[120:123]
	v_mfma_f32_16x16x32_bf16 v[116:119], v[168:171], v[188:191], v[116:119]
	v_mfma_f32_16x16x32_bf16 v[112:115], v[172:175], v[188:191], v[112:115]
	v_mfma_f32_16x16x32_bf16 v[108:111], v[168:171], v[196:199], v[108:111]
	v_mfma_f32_16x16x32_bf16 v[104:107], v[172:175], v[196:199], v[104:107]
	v_mfma_f32_16x16x32_bf16 v[100:103], v[168:171], v[204:207], v[100:103]
	v_mfma_f32_16x16x32_bf16 v[96:99], v[172:175], v[204:207], v[96:99]
	v_mfma_f32_16x16x32_bf16 v[92:95], v[208:211], v[176:179], v[92:95]
	v_mfma_f32_16x16x32_bf16 v[88:91], v[212:215], v[176:179], v[88:91]
	v_mfma_f32_16x16x32_bf16 v[84:87], v[208:211], v[184:187], v[84:87]
	v_mfma_f32_16x16x32_bf16 v[80:83], v[212:215], v[184:187], v[80:83]
	v_mfma_f32_16x16x32_bf16 v[76:79], v[208:211], v[192:195], v[76:79]
	v_mfma_f32_16x16x32_bf16 v[72:75], v[212:215], v[192:195], v[72:75]
	v_mfma_f32_16x16x32_bf16 v[68:71], v[208:211], v[200:203], v[68:71]
	v_mfma_f32_16x16x32_bf16 v[64:67], v[212:215], v[200:203], v[64:67]
	v_mfma_f32_16x16x32_bf16 v[92:95], v[216:219], v[180:183], v[92:95]
	v_mfma_f32_16x16x32_bf16 v[88:91], v[220:223], v[180:183], v[88:91]
	v_mfma_f32_16x16x32_bf16 v[84:87], v[216:219], v[188:191], v[84:87]
	v_mfma_f32_16x16x32_bf16 v[80:83], v[220:223], v[188:191], v[80:83]
	v_mfma_f32_16x16x32_bf16 v[76:79], v[216:219], v[196:199], v[76:79]
	v_mfma_f32_16x16x32_bf16 v[72:75], v[220:223], v[196:199], v[72:75]
	v_mfma_f32_16x16x32_bf16 v[68:71], v[216:219], v[204:207], v[68:71]
	v_mfma_f32_16x16x32_bf16 v[64:67], v[220:223], v[204:207], v[64:67]
	s_barrier
	s_setprio 0
	v_lshl_add_u64 v[226:227], s[66:67], 0, v[132:133]
	v_readfirstlane_b32 s70, v135
	v_lshl_add_u64 v[228:229], v[226:227], 0, s[20:21]
	s_mov_b32 m0, s70
	v_readfirstlane_b32 s70, v136
	global_load_lds_dwordx4 v[228:229], off
	v_lshl_add_u64 v[228:229], v[226:227], 0, s[22:23]
	s_mov_b32 m0, s70
	s_nop 0
	global_load_lds_dwordx4 v[228:229], off
	v_readfirstlane_b32 s70, v137
	v_lshl_add_u64 v[228:229], v[224:225], 0, s[26:27]
	s_mov_b32 m0, s70
	v_readfirstlane_b32 s70, v138
	ds_read_b128 v[176:179], v149 offset:16384
	ds_read_b128 v[180:183], v149 offset:17408
	ds_read_b128 v[184:187], v149 offset:18432
	ds_read_b128 v[188:191], v149 offset:19456
	ds_read_b128 v[192:195], v149 offset:20480
	ds_read_b128 v[196:199], v149 offset:21504
	ds_read_b128 v[200:203], v149 offset:22528
	ds_read_b128 v[204:207], v149 offset:23552
	global_load_lds_dwordx4 v[228:229], off
	v_lshl_add_u64 v[228:229], v[224:225], 0, s[28:29]
	s_mov_b32 m0, s70
	s_nop 0
	global_load_lds_dwordx4 v[228:229], off
	v_readfirstlane_b32 s70, v139
	v_lshl_add_u64 v[246:247], v[226:227], 0, s[30:31]
	s_mov_b32 m0, s70
	v_readfirstlane_b32 s70, v140
	global_load_lds_dwordx4 v[246:247], off
	s_waitcnt vmcnt(5)
	s_waitcnt lgkmcnt(0)
	s_setprio 1
	s_barrier
; #define STAGE(P, BASE, br, kt) do { const char* _gb = (const char*)(BASE) + ((size_t)(br) * K + (size_t)(kt) * BK) * 2; \
;     __builtin_amdgcn_global_load_lds((const unsigned*)(_gb + loff0), (unsigned*)((char*)(P) + tid * 16), 16, 0, 0); \
;     __builtin_amdgcn_global_load_lds((const unsigned*)(_gb + (size_t)K * 128 + loff0), (unsigned*)((char*)(P) + tid * 16 + 8192), 16, 0, 0); } while (0)
; #define LDA(dst, b, h) for (int m = 0; m < 4; ++m) { \
;     dst[m][0] = *reinterpret_cast<const bf16x8*>((char*)SA(b, h) + aoff0 + m * 2048); \
;     dst[m][1] = *reinterpret_cast<const bf16x8*>((char*)SA(b, h) + aoff1 + m * 2048); }
; #define LDB(dst, b, h) for (int n = 0; n < 2; ++n) { \
;     dst[n][0] = *reinterpret_cast<const bf16x8*>((char*)SB(b, h) + boff0 + n * 256); \
;     dst[n][1] = *reinterpret_cast<const bf16x8*>((char*)SB(b, h) + boff1 + n * 256); }
; #define MMA(ai, bj, At, Btf) do { __builtin_amdgcn_s_setprio(1); \
;     for (int m = 0; m < 4; ++m) for (int n = 0; n < 2; ++n) for (int k = 0; k < 2; ++k) \
;       acc[ai][bj][m][n] = __builtin_amdgcn_mfma_f32_16x16x32_bf16(Btf[n][k], At[m][k], acc[ai][bj][m][n], 0, 0, 0); \
;     __builtin_amdgcn_s_setprio(0); } while (0)
; #define WAIT_V(n) asm volatile("s_waitcnt vmcnt(" #n ")" ::: "memory")
; #define WAIT_L(n) asm volatile("s_waitcnt lgkmcnt(" #n ")" ::: "memory")
; #define BAR __builtin_amdgcn_s_barrier()
; #define SCHED __builtin_amdgcn_sched_barrier(0)
; template <int EPI> ...
;     ...
;     BAR; WAIT_L(0); MMA(1, 0, At, B0); BAR; SCHED;
;     STAGE(SB(0, 1), Bt, bcol + HALF, t + 2);
;     WAIT_V(6); BAR; MMA(1, 1, At, B1); BAR;
;     LDB(B0, 1, 0); SCHED; LDA(At, 1, 0); STAGE(SA(0, 1), A, brow + HALF, t + 2);
;     WAIT_L(8); BAR; WAIT_L(0); MMA(0, 0, At, B0); BAR; SCHED;
;     LDB(B1, 1, 1); STAGE(SB(1, 0), Bt, bcol, t + 3);
;     BAR; WAIT_L(0); MMA(0, 1, At, B1); BAR;
	v_mfma_f32_16x16x32_bf16 v[60:63], v[160:163], v[176:179], v[60:63]
	v_mfma_f32_16x16x32_bf16 v[56:59], v[164:167], v[176:179], v[56:59]
	v_mfma_f32_16x16x32_bf16 v[52:55], v[160:163], v[184:187], v[52:55]
	v_mfma_f32_16x16x32_bf16 v[48:51], v[164:167], v[184:187], v[48:51]
	v_mfma_f32_16x16x32_bf16 v[44:47], v[160:163], v[192:195], v[44:47]
	v_mfma_f32_16x16x32_bf16 v[40:43], v[164:167], v[192:195], v[40:43]
	v_mfma_f32_16x16x32_bf16 v[36:39], v[160:163], v[200:203], v[36:39]
	v_mfma_f32_16x16x32_bf16 v[32:35], v[164:167], v[200:203], v[32:35]
	v_mfma_f32_16x16x32_bf16 v[60:63], v[168:171], v[180:183], v[60:63]
	v_mfma_f32_16x16x32_bf16 v[56:59], v[172:175], v[180:183], v[56:59]
	v_mfma_f32_16x16x32_bf16 v[52:55], v[168:171], v[188:191], v[52:55]
	v_mfma_f32_16x16x32_bf16 v[48:51], v[172:175], v[188:191], v[48:51]
	v_mfma_f32_16x16x32_bf16 v[44:47], v[168:171], v[196:199], v[44:47]
	v_mfma_f32_16x16x32_bf16 v[40:43], v[172:175], v[196:199], v[40:43]
	v_mfma_f32_16x16x32_bf16 v[36:39], v[168:171], v[204:207], v[36:39]
	v_mfma_f32_16x16x32_bf16 v[32:35], v[172:175], v[204:207], v[32:35]
	v_mfma_f32_16x16x32_bf16 v[28:31], v[208:211], v[176:179], v[28:31]
	v_mfma_f32_16x16x32_bf16 v[24:27], v[212:215], v[176:179], v[24:27]
	v_mfma_f32_16x16x32_bf16 v[20:23], v[208:211], v[184:187], v[20:23]
	v_mfma_f32_16x16x32_bf16 v[16:19], v[212:215], v[184:187], v[16:19]
	v_mfma_f32_16x16x32_bf16 v[12:15], v[208:211], v[192:195], v[12:15]
	v_mfma_f32_16x16x32_bf16 v[8:11], v[212:215], v[192:195], v[8:11]
	v_mfma_f32_16x16x32_bf16 v[4:7], v[208:211], v[200:203], v[4:7]
	v_mfma_f32_16x16x32_bf16 v[0:3], v[212:215], v[200:203], v[0:3]
	v_mfma_f32_16x16x32_bf16 v[28:31], v[216:219], v[180:183], v[28:31]
	v_mfma_f32_16x16x32_bf16 v[24:27], v[220:223], v[180:183], v[24:27]
	v_mfma_f32_16x16x32_bf16 v[20:23], v[216:219], v[188:191], v[20:23]
	v_mfma_f32_16x16x32_bf16 v[16:19], v[220:223], v[188:191], v[16:19]
	v_mfma_f32_16x16x32_bf16 v[12:15], v[216:219], v[196:199], v[12:15]
	v_mfma_f32_16x16x32_bf16 v[8:11], v[220:223], v[196:199], v[8:11]
	v_mfma_f32_16x16x32_bf16 v[4:7], v[216:219], v[204:207], v[4:7]
	v_mfma_f32_16x16x32_bf16 v[0:3], v[220:223], v[204:207], v[0:3]
	s_barrier
	s_setprio 0
	ds_read_b128 v[160:163], v156
	ds_read_b128 v[164:167], v156 offset:256
	ds_read_b128 v[168:171], v157
	ds_read_b128 v[172:175], v157 offset:256
	v_readfirstlane_b32 s70, v141
	v_lshl_add_u64 v[208:209], v[224:225], 0, s[38:39]
	s_mov_b32 m0, s70
	v_readfirstlane_b32 s70, v142
	ds_read_b128 v[176:179], v149 offset:32768
	ds_read_b128 v[180:183], v149 offset:33792
	ds_read_b128 v[184:187], v149 offset:34816
	ds_read_b128 v[188:191], v149 offset:35840
	ds_read_b128 v[192:195], v149 offset:36864
	ds_read_b128 v[196:199], v149 offset:37888
	ds_read_b128 v[200:203], v149 offset:38912
	ds_read_b128 v[204:207], v149 offset:39936
	global_load_lds_dwordx4 v[208:209], off
	v_lshl_add_u64 v[208:209], v[224:225], 0, s[46:47]
	s_mov_b32 m0, s70
	s_nop 0
	global_load_lds_dwordx4 v[208:209], off
	s_waitcnt lgkmcnt(8)
	v_readfirstlane_b32 s70, v140
	v_lshl_add_u64 v[246:247], v[226:227], 0, s[36:37]
	s_mov_b32 m0, s70
	s_nop 0
	global_load_lds_dwordx4 v[246:247], off
	ds_read_b128 v[208:211], v158
	ds_read_b128 v[212:215], v158 offset:256
	ds_read_b128 v[216:219], v159
	ds_read_b128 v[220:223], v159 offset:256
	s_waitcnt lgkmcnt(0)
	s_setprio 1
	s_barrier
	v_mfma_f32_16x16x32_bf16 v[124:127], v[160:163], v[176:179], v[124:127]
	v_mfma_f32_16x16x32_bf16 v[120:123], v[164:167], v[176:179], v[120:123]
	v_mfma_f32_16x16x32_bf16 v[116:119], v[160:163], v[184:187], v[116:119]
	v_mfma_f32_16x16x32_bf16 v[112:115], v[164:167], v[184:187], v[112:115]
	v_mfma_f32_16x16x32_bf16 v[108:111], v[160:163], v[192:195], v[108:111]
	v_mfma_f32_16x16x32_bf16 v[104:107], v[164:167], v[192:195], v[104:107]
	v_mfma_f32_16x16x32_bf16 v[100:103], v[160:163], v[200:203], v[100:103]
	v_mfma_f32_16x16x32_bf16 v[96:99], v[164:167], v[200:203], v[96:99]
	v_mfma_f32_16x16x32_bf16 v[124:127], v[168:171], v[180:183], v[124:127]
	v_mfma_f32_16x16x32_bf16 v[120:123], v[172:175], v[180:183], v[120:123]
	v_mfma_f32_16x16x32_bf16 v[116:119], v[168:171], v[188:191], v[116:119]
	v_mfma_f32_16x16x32_bf16 v[112:115], v[172:175], v[188:191], v[112:115]
	v_mfma_f32_16x16x32_bf16 v[108:111], v[168:171], v[196:199], v[108:111]
	v_mfma_f32_16x16x32_bf16 v[104:107], v[172:175], v[196:199], v[104:107]
	v_mfma_f32_16x16x32_bf16 v[100:103], v[168:171], v[204:207], v[100:103]
	v_mfma_f32_16x16x32_bf16 v[96:99], v[172:175], v[204:207], v[96:99]
	v_mfma_f32_16x16x32_bf16 v[92:95], v[208:211], v[176:179], v[92:95]
	v_mfma_f32_16x16x32_bf16 v[88:91], v[212:215], v[176:179], v[88:91]
	v_mfma_f32_16x16x32_bf16 v[84:87], v[208:211], v[184:187], v[84:87]
	v_mfma_f32_16x16x32_bf16 v[80:83], v[212:215], v[184:187], v[80:83]
	v_mfma_f32_16x16x32_bf16 v[76:79], v[208:211], v[192:195], v[76:79]
	v_mfma_f32_16x16x32_bf16 v[72:75], v[212:215], v[192:195], v[72:75]
	v_mfma_f32_16x16x32_bf16 v[68:71], v[208:211], v[200:203], v[68:71]
	v_mfma_f32_16x16x32_bf16 v[64:67], v[212:215], v[200:203], v[64:67]
	v_mfma_f32_16x16x32_bf16 v[92:95], v[216:219], v[180:183], v[92:95]
	v_mfma_f32_16x16x32_bf16 v[88:91], v[220:223], v[180:183], v[88:91]
	v_mfma_f32_16x16x32_bf16 v[84:87], v[216:219], v[188:191], v[84:87]
	v_mfma_f32_16x16x32_bf16 v[80:83], v[220:223], v[188:191], v[80:83]
	v_mfma_f32_16x16x32_bf16 v[76:79], v[216:219], v[196:199], v[76:79]
	v_mfma_f32_16x16x32_bf16 v[72:75], v[220:223], v[196:199], v[72:75]
	v_mfma_f32_16x16x32_bf16 v[68:71], v[216:219], v[204:207], v[68:71]
	v_mfma_f32_16x16x32_bf16 v[64:67], v[220:223], v[204:207], v[64:67]
	s_barrier
; #define STAGE(P, BASE, br, kt) do { const char* _gb = (const char*)(BASE) + ((size_t)(br) * K + (size_t)(kt) * BK) * 2; \
;     __builtin_amdgcn_global_load_lds((const unsigned*)(_gb + loff0), (unsigned*)((char*)(P) + tid * 16), 16, 0, 0); \
;     __builtin_amdgcn_global_load_lds((const unsigned*)(_gb + (size_t)K * 128 + loff0), (unsigned*)((char*)(P) + tid * 16 + 8192), 16, 0, 0); } while (0)
; #define LDA(dst, b, h) for (int m = 0; m < 4; ++m) { \
;     dst[m][0] = *reinterpret_cast<const bf16x8*>((char*)SA(b, h) + aoff0 + m * 2048); \
;     dst[m][1] = *reinterpret_cast<const bf16x8*>((char*)SA(b, h) + aoff1 + m * 2048); }
; #define LDB(dst, b, h) for (int n = 0; n < 2; ++n) { \
;     dst[n][0] = *reinterpret_cast<const bf16x8*>((char*)SB(b, h) + boff0 + n * 256); \
;     dst[n][1] = *reinterpret_cast<const bf16x8*>((char*)SB(b, h) + boff1 + n * 256); }
; #define MMA(ai, bj, At, Btf) do { __builtin_amdgcn_s_setprio(1); \
;     for (int m = 0; m < 4; ++m) for (int n = 0; n < 2; ++n) for (int k = 0; k < 2; ++k) \
;       acc[ai][bj][m][n] = __builtin_amdgcn_mfma_f32_16x16x32_bf16(Btf[n][k], At[m][k], acc[ai][bj][m][n], 0, 0, 0); \
;     __builtin_amdgcn_s_setprio(0); } while (0)
; #define WAIT_V(n) asm volatile("s_waitcnt vmcnt(" #n ")" ::: "memory")
; #define WAIT_L(n) asm volatile("s_waitcnt lgkmcnt(" #n ")" ::: "memory")
; #define BAR __builtin_amdgcn_s_barrier()
; #define SCHED __builtin_amdgcn_sched_barrier(0)
; template <int EPI> ...
;     ...
;     LDA(At, 1, 1); STAGE(SA(1, 0), A, brow, t + 3);
;     BAR; WAIT_L(0); MMA(1, 0, At, B0); BAR; SCHED;
;     STAGE(SB(1, 1), Bt, bcol + HALF, t + 3);
;     WAIT_V(6); BAR; MMA(1, 1, At, B1); BAR;
;   }
;   { LDB(B0, 0, 0); LDA(At, 0, 0); STAGE(SA(1, 1), A, brow + HALF, nt - 1);
;     BAR; WAIT_L(0); MMA(0, 0, At, B0); BAR;
	s_setprio 0
	v_readfirstlane_b32 s70, v143
	v_lshl_add_u64 v[228:229], v[226:227], 0, s[48:49]
	s_mov_b32 m0, s70
	v_readfirstlane_b32 s70, v144
	global_load_lds_dwordx4 v[228:229], off
	v_lshl_add_u64 v[228:229], v[226:227], 0, s[50:51]
	s_mov_b32 m0, s70
	s_nop 0
	global_load_lds_dwordx4 v[228:229], off
	v_readfirstlane_b32 s70, v145
	v_lshl_add_u64 v[228:229], v[224:225], 0, s[52:53]
	s_mov_b32 m0, s70
	v_readfirstlane_b32 s70, v146
	ds_read_b128 v[176:179], v149 offset:49152
	ds_read_b128 v[180:183], v149 offset:50176
	ds_read_b128 v[184:187], v149 offset:51200
	ds_read_b128 v[188:191], v149 offset:52224
	ds_read_b128 v[192:195], v149 offset:53248
	ds_read_b128 v[196:199], v149 offset:54272
	ds_read_b128 v[200:203], v149 offset:55296
	ds_read_b128 v[204:207], v149 offset:56320
	global_load_lds_dwordx4 v[228:229], off
	v_lshl_add_u64 v[224:225], v[224:225], 0, s[54:55]
	s_mov_b32 m0, s70
	s_nop 0
	global_load_lds_dwordx4 v[224:225], off
	v_readfirstlane_b32 s70, v147
	v_lshl_add_u64 v[246:247], v[226:227], 0, s[56:57]
	s_mov_b32 m0, s70
	v_readfirstlane_b32 s70, v148
	global_load_lds_dwordx4 v[246:247], off
	s_waitcnt vmcnt(5)
	s_barrier
	s_waitcnt lgkmcnt(0)
	s_setprio 1
	s_waitcnt lgkmcnt(0)
	v_mfma_f32_16x16x32_bf16 v[60:63], v[160:163], v[176:179], v[60:63]
	v_mfma_f32_16x16x32_bf16 v[56:59], v[164:167], v[176:179], v[56:59]
	v_mfma_f32_16x16x32_bf16 v[52:55], v[160:163], v[184:187], v[52:55]
	v_mfma_f32_16x16x32_bf16 v[48:51], v[164:167], v[184:187], v[48:51]
	v_mfma_f32_16x16x32_bf16 v[44:47], v[160:163], v[192:195], v[44:47]
	v_mfma_f32_16x16x32_bf16 v[40:43], v[164:167], v[192:195], v[40:43]
	v_mfma_f32_16x16x32_bf16 v[36:39], v[160:163], v[200:203], v[36:39]
	v_mfma_f32_16x16x32_bf16 v[32:35], v[164:167], v[200:203], v[32:35]
	v_mfma_f32_16x16x32_bf16 v[60:63], v[168:171], v[180:183], v[60:63]
	v_mfma_f32_16x16x32_bf16 v[56:59], v[172:175], v[180:183], v[56:59]
	v_mfma_f32_16x16x32_bf16 v[52:55], v[168:171], v[188:191], v[52:55]
	v_mfma_f32_16x16x32_bf16 v[48:51], v[172:175], v[188:191], v[48:51]
	v_mfma_f32_16x16x32_bf16 v[44:47], v[168:171], v[196:199], v[44:47]
	v_mfma_f32_16x16x32_bf16 v[40:43], v[172:175], v[196:199], v[40:43]
	v_mfma_f32_16x16x32_bf16 v[36:39], v[168:171], v[204:207], v[36:39]
	v_mfma_f32_16x16x32_bf16 v[32:35], v[172:175], v[204:207], v[32:35]
	s_setprio 0
	s_setprio 1
	v_mfma_f32_16x16x32_bf16 v[28:31], v[208:211], v[176:179], v[28:31]
	v_mfma_f32_16x16x32_bf16 v[24:27], v[212:215], v[176:179], v[24:27]
	v_mfma_f32_16x16x32_bf16 v[20:23], v[208:211], v[184:187], v[20:23]
	v_mfma_f32_16x16x32_bf16 v[16:19], v[212:215], v[184:187], v[16:19]
	v_mfma_f32_16x16x32_bf16 v[12:15], v[208:211], v[192:195], v[12:15]
	v_mfma_f32_16x16x32_bf16 v[8:11], v[212:215], v[192:195], v[8:11]
	v_mfma_f32_16x16x32_bf16 v[4:7], v[208:211], v[200:203], v[4:7]
	v_mfma_f32_16x16x32_bf16 v[0:3], v[212:215], v[200:203], v[0:3]
	v_mfma_f32_16x16x32_bf16 v[28:31], v[216:219], v[180:183], v[28:31]
	v_mfma_f32_16x16x32_bf16 v[24:27], v[220:223], v[180:183], v[24:27]
	v_mfma_f32_16x16x32_bf16 v[20:23], v[216:219], v[188:191], v[20:23]
	v_mfma_f32_16x16x32_bf16 v[16:19], v[220:223], v[188:191], v[16:19]
	v_mfma_f32_16x16x32_bf16 v[12:15], v[216:219], v[196:199], v[12:15]
	v_mfma_f32_16x16x32_bf16 v[8:11], v[220:223], v[196:199], v[8:11]
	v_mfma_f32_16x16x32_bf16 v[4:7], v[216:219], v[204:207], v[4:7]
	v_mfma_f32_16x16x32_bf16 v[0:3], v[220:223], v[204:207], v[0:3]
	s_setprio 0
	s_add_i32 s61, s61, 2
	s_add_u32 s66, s66, 0x100
	s_addc_u32 s67, s67, 0
	s_add_u32 s68, s68, 0x100
	s_addc_u32 s69, s69, 0
	s_cmp_lt_u32 s61, 28
	s_barrier
	s_cbranch_scc1 .LBB0_411
	v_readfirstlane_b32 s70, v148
	v_lshl_add_u64 v[246:247], v[226:227], 0, s[58:59]
	s_mov_b32 m0, s70
	s_nop 0
	global_load_lds_dwordx4 v[246:247], off
	s_add_u32 s64, s74, s64
	s_addc_u32 s65, s75, s65
	v_readfirstlane_b32 s61, v150
	v_lshl_add_u64 v[208:209], s[64:65], 0, v[128:129]
	s_mov_b32 m0, s61
	v_readfirstlane_b32 s61, v151
	ds_read_b128 v[160:163], v152
	ds_read_b128 v[164:167], v152 offset:256
	ds_read_b128 v[168:171], v153
	ds_read_b128 v[172:175], v153 offset:256
	ds_read_b128 v[176:179], v149
	ds_read_b128 v[180:183], v149 offset:1024
	ds_read_b128 v[184:187], v149 offset:2048
	ds_read_b128 v[188:191], v149 offset:3072
	ds_read_b128 v[192:195], v149 offset:4096
	ds_read_b128 v[196:199], v149 offset:5120
	ds_read_b128 v[200:203], v149 offset:6144
	ds_read_b128 v[204:207], v149 offset:7168
	global_load_lds_dwordx4 v[208:209], off
	v_lshl_add_u64 v[208:209], v[208:209], 0, s[8:9]
	s_mov_b32 m0, s61
	s_nop 0
	global_load_lds_dwordx4 v[208:209], off
	s_waitcnt lgkmcnt(0)
	s_setprio 1
	s_barrier
	v_mfma_f32_16x16x32_bf16 v[124:127], v[160:163], v[176:179], v[124:127]
	v_mfma_f32_16x16x32_bf16 v[116:119], v[160:163], v[184:187], v[116:119]
	v_mfma_f32_16x16x32_bf16 v[108:111], v[160:163], v[192:195], v[108:111]
	v_mfma_f32_16x16x32_bf16 v[100:103], v[160:163], v[200:203], v[100:103]
	v_mfma_f32_16x16x32_bf16 v[96:99], v[164:167], v[200:203], v[96:99]
	v_mfma_f32_16x16x32_bf16 v[124:127], v[168:171], v[180:183], v[124:127]
	v_mfma_f32_16x16x32_bf16 v[120:123], v[164:167], v[176:179], v[120:123]
	v_mfma_f32_16x16x32_bf16 v[116:119], v[168:171], v[188:191], v[116:119]
	v_mfma_f32_16x16x32_bf16 v[112:115], v[164:167], v[184:187], v[112:115]
	v_mfma_f32_16x16x32_bf16 v[108:111], v[168:171], v[196:199], v[108:111]
	v_mfma_f32_16x16x32_bf16 v[104:107], v[164:167], v[192:195], v[104:107]
	v_mfma_f32_16x16x32_bf16 v[100:103], v[168:171], v[204:207], v[100:103]
	v_mfma_f32_16x16x32_bf16 v[96:99], v[172:175], v[204:207], v[96:99]
	v_mfma_f32_16x16x32_bf16 v[208:211], v[172:175], v[180:183], v[120:123]
	v_mfma_f32_16x16x32_bf16 v[212:215], v[172:175], v[188:191], v[112:115]
	v_mfma_f32_16x16x32_bf16 v[216:219], v[172:175], v[196:199], v[104:107]
	s_barrier
; #define STAGE(P, BASE, br, kt) do { const char* _gb = (const char*)(BASE) + ((size_t)(br) * K + (size_t)(kt) * BK) * 2; \
;     __builtin_amdgcn_global_load_lds((const unsigned*)(_gb + loff0), (unsigned*)((char*)(P) + tid * 16), 16, 0, 0); \
;     __builtin_amdgcn_global_load_lds((const unsigned*)(_gb + (size_t)K * 128 + loff0), (unsigned*)((char*)(P) + tid * 16 + 8192), 16, 0, 0); } while (0)
; #define LDA(dst, b, h) for (int m = 0; m < 4; ++m) { \
;     dst[m][0] = *reinterpret_cast<const bf16x8*>((char*)SA(b, h) + aoff0 + m * 2048); \
;     dst[m][1] = *reinterpret_cast<const bf16x8*>((char*)SA(b, h) + aoff1 + m * 2048); }
; #define LDB(dst, b, h) for (int n = 0; n < 2; ++n) { \
;     dst[n][0] = *reinterpret_cast<const bf16x8*>((char*)SB(b, h) + boff0 + n * 256); \
;     dst[n][1] = *reinterpret_cast<const bf16x8*>((char*)SB(b, h) + boff1 + n * 256); }
; #define MMA(ai, bj, At, Btf) do { __builtin_amdgcn_s_setprio(1); \
;     for (int m = 0; m < 4; ++m) for (int n = 0; n < 2; ++n) for (int k = 0; k < 2; ++k) \
;       acc[ai][bj][m][n] = __builtin_amdgcn_mfma_f32_16x16x32_bf16(Btf[n][k], At[m][k], acc[ai][bj][m][n], 0, 0, 0); \
;     __builtin_amdgcn_s_setprio(0); } while (0)
; #define WAIT_V(n) asm volatile("s_waitcnt vmcnt(" #n ")" ::: "memory")
; #define WAIT_L(n) asm volatile("s_waitcnt lgkmcnt(" #n ")" ::: "memory")
; #define BAR __builtin_amdgcn_s_barrier()
; template <int EPI> ...
;     ...
;   { LDB(B0, 0, 0); LDA(At, 0, 0); STAGE(SA(1, 1), A, brow + HALF, nt - 1);
;     BAR; WAIT_L(0); MMA(0, 0, At, B0); BAR;
;     LDB(B1, 0, 1); BAR; WAIT_L(0); MMA(0, 1, At, B1); BAR;
;     LDA(At, 0, 1); WAIT_V(4); BAR; WAIT_L(0); MMA(1, 0, At, B0); MMA(1, 1, At, B1); BAR; }
;   { LDB(B0, 1, 0); LDA(At, 1, 0); WAIT_V(2); BAR; WAIT_L(0); MMA(0, 0, At, B0); BAR;
;     LDB(B1, 1, 1); WAIT_V(0); BAR; WAIT_L(0); MMA(0, 1, At, B1); BAR;
	s_setprio 0
	s_nop 0
	ds_read_b128 v[104:107], v154
	ds_read_b128 v[112:115], v154 offset:256
	ds_read_b128 v[120:123], v155
	ds_read_b128 v[220:223], v155 offset:256
	s_waitcnt lgkmcnt(0)
	s_setprio 1
	s_barrier
	v_mfma_f32_16x16x32_bf16 v[92:95], v[104:107], v[176:179], v[92:95]
	v_mfma_f32_16x16x32_bf16 v[88:91], v[112:115], v[176:179], v[88:91]
	v_mfma_f32_16x16x32_bf16 v[76:79], v[104:107], v[192:195], v[76:79]
	v_mfma_f32_16x16x32_bf16 v[72:75], v[112:115], v[192:195], v[72:75]
	v_mfma_f32_16x16x32_bf16 v[92:95], v[120:123], v[180:183], v[92:95]
	v_mfma_f32_16x16x32_bf16 v[88:91], v[220:223], v[180:183], v[88:91]
	v_mfma_f32_16x16x32_bf16 v[84:87], v[104:107], v[184:187], v[84:87]
	v_mfma_f32_16x16x32_bf16 v[80:83], v[112:115], v[184:187], v[80:83]
	v_mfma_f32_16x16x32_bf16 v[76:79], v[120:123], v[196:199], v[76:79]
	v_mfma_f32_16x16x32_bf16 v[72:75], v[220:223], v[196:199], v[72:75]
	v_mfma_f32_16x16x32_bf16 v[68:71], v[104:107], v[200:203], v[68:71]
	v_mfma_f32_16x16x32_bf16 v[64:67], v[112:115], v[200:203], v[64:67]
	v_mfma_f32_16x16x32_bf16 v[176:179], v[120:123], v[188:191], v[84:87]
	v_mfma_f32_16x16x32_bf16 v[180:183], v[220:223], v[188:191], v[80:83]
	v_mfma_f32_16x16x32_bf16 v[184:187], v[120:123], v[204:207], v[68:71]
	v_mfma_f32_16x16x32_bf16 v[188:191], v[220:223], v[204:207], v[64:67]
	s_barrier
	s_setprio 0
	s_nop 1
	ds_read_b128 v[64:67], v149 offset:16384
	ds_read_b128 v[68:71], v149 offset:17408
	ds_read_b128 v[80:83], v149 offset:18432
	ds_read_b128 v[84:87], v149 offset:19456
	ds_read_b128 v[192:195], v149 offset:20480
	ds_read_b128 v[196:199], v149 offset:21504
	ds_read_b128 v[200:203], v149 offset:22528
	ds_read_b128 v[204:207], v149 offset:23552
	s_waitcnt vmcnt(4)
	s_waitcnt lgkmcnt(0)
	s_setprio 1
	s_barrier
	v_mfma_f32_16x16x32_bf16 v[60:63], v[160:163], v[64:67], v[60:63]
	v_mfma_f32_16x16x32_bf16 v[56:59], v[164:167], v[64:67], v[56:59]
	v_mfma_f32_16x16x32_bf16 v[44:47], v[160:163], v[192:195], v[44:47]
	v_mfma_f32_16x16x32_bf16 v[36:39], v[160:163], v[200:203], v[36:39]
	v_mfma_f32_16x16x32_bf16 v[60:63], v[168:171], v[68:71], v[60:63]
	v_mfma_f32_16x16x32_bf16 v[56:59], v[172:175], v[68:71], v[56:59]
	v_mfma_f32_16x16x32_bf16 v[52:55], v[160:163], v[80:83], v[52:55]
	v_mfma_f32_16x16x32_bf16 v[48:51], v[164:167], v[80:83], v[48:51]
	v_mfma_f32_16x16x32_bf16 v[44:47], v[168:171], v[196:199], v[44:47]
	v_mfma_f32_16x16x32_bf16 v[40:43], v[164:167], v[192:195], v[40:43]
	v_mfma_f32_16x16x32_bf16 v[36:39], v[168:171], v[204:207], v[36:39]
	v_mfma_f32_16x16x32_bf16 v[32:35], v[164:167], v[200:203], v[32:35]
	v_mfma_f32_16x16x32_bf16 v[224:227], v[168:171], v[84:87], v[52:55]
	v_mfma_f32_16x16x32_bf16 v[228:231], v[172:175], v[84:87], v[48:51]
	v_mfma_f32_16x16x32_bf16 v[232:235], v[172:175], v[196:199], v[40:43]
	v_mfma_f32_16x16x32_bf16 v[160:163], v[172:175], v[204:207], v[32:35]
	v_mfma_f32_16x16x32_bf16 v[28:31], v[104:107], v[64:67], v[28:31]
	v_mfma_f32_16x16x32_bf16 v[20:23], v[104:107], v[80:83], v[20:23]
	v_mfma_f32_16x16x32_bf16 v[12:15], v[104:107], v[192:195], v[12:15]
	v_mfma_f32_16x16x32_bf16 v[4:7], v[104:107], v[200:203], v[4:7]
	v_mfma_f32_16x16x32_bf16 v[28:31], v[120:123], v[68:71], v[28:31]
	v_mfma_f32_16x16x32_bf16 v[24:27], v[112:115], v[64:67], v[24:27]
	v_mfma_f32_16x16x32_bf16 v[20:23], v[120:123], v[84:87], v[20:23]
	v_mfma_f32_16x16x32_bf16 v[16:19], v[112:115], v[80:83], v[16:19]
	v_mfma_f32_16x16x32_bf16 v[12:15], v[120:123], v[196:199], v[12:15]
	v_mfma_f32_16x16x32_bf16 v[8:11], v[112:115], v[192:195], v[8:11]
	v_mfma_f32_16x16x32_bf16 v[4:7], v[120:123], v[204:207], v[4:7]
	v_mfma_f32_16x16x32_bf16 v[0:3], v[112:115], v[200:203], v[0:3]
	v_mfma_f32_16x16x32_bf16 v[164:167], v[220:223], v[68:71], v[24:27]
	v_mfma_f32_16x16x32_bf16 v[168:171], v[220:223], v[84:87], v[16:19]
	v_mfma_f32_16x16x32_bf16 v[172:175], v[220:223], v[196:199], v[8:11]
	v_mfma_f32_16x16x32_bf16 v[192:195], v[220:223], v[204:207], v[0:3]
	s_barrier
	s_setprio 0
	s_nop 1
	ds_read_b128 v[0:3], v156
	ds_read_b128 v[8:11], v156 offset:256
	ds_read_b128 v[16:19], v157
	ds_read_b128 v[24:27], v157 offset:256
	ds_read_b128 v[32:35], v149 offset:32768
	ds_read_b128 v[40:43], v149 offset:33792
	ds_read_b128 v[48:51], v149 offset:34816
	ds_read_b128 v[52:55], v149 offset:35840
	ds_read_b128 v[68:71], v149 offset:36864
	ds_read_b128 v[196:199], v149 offset:37888
	ds_read_b128 v[200:203], v149 offset:38912
	ds_read_b128 v[204:207], v149 offset:39936
	s_waitcnt vmcnt(2)
	s_waitcnt lgkmcnt(0)
	s_setprio 1
	s_barrier
; #define LDA(dst, b, h) for (int m = 0; m < 4; ++m) { \
;     dst[m][0] = *reinterpret_cast<const bf16x8*>((char*)SA(b, h) + aoff0 + m * 2048); \
;     dst[m][1] = *reinterpret_cast<const bf16x8*>((char*)SA(b, h) + aoff1 + m * 2048); }
; #define LDB(dst, b, h) for (int n = 0; n < 2; ++n) { \
;     dst[n][0] = *reinterpret_cast<const bf16x8*>((char*)SB(b, h) + boff0 + n * 256); \
;     dst[n][1] = *reinterpret_cast<const bf16x8*>((char*)SB(b, h) + boff1 + n * 256); }
; #define MMA(ai, bj, At, Btf) do { __builtin_amdgcn_s_setprio(1); \
;     for (int m = 0; m < 4; ++m) for (int n = 0; n < 2; ++n) for (int k = 0; k < 2; ++k) \
;       acc[ai][bj][m][n] = __builtin_amdgcn_mfma_f32_16x16x32_bf16(Btf[n][k], At[m][k], acc[ai][bj][m][n], 0, 0, 0); \
;     __builtin_amdgcn_s_setprio(0); } while (0)
; #define WAIT_V(n) asm volatile("s_waitcnt vmcnt(" #n ")" ::: "memory")
; #define WAIT_L(n) asm volatile("s_waitcnt lgkmcnt(" #n ")" ::: "memory")
; #define BAR __builtin_amdgcn_s_barrier()
; template <int EPI> ...
;     ...
;   { LDB(B0, 1, 0); LDA(At, 1, 0); WAIT_V(2); BAR; WAIT_L(0); MMA(0, 0, At, B0); BAR;
;     LDB(B1, 1, 1); WAIT_V(0); BAR; WAIT_L(0); MMA(0, 1, At, B1); BAR;
;     LDA(At, 1, 1); BAR; WAIT_L(0); MMA(1, 0, At, B0); MMA(1, 1, At, B1); BAR; }
;   if (wr == 0) BAR;
	v_mfma_f32_16x16x32_bf16 v[64:67], v[0:3], v[32:35], v[124:127]
	v_mfma_f32_16x16x32_bf16 v[120:123], v[16:19], v[40:43], v[64:67]
	v_mfma_f32_16x16x32_bf16 v[64:67], v[8:11], v[32:35], v[208:211]
	v_mfma_f32_16x16x32_bf16 v[124:127], v[24:27], v[40:43], v[64:67]
	v_mfma_f32_16x16x32_bf16 v[64:67], v[0:3], v[48:51], v[116:119]
	v_mfma_f32_16x16x32_bf16 v[112:115], v[16:19], v[52:55], v[64:67]
	v_mfma_f32_16x16x32_bf16 v[64:67], v[8:11], v[48:51], v[212:215]
	v_mfma_f32_16x16x32_bf16 v[116:119], v[24:27], v[52:55], v[64:67]
	v_mfma_f32_16x16x32_bf16 v[64:67], v[0:3], v[68:71], v[108:111]
	v_mfma_f32_16x16x32_bf16 v[104:107], v[16:19], v[196:199], v[64:67]
	v_mfma_f32_16x16x32_bf16 v[64:67], v[8:11], v[68:71], v[216:219]
	v_mfma_f32_16x16x32_bf16 v[108:111], v[24:27], v[196:199], v[64:67]
	v_mfma_f32_16x16x32_bf16 v[64:67], v[0:3], v[200:203], v[100:103]
	v_mfma_f32_16x16x32_bf16 v[80:83], v[16:19], v[204:207], v[64:67]
	v_mfma_f32_16x16x32_bf16 v[64:67], v[8:11], v[200:203], v[96:99]
	v_mfma_f32_16x16x32_bf16 v[84:87], v[24:27], v[204:207], v[64:67]
	s_barrier
	s_setprio 0
	ds_read_b128 v[208:211], v158
	ds_read_b128 v[212:215], v158 offset:256
	ds_read_b128 v[216:219], v159
	ds_read_b128 v[220:223], v159 offset:256
	s_waitcnt vmcnt(0)
	s_waitcnt lgkmcnt(0)
	s_setprio 1
	s_barrier
	v_mfma_f32_16x16x32_bf16 v[64:67], v[208:211], v[32:35], v[92:95]
	v_mfma_f32_16x16x32_bf16 v[32:35], v[212:215], v[32:35], v[88:91]
	v_mfma_f32_16x16x32_bf16 v[100:103], v[220:223], v[40:43], v[32:35]
	v_mfma_f32_16x16x32_bf16 v[32:35], v[208:211], v[48:51], v[176:179]
	v_mfma_f32_16x16x32_bf16 v[88:91], v[216:219], v[52:55], v[32:35]
	v_mfma_f32_16x16x32_bf16 v[32:35], v[212:215], v[48:51], v[180:183]
	v_mfma_f32_16x16x32_bf16 v[92:95], v[220:223], v[52:55], v[32:35]
	v_mfma_f32_16x16x32_bf16 v[32:35], v[208:211], v[68:71], v[76:79]
	v_mfma_f32_16x16x32_bf16 v[96:99], v[216:219], v[40:43], v[64:67]
	v_mfma_f32_16x16x32_bf16 v[64:67], v[216:219], v[196:199], v[32:35]
	v_mfma_f32_16x16x32_bf16 v[32:35], v[212:215], v[68:71], v[72:75]
	v_mfma_f32_16x16x32_bf16 v[68:71], v[220:223], v[196:199], v[32:35]
	v_mfma_f32_16x16x32_bf16 v[32:35], v[208:211], v[200:203], v[184:187]
	v_mfma_f32_16x16x32_bf16 v[48:51], v[216:219], v[204:207], v[32:35]
	v_mfma_f32_16x16x32_bf16 v[32:35], v[212:215], v[200:203], v[188:191]
	v_mfma_f32_16x16x32_bf16 v[52:55], v[220:223], v[204:207], v[32:35]
	s_barrier
	s_setprio 0
	ds_read_b128 v[176:179], v149 offset:49152
	ds_read_b128 v[180:183], v149 offset:50176
	ds_read_b128 v[184:187], v149 offset:51200
	ds_read_b128 v[188:191], v149 offset:52224
	ds_read_b128 v[196:199], v149 offset:53248
	ds_read_b128 v[200:203], v149 offset:54272
	ds_read_b128 v[204:207], v149 offset:55296
	ds_read_b128 v[236:239], v149 offset:56320
	s_waitcnt lgkmcnt(0)
	s_setprio 1
	s_barrier
	v_mfma_f32_16x16x32_bf16 v[32:35], v[0:3], v[176:179], v[60:63]
	v_mfma_f32_16x16x32_bf16 v[72:75], v[16:19], v[180:183], v[32:35]
	v_mfma_f32_16x16x32_bf16 v[32:35], v[8:11], v[176:179], v[56:59]
	v_mfma_f32_16x16x32_bf16 v[76:79], v[24:27], v[180:183], v[32:35]
	v_mfma_f32_16x16x32_bf16 v[32:35], v[0:3], v[184:187], v[224:227]
	v_mfma_f32_16x16x32_bf16 v[56:59], v[16:19], v[188:191], v[32:35]
	v_mfma_f32_16x16x32_bf16 v[32:35], v[8:11], v[184:187], v[228:231]
	v_mfma_f32_16x16x32_bf16 v[60:63], v[24:27], v[188:191], v[32:35]
	v_mfma_f32_16x16x32_bf16 v[32:35], v[0:3], v[196:199], v[44:47]
	v_mfma_f32_16x16x32_bf16 v[40:43], v[16:19], v[200:203], v[32:35]
	v_mfma_f32_16x16x32_bf16 v[32:35], v[8:11], v[196:199], v[232:235]
	v_mfma_f32_16x16x32_bf16 v[0:3], v[0:3], v[204:207], v[36:39]
	v_mfma_f32_16x16x32_bf16 v[44:47], v[24:27], v[200:203], v[32:35]
	v_mfma_f32_16x16x32_bf16 v[32:35], v[16:19], v[236:239], v[0:3]
	v_mfma_f32_16x16x32_bf16 v[0:3], v[8:11], v[204:207], v[160:163]
	v_mfma_f32_16x16x32_bf16 v[36:39], v[24:27], v[236:239], v[0:3]
	v_mfma_f32_16x16x32_bf16 v[0:3], v[208:211], v[176:179], v[28:31]
	v_mfma_f32_16x16x32_bf16 v[24:27], v[216:219], v[180:183], v[0:3]
	v_mfma_f32_16x16x32_bf16 v[0:3], v[212:215], v[176:179], v[164:167]
	v_mfma_f32_16x16x32_bf16 v[28:31], v[220:223], v[180:183], v[0:3]
	v_mfma_f32_16x16x32_bf16 v[0:3], v[208:211], v[184:187], v[20:23]
	v_mfma_f32_16x16x32_bf16 v[16:19], v[216:219], v[188:191], v[0:3]
	v_mfma_f32_16x16x32_bf16 v[0:3], v[212:215], v[184:187], v[168:171]
	v_mfma_f32_16x16x32_bf16 v[20:23], v[220:223], v[188:191], v[0:3]
	v_mfma_f32_16x16x32_bf16 v[0:3], v[208:211], v[196:199], v[12:15]
	v_mfma_f32_16x16x32_bf16 v[8:11], v[216:219], v[200:203], v[0:3]
	v_mfma_f32_16x16x32_bf16 v[0:3], v[212:215], v[196:199], v[172:175]
	v_mfma_f32_16x16x32_bf16 v[12:15], v[220:223], v[200:203], v[0:3]
	v_mfma_f32_16x16x32_bf16 v[0:3], v[208:211], v[204:207], v[4:7]
	v_mfma_f32_16x16x32_bf16 v[4:7], v[212:215], v[204:207], v[192:195]
	v_mfma_f32_16x16x32_bf16 v[0:3], v[216:219], v[236:239], v[0:3]
	v_mfma_f32_16x16x32_bf16 v[4:7], v[220:223], v[236:239], v[4:7]
	s_barrier
	s_setprio 0
	s_and_saveexec_b64 s[64:65], s[2:3]
	s_cbranch_execz .LBB0_405
	s_barrier
	s_branch .LBB0_405

; #define STAGE(P, BASE, br, kt) do { const char* _gb = (const char*)(BASE) + ((size_t)(br) * K + (size_t)(kt) * BK) * 2; \
;     __builtin_amdgcn_global_load_lds((const unsigned*)(_gb + loff0), (unsigned*)((char*)(P) + tid * 16), 16, 0, 0); \
;     __builtin_amdgcn_global_load_lds((const unsigned*)(_gb + (size_t)K * 128 + loff0), (unsigned*)((char*)(P) + tid * 16 + 8192), 16, 0, 0); } while (0)
; #define LDA(dst, b, h) for (int m = 0; m < 4; ++m) { \
;     dst[m][0] = *reinterpret_cast<const bf16x8*>((char*)SA(b, h) + aoff0 + m * 2048); \
;     dst[m][1] = *reinterpret_cast<const bf16x8*>((char*)SA(b, h) + aoff1 + m * 2048); }
; #define LDB(dst, b, h) for (int n = 0; n < 2; ++n) { \
;     dst[n][0] = *reinterpret_cast<const bf16x8*>((char*)SB(b, h) + boff0 + n * 256); \
;     dst[n][1] = *reinterpret_cast<const bf16x8*>((char*)SB(b, h) + boff1 + n * 256); }
; #define MMA(ai, bj, At, Btf) do { __builtin_amdgcn_s_setprio(1); \
;     for (int m = 0; m < 4; ++m) for (int n = 0; n < 2; ++n) for (int k = 0; k < 2; ++k) \
;       acc[ai][bj][m][n] = __builtin_amdgcn_mfma_f32_16x16x32_bf16(Btf[n][k], At[m][k], acc[ai][bj][m][n], 0, 0, 0); \
;     __builtin_amdgcn_s_setprio(0); } while (0)
; #define WAIT_V(n) asm volatile("s_waitcnt vmcnt(" #n ")" ::: "memory")
; #define WAIT_L(n) asm volatile("s_waitcnt lgkmcnt(" #n ")" ::: "memory")
; #define BAR __builtin_amdgcn_s_barrier()
; #define SCHED __builtin_amdgcn_sched_barrier(0)
; template <int EPI> ...
;     ...
;   WAIT_V(4); BAR;
;   STAGE(SB(1, 0), Bt, bcol, 1); STAGE(SA(1, 0), A, brow, 1); STAGE(SB(1, 1), Bt, bcol + HALF, 1);
;   WAIT_V(6); BAR;
;   for (int t = 0; t < nt - 2; t += 2) {
;     LDB(B0, 0, 0); SCHED; LDA(At, 0, 0); STAGE(SA(1, 1), A, brow + HALF, t + 1);
;     WAIT_L(8); BAR; WAIT_L(0); MMA(0, 0, At, B0); BAR; SCHED;
;     LDB(B1, 0, 1); STAGE(SB(0, 0), Bt, bcol, t + 2);
;     BAR; WAIT_L(0); MMA(0, 1, At, B1); BAR;
;     LDA(At, 0, 1); STAGE(SA(0, 0), A, brow, t + 2);
;     BAR; WAIT_L(0); MMA(1, 0, At, B0); BAR; SCHED;
.LBB0_826:
	s_or_b64 exec, exec, s[54:55]
	v_readfirstlane_b32 s54, v164
	v_add_u32_e32 v10, 0x2000, v164
	v_lshl_add_u64 v[8:9], v[6:7], 0, s[10:11]
	s_mov_b32 m0, s54
	v_readfirstlane_b32 s51, v10
	s_waitcnt vmcnt(4)
	s_barrier
	global_load_lds_dwordx4 v[8:9], off
	v_lshl_add_u64 v[8:9], v[6:7], 0, s[12:13]
	s_mov_b32 m0, s51
	v_readfirstlane_b32 s71, v254
	global_load_lds_dwordx4 v[8:9], off
	v_lshl_add_u64 v[8:9], v[4:5], 0, s[10:11]
	s_mov_b32 m0, s71
	v_readfirstlane_b32 s70, v165
	global_load_lds_dwordx4 v[8:9], off
	v_lshl_add_u64 v[8:9], v[4:5], 0, s[12:13]
	s_mov_b32 m0, s70
	v_readfirstlane_b32 s69, v168
	global_load_lds_dwordx4 v[8:9], off
	v_lshl_add_u64 v[8:9], v[2:3], 0, s[10:11]
	s_mov_b32 m0, s69
	v_readfirstlane_b32 s68, v169
	global_load_lds_dwordx4 v[8:9], off
	v_lshl_add_u64 v[8:9], v[2:3], 0, s[12:13]
	s_mov_b32 m0, s68
	s_nop 0
	global_load_lds_dwordx4 v[8:9], off
	s_waitcnt vmcnt(6)
	s_barrier
	ds_read_b128 v[8:11], v176
	ds_read_b128 v[12:15], v176 offset:256
	ds_read_b128 v[16:19], v177
	ds_read_b128 v[20:23], v177 offset:256
	v_readfirstlane_b32 s65, v170
	v_lshl_add_u64 v[56:57], v[0:1], 0, s[10:11]
	s_mov_b32 m0, s65
	v_readfirstlane_b32 s55, v171
	ds_read_b128 v[24:27], v154
	ds_read_b128 v[28:31], v154 offset:1024
	ds_read_b128 v[32:35], v154 offset:2048
	ds_read_b128 v[36:39], v154 offset:3072
	ds_read_b128 v[40:43], v154 offset:4096
	ds_read_b128 v[44:47], v154 offset:5120
	ds_read_b128 v[48:51], v154 offset:6144
	ds_read_b128 v[52:55], v154 offset:7168
	global_load_lds_dwordx4 v[56:57], off
	v_lshl_add_u64 v[56:57], v[0:1], 0, s[12:13]
	s_mov_b32 m0, s55
	s_nop 0
	global_load_lds_dwordx4 v[56:57], off
	s_waitcnt lgkmcnt(8)
	s_waitcnt lgkmcnt(0)
	s_setprio 1
	s_barrier
	v_mfma_f32_16x16x32_bf16 v[56:59], v[8:11], v[24:27], 0
	v_mfma_f32_16x16x32_bf16 v[60:63], v[12:15], v[24:27], 0
	v_mfma_f32_16x16x32_bf16 v[64:67], v[8:11], v[32:35], 0
	v_mfma_f32_16x16x32_bf16 v[68:71], v[12:15], v[32:35], 0
	v_mfma_f32_16x16x32_bf16 v[72:75], v[8:11], v[40:43], 0
	v_mfma_f32_16x16x32_bf16 v[76:79], v[12:15], v[40:43], 0
	v_mfma_f32_16x16x32_bf16 v[80:83], v[8:11], v[48:51], 0
	v_mfma_f32_16x16x32_bf16 v[84:87], v[12:15], v[48:51], 0
	v_mfma_f32_16x16x32_bf16 v[56:59], v[16:19], v[28:31], v[56:59]
	v_mfma_f32_16x16x32_bf16 v[60:63], v[20:23], v[28:31], v[60:63]
	v_mfma_f32_16x16x32_bf16 v[64:67], v[16:19], v[36:39], v[64:67]
	v_mfma_f32_16x16x32_bf16 v[68:71], v[20:23], v[36:39], v[68:71]
	v_mfma_f32_16x16x32_bf16 v[72:75], v[16:19], v[44:47], v[72:75]
	v_mfma_f32_16x16x32_bf16 v[76:79], v[20:23], v[44:47], v[76:79]
	v_mfma_f32_16x16x32_bf16 v[80:83], v[16:19], v[52:55], v[80:83]
	v_mfma_f32_16x16x32_bf16 v[84:87], v[20:23], v[52:55], v[84:87]
	s_barrier
	s_setprio 0
	v_readfirstlane_b32 s64, v156
	v_lshl_add_u64 v[104:105], v[6:7], 0, s[16:17]
	s_mov_b32 m0, s64
	v_readfirstlane_b32 s59, v157
	ds_read_b128 v[88:91], v178
	ds_read_b128 v[92:95], v178 offset:256
	ds_read_b128 v[96:99], v179
	ds_read_b128 v[100:103], v179 offset:256
	global_load_lds_dwordx4 v[104:105], off
	v_lshl_add_u64 v[104:105], v[6:7], 0, s[18:19]
	s_mov_b32 m0, s59
	s_nop 0
	global_load_lds_dwordx4 v[104:105], off
	s_barrier
	s_waitcnt lgkmcnt(0)
	s_setprio 1
	s_waitcnt lgkmcnt(0)
	v_mfma_f32_16x16x32_bf16 v[104:107], v[88:91], v[24:27], 0
	v_mfma_f32_16x16x32_bf16 v[24:27], v[92:95], v[24:27], 0
	v_mfma_f32_16x16x32_bf16 v[104:107], v[96:99], v[28:31], v[104:107]
	v_mfma_f32_16x16x32_bf16 v[24:27], v[100:103], v[28:31], v[24:27]
	v_mfma_f32_16x16x32_bf16 v[28:31], v[88:91], v[32:35], 0
	v_mfma_f32_16x16x32_bf16 v[32:35], v[92:95], v[32:35], 0
	v_mfma_f32_16x16x32_bf16 v[28:31], v[96:99], v[36:39], v[28:31]
	v_mfma_f32_16x16x32_bf16 v[32:35], v[100:103], v[36:39], v[32:35]
	v_mfma_f32_16x16x32_bf16 v[36:39], v[88:91], v[40:43], 0
	v_mfma_f32_16x16x32_bf16 v[40:43], v[92:95], v[40:43], 0
	v_mfma_f32_16x16x32_bf16 v[36:39], v[96:99], v[44:47], v[36:39]
	v_mfma_f32_16x16x32_bf16 v[40:43], v[100:103], v[44:47], v[40:43]
	v_mfma_f32_16x16x32_bf16 v[44:47], v[88:91], v[48:51], 0
	v_mfma_f32_16x16x32_bf16 v[48:51], v[92:95], v[48:51], 0
	v_mfma_f32_16x16x32_bf16 v[44:47], v[96:99], v[52:55], v[44:47]
	v_mfma_f32_16x16x32_bf16 v[48:51], v[100:103], v[52:55], v[48:51]
	s_setprio 0
	v_readfirstlane_b32 s66, v158
	v_lshl_add_u64 v[138:139], v[4:5], 0, s[16:17]
	s_mov_b32 m0, s66
	v_readfirstlane_b32 s60, v159
	s_barrier
	ds_read_b128 v[52:55], v154 offset:16384
	ds_read_b128 v[108:111], v154 offset:17408
	ds_read_b128 v[112:115], v154 offset:18432
	ds_read_b128 v[116:119], v154 offset:19456
	ds_read_b128 v[120:123], v154 offset:20480
	ds_read_b128 v[124:127], v154 offset:21504
	ds_read_b128 v[128:131], v154 offset:22528
	ds_read_b128 v[132:135], v154 offset:23552
	global_load_lds_dwordx4 v[138:139], off
	v_lshl_add_u64 v[138:139], v[4:5], 0, s[18:19]
	s_mov_b32 m0, s60
	s_nop 0
	global_load_lds_dwordx4 v[138:139], off
	s_waitcnt lgkmcnt(0)
	s_setprio 1
	s_barrier
	v_mfma_f32_16x16x32_bf16 v[142:145], v[8:11], v[52:55], 0
	v_mfma_f32_16x16x32_bf16 v[146:149], v[12:15], v[52:55], 0
	v_mfma_f32_16x16x32_bf16 v[150:153], v[8:11], v[112:115], 0
	v_mfma_f32_16x16x32_bf16 v[180:183], v[12:15], v[112:115], 0
	v_mfma_f32_16x16x32_bf16 v[184:187], v[8:11], v[120:123], 0
	v_mfma_f32_16x16x32_bf16 v[188:191], v[12:15], v[120:123], 0
	v_mfma_f32_16x16x32_bf16 v[8:11], v[8:11], v[128:131], 0
	v_mfma_f32_16x16x32_bf16 v[12:15], v[12:15], v[128:131], 0
	v_mfma_f32_16x16x32_bf16 v[8:11], v[16:19], v[132:135], v[8:11]
	v_mfma_f32_16x16x32_bf16 v[12:15], v[20:23], v[132:135], v[12:15]
	v_mfma_f32_16x16x32_bf16 v[142:145], v[16:19], v[108:111], v[142:145]
	v_mfma_f32_16x16x32_bf16 v[146:149], v[20:23], v[108:111], v[146:149]
	v_mfma_f32_16x16x32_bf16 v[150:153], v[16:19], v[116:119], v[150:153]
	v_mfma_f32_16x16x32_bf16 v[180:183], v[20:23], v[116:119], v[180:183]
	v_mfma_f32_16x16x32_bf16 v[184:187], v[16:19], v[124:127], v[184:187]
	v_mfma_f32_16x16x32_bf16 v[188:191], v[20:23], v[124:127], v[188:191]
	s_barrier
; #define STAGE(P, BASE, br, kt) do { const char* _gb = (const char*)(BASE) + ((size_t)(br) * K + (size_t)(kt) * BK) * 2; \
;     __builtin_amdgcn_global_load_lds((const unsigned*)(_gb + loff0), (unsigned*)((char*)(P) + tid * 16), 16, 0, 0); \
;     __builtin_amdgcn_global_load_lds((const unsigned*)(_gb + (size_t)K * 128 + loff0), (unsigned*)((char*)(P) + tid * 16 + 8192), 16, 0, 0); } while (0)
; #define LDA(dst, b, h) for (int m = 0; m < 4; ++m) { \
;     dst[m][0] = *reinterpret_cast<const bf16x8*>((char*)SA(b, h) + aoff0 + m * 2048); \
;     dst[m][1] = *reinterpret_cast<const bf16x8*>((char*)SA(b, h) + aoff1 + m * 2048); }
; #define LDB(dst, b, h) for (int n = 0; n < 2; ++n) { \
;     dst[n][0] = *reinterpret_cast<const bf16x8*>((char*)SB(b, h) + boff0 + n * 256); \
;     dst[n][1] = *reinterpret_cast<const bf16x8*>((char*)SB(b, h) + boff1 + n * 256); }
; #define MMA(ai, bj, At, Btf) do { __builtin_amdgcn_s_setprio(1); \
;     for (int m = 0; m < 4; ++m) for (int n = 0; n < 2; ++n) for (int k = 0; k < 2; ++k) \
;       acc[ai][bj][m][n] = __builtin_amdgcn_mfma_f32_16x16x32_bf16(Btf[n][k], At[m][k], acc[ai][bj][m][n], 0, 0, 0); \
;     __builtin_amdgcn_s_setprio(0); } while (0)
; #define WAIT_V(n) asm volatile("s_waitcnt vmcnt(" #n ")" ::: "memory")
; #define WAIT_L(n) asm volatile("s_waitcnt lgkmcnt(" #n ")" ::: "memory")
; #define BAR __builtin_amdgcn_s_barrier()
; #define SCHED __builtin_amdgcn_sched_barrier(0)
; template <int EPI> ...
;     ...
;     STAGE(SB(0, 1), Bt, bcol + HALF, t + 2);
;     WAIT_V(6); BAR; MMA(1, 1, At, B1); BAR;
;     LDB(B0, 1, 0); SCHED; LDA(At, 1, 0); STAGE(SA(0, 1), A, brow + HALF, t + 2);
;     WAIT_L(8); BAR; WAIT_L(0); MMA(0, 0, At, B0); BAR; SCHED;
;     LDB(B1, 1, 1); STAGE(SB(1, 0), Bt, bcol, t + 3);
;     BAR; WAIT_L(0); MMA(0, 1, At, B1); BAR;
;     LDA(At, 1, 1); STAGE(SA(1, 0), A, brow, t + 3);
;     BAR; WAIT_L(0); MMA(1, 0, At, B0); BAR; SCHED;
	s_setprio 0
	v_readfirstlane_b32 s63, v160
	v_lshl_add_u64 v[16:17], v[2:3], 0, s[16:17]
	s_mov_b32 m0, s63
	v_readfirstlane_b32 s61, v161
	global_load_lds_dwordx4 v[16:17], off
	v_lshl_add_u64 v[16:17], v[2:3], 0, s[18:19]
	s_mov_b32 m0, s61
	s_nop 0
	global_load_lds_dwordx4 v[16:17], off
	s_waitcnt vmcnt(6)
	s_barrier
	s_setprio 1
	v_mfma_f32_16x16x32_bf16 v[16:19], v[88:91], v[52:55], 0
	v_mfma_f32_16x16x32_bf16 v[20:23], v[92:95], v[52:55], 0
	v_mfma_f32_16x16x32_bf16 v[16:19], v[96:99], v[108:111], v[16:19]
	v_mfma_f32_16x16x32_bf16 v[20:23], v[100:103], v[108:111], v[20:23]
	v_mfma_f32_16x16x32_bf16 v[52:55], v[88:91], v[112:115], 0
	v_mfma_f32_16x16x32_bf16 v[108:111], v[92:95], v[112:115], 0
	v_mfma_f32_16x16x32_bf16 v[52:55], v[96:99], v[116:119], v[52:55]
	v_mfma_f32_16x16x32_bf16 v[108:111], v[100:103], v[116:119], v[108:111]
	v_mfma_f32_16x16x32_bf16 v[112:115], v[88:91], v[120:123], 0
	v_mfma_f32_16x16x32_bf16 v[116:119], v[92:95], v[120:123], 0
	v_mfma_f32_16x16x32_bf16 v[88:91], v[88:91], v[128:131], 0
	v_mfma_f32_16x16x32_bf16 v[92:95], v[92:95], v[128:131], 0
	v_mfma_f32_16x16x32_bf16 v[112:115], v[96:99], v[124:127], v[112:115]
	v_mfma_f32_16x16x32_bf16 v[116:119], v[100:103], v[124:127], v[116:119]
	v_mfma_f32_16x16x32_bf16 v[88:91], v[96:99], v[132:135], v[88:91]
	v_mfma_f32_16x16x32_bf16 v[92:95], v[100:103], v[132:135], v[92:95]
	s_setprio 0
	s_barrier
	ds_read_b128 v[96:99], v172
	ds_read_b128 v[100:103], v172 offset:256
	ds_read_b128 v[120:123], v173
	ds_read_b128 v[124:127], v173 offset:256
	v_readfirstlane_b32 s67, v162
	v_lshl_add_u64 v[138:139], v[0:1], 0, s[16:17]
	s_mov_b32 m0, s67
	v_readfirstlane_b32 s62, v163
	ds_read_b128 v[128:131], v154 offset:32768
	ds_read_b128 v[132:135], v154 offset:33792
	ds_read_b128 v[192:195], v154 offset:34816
	ds_read_b128 v[196:199], v154 offset:35840
	ds_read_b128 v[200:203], v154 offset:36864
	ds_read_b128 v[204:207], v154 offset:37888
	ds_read_b128 v[208:211], v154 offset:38912
	ds_read_b128 v[212:215], v154 offset:39936
	global_load_lds_dwordx4 v[138:139], off
	v_lshl_add_u64 v[138:139], v[0:1], 0, s[18:19]
	s_mov_b32 m0, s62
	s_nop 0
	global_load_lds_dwordx4 v[138:139], off
	s_waitcnt lgkmcnt(8)
	s_waitcnt lgkmcnt(0)
	s_setprio 1
	s_barrier
	v_mfma_f32_16x16x32_bf16 v[56:59], v[96:99], v[128:131], v[56:59]
	v_mfma_f32_16x16x32_bf16 v[60:63], v[100:103], v[128:131], v[60:63]
	v_mfma_f32_16x16x32_bf16 v[64:67], v[96:99], v[192:195], v[64:67]
	v_mfma_f32_16x16x32_bf16 v[68:71], v[100:103], v[192:195], v[68:71]
	v_mfma_f32_16x16x32_bf16 v[72:75], v[96:99], v[200:203], v[72:75]
	v_mfma_f32_16x16x32_bf16 v[76:79], v[100:103], v[200:203], v[76:79]
	v_mfma_f32_16x16x32_bf16 v[80:83], v[96:99], v[208:211], v[80:83]
	v_mfma_f32_16x16x32_bf16 v[84:87], v[100:103], v[208:211], v[84:87]
	v_mfma_f32_16x16x32_bf16 v[56:59], v[120:123], v[132:135], v[56:59]
	v_mfma_f32_16x16x32_bf16 v[60:63], v[124:127], v[132:135], v[60:63]
	v_mfma_f32_16x16x32_bf16 v[64:67], v[120:123], v[196:199], v[64:67]
	v_mfma_f32_16x16x32_bf16 v[68:71], v[124:127], v[196:199], v[68:71]
	v_mfma_f32_16x16x32_bf16 v[72:75], v[120:123], v[204:207], v[72:75]
	v_mfma_f32_16x16x32_bf16 v[76:79], v[124:127], v[204:207], v[76:79]
	v_mfma_f32_16x16x32_bf16 v[80:83], v[120:123], v[212:215], v[80:83]
	v_mfma_f32_16x16x32_bf16 v[84:87], v[124:127], v[212:215], v[84:87]
	s_barrier
	s_setprio 0
	s_mov_b32 m0, s54
	v_lshl_add_u64 v[138:139], v[6:7], 0, s[20:21]
	ds_read_b128 v[216:219], v174
	ds_read_b128 v[220:223], v174 offset:256
	ds_read_b128 v[224:227], v175
	ds_read_b128 v[228:231], v175 offset:256
	global_load_lds_dwordx4 v[138:139], off
	v_lshl_add_u64 v[138:139], v[6:7], 0, s[22:23]
	s_mov_b32 m0, s51
	s_nop 0
	global_load_lds_dwordx4 v[138:139], off
	s_barrier
	s_waitcnt lgkmcnt(0)
	s_setprio 1
	s_waitcnt lgkmcnt(0)
	v_mfma_f32_16x16x32_bf16 v[104:107], v[216:219], v[128:131], v[104:107]
	v_mfma_f32_16x16x32_bf16 v[24:27], v[220:223], v[128:131], v[24:27]
	v_mfma_f32_16x16x32_bf16 v[28:31], v[216:219], v[192:195], v[28:31]
	v_mfma_f32_16x16x32_bf16 v[32:35], v[220:223], v[192:195], v[32:35]
	v_mfma_f32_16x16x32_bf16 v[36:39], v[216:219], v[200:203], v[36:39]
	v_mfma_f32_16x16x32_bf16 v[40:43], v[220:223], v[200:203], v[40:43]
	v_mfma_f32_16x16x32_bf16 v[44:47], v[216:219], v[208:211], v[44:47]
	v_mfma_f32_16x16x32_bf16 v[48:51], v[220:223], v[208:211], v[48:51]
	v_mfma_f32_16x16x32_bf16 v[104:107], v[224:227], v[132:135], v[104:107]
	v_mfma_f32_16x16x32_bf16 v[24:27], v[228:231], v[132:135], v[24:27]
	v_mfma_f32_16x16x32_bf16 v[28:31], v[224:227], v[196:199], v[28:31]
	v_mfma_f32_16x16x32_bf16 v[32:35], v[228:231], v[196:199], v[32:35]
	v_mfma_f32_16x16x32_bf16 v[36:39], v[224:227], v[204:207], v[36:39]
	v_mfma_f32_16x16x32_bf16 v[40:43], v[228:231], v[204:207], v[40:43]
	v_mfma_f32_16x16x32_bf16 v[44:47], v[224:227], v[212:215], v[44:47]
	v_mfma_f32_16x16x32_bf16 v[48:51], v[228:231], v[212:215], v[48:51]
	s_setprio 0
	s_mov_b32 m0, s71
	v_lshl_add_u64 v[138:139], v[4:5], 0, s[20:21]
	s_barrier
	ds_read_b128 v[128:131], v154 offset:49152
	ds_read_b128 v[132:135], v154 offset:50176
	ds_read_b128 v[192:195], v154 offset:51200
	ds_read_b128 v[196:199], v154 offset:52224
	ds_read_b128 v[200:203], v154 offset:53248
	ds_read_b128 v[204:207], v154 offset:54272
	ds_read_b128 v[208:211], v154 offset:55296
	ds_read_b128 v[212:215], v154 offset:56320
	global_load_lds_dwordx4 v[138:139], off
	v_lshl_add_u64 v[138:139], v[4:5], 0, s[22:23]
	s_mov_b32 m0, s70
	s_nop 0
	global_load_lds_dwordx4 v[138:139], off
	s_waitcnt lgkmcnt(0)
	s_setprio 1
	s_barrier
; #define STAGE(P, BASE, br, kt) do { const char* _gb = (const char*)(BASE) + ((size_t)(br) * K + (size_t)(kt) * BK) * 2; \
;     __builtin_amdgcn_global_load_lds((const unsigned*)(_gb + loff0), (unsigned*)((char*)(P) + tid * 16), 16, 0, 0); \
;     __builtin_amdgcn_global_load_lds((const unsigned*)(_gb + (size_t)K * 128 + loff0), (unsigned*)((char*)(P) + tid * 16 + 8192), 16, 0, 0); } while (0)
; #define LDA(dst, b, h) for (int m = 0; m < 4; ++m) { \
;     dst[m][0] = *reinterpret_cast<const bf16x8*>((char*)SA(b, h) + aoff0 + m * 2048); \
;     dst[m][1] = *reinterpret_cast<const bf16x8*>((char*)SA(b, h) + aoff1 + m * 2048); }
; #define LDB(dst, b, h) for (int n = 0; n < 2; ++n) { \
;     dst[n][0] = *reinterpret_cast<const bf16x8*>((char*)SB(b, h) + boff0 + n * 256); \
;     dst[n][1] = *reinterpret_cast<const bf16x8*>((char*)SB(b, h) + boff1 + n * 256); }
; #define MMA(ai, bj, At, Btf) do { __builtin_amdgcn_s_setprio(1); \
;     for (int m = 0; m < 4; ++m) for (int n = 0; n < 2; ++n) for (int k = 0; k < 2; ++k) \
;       acc[ai][bj][m][n] = __builtin_amdgcn_mfma_f32_16x16x32_bf16(Btf[n][k], At[m][k], acc[ai][bj][m][n], 0, 0, 0); \
;     __builtin_amdgcn_s_setprio(0); } while (0)
; #define WAIT_V(n) asm volatile("s_waitcnt vmcnt(" #n ")" ::: "memory")
; #define WAIT_L(n) asm volatile("s_waitcnt lgkmcnt(" #n ")" ::: "memory")
; #define BAR __builtin_amdgcn_s_barrier()
; #define SCHED __builtin_amdgcn_sched_barrier(0)
; template <int EPI> ...
;     ...
;     LDB(B0, 0, 0); SCHED; LDA(At, 0, 0); STAGE(SA(1, 1), A, brow + HALF, t + 1);
;     WAIT_L(8); BAR; WAIT_L(0); MMA(0, 0, At, B0); BAR; SCHED;
;     LDB(B1, 0, 1); STAGE(SB(0, 0), Bt, bcol, t + 2);
;     BAR; WAIT_L(0); MMA(0, 1, At, B1); BAR;
;     LDA(At, 0, 1); STAGE(SA(0, 0), A, brow, t + 2);
;     ...
;     BAR; WAIT_L(0); MMA(1, 0, At, B0); BAR; SCHED;
;     STAGE(SB(1, 1), Bt, bcol + HALF, t + 3);
;     WAIT_V(6); BAR; MMA(1, 1, At, B1); BAR;
	v_mfma_f32_16x16x32_bf16 v[8:11], v[96:99], v[208:211], v[8:11]
	v_mfma_f32_16x16x32_bf16 v[12:15], v[100:103], v[208:211], v[12:15]
	v_mfma_f32_16x16x32_bf16 v[142:145], v[96:99], v[128:131], v[142:145]
	v_mfma_f32_16x16x32_bf16 v[146:149], v[100:103], v[128:131], v[146:149]
	v_mfma_f32_16x16x32_bf16 v[150:153], v[96:99], v[192:195], v[150:153]
	v_mfma_f32_16x16x32_bf16 v[180:183], v[100:103], v[192:195], v[180:183]
	v_mfma_f32_16x16x32_bf16 v[184:187], v[96:99], v[200:203], v[184:187]
	v_mfma_f32_16x16x32_bf16 v[188:191], v[100:103], v[200:203], v[188:191]
	v_mfma_f32_16x16x32_bf16 v[8:11], v[120:123], v[212:215], v[8:11]
	v_mfma_f32_16x16x32_bf16 v[12:15], v[124:127], v[212:215], v[12:15]
	v_mfma_f32_16x16x32_bf16 v[142:145], v[120:123], v[132:135], v[142:145]
	v_mfma_f32_16x16x32_bf16 v[146:149], v[124:127], v[132:135], v[146:149]
	v_mfma_f32_16x16x32_bf16 v[150:153], v[120:123], v[196:199], v[150:153]
	v_mfma_f32_16x16x32_bf16 v[180:183], v[124:127], v[196:199], v[180:183]
	v_mfma_f32_16x16x32_bf16 v[184:187], v[120:123], v[204:207], v[184:187]
	v_mfma_f32_16x16x32_bf16 v[188:191], v[124:127], v[204:207], v[188:191]
	s_barrier
	s_setprio 0
	s_mov_b32 m0, s69
	v_lshl_add_u64 v[96:97], v[2:3], 0, s[20:21]
	global_load_lds_dwordx4 v[96:97], off
	v_lshl_add_u64 v[96:97], v[2:3], 0, s[22:23]
	s_mov_b32 m0, s68
	s_nop 0
	global_load_lds_dwordx4 v[96:97], off
	s_waitcnt vmcnt(6)
	s_barrier
	s_setprio 1
	v_mfma_f32_16x16x32_bf16 v[16:19], v[216:219], v[128:131], v[16:19]
	v_mfma_f32_16x16x32_bf16 v[20:23], v[220:223], v[128:131], v[20:23]
	v_mfma_f32_16x16x32_bf16 v[52:55], v[216:219], v[192:195], v[52:55]
	v_mfma_f32_16x16x32_bf16 v[96:99], v[220:223], v[192:195], v[108:111]
	v_mfma_f32_16x16x32_bf16 v[108:111], v[220:223], v[200:203], v[116:119]
	v_mfma_f32_16x16x32_bf16 v[88:91], v[216:219], v[208:211], v[88:91]
	v_mfma_f32_16x16x32_bf16 v[92:95], v[220:223], v[208:211], v[92:95]
	v_mfma_f32_16x16x32_bf16 v[16:19], v[224:227], v[132:135], v[16:19]
	v_mfma_f32_16x16x32_bf16 v[20:23], v[228:231], v[132:135], v[20:23]
	v_mfma_f32_16x16x32_bf16 v[52:55], v[224:227], v[196:199], v[52:55]
	v_mfma_f32_16x16x32_bf16 v[100:103], v[216:219], v[200:203], v[112:115]
	v_mfma_f32_16x16x32_bf16 v[108:111], v[228:231], v[204:207], v[108:111]
	v_mfma_f32_16x16x32_bf16 v[88:91], v[224:227], v[212:215], v[88:91]
	v_mfma_f32_16x16x32_bf16 v[92:95], v[228:231], v[212:215], v[92:95]
	v_mfma_f32_16x16x32_bf16 v[96:99], v[228:231], v[196:199], v[96:99]
	v_mfma_f32_16x16x32_bf16 v[100:103], v[224:227], v[204:207], v[100:103]
	s_setprio 0
	s_barrier
	ds_read_b128 v[112:115], v176
	ds_read_b128 v[116:119], v176 offset:256
	ds_read_b128 v[120:123], v177
	ds_read_b128 v[124:127], v177 offset:256
	s_mov_b32 m0, s65
	v_lshl_add_u64 v[138:139], v[0:1], 0, s[20:21]
	ds_read_b128 v[128:131], v154
	ds_read_b128 v[132:135], v154 offset:1024
	ds_read_b128 v[192:195], v154 offset:2048
	ds_read_b128 v[196:199], v154 offset:3072
	ds_read_b128 v[200:203], v154 offset:4096
	ds_read_b128 v[204:207], v154 offset:5120
	ds_read_b128 v[208:211], v154 offset:6144
	ds_read_b128 v[212:215], v154 offset:7168
	global_load_lds_dwordx4 v[138:139], off
	v_lshl_add_u64 v[138:139], v[0:1], 0, s[22:23]
	s_mov_b32 m0, s55
	s_nop 0
	global_load_lds_dwordx4 v[138:139], off
	s_waitcnt lgkmcnt(8)
	s_waitcnt lgkmcnt(0)
	s_setprio 1
	s_barrier
	v_mfma_f32_16x16x32_bf16 v[56:59], v[112:115], v[128:131], v[56:59]
	v_mfma_f32_16x16x32_bf16 v[60:63], v[116:119], v[128:131], v[60:63]
	v_mfma_f32_16x16x32_bf16 v[64:67], v[112:115], v[192:195], v[64:67]
	v_mfma_f32_16x16x32_bf16 v[68:71], v[116:119], v[192:195], v[68:71]
	v_mfma_f32_16x16x32_bf16 v[72:75], v[112:115], v[200:203], v[72:75]
	v_mfma_f32_16x16x32_bf16 v[76:79], v[116:119], v[200:203], v[76:79]
	v_mfma_f32_16x16x32_bf16 v[80:83], v[112:115], v[208:211], v[80:83]
	v_mfma_f32_16x16x32_bf16 v[84:87], v[116:119], v[208:211], v[84:87]
	v_mfma_f32_16x16x32_bf16 v[56:59], v[120:123], v[132:135], v[56:59]
	v_mfma_f32_16x16x32_bf16 v[60:63], v[124:127], v[132:135], v[60:63]
	v_mfma_f32_16x16x32_bf16 v[64:67], v[120:123], v[196:199], v[64:67]
	v_mfma_f32_16x16x32_bf16 v[68:71], v[124:127], v[196:199], v[68:71]
	v_mfma_f32_16x16x32_bf16 v[72:75], v[120:123], v[204:207], v[72:75]
	v_mfma_f32_16x16x32_bf16 v[76:79], v[124:127], v[204:207], v[76:79]
	v_mfma_f32_16x16x32_bf16 v[80:83], v[120:123], v[212:215], v[80:83]
	v_mfma_f32_16x16x32_bf16 v[84:87], v[124:127], v[212:215], v[84:87]
	s_barrier
	s_setprio 0
	s_mov_b32 m0, s64
	v_lshl_add_u64 v[138:139], v[6:7], 0, s[24:25]
	ds_read_b128 v[216:219], v178
	ds_read_b128 v[220:223], v178 offset:256
	ds_read_b128 v[224:227], v179
	ds_read_b128 v[228:231], v179 offset:256
	global_load_lds_dwordx4 v[138:139], off
	v_lshl_add_u64 v[138:139], v[6:7], 0, s[26:27]
	s_mov_b32 m0, s59
	s_nop 0
	global_load_lds_dwordx4 v[138:139], off
	s_barrier
	s_waitcnt lgkmcnt(0)
	s_setprio 1
	s_waitcnt lgkmcnt(0)
	v_mfma_f32_16x16x32_bf16 v[104:107], v[216:219], v[128:131], v[104:107]
	v_mfma_f32_16x16x32_bf16 v[24:27], v[220:223], v[128:131], v[24:27]
	v_mfma_f32_16x16x32_bf16 v[28:31], v[216:219], v[192:195], v[28:31]
	v_mfma_f32_16x16x32_bf16 v[32:35], v[220:223], v[192:195], v[32:35]
	v_mfma_f32_16x16x32_bf16 v[36:39], v[216:219], v[200:203], v[36:39]
	v_mfma_f32_16x16x32_bf16 v[40:43], v[220:223], v[200:203], v[40:43]
	v_mfma_f32_16x16x32_bf16 v[44:47], v[216:219], v[208:211], v[44:47]
	v_mfma_f32_16x16x32_bf16 v[48:51], v[220:223], v[208:211], v[48:51]
	v_mfma_f32_16x16x32_bf16 v[104:107], v[224:227], v[132:135], v[104:107]
	v_mfma_f32_16x16x32_bf16 v[24:27], v[228:231], v[132:135], v[24:27]
	v_mfma_f32_16x16x32_bf16 v[28:31], v[224:227], v[196:199], v[28:31]
	v_mfma_f32_16x16x32_bf16 v[32:35], v[228:231], v[196:199], v[32:35]
	v_mfma_f32_16x16x32_bf16 v[36:39], v[224:227], v[204:207], v[36:39]
	v_mfma_f32_16x16x32_bf16 v[40:43], v[228:231], v[204:207], v[40:43]
	v_mfma_f32_16x16x32_bf16 v[44:47], v[224:227], v[212:215], v[44:47]
	v_mfma_f32_16x16x32_bf16 v[48:51], v[228:231], v[212:215], v[48:51]
	s_setprio 0
	s_mov_b32 m0, s66
	v_lshl_add_u64 v[138:139], v[4:5], 0, s[24:25]
	s_barrier
; #define STAGE(P, BASE, br, kt) do { const char* _gb = (const char*)(BASE) + ((size_t)(br) * K + (size_t)(kt) * BK) * 2; \
;     __builtin_amdgcn_global_load_lds((const unsigned*)(_gb + loff0), (unsigned*)((char*)(P) + tid * 16), 16, 0, 0); \
;     __builtin_amdgcn_global_load_lds((const unsigned*)(_gb + (size_t)K * 128 + loff0), (unsigned*)((char*)(P) + tid * 16 + 8192), 16, 0, 0); } while (0)
; #define LDA(dst, b, h) for (int m = 0; m < 4; ++m) { \
;     dst[m][0] = *reinterpret_cast<const bf16x8*>((char*)SA(b, h) + aoff0 + m * 2048); \
;     dst[m][1] = *reinterpret_cast<const bf16x8*>((char*)SA(b, h) + aoff1 + m * 2048); }
; #define LDB(dst, b, h) for (int n = 0; n < 2; ++n) { \
;     dst[n][0] = *reinterpret_cast<const bf16x8*>((char*)SB(b, h) + boff0 + n * 256); \
;     dst[n][1] = *reinterpret_cast<const bf16x8*>((char*)SB(b, h) + boff1 + n * 256); }
; #define MMA(ai, bj, At, Btf) do { __builtin_amdgcn_s_setprio(1); \
;     for (int m = 0; m < 4; ++m) for (int n = 0; n < 2; ++n) for (int k = 0; k < 2; ++k) \
;       acc[ai][bj][m][n] = __builtin_amdgcn_mfma_f32_16x16x32_bf16(Btf[n][k], At[m][k], acc[ai][bj][m][n], 0, 0, 0); \
;     __builtin_amdgcn_s_setprio(0); } while (0)
; #define WAIT_V(n) asm volatile("s_waitcnt vmcnt(" #n ")" ::: "memory")
; #define WAIT_L(n) asm volatile("s_waitcnt lgkmcnt(" #n ")" ::: "memory")
; #define BAR __builtin_amdgcn_s_barrier()
; #define SCHED __builtin_amdgcn_sched_barrier(0)
; template <int EPI> ...
;     ...
;     LDA(At, 0, 1); STAGE(SA(0, 0), A, brow, t + 2);
;     BAR; WAIT_L(0); MMA(1, 0, At, B0); BAR; SCHED;
;     STAGE(SB(0, 1), Bt, bcol + HALF, t + 2);
;     WAIT_V(6); BAR; MMA(1, 1, At, B1); BAR;
;     LDB(B0, 1, 0); SCHED; LDA(At, 1, 0); STAGE(SA(0, 1), A, brow + HALF, t + 2);
;     WAIT_L(8); BAR; WAIT_L(0); MMA(0, 0, At, B0); BAR; SCHED;
;     LDB(B1, 1, 1); STAGE(SB(1, 0), Bt, bcol, t + 3);
	ds_read_b128 v[128:131], v154 offset:16384
	ds_read_b128 v[132:135], v154 offset:17408
	ds_read_b128 v[192:195], v154 offset:18432
	ds_read_b128 v[196:199], v154 offset:19456
	ds_read_b128 v[200:203], v154 offset:20480
	ds_read_b128 v[204:207], v154 offset:21504
	ds_read_b128 v[208:211], v154 offset:22528
	ds_read_b128 v[212:215], v154 offset:23552
	global_load_lds_dwordx4 v[138:139], off
	v_lshl_add_u64 v[138:139], v[4:5], 0, s[26:27]
	s_mov_b32 m0, s60
	s_nop 0
	global_load_lds_dwordx4 v[138:139], off
	s_waitcnt lgkmcnt(0)
	s_setprio 1
	s_barrier
	v_mfma_f32_16x16x32_bf16 v[8:11], v[112:115], v[208:211], v[8:11]
	v_mfma_f32_16x16x32_bf16 v[12:15], v[116:119], v[208:211], v[12:15]
	v_mfma_f32_16x16x32_bf16 v[142:145], v[112:115], v[128:131], v[142:145]
	v_mfma_f32_16x16x32_bf16 v[146:149], v[116:119], v[128:131], v[146:149]
	v_mfma_f32_16x16x32_bf16 v[150:153], v[112:115], v[192:195], v[150:153]
	v_mfma_f32_16x16x32_bf16 v[180:183], v[116:119], v[192:195], v[180:183]
	v_mfma_f32_16x16x32_bf16 v[184:187], v[112:115], v[200:203], v[184:187]
	v_mfma_f32_16x16x32_bf16 v[188:191], v[116:119], v[200:203], v[188:191]
	v_mfma_f32_16x16x32_bf16 v[8:11], v[120:123], v[212:215], v[8:11]
	v_mfma_f32_16x16x32_bf16 v[12:15], v[124:127], v[212:215], v[12:15]
	v_mfma_f32_16x16x32_bf16 v[142:145], v[120:123], v[132:135], v[142:145]
	v_mfma_f32_16x16x32_bf16 v[146:149], v[124:127], v[132:135], v[146:149]
	v_mfma_f32_16x16x32_bf16 v[150:153], v[120:123], v[196:199], v[150:153]
	v_mfma_f32_16x16x32_bf16 v[180:183], v[124:127], v[196:199], v[180:183]
	v_mfma_f32_16x16x32_bf16 v[184:187], v[120:123], v[204:207], v[184:187]
	v_mfma_f32_16x16x32_bf16 v[188:191], v[124:127], v[204:207], v[188:191]
	s_barrier
	s_setprio 0
	s_mov_b32 m0, s63
	v_lshl_add_u64 v[112:113], v[2:3], 0, s[24:25]
	global_load_lds_dwordx4 v[112:113], off
	v_lshl_add_u64 v[112:113], v[2:3], 0, s[26:27]
	s_mov_b32 m0, s61
	s_nop 0
	global_load_lds_dwordx4 v[112:113], off
	s_waitcnt vmcnt(6)
	s_barrier
	s_setprio 1
	v_mfma_f32_16x16x32_bf16 v[16:19], v[216:219], v[128:131], v[16:19]
	v_mfma_f32_16x16x32_bf16 v[20:23], v[220:223], v[128:131], v[20:23]
	v_mfma_f32_16x16x32_bf16 v[52:55], v[216:219], v[192:195], v[52:55]
	v_mfma_f32_16x16x32_bf16 v[108:111], v[220:223], v[200:203], v[108:111]
	v_mfma_f32_16x16x32_bf16 v[88:91], v[216:219], v[208:211], v[88:91]
	v_mfma_f32_16x16x32_bf16 v[92:95], v[220:223], v[208:211], v[92:95]
	v_mfma_f32_16x16x32_bf16 v[16:19], v[224:227], v[132:135], v[16:19]
	v_mfma_f32_16x16x32_bf16 v[20:23], v[228:231], v[132:135], v[20:23]
	v_mfma_f32_16x16x32_bf16 v[52:55], v[224:227], v[196:199], v[52:55]
	v_mfma_f32_16x16x32_bf16 v[96:99], v[220:223], v[192:195], v[96:99]
	v_mfma_f32_16x16x32_bf16 v[100:103], v[216:219], v[200:203], v[100:103]
	v_mfma_f32_16x16x32_bf16 v[108:111], v[228:231], v[204:207], v[108:111]
	v_mfma_f32_16x16x32_bf16 v[88:91], v[224:227], v[212:215], v[88:91]
	v_mfma_f32_16x16x32_bf16 v[92:95], v[228:231], v[212:215], v[92:95]
	v_mfma_f32_16x16x32_bf16 v[96:99], v[228:231], v[196:199], v[96:99]
	v_mfma_f32_16x16x32_bf16 v[100:103], v[224:227], v[204:207], v[100:103]
	s_setprio 0
	s_barrier
	ds_read_b128 v[112:115], v172
	ds_read_b128 v[116:119], v172 offset:256
	ds_read_b128 v[120:123], v173
	ds_read_b128 v[124:127], v173 offset:256
	s_mov_b32 m0, s67
	v_lshl_add_u64 v[138:139], v[0:1], 0, s[24:25]
	ds_read_b128 v[128:131], v154 offset:32768
	ds_read_b128 v[132:135], v154 offset:33792
	ds_read_b128 v[192:195], v154 offset:34816
	ds_read_b128 v[196:199], v154 offset:35840
	ds_read_b128 v[200:203], v154 offset:36864
	ds_read_b128 v[204:207], v154 offset:37888
	ds_read_b128 v[208:211], v154 offset:38912
	ds_read_b128 v[212:215], v154 offset:39936
	global_load_lds_dwordx4 v[138:139], off
	v_lshl_add_u64 v[138:139], v[0:1], 0, s[26:27]
	s_mov_b32 m0, s62
	s_nop 0
	global_load_lds_dwordx4 v[138:139], off
	s_waitcnt lgkmcnt(8)
	s_waitcnt lgkmcnt(0)
	s_setprio 1
	s_barrier
	v_mfma_f32_16x16x32_bf16 v[56:59], v[112:115], v[128:131], v[56:59]
	v_mfma_f32_16x16x32_bf16 v[60:63], v[116:119], v[128:131], v[60:63]
	v_mfma_f32_16x16x32_bf16 v[64:67], v[112:115], v[192:195], v[64:67]
	v_mfma_f32_16x16x32_bf16 v[68:71], v[116:119], v[192:195], v[68:71]
	v_mfma_f32_16x16x32_bf16 v[72:75], v[112:115], v[200:203], v[72:75]
	v_mfma_f32_16x16x32_bf16 v[76:79], v[116:119], v[200:203], v[76:79]
	v_mfma_f32_16x16x32_bf16 v[80:83], v[112:115], v[208:211], v[80:83]
	v_mfma_f32_16x16x32_bf16 v[84:87], v[116:119], v[208:211], v[84:87]
	v_mfma_f32_16x16x32_bf16 v[56:59], v[120:123], v[132:135], v[56:59]
	v_mfma_f32_16x16x32_bf16 v[60:63], v[124:127], v[132:135], v[60:63]
	v_mfma_f32_16x16x32_bf16 v[64:67], v[120:123], v[196:199], v[64:67]
	v_mfma_f32_16x16x32_bf16 v[68:71], v[124:127], v[196:199], v[68:71]
	v_mfma_f32_16x16x32_bf16 v[72:75], v[120:123], v[204:207], v[72:75]
	v_mfma_f32_16x16x32_bf16 v[76:79], v[124:127], v[204:207], v[76:79]
	v_mfma_f32_16x16x32_bf16 v[80:83], v[120:123], v[212:215], v[80:83]
	v_mfma_f32_16x16x32_bf16 v[84:87], v[124:127], v[212:215], v[84:87]
	s_barrier
	s_setprio 0
	s_mov_b32 m0, s54
	v_lshl_add_u64 v[138:139], v[6:7], 0, s[28:29]
	ds_read_b128 v[216:219], v174
	ds_read_b128 v[220:223], v174 offset:256
	ds_read_b128 v[224:227], v175
	ds_read_b128 v[228:231], v175 offset:256
	global_load_lds_dwordx4 v[138:139], off
	v_lshl_add_u64 v[138:139], v[6:7], 0, s[30:31]
	s_mov_b32 m0, s51
	s_nop 0
	global_load_lds_dwordx4 v[138:139], off
	s_barrier
; #define STAGE(P, BASE, br, kt) do { const char* _gb = (const char*)(BASE) + ((size_t)(br) * K + (size_t)(kt) * BK) * 2; \
;     __builtin_amdgcn_global_load_lds((const unsigned*)(_gb + loff0), (unsigned*)((char*)(P) + tid * 16), 16, 0, 0); \
;     __builtin_amdgcn_global_load_lds((const unsigned*)(_gb + (size_t)K * 128 + loff0), (unsigned*)((char*)(P) + tid * 16 + 8192), 16, 0, 0); } while (0)
; #define LDA(dst, b, h) for (int m = 0; m < 4; ++m) { \
;     dst[m][0] = *reinterpret_cast<const bf16x8*>((char*)SA(b, h) + aoff0 + m * 2048); \
;     dst[m][1] = *reinterpret_cast<const bf16x8*>((char*)SA(b, h) + aoff1 + m * 2048); }
; #define LDB(dst, b, h) for (int n = 0; n < 2; ++n) { \
;     dst[n][0] = *reinterpret_cast<const bf16x8*>((char*)SB(b, h) + boff0 + n * 256); \
;     dst[n][1] = *reinterpret_cast<const bf16x8*>((char*)SB(b, h) + boff1 + n * 256); }
; #define MMA(ai, bj, At, Btf) do { __builtin_amdgcn_s_setprio(1); \
;     for (int m = 0; m < 4; ++m) for (int n = 0; n < 2; ++n) for (int k = 0; k < 2; ++k) \
;       acc[ai][bj][m][n] = __builtin_amdgcn_mfma_f32_16x16x32_bf16(Btf[n][k], At[m][k], acc[ai][bj][m][n], 0, 0, 0); \
;     __builtin_amdgcn_s_setprio(0); } while (0)
; #define WAIT_V(n) asm volatile("s_waitcnt vmcnt(" #n ")" ::: "memory")
; #define WAIT_L(n) asm volatile("s_waitcnt lgkmcnt(" #n ")" ::: "memory")
; #define BAR __builtin_amdgcn_s_barrier()
; #define SCHED __builtin_amdgcn_sched_barrier(0)
; template <int EPI> ...
;     ...
;     LDB(B0, 0, 0); SCHED; LDA(At, 0, 0); STAGE(SA(1, 1), A, brow + HALF, t + 1);
;     WAIT_L(8); BAR; WAIT_L(0); MMA(0, 0, At, B0); BAR; SCHED;
;     LDB(B1, 0, 1); STAGE(SB(0, 0), Bt, bcol, t + 2);
;     BAR; WAIT_L(0); MMA(0, 1, At, B1); BAR;
;     LDA(At, 0, 1); STAGE(SA(0, 0), A, brow, t + 2);
;     BAR; WAIT_L(0); MMA(1, 0, At, B0); BAR; SCHED;
;     STAGE(SB(0, 1), Bt, bcol + HALF, t + 2);
;     WAIT_V(6); BAR; MMA(1, 1, At, B1); BAR;
;     LDB(B0, 1, 0); SCHED; LDA(At, 1, 0); STAGE(SA(0, 1), A, brow + HALF, t + 2);
;     WAIT_L(8); BAR; WAIT_L(0); MMA(0, 0, At, B0); BAR; SCHED;
;     LDB(B1, 1, 1); STAGE(SB(1, 0), Bt, bcol, t + 3);
;     BAR; WAIT_L(0); MMA(0, 1, At, B1); BAR;
;     LDA(At, 1, 1); STAGE(SA(1, 0), A, brow, t + 3);
;     BAR; WAIT_L(0); MMA(1, 0, At, B0); BAR; SCHED;
;     STAGE(SB(1, 1), Bt, bcol + HALF, t + 3);
;     WAIT_V(6); BAR; MMA(1, 1, At, B1); BAR;
	s_waitcnt lgkmcnt(0)
	s_setprio 1
	s_waitcnt lgkmcnt(0)
	v_mfma_f32_16x16x32_bf16 v[104:107], v[216:219], v[128:131], v[104:107]
	v_mfma_f32_16x16x32_bf16 v[24:27], v[220:223], v[128:131], v[24:27]
	v_mfma_f32_16x16x32_bf16 v[28:31], v[216:219], v[192:195], v[28:31]
	v_mfma_f32_16x16x32_bf16 v[32:35], v[220:223], v[192:195], v[32:35]
	v_mfma_f32_16x16x32_bf16 v[36:39], v[216:219], v[200:203], v[36:39]
	v_mfma_f32_16x16x32_bf16 v[40:43], v[220:223], v[200:203], v[40:43]
	v_mfma_f32_16x16x32_bf16 v[44:47], v[216:219], v[208:211], v[44:47]
	v_mfma_f32_16x16x32_bf16 v[48:51], v[220:223], v[208:211], v[48:51]
	v_mfma_f32_16x16x32_bf16 v[104:107], v[224:227], v[132:135], v[104:107]
	v_mfma_f32_16x16x32_bf16 v[24:27], v[228:231], v[132:135], v[24:27]
	v_mfma_f32_16x16x32_bf16 v[28:31], v[224:227], v[196:199], v[28:31]
	v_mfma_f32_16x16x32_bf16 v[32:35], v[228:231], v[196:199], v[32:35]
	v_mfma_f32_16x16x32_bf16 v[36:39], v[224:227], v[204:207], v[36:39]
	v_mfma_f32_16x16x32_bf16 v[40:43], v[228:231], v[204:207], v[40:43]
	v_mfma_f32_16x16x32_bf16 v[44:47], v[224:227], v[212:215], v[44:47]
	v_mfma_f32_16x16x32_bf16 v[48:51], v[228:231], v[212:215], v[48:51]
	s_setprio 0
	v_readfirstlane_b32 s62, v254
	v_lshl_add_u64 v[138:139], v[4:5], 0, s[28:29]
	s_mov_b32 m0, s62
	v_readfirstlane_b32 s55, v165
	s_barrier
	ds_read_b128 v[128:131], v154 offset:49152
	ds_read_b128 v[132:135], v154 offset:50176
	ds_read_b128 v[192:195], v154 offset:51200
	ds_read_b128 v[196:199], v154 offset:52224
	ds_read_b128 v[200:203], v154 offset:53248
	ds_read_b128 v[204:207], v154 offset:54272
	ds_read_b128 v[208:211], v154 offset:55296
	ds_read_b128 v[212:215], v154 offset:56320
	global_load_lds_dwordx4 v[138:139], off
	v_lshl_add_u64 v[138:139], v[4:5], 0, s[30:31]
	s_mov_b32 m0, s55
	s_nop 0
	global_load_lds_dwordx4 v[138:139], off
	s_waitcnt lgkmcnt(0)
	s_setprio 1
	s_barrier
	v_mfma_f32_16x16x32_bf16 v[8:11], v[112:115], v[208:211], v[8:11]
	v_mfma_f32_16x16x32_bf16 v[12:15], v[116:119], v[208:211], v[12:15]
	v_mfma_f32_16x16x32_bf16 v[142:145], v[112:115], v[128:131], v[142:145]
	v_mfma_f32_16x16x32_bf16 v[146:149], v[116:119], v[128:131], v[146:149]
	v_mfma_f32_16x16x32_bf16 v[150:153], v[112:115], v[192:195], v[150:153]
	v_mfma_f32_16x16x32_bf16 v[180:183], v[116:119], v[192:195], v[180:183]
	v_mfma_f32_16x16x32_bf16 v[184:187], v[112:115], v[200:203], v[184:187]
	v_mfma_f32_16x16x32_bf16 v[188:191], v[116:119], v[200:203], v[188:191]
	v_mfma_f32_16x16x32_bf16 v[8:11], v[120:123], v[212:215], v[8:11]
	v_mfma_f32_16x16x32_bf16 v[12:15], v[124:127], v[212:215], v[12:15]
	v_mfma_f32_16x16x32_bf16 v[142:145], v[120:123], v[132:135], v[142:145]
	v_mfma_f32_16x16x32_bf16 v[146:149], v[124:127], v[132:135], v[146:149]
	v_mfma_f32_16x16x32_bf16 v[150:153], v[120:123], v[196:199], v[150:153]
	v_mfma_f32_16x16x32_bf16 v[180:183], v[124:127], v[196:199], v[180:183]
	v_mfma_f32_16x16x32_bf16 v[184:187], v[120:123], v[204:207], v[184:187]
	v_mfma_f32_16x16x32_bf16 v[188:191], v[124:127], v[204:207], v[188:191]
	s_barrier
	s_setprio 0
	v_readfirstlane_b32 s60, v168
	v_lshl_add_u64 v[112:113], v[2:3], 0, s[28:29]
	s_mov_b32 m0, s60
	v_readfirstlane_b32 s59, v169
	global_load_lds_dwordx4 v[112:113], off
	v_lshl_add_u64 v[112:113], v[2:3], 0, s[30:31]
	s_mov_b32 m0, s59
	s_nop 0
	global_load_lds_dwordx4 v[112:113], off
	s_waitcnt vmcnt(6)
	s_barrier
	s_setprio 1
	v_mfma_f32_16x16x32_bf16 v[16:19], v[216:219], v[128:131], v[16:19]
	v_mfma_f32_16x16x32_bf16 v[20:23], v[220:223], v[128:131], v[20:23]
	v_mfma_f32_16x16x32_bf16 v[52:55], v[216:219], v[192:195], v[52:55]
	v_mfma_f32_16x16x32_bf16 v[108:111], v[220:223], v[200:203], v[108:111]
	v_mfma_f32_16x16x32_bf16 v[88:91], v[216:219], v[208:211], v[88:91]
	v_mfma_f32_16x16x32_bf16 v[92:95], v[220:223], v[208:211], v[92:95]
	v_mfma_f32_16x16x32_bf16 v[16:19], v[224:227], v[132:135], v[16:19]
	v_mfma_f32_16x16x32_bf16 v[20:23], v[228:231], v[132:135], v[20:23]
	v_mfma_f32_16x16x32_bf16 v[52:55], v[224:227], v[196:199], v[52:55]
	v_mfma_f32_16x16x32_bf16 v[96:99], v[220:223], v[192:195], v[96:99]
	v_mfma_f32_16x16x32_bf16 v[100:103], v[216:219], v[200:203], v[100:103]
	v_mfma_f32_16x16x32_bf16 v[108:111], v[228:231], v[204:207], v[108:111]
	v_mfma_f32_16x16x32_bf16 v[88:91], v[224:227], v[212:215], v[88:91]
	v_mfma_f32_16x16x32_bf16 v[92:95], v[228:231], v[212:215], v[92:95]
	v_mfma_f32_16x16x32_bf16 v[96:99], v[228:231], v[196:199], v[96:99]
	v_mfma_f32_16x16x32_bf16 v[100:103], v[224:227], v[204:207], v[100:103]
	s_setprio 0
	s_barrier
	ds_read_b128 v[112:115], v176
	ds_read_b128 v[116:119], v176 offset:256
	ds_read_b128 v[120:123], v177
	ds_read_b128 v[124:127], v177 offset:256
	v_readfirstlane_b32 s63, v170
	v_lshl_add_u64 v[138:139], v[0:1], 0, s[28:29]
	s_mov_b32 m0, s63
	v_readfirstlane_b32 s61, v171
	ds_read_b128 v[128:131], v154
	ds_read_b128 v[132:135], v154 offset:1024
	ds_read_b128 v[192:195], v154 offset:2048
	ds_read_b128 v[196:199], v154 offset:3072
	ds_read_b128 v[200:203], v154 offset:4096
	ds_read_b128 v[204:207], v154 offset:5120
	ds_read_b128 v[208:211], v154 offset:6144
	ds_read_b128 v[212:215], v154 offset:7168
	global_load_lds_dwordx4 v[138:139], off
	v_lshl_add_u64 v[138:139], v[0:1], 0, s[30:31]
	s_mov_b32 m0, s61
	s_nop 0
	global_load_lds_dwordx4 v[138:139], off
	s_waitcnt lgkmcnt(8)
	s_waitcnt lgkmcnt(0)
	s_setprio 1
	s_barrier
; #define STAGE(P, BASE, br, kt) do { const char* _gb = (const char*)(BASE) + ((size_t)(br) * K + (size_t)(kt) * BK) * 2; \
;     __builtin_amdgcn_global_load_lds((const unsigned*)(_gb + loff0), (unsigned*)((char*)(P) + tid * 16), 16, 0, 0); \
;     __builtin_amdgcn_global_load_lds((const unsigned*)(_gb + (size_t)K * 128 + loff0), (unsigned*)((char*)(P) + tid * 16 + 8192), 16, 0, 0); } while (0)
; #define LDA(dst, b, h) for (int m = 0; m < 4; ++m) { \
;     dst[m][0] = *reinterpret_cast<const bf16x8*>((char*)SA(b, h) + aoff0 + m * 2048); \
;     dst[m][1] = *reinterpret_cast<const bf16x8*>((char*)SA(b, h) + aoff1 + m * 2048); }
; #define LDB(dst, b, h) for (int n = 0; n < 2; ++n) { \
;     dst[n][0] = *reinterpret_cast<const bf16x8*>((char*)SB(b, h) + boff0 + n * 256); \
;     dst[n][1] = *reinterpret_cast<const bf16x8*>((char*)SB(b, h) + boff1 + n * 256); }
; #define MMA(ai, bj, At, Btf) do { __builtin_amdgcn_s_setprio(1); \
;     for (int m = 0; m < 4; ++m) for (int n = 0; n < 2; ++n) for (int k = 0; k < 2; ++k) \
;       acc[ai][bj][m][n] = __builtin_amdgcn_mfma_f32_16x16x32_bf16(Btf[n][k], At[m][k], acc[ai][bj][m][n], 0, 0, 0); \
;     __builtin_amdgcn_s_setprio(0); } while (0)
; #define WAIT_V(n) asm volatile("s_waitcnt vmcnt(" #n ")" ::: "memory")
; #define WAIT_L(n) asm volatile("s_waitcnt lgkmcnt(" #n ")" ::: "memory")
; #define BAR __builtin_amdgcn_s_barrier()
; #define SCHED __builtin_amdgcn_sched_barrier(0)
; template <int EPI> ...
;     ...
;     WAIT_L(8); BAR; WAIT_L(0); MMA(0, 0, At, B0); BAR; SCHED;
;     LDB(B1, 0, 1); STAGE(SB(0, 0), Bt, bcol, t + 2);
;     BAR; WAIT_L(0); MMA(0, 1, At, B1); BAR;
;     LDA(At, 0, 1); STAGE(SA(0, 0), A, brow, t + 2);
;     BAR; WAIT_L(0); MMA(1, 0, At, B0); BAR; SCHED;
;     STAGE(SB(0, 1), Bt, bcol + HALF, t + 2);
;     WAIT_V(6); BAR; MMA(1, 1, At, B1); BAR;
	v_mfma_f32_16x16x32_bf16 v[56:59], v[112:115], v[128:131], v[56:59]
	v_mfma_f32_16x16x32_bf16 v[60:63], v[116:119], v[128:131], v[60:63]
	v_mfma_f32_16x16x32_bf16 v[64:67], v[112:115], v[192:195], v[64:67]
	v_mfma_f32_16x16x32_bf16 v[68:71], v[116:119], v[192:195], v[68:71]
	v_mfma_f32_16x16x32_bf16 v[72:75], v[112:115], v[200:203], v[72:75]
	v_mfma_f32_16x16x32_bf16 v[76:79], v[116:119], v[200:203], v[76:79]
	v_mfma_f32_16x16x32_bf16 v[80:83], v[112:115], v[208:211], v[80:83]
	v_mfma_f32_16x16x32_bf16 v[84:87], v[116:119], v[208:211], v[84:87]
	v_mfma_f32_16x16x32_bf16 v[56:59], v[120:123], v[132:135], v[56:59]
	v_mfma_f32_16x16x32_bf16 v[60:63], v[124:127], v[132:135], v[60:63]
	v_mfma_f32_16x16x32_bf16 v[64:67], v[120:123], v[196:199], v[64:67]
	v_mfma_f32_16x16x32_bf16 v[68:71], v[124:127], v[196:199], v[68:71]
	v_mfma_f32_16x16x32_bf16 v[72:75], v[120:123], v[204:207], v[72:75]
	v_mfma_f32_16x16x32_bf16 v[76:79], v[124:127], v[204:207], v[76:79]
	v_mfma_f32_16x16x32_bf16 v[80:83], v[120:123], v[212:215], v[80:83]
	v_mfma_f32_16x16x32_bf16 v[84:87], v[124:127], v[212:215], v[84:87]
	s_barrier
	s_setprio 0
	v_readfirstlane_b32 s64, v156
	v_lshl_add_u64 v[138:139], v[6:7], 0, s[36:37]
	s_mov_b32 m0, s64
	v_readfirstlane_b32 s64, v157
	ds_read_b128 v[216:219], v178
	ds_read_b128 v[220:223], v178 offset:256
	ds_read_b128 v[224:227], v179
	ds_read_b128 v[228:231], v179 offset:256
	global_load_lds_dwordx4 v[138:139], off
	v_lshl_add_u64 v[138:139], v[6:7], 0, s[38:39]
	s_mov_b32 m0, s64
	s_nop 0
	global_load_lds_dwordx4 v[138:139], off
	s_barrier
	s_waitcnt lgkmcnt(0)
	s_setprio 1
	s_waitcnt lgkmcnt(0)
	v_mfma_f32_16x16x32_bf16 v[104:107], v[216:219], v[128:131], v[104:107]
	v_mfma_f32_16x16x32_bf16 v[24:27], v[220:223], v[128:131], v[24:27]
	v_mfma_f32_16x16x32_bf16 v[28:31], v[216:219], v[192:195], v[28:31]
	v_mfma_f32_16x16x32_bf16 v[32:35], v[220:223], v[192:195], v[32:35]
	v_mfma_f32_16x16x32_bf16 v[36:39], v[216:219], v[200:203], v[36:39]
	v_mfma_f32_16x16x32_bf16 v[40:43], v[220:223], v[200:203], v[40:43]
	v_mfma_f32_16x16x32_bf16 v[44:47], v[216:219], v[208:211], v[44:47]
	v_mfma_f32_16x16x32_bf16 v[48:51], v[220:223], v[208:211], v[48:51]
	v_mfma_f32_16x16x32_bf16 v[104:107], v[224:227], v[132:135], v[104:107]
	v_mfma_f32_16x16x32_bf16 v[24:27], v[228:231], v[132:135], v[24:27]
	v_mfma_f32_16x16x32_bf16 v[28:31], v[224:227], v[196:199], v[28:31]
	v_mfma_f32_16x16x32_bf16 v[32:35], v[228:231], v[196:199], v[32:35]
	v_mfma_f32_16x16x32_bf16 v[36:39], v[224:227], v[204:207], v[36:39]
	v_mfma_f32_16x16x32_bf16 v[40:43], v[228:231], v[204:207], v[40:43]
	v_mfma_f32_16x16x32_bf16 v[44:47], v[224:227], v[212:215], v[44:47]
	v_mfma_f32_16x16x32_bf16 v[48:51], v[228:231], v[212:215], v[48:51]
	s_setprio 0
	v_readfirstlane_b32 s64, v158
	v_lshl_add_u64 v[138:139], v[4:5], 0, s[36:37]
	s_mov_b32 m0, s64
	v_readfirstlane_b32 s64, v159
	s_barrier
	ds_read_b128 v[128:131], v154 offset:16384
	ds_read_b128 v[132:135], v154 offset:17408
	ds_read_b128 v[192:195], v154 offset:18432
	ds_read_b128 v[196:199], v154 offset:19456
	ds_read_b128 v[200:203], v154 offset:20480
	ds_read_b128 v[204:207], v154 offset:21504
	ds_read_b128 v[208:211], v154 offset:22528
	ds_read_b128 v[212:215], v154 offset:23552
	global_load_lds_dwordx4 v[138:139], off
	v_lshl_add_u64 v[138:139], v[4:5], 0, s[38:39]
	s_mov_b32 m0, s64
	s_nop 0
	global_load_lds_dwordx4 v[138:139], off
	s_waitcnt lgkmcnt(0)
	s_setprio 1
	s_barrier
	v_mfma_f32_16x16x32_bf16 v[8:11], v[112:115], v[208:211], v[8:11]
	v_mfma_f32_16x16x32_bf16 v[12:15], v[116:119], v[208:211], v[12:15]
	v_mfma_f32_16x16x32_bf16 v[142:145], v[112:115], v[128:131], v[142:145]
	v_mfma_f32_16x16x32_bf16 v[146:149], v[116:119], v[128:131], v[146:149]
	v_mfma_f32_16x16x32_bf16 v[150:153], v[112:115], v[192:195], v[150:153]
	v_mfma_f32_16x16x32_bf16 v[180:183], v[116:119], v[192:195], v[180:183]
	v_mfma_f32_16x16x32_bf16 v[184:187], v[112:115], v[200:203], v[184:187]
	v_mfma_f32_16x16x32_bf16 v[188:191], v[116:119], v[200:203], v[188:191]
	v_mfma_f32_16x16x32_bf16 v[8:11], v[120:123], v[212:215], v[8:11]
	v_mfma_f32_16x16x32_bf16 v[12:15], v[124:127], v[212:215], v[12:15]
	v_mfma_f32_16x16x32_bf16 v[142:145], v[120:123], v[132:135], v[142:145]
	v_mfma_f32_16x16x32_bf16 v[146:149], v[124:127], v[132:135], v[146:149]
	v_mfma_f32_16x16x32_bf16 v[150:153], v[120:123], v[196:199], v[150:153]
	v_mfma_f32_16x16x32_bf16 v[180:183], v[124:127], v[196:199], v[180:183]
	v_mfma_f32_16x16x32_bf16 v[184:187], v[120:123], v[204:207], v[184:187]
	v_mfma_f32_16x16x32_bf16 v[188:191], v[124:127], v[204:207], v[188:191]
	s_barrier
	s_setprio 0
	v_readfirstlane_b32 s64, v160
	v_lshl_add_u64 v[112:113], v[2:3], 0, s[36:37]
	s_mov_b32 m0, s64
	v_readfirstlane_b32 s64, v161
	global_load_lds_dwordx4 v[112:113], off
	v_lshl_add_u64 v[112:113], v[2:3], 0, s[38:39]
	s_mov_b32 m0, s64
	s_nop 0
	global_load_lds_dwordx4 v[112:113], off
	s_waitcnt vmcnt(6)
	s_barrier
	s_setprio 1
	v_mfma_f32_16x16x32_bf16 v[16:19], v[216:219], v[128:131], v[16:19]
	v_mfma_f32_16x16x32_bf16 v[20:23], v[220:223], v[128:131], v[20:23]
	v_mfma_f32_16x16x32_bf16 v[52:55], v[216:219], v[192:195], v[52:55]
	v_mfma_f32_16x16x32_bf16 v[108:111], v[220:223], v[200:203], v[108:111]
	v_mfma_f32_16x16x32_bf16 v[88:91], v[216:219], v[208:211], v[88:91]
	v_mfma_f32_16x16x32_bf16 v[92:95], v[220:223], v[208:211], v[92:95]
	v_mfma_f32_16x16x32_bf16 v[16:19], v[224:227], v[132:135], v[16:19]
	v_mfma_f32_16x16x32_bf16 v[20:23], v[228:231], v[132:135], v[20:23]
	v_mfma_f32_16x16x32_bf16 v[52:55], v[224:227], v[196:199], v[52:55]
	v_mfma_f32_16x16x32_bf16 v[96:99], v[220:223], v[192:195], v[96:99]
	v_mfma_f32_16x16x32_bf16 v[100:103], v[216:219], v[200:203], v[100:103]
	v_mfma_f32_16x16x32_bf16 v[108:111], v[228:231], v[204:207], v[108:111]
	v_mfma_f32_16x16x32_bf16 v[88:91], v[224:227], v[212:215], v[88:91]
	v_mfma_f32_16x16x32_bf16 v[92:95], v[228:231], v[212:215], v[92:95]
	v_mfma_f32_16x16x32_bf16 v[96:99], v[228:231], v[196:199], v[96:99]
	v_mfma_f32_16x16x32_bf16 v[100:103], v[224:227], v[204:207], v[100:103]
	s_setprio 0
	s_barrier
; #define STAGE(P, BASE, br, kt) do { const char* _gb = (const char*)(BASE) + ((size_t)(br) * K + (size_t)(kt) * BK) * 2; \
;     __builtin_amdgcn_global_load_lds((const unsigned*)(_gb + loff0), (unsigned*)((char*)(P) + tid * 16), 16, 0, 0); \
;     __builtin_amdgcn_global_load_lds((const unsigned*)(_gb + (size_t)K * 128 + loff0), (unsigned*)((char*)(P) + tid * 16 + 8192), 16, 0, 0); } while (0)
; #define LDA(dst, b, h) for (int m = 0; m < 4; ++m) { \
;     dst[m][0] = *reinterpret_cast<const bf16x8*>((char*)SA(b, h) + aoff0 + m * 2048); \
;     dst[m][1] = *reinterpret_cast<const bf16x8*>((char*)SA(b, h) + aoff1 + m * 2048); }
; #define LDB(dst, b, h) for (int n = 0; n < 2; ++n) { \
;     dst[n][0] = *reinterpret_cast<const bf16x8*>((char*)SB(b, h) + boff0 + n * 256); \
;     dst[n][1] = *reinterpret_cast<const bf16x8*>((char*)SB(b, h) + boff1 + n * 256); }
; #define MMA(ai, bj, At, Btf) do { __builtin_amdgcn_s_setprio(1); \
;     for (int m = 0; m < 4; ++m) for (int n = 0; n < 2; ++n) for (int k = 0; k < 2; ++k) \
;       acc[ai][bj][m][n] = __builtin_amdgcn_mfma_f32_16x16x32_bf16(Btf[n][k], At[m][k], acc[ai][bj][m][n], 0, 0, 0); \
;     __builtin_amdgcn_s_setprio(0); } while (0)
; #define WAIT_V(n) asm volatile("s_waitcnt vmcnt(" #n ")" ::: "memory")
; #define WAIT_L(n) asm volatile("s_waitcnt lgkmcnt(" #n ")" ::: "memory")
; #define BAR __builtin_amdgcn_s_barrier()
; #define SCHED __builtin_amdgcn_sched_barrier(0)
; template <int EPI> ...
;     ...
;     LDB(B0, 1, 0); SCHED; LDA(At, 1, 0); STAGE(SA(0, 1), A, brow + HALF, t + 2);
;     WAIT_L(8); BAR; WAIT_L(0); MMA(0, 0, At, B0); BAR; SCHED;
;     LDB(B1, 1, 1); STAGE(SB(1, 0), Bt, bcol, t + 3);
;     BAR; WAIT_L(0); MMA(0, 1, At, B1); BAR;
;     LDA(At, 1, 1); STAGE(SA(1, 0), A, brow, t + 3);
;     BAR; WAIT_L(0); MMA(1, 0, At, B0); BAR; SCHED;
;     STAGE(SB(1, 1), Bt, bcol + HALF, t + 3);
;     WAIT_V(6); BAR; MMA(1, 1, At, B1); BAR;
	ds_read_b128 v[112:115], v172
	ds_read_b128 v[116:119], v172 offset:256
	ds_read_b128 v[120:123], v173
	ds_read_b128 v[124:127], v173 offset:256
	v_readfirstlane_b32 s64, v162
	v_lshl_add_u64 v[138:139], v[0:1], 0, s[36:37]
	s_mov_b32 m0, s64
	v_readfirstlane_b32 s64, v163
	ds_read_b128 v[128:131], v154 offset:32768
	ds_read_b128 v[132:135], v154 offset:33792
	ds_read_b128 v[192:195], v154 offset:34816
	ds_read_b128 v[196:199], v154 offset:35840
	ds_read_b128 v[200:203], v154 offset:36864
	ds_read_b128 v[204:207], v154 offset:37888
	ds_read_b128 v[208:211], v154 offset:38912
	ds_read_b128 v[212:215], v154 offset:39936
	global_load_lds_dwordx4 v[138:139], off
	v_lshl_add_u64 v[138:139], v[0:1], 0, s[38:39]
	s_mov_b32 m0, s64
	s_nop 0
	global_load_lds_dwordx4 v[138:139], off
	s_waitcnt lgkmcnt(8)
	s_waitcnt lgkmcnt(0)
	s_setprio 1
	s_barrier
	v_mfma_f32_16x16x32_bf16 v[56:59], v[112:115], v[128:131], v[56:59]
	v_mfma_f32_16x16x32_bf16 v[60:63], v[116:119], v[128:131], v[60:63]
	v_mfma_f32_16x16x32_bf16 v[64:67], v[112:115], v[192:195], v[64:67]
	v_mfma_f32_16x16x32_bf16 v[68:71], v[116:119], v[192:195], v[68:71]
	v_mfma_f32_16x16x32_bf16 v[72:75], v[112:115], v[200:203], v[72:75]
	v_mfma_f32_16x16x32_bf16 v[76:79], v[116:119], v[200:203], v[76:79]
	v_mfma_f32_16x16x32_bf16 v[80:83], v[112:115], v[208:211], v[80:83]
	v_mfma_f32_16x16x32_bf16 v[84:87], v[116:119], v[208:211], v[84:87]
	v_mfma_f32_16x16x32_bf16 v[56:59], v[120:123], v[132:135], v[56:59]
	v_mfma_f32_16x16x32_bf16 v[60:63], v[124:127], v[132:135], v[60:63]
	v_mfma_f32_16x16x32_bf16 v[64:67], v[120:123], v[196:199], v[64:67]
	v_mfma_f32_16x16x32_bf16 v[68:71], v[124:127], v[196:199], v[68:71]
	v_mfma_f32_16x16x32_bf16 v[72:75], v[120:123], v[204:207], v[72:75]
	v_mfma_f32_16x16x32_bf16 v[76:79], v[124:127], v[204:207], v[76:79]
	v_mfma_f32_16x16x32_bf16 v[80:83], v[120:123], v[212:215], v[80:83]
	v_mfma_f32_16x16x32_bf16 v[84:87], v[124:127], v[212:215], v[84:87]
	s_barrier
	s_setprio 0
	s_mov_b32 m0, s54
	v_lshl_add_u64 v[138:139], v[6:7], 0, s[46:47]
	ds_read_b128 v[216:219], v174
	ds_read_b128 v[220:223], v174 offset:256
	ds_read_b128 v[224:227], v175
	ds_read_b128 v[228:231], v175 offset:256
	global_load_lds_dwordx4 v[138:139], off
	v_lshl_add_u64 v[6:7], v[6:7], 0, s[48:49]
	s_mov_b32 m0, s51
	s_nop 0
	global_load_lds_dwordx4 v[6:7], off
	s_barrier
	s_waitcnt lgkmcnt(0)
	s_setprio 1
	s_waitcnt lgkmcnt(0)
	v_mfma_f32_16x16x32_bf16 v[104:107], v[216:219], v[128:131], v[104:107]
	v_mfma_f32_16x16x32_bf16 v[24:27], v[220:223], v[128:131], v[24:27]
	v_mfma_f32_16x16x32_bf16 v[28:31], v[216:219], v[192:195], v[28:31]
	v_mfma_f32_16x16x32_bf16 v[32:35], v[220:223], v[192:195], v[32:35]
	v_mfma_f32_16x16x32_bf16 v[36:39], v[216:219], v[200:203], v[36:39]
	v_mfma_f32_16x16x32_bf16 v[40:43], v[220:223], v[200:203], v[40:43]
	v_mfma_f32_16x16x32_bf16 v[44:47], v[216:219], v[208:211], v[44:47]
	v_mfma_f32_16x16x32_bf16 v[48:51], v[220:223], v[208:211], v[48:51]
	v_mfma_f32_16x16x32_bf16 v[104:107], v[224:227], v[132:135], v[104:107]
	v_mfma_f32_16x16x32_bf16 v[24:27], v[228:231], v[132:135], v[24:27]
	v_mfma_f32_16x16x32_bf16 v[28:31], v[224:227], v[196:199], v[28:31]
	v_mfma_f32_16x16x32_bf16 v[32:35], v[228:231], v[196:199], v[32:35]
	v_mfma_f32_16x16x32_bf16 v[36:39], v[224:227], v[204:207], v[36:39]
	v_mfma_f32_16x16x32_bf16 v[40:43], v[228:231], v[204:207], v[40:43]
	v_mfma_f32_16x16x32_bf16 v[44:47], v[224:227], v[212:215], v[44:47]
	v_mfma_f32_16x16x32_bf16 v[48:51], v[228:231], v[212:215], v[48:51]
	s_setprio 0
	s_mov_b32 m0, s62
	v_lshl_add_u64 v[6:7], v[4:5], 0, s[46:47]
	s_barrier
	ds_read_b128 v[128:131], v154 offset:49152
	ds_read_b128 v[132:135], v154 offset:50176
	ds_read_b128 v[192:195], v154 offset:51200
	ds_read_b128 v[196:199], v154 offset:52224
	ds_read_b128 v[200:203], v154 offset:53248
	ds_read_b128 v[204:207], v154 offset:54272
	ds_read_b128 v[208:211], v154 offset:55296
	ds_read_b128 v[212:215], v154 offset:56320
	global_load_lds_dwordx4 v[6:7], off
	v_lshl_add_u64 v[4:5], v[4:5], 0, s[48:49]
	s_mov_b32 m0, s55
	s_nop 0
	global_load_lds_dwordx4 v[4:5], off
	s_waitcnt lgkmcnt(0)
	s_setprio 1
	s_barrier
	v_mfma_f32_16x16x32_bf16 v[4:7], v[112:115], v[128:131], v[142:145]
	v_mfma_f32_16x16x32_bf16 v[8:11], v[112:115], v[208:211], v[8:11]
	v_mfma_f32_16x16x32_bf16 v[12:15], v[116:119], v[208:211], v[12:15]
	v_mfma_f32_16x16x32_bf16 v[4:7], v[120:123], v[132:135], v[4:7]
	v_mfma_f32_16x16x32_bf16 v[142:145], v[116:119], v[128:131], v[146:149]
	v_mfma_f32_16x16x32_bf16 v[146:149], v[112:115], v[192:195], v[150:153]
	v_mfma_f32_16x16x32_bf16 v[150:153], v[116:119], v[192:195], v[180:183]
	v_mfma_f32_16x16x32_bf16 v[180:183], v[112:115], v[200:203], v[184:187]
	v_mfma_f32_16x16x32_bf16 v[184:187], v[116:119], v[200:203], v[188:191]
	v_mfma_f32_16x16x32_bf16 v[8:11], v[120:123], v[212:215], v[8:11]
	v_mfma_f32_16x16x32_bf16 v[12:15], v[124:127], v[212:215], v[12:15]
	v_mfma_f32_16x16x32_bf16 v[142:145], v[124:127], v[132:135], v[142:145]
	v_mfma_f32_16x16x32_bf16 v[146:149], v[120:123], v[196:199], v[146:149]
	v_mfma_f32_16x16x32_bf16 v[150:153], v[124:127], v[196:199], v[150:153]
	v_mfma_f32_16x16x32_bf16 v[180:183], v[120:123], v[204:207], v[180:183]
	v_mfma_f32_16x16x32_bf16 v[184:187], v[124:127], v[204:207], v[184:187]
	s_barrier
	s_setprio 0
	s_mov_b32 m0, s60
	v_lshl_add_u64 v[112:113], v[2:3], 0, s[46:47]
	global_load_lds_dwordx4 v[112:113], off
	v_lshl_add_u64 v[2:3], v[2:3], 0, s[48:49]
	s_mov_b32 m0, s59
	s_nop 0
	global_load_lds_dwordx4 v[2:3], off
	s_waitcnt vmcnt(6)
	s_barrier
; #define STAGE(P, BASE, br, kt) do { const char* _gb = (const char*)(BASE) + ((size_t)(br) * K + (size_t)(kt) * BK) * 2; \
;     __builtin_amdgcn_global_load_lds((const unsigned*)(_gb + loff0), (unsigned*)((char*)(P) + tid * 16), 16, 0, 0); \
;     __builtin_amdgcn_global_load_lds((const unsigned*)(_gb + (size_t)K * 128 + loff0), (unsigned*)((char*)(P) + tid * 16 + 8192), 16, 0, 0); } while (0)
; #define LDA(dst, b, h) for (int m = 0; m < 4; ++m) { \
;     dst[m][0] = *reinterpret_cast<const bf16x8*>((char*)SA(b, h) + aoff0 + m * 2048); \
;     dst[m][1] = *reinterpret_cast<const bf16x8*>((char*)SA(b, h) + aoff1 + m * 2048); }
; #define LDB(dst, b, h) for (int n = 0; n < 2; ++n) { \
;     dst[n][0] = *reinterpret_cast<const bf16x8*>((char*)SB(b, h) + boff0 + n * 256); \
;     dst[n][1] = *reinterpret_cast<const bf16x8*>((char*)SB(b, h) + boff1 + n * 256); }
; #define MMA(ai, bj, At, Btf) do { __builtin_amdgcn_s_setprio(1); \
;     for (int m = 0; m < 4; ++m) for (int n = 0; n < 2; ++n) for (int k = 0; k < 2; ++k) \
;       acc[ai][bj][m][n] = __builtin_amdgcn_mfma_f32_16x16x32_bf16(Btf[n][k], At[m][k], acc[ai][bj][m][n], 0, 0, 0); \
;     __builtin_amdgcn_s_setprio(0); } while (0)
; #define WAIT_V(n) asm volatile("s_waitcnt vmcnt(" #n ")" ::: "memory")
; #define WAIT_L(n) asm volatile("s_waitcnt lgkmcnt(" #n ")" ::: "memory")
; #define BAR __builtin_amdgcn_s_barrier()
; template <int EPI> ...
;     ...
;     WAIT_V(6); BAR; MMA(1, 1, At, B1); BAR;
;   }
;   { LDB(B0, 0, 0); LDA(At, 0, 0); STAGE(SA(1, 1), A, brow + HALF, nt - 1);
;     BAR; WAIT_L(0); MMA(0, 0, At, B0); BAR;
;     LDB(B1, 0, 1); BAR; WAIT_L(0); MMA(0, 1, At, B1); BAR;
;     LDA(At, 0, 1); WAIT_V(4); BAR; WAIT_L(0); MMA(1, 0, At, B0); MMA(1, 1, At, B1); BAR; }
	s_setprio 1
	v_mfma_f32_16x16x32_bf16 v[16:19], v[216:219], v[128:131], v[16:19]
	v_mfma_f32_16x16x32_bf16 v[20:23], v[220:223], v[128:131], v[20:23]
	v_mfma_f32_16x16x32_bf16 v[52:55], v[216:219], v[192:195], v[52:55]
	v_mfma_f32_16x16x32_bf16 v[108:111], v[220:223], v[200:203], v[108:111]
	v_mfma_f32_16x16x32_bf16 v[88:91], v[216:219], v[208:211], v[88:91]
	v_mfma_f32_16x16x32_bf16 v[92:95], v[220:223], v[208:211], v[92:95]
	v_mfma_f32_16x16x32_bf16 v[16:19], v[224:227], v[132:135], v[16:19]
	v_mfma_f32_16x16x32_bf16 v[20:23], v[228:231], v[132:135], v[20:23]
	v_mfma_f32_16x16x32_bf16 v[52:55], v[224:227], v[196:199], v[52:55]
	v_mfma_f32_16x16x32_bf16 v[96:99], v[220:223], v[192:195], v[96:99]
	v_mfma_f32_16x16x32_bf16 v[100:103], v[216:219], v[200:203], v[100:103]
	v_mfma_f32_16x16x32_bf16 v[108:111], v[228:231], v[204:207], v[108:111]
	v_mfma_f32_16x16x32_bf16 v[88:91], v[224:227], v[212:215], v[88:91]
	v_mfma_f32_16x16x32_bf16 v[92:95], v[228:231], v[212:215], v[92:95]
	v_mfma_f32_16x16x32_bf16 v[96:99], v[228:231], v[196:199], v[96:99]
	v_mfma_f32_16x16x32_bf16 v[100:103], v[224:227], v[204:207], v[100:103]
	s_setprio 0
	s_mov_b32 m0, s63
	v_lshl_add_u64 v[2:3], v[0:1], 0, s[46:47]
	s_barrier
	ds_read_b128 v[112:115], v176
	ds_read_b128 v[116:119], v176 offset:256
	ds_read_b128 v[120:123], v177
	ds_read_b128 v[124:127], v177 offset:256
	ds_read_b128 v[128:131], v154
	ds_read_b128 v[132:135], v154 offset:1024
	ds_read_b128 v[188:191], v154 offset:2048
	ds_read_b128 v[192:195], v154 offset:3072
	ds_read_b128 v[196:199], v154 offset:4096
	ds_read_b128 v[200:203], v154 offset:5120
	ds_read_b128 v[204:207], v154 offset:6144
	ds_read_b128 v[208:211], v154 offset:7168
	global_load_lds_dwordx4 v[2:3], off
	v_lshl_add_u64 v[0:1], v[0:1], 0, s[48:49]
	s_mov_b32 m0, s61
	s_nop 0
	global_load_lds_dwordx4 v[0:1], off
	s_waitcnt lgkmcnt(0)
	s_setprio 1
	s_barrier
	v_mfma_f32_16x16x32_bf16 v[0:3], v[112:115], v[128:131], v[56:59]
	v_mfma_f32_16x16x32_bf16 v[56:59], v[116:119], v[128:131], v[60:63]
	v_mfma_f32_16x16x32_bf16 v[60:63], v[112:115], v[188:191], v[64:67]
	v_mfma_f32_16x16x32_bf16 v[64:67], v[116:119], v[188:191], v[68:71]
	v_mfma_f32_16x16x32_bf16 v[68:71], v[112:115], v[196:199], v[72:75]
	v_mfma_f32_16x16x32_bf16 v[72:75], v[116:119], v[196:199], v[76:79]
	v_mfma_f32_16x16x32_bf16 v[76:79], v[112:115], v[204:207], v[80:83]
	v_mfma_f32_16x16x32_bf16 v[80:83], v[116:119], v[204:207], v[84:87]
	v_mfma_f32_16x16x32_bf16 v[0:3], v[120:123], v[132:135], v[0:3]
	v_mfma_f32_16x16x32_bf16 v[56:59], v[124:127], v[132:135], v[56:59]
	v_mfma_f32_16x16x32_bf16 v[60:63], v[120:123], v[192:195], v[60:63]
	v_mfma_f32_16x16x32_bf16 v[64:67], v[124:127], v[192:195], v[64:67]
	v_mfma_f32_16x16x32_bf16 v[68:71], v[120:123], v[200:203], v[68:71]
	v_mfma_f32_16x16x32_bf16 v[72:75], v[124:127], v[200:203], v[72:75]
	v_mfma_f32_16x16x32_bf16 v[76:79], v[120:123], v[208:211], v[76:79]
	v_mfma_f32_16x16x32_bf16 v[80:83], v[124:127], v[208:211], v[80:83]
	s_barrier
	s_setprio 0
	ds_read_b128 v[84:87], v178
	ds_read_b128 v[212:215], v178 offset:256
	ds_read_b128 v[216:219], v179
	ds_read_b128 v[220:223], v179 offset:256
	s_waitcnt lgkmcnt(0)
	s_setprio 1
	s_barrier
	v_mfma_f32_16x16x32_bf16 v[24:27], v[212:215], v[128:131], v[24:27]
	v_mfma_f32_16x16x32_bf16 v[28:31], v[84:87], v[188:191], v[28:31]
	v_mfma_f32_16x16x32_bf16 v[32:35], v[212:215], v[188:191], v[32:35]
	v_mfma_f32_16x16x32_bf16 v[36:39], v[84:87], v[196:199], v[36:39]
	v_mfma_f32_16x16x32_bf16 v[40:43], v[212:215], v[196:199], v[40:43]
	v_mfma_f32_16x16x32_bf16 v[44:47], v[84:87], v[204:207], v[44:47]
	v_mfma_f32_16x16x32_bf16 v[48:51], v[212:215], v[204:207], v[48:51]
	v_mfma_f32_16x16x32_bf16 v[104:107], v[84:87], v[128:131], v[104:107]
	v_mfma_f32_16x16x32_bf16 v[24:27], v[220:223], v[132:135], v[24:27]
	v_mfma_f32_16x16x32_bf16 v[28:31], v[216:219], v[192:195], v[28:31]
	v_mfma_f32_16x16x32_bf16 v[32:35], v[220:223], v[192:195], v[32:35]
	v_mfma_f32_16x16x32_bf16 v[36:39], v[216:219], v[200:203], v[36:39]
	v_mfma_f32_16x16x32_bf16 v[40:43], v[220:223], v[200:203], v[40:43]
	v_mfma_f32_16x16x32_bf16 v[44:47], v[216:219], v[208:211], v[44:47]
	v_mfma_f32_16x16x32_bf16 v[48:51], v[220:223], v[208:211], v[48:51]
	v_mfma_f32_16x16x32_bf16 v[224:227], v[216:219], v[132:135], v[104:107]
	s_barrier
	s_setprio 0
	s_nop 0
	ds_read_b128 v[104:107], v154 offset:16384
	ds_read_b128 v[128:131], v154 offset:17408
	ds_read_b128 v[132:135], v154 offset:18432
	ds_read_b128 v[188:191], v154 offset:19456
	ds_read_b128 v[192:195], v154 offset:20480
	ds_read_b128 v[196:199], v154 offset:21504
	ds_read_b128 v[200:203], v154 offset:22528
	ds_read_b128 v[204:207], v154 offset:23552
	s_waitcnt vmcnt(4)
	s_waitcnt lgkmcnt(0)
	s_setprio 1
	s_barrier
; #define LDA(dst, b, h) for (int m = 0; m < 4; ++m) { \
;     dst[m][0] = *reinterpret_cast<const bf16x8*>((char*)SA(b, h) + aoff0 + m * 2048); \
;     dst[m][1] = *reinterpret_cast<const bf16x8*>((char*)SA(b, h) + aoff1 + m * 2048); }
; #define LDB(dst, b, h) for (int n = 0; n < 2; ++n) { \
;     dst[n][0] = *reinterpret_cast<const bf16x8*>((char*)SB(b, h) + boff0 + n * 256); \
;     dst[n][1] = *reinterpret_cast<const bf16x8*>((char*)SB(b, h) + boff1 + n * 256); }
; #define MMA(ai, bj, At, Btf) do { __builtin_amdgcn_s_setprio(1); \
;     for (int m = 0; m < 4; ++m) for (int n = 0; n < 2; ++n) for (int k = 0; k < 2; ++k) \
;       acc[ai][bj][m][n] = __builtin_amdgcn_mfma_f32_16x16x32_bf16(Btf[n][k], At[m][k], acc[ai][bj][m][n], 0, 0, 0); \
;     __builtin_amdgcn_s_setprio(0); } while (0)
; #define WAIT_V(n) asm volatile("s_waitcnt vmcnt(" #n ")" ::: "memory")
; #define WAIT_L(n) asm volatile("s_waitcnt lgkmcnt(" #n ")" ::: "memory")
; #define BAR __builtin_amdgcn_s_barrier()
; template <int EPI> ...
;     ...
;     LDA(At, 0, 1); WAIT_V(4); BAR; WAIT_L(0); MMA(1, 0, At, B0); MMA(1, 1, At, B1); BAR; }
;   { LDB(B0, 1, 0); LDA(At, 1, 0); WAIT_V(2); BAR; WAIT_L(0); MMA(0, 0, At, B0); BAR;
	v_mfma_f32_16x16x32_bf16 v[4:7], v[112:115], v[104:107], v[4:7]
	v_mfma_f32_16x16x32_bf16 v[8:11], v[112:115], v[200:203], v[8:11]
	v_mfma_f32_16x16x32_bf16 v[4:7], v[120:123], v[128:131], v[4:7]
	v_mfma_f32_16x16x32_bf16 v[142:145], v[116:119], v[104:107], v[142:145]
	v_mfma_f32_16x16x32_bf16 v[146:149], v[112:115], v[132:135], v[146:149]
	v_mfma_f32_16x16x32_bf16 v[150:153], v[116:119], v[132:135], v[150:153]
	v_mfma_f32_16x16x32_bf16 v[180:183], v[112:115], v[192:195], v[180:183]
	v_mfma_f32_16x16x32_bf16 v[184:187], v[116:119], v[192:195], v[184:187]
	v_mfma_f32_16x16x32_bf16 v[8:11], v[120:123], v[204:207], v[8:11]
	v_mfma_f32_16x16x32_bf16 v[12:15], v[116:119], v[200:203], v[12:15]
	v_mfma_f32_16x16x32_bf16 v[142:145], v[124:127], v[128:131], v[142:145]
	v_mfma_f32_16x16x32_bf16 v[146:149], v[120:123], v[188:191], v[146:149]
	v_mfma_f32_16x16x32_bf16 v[150:153], v[124:127], v[188:191], v[150:153]
	v_mfma_f32_16x16x32_bf16 v[180:183], v[120:123], v[196:199], v[180:183]
	v_mfma_f32_16x16x32_bf16 v[184:187], v[124:127], v[196:199], v[184:187]
	v_mfma_f32_16x16x32_bf16 v[208:211], v[124:127], v[204:207], v[12:15]
	v_mfma_f32_16x16x32_bf16 v[12:15], v[84:87], v[104:107], v[16:19]
	v_mfma_f32_16x16x32_bf16 v[228:231], v[216:219], v[128:131], v[12:15]
	v_mfma_f32_16x16x32_bf16 v[12:15], v[212:215], v[104:107], v[20:23]
	v_mfma_f32_16x16x32_bf16 v[232:235], v[220:223], v[128:131], v[12:15]
	v_mfma_f32_16x16x32_bf16 v[12:15], v[84:87], v[132:135], v[52:55]
	v_mfma_f32_16x16x32_bf16 v[52:55], v[216:219], v[188:191], v[12:15]
	v_mfma_f32_16x16x32_bf16 v[12:15], v[212:215], v[132:135], v[96:99]
	v_mfma_f32_16x16x32_bf16 v[96:99], v[220:223], v[188:191], v[12:15]
	v_mfma_f32_16x16x32_bf16 v[12:15], v[84:87], v[192:195], v[100:103]
	v_mfma_f32_16x16x32_bf16 v[100:103], v[216:219], v[196:199], v[12:15]
	v_mfma_f32_16x16x32_bf16 v[12:15], v[212:215], v[192:195], v[108:111]
	v_mfma_f32_16x16x32_bf16 v[188:191], v[220:223], v[196:199], v[12:15]
	v_mfma_f32_16x16x32_bf16 v[12:15], v[84:87], v[200:203], v[88:91]
	v_mfma_f32_16x16x32_bf16 v[192:195], v[216:219], v[204:207], v[12:15]
	v_mfma_f32_16x16x32_bf16 v[12:15], v[212:215], v[200:203], v[92:95]
	v_mfma_f32_16x16x32_bf16 v[196:199], v[220:223], v[204:207], v[12:15]
	s_barrier
	s_setprio 0
	ds_read_b128 v[88:91], v172
	ds_read_b128 v[92:95], v172 offset:256
	ds_read_b128 v[200:203], v173
	ds_read_b128 v[204:207], v173 offset:256
	ds_read_b128 v[16:19], v154 offset:32768
	ds_read_b128 v[20:23], v154 offset:33792
	ds_read_b128 v[84:87], v154 offset:34816
	ds_read_b128 v[212:215], v154 offset:35840
	ds_read_b128 v[216:219], v154 offset:36864
	ds_read_b128 v[220:223], v154 offset:37888
	ds_read_b128 v[236:239], v154 offset:38912
	ds_read_b128 v[240:243], v154 offset:39936
	s_waitcnt vmcnt(2)
	s_waitcnt lgkmcnt(0)
	s_setprio 1
	s_barrier
	v_mfma_f32_16x16x32_bf16 v[0:3], v[88:91], v[16:19], v[0:3]
	v_mfma_f32_16x16x32_bf16 v[104:107], v[200:203], v[20:23], v[0:3]
	v_mfma_f32_16x16x32_bf16 v[0:3], v[92:95], v[16:19], v[56:59]
	v_mfma_f32_16x16x32_bf16 v[108:111], v[204:207], v[20:23], v[0:3]
	v_mfma_f32_16x16x32_bf16 v[0:3], v[88:91], v[84:87], v[60:63]
	v_mfma_f32_16x16x32_bf16 v[112:115], v[200:203], v[212:215], v[0:3]
	v_mfma_f32_16x16x32_bf16 v[0:3], v[92:95], v[84:87], v[64:67]
	v_mfma_f32_16x16x32_bf16 v[116:119], v[204:207], v[212:215], v[0:3]
	v_mfma_f32_16x16x32_bf16 v[0:3], v[88:91], v[216:219], v[68:71]
	v_mfma_f32_16x16x32_bf16 v[120:123], v[200:203], v[220:223], v[0:3]
	v_mfma_f32_16x16x32_bf16 v[0:3], v[92:95], v[216:219], v[72:75]
	v_mfma_f32_16x16x32_bf16 v[124:127], v[204:207], v[220:223], v[0:3]
	v_mfma_f32_16x16x32_bf16 v[0:3], v[88:91], v[236:239], v[76:79]
	v_mfma_f32_16x16x32_bf16 v[128:131], v[200:203], v[240:243], v[0:3]
	v_mfma_f32_16x16x32_bf16 v[0:3], v[92:95], v[236:239], v[80:83]
	v_mfma_f32_16x16x32_bf16 v[132:135], v[204:207], v[240:243], v[0:3]
	s_barrier
; #define LDA(dst, b, h) for (int m = 0; m < 4; ++m) { \
;     dst[m][0] = *reinterpret_cast<const bf16x8*>((char*)SA(b, h) + aoff0 + m * 2048); \
;     dst[m][1] = *reinterpret_cast<const bf16x8*>((char*)SA(b, h) + aoff1 + m * 2048); }
; #define LDB(dst, b, h) for (int n = 0; n < 2; ++n) { \
;     dst[n][0] = *reinterpret_cast<const bf16x8*>((char*)SB(b, h) + boff0 + n * 256); \
;     dst[n][1] = *reinterpret_cast<const bf16x8*>((char*)SB(b, h) + boff1 + n * 256); }
; #define MMA(ai, bj, At, Btf) do { __builtin_amdgcn_s_setprio(1); \
;     for (int m = 0; m < 4; ++m) for (int n = 0; n < 2; ++n) for (int k = 0; k < 2; ++k) \
;       acc[ai][bj][m][n] = __builtin_amdgcn_mfma_f32_16x16x32_bf16(Btf[n][k], At[m][k], acc[ai][bj][m][n], 0, 0, 0); \
;     __builtin_amdgcn_s_setprio(0); } while (0)
; #define WAIT_V(n) asm volatile("s_waitcnt vmcnt(" #n ")" ::: "memory")
; #define WAIT_L(n) asm volatile("s_waitcnt lgkmcnt(" #n ")" ::: "memory")
; #define BAR __builtin_amdgcn_s_barrier()
; template <int EPI> ...
;     ...
;   { LDB(B0, 1, 0); LDA(At, 1, 0); WAIT_V(2); BAR; WAIT_L(0); MMA(0, 0, At, B0); BAR;
;     LDB(B1, 1, 1); WAIT_V(0); BAR; WAIT_L(0); MMA(0, 1, At, B1); BAR;
;     LDA(At, 1, 1); BAR; WAIT_L(0); MMA(1, 0, At, B0); MMA(1, 1, At, B1); BAR; }
;   if (wr == 0) BAR;
	s_setprio 0
	s_nop 4
	ds_read_b128 v[0:3], v174
	ds_read_b128 v[244:247], v174 offset:256
	ds_read_b128 v[248:251], v175
	ds_read_b128 v[138:141], v175 offset:256
	s_waitcnt vmcnt(0)
	s_waitcnt lgkmcnt(0)
	s_setprio 1
	s_barrier
	v_mfma_f32_16x16x32_bf16 v[12:15], v[0:3], v[16:19], v[224:227]
	v_mfma_f32_16x16x32_bf16 v[16:19], v[244:247], v[16:19], v[24:27]
	v_mfma_f32_16x16x32_bf16 v[12:15], v[248:251], v[20:23], v[12:15]
	v_mfma_f32_16x16x32_bf16 v[16:19], v[138:141], v[20:23], v[16:19]
	v_mfma_f32_16x16x32_bf16 v[20:23], v[0:3], v[84:87], v[28:31]
	v_mfma_f32_16x16x32_bf16 v[24:27], v[244:247], v[84:87], v[32:35]
	v_mfma_f32_16x16x32_bf16 v[28:31], v[0:3], v[216:219], v[36:39]
	v_mfma_f32_16x16x32_bf16 v[32:35], v[244:247], v[216:219], v[40:43]
	v_mfma_f32_16x16x32_bf16 v[36:39], v[0:3], v[236:239], v[44:47]
	v_mfma_f32_16x16x32_bf16 v[40:43], v[244:247], v[236:239], v[48:51]
	v_mfma_f32_16x16x32_bf16 v[20:23], v[248:251], v[212:215], v[20:23]
	v_mfma_f32_16x16x32_bf16 v[24:27], v[138:141], v[212:215], v[24:27]
	v_mfma_f32_16x16x32_bf16 v[28:31], v[248:251], v[220:223], v[28:31]
	v_mfma_f32_16x16x32_bf16 v[32:35], v[138:141], v[220:223], v[32:35]
	v_mfma_f32_16x16x32_bf16 v[36:39], v[248:251], v[240:243], v[36:39]
	v_mfma_f32_16x16x32_bf16 v[40:43], v[138:141], v[240:243], v[40:43]
	s_barrier
	s_setprio 0
	ds_read_b128 v[44:47], v154 offset:49152
	ds_read_b128 v[48:51], v154 offset:50176
	ds_read_b128 v[212:215], v154 offset:51200
	ds_read_b128 v[216:219], v154 offset:52224
	ds_read_b128 v[220:223], v154 offset:53248
	ds_read_b128 v[224:227], v154 offset:54272
	ds_read_b128 v[236:239], v154 offset:55296
	ds_read_b128 v[240:243], v154 offset:56320
	s_waitcnt lgkmcnt(0)
	s_setprio 1
	s_barrier
	v_mfma_f32_16x16x32_bf16 v[4:7], v[88:91], v[44:47], v[4:7]
	v_mfma_f32_16x16x32_bf16 v[64:67], v[200:203], v[48:51], v[4:7]
	v_mfma_f32_16x16x32_bf16 v[4:7], v[92:95], v[44:47], v[142:145]
	v_mfma_f32_16x16x32_bf16 v[68:71], v[204:207], v[48:51], v[4:7]
	v_mfma_f32_16x16x32_bf16 v[4:7], v[88:91], v[212:215], v[146:149]
	v_mfma_f32_16x16x32_bf16 v[72:75], v[200:203], v[216:219], v[4:7]
	v_mfma_f32_16x16x32_bf16 v[4:7], v[92:95], v[212:215], v[150:153]
	v_mfma_f32_16x16x32_bf16 v[76:79], v[204:207], v[216:219], v[4:7]
	v_mfma_f32_16x16x32_bf16 v[4:7], v[88:91], v[220:223], v[180:183]
	v_mfma_f32_16x16x32_bf16 v[80:83], v[200:203], v[224:227], v[4:7]
	v_mfma_f32_16x16x32_bf16 v[4:7], v[92:95], v[220:223], v[184:187]
	v_mfma_f32_16x16x32_bf16 v[84:87], v[204:207], v[224:227], v[4:7]
	v_mfma_f32_16x16x32_bf16 v[4:7], v[88:91], v[236:239], v[8:11]
	v_mfma_f32_16x16x32_bf16 v[88:91], v[200:203], v[240:243], v[4:7]
	v_mfma_f32_16x16x32_bf16 v[4:7], v[92:95], v[236:239], v[208:211]
	v_mfma_f32_16x16x32_bf16 v[92:95], v[204:207], v[240:243], v[4:7]
	v_mfma_f32_16x16x32_bf16 v[4:7], v[0:3], v[44:47], v[228:231]
	v_mfma_f32_16x16x32_bf16 v[60:63], v[248:251], v[48:51], v[4:7]
	v_mfma_f32_16x16x32_bf16 v[4:7], v[244:247], v[44:47], v[232:235]
	v_mfma_f32_16x16x32_bf16 v[56:59], v[138:141], v[48:51], v[4:7]
	v_mfma_f32_16x16x32_bf16 v[4:7], v[0:3], v[212:215], v[52:55]
	v_mfma_f32_16x16x32_bf16 v[52:55], v[248:251], v[216:219], v[4:7]
	v_mfma_f32_16x16x32_bf16 v[4:7], v[244:247], v[212:215], v[96:99]
	v_mfma_f32_16x16x32_bf16 v[48:51], v[138:141], v[216:219], v[4:7]
	v_mfma_f32_16x16x32_bf16 v[4:7], v[0:3], v[220:223], v[100:103]
	v_mfma_f32_16x16x32_bf16 v[44:47], v[248:251], v[224:227], v[4:7]
	v_mfma_f32_16x16x32_bf16 v[4:7], v[244:247], v[220:223], v[188:191]
	v_mfma_f32_16x16x32_bf16 v[0:3], v[0:3], v[236:239], v[192:195]
	v_mfma_f32_16x16x32_bf16 v[8:11], v[138:141], v[224:227], v[4:7]
	v_mfma_f32_16x16x32_bf16 v[4:7], v[248:251], v[240:243], v[0:3]
	v_mfma_f32_16x16x32_bf16 v[0:3], v[244:247], v[236:239], v[196:199]
	v_mfma_f32_16x16x32_bf16 v[0:3], v[138:141], v[240:243], v[0:3]
	s_barrier
	s_setprio 0
	s_and_saveexec_b64 s[54:55], s[2:3]
	s_cbranch_execz .LBB0_821
	s_barrier
	s_branch .LBB0_821

; #define STAGE(P, BASE, br, kt) do { const char* _gb = (const char*)(BASE) + ((size_t)(br) * K + (size_t)(kt) * BK) * 2; \
;     __builtin_amdgcn_global_load_lds((const unsigned*)(_gb + loff0), (unsigned*)((char*)(P) + tid * 16), 16, 0, 0); \
;     __builtin_amdgcn_global_load_lds((const unsigned*)(_gb + (size_t)K * 128 + loff0), (unsigned*)((char*)(P) + tid * 16 + 8192), 16, 0, 0); } while (0)
; #define LDA(dst, b, h) for (int m = 0; m < 4; ++m) { \
;     dst[m][0] = *reinterpret_cast<const bf16x8*>((char*)SA(b, h) + aoff0 + m * 2048); \
;     dst[m][1] = *reinterpret_cast<const bf16x8*>((char*)SA(b, h) + aoff1 + m * 2048); }
; #define LDB(dst, b, h) for (int n = 0; n < 2; ++n) { \
;     dst[n][0] = *reinterpret_cast<const bf16x8*>((char*)SB(b, h) + boff0 + n * 256); \
;     dst[n][1] = *reinterpret_cast<const bf16x8*>((char*)SB(b, h) + boff1 + n * 256); }
; #define WAIT_V(n) asm volatile("s_waitcnt vmcnt(" #n ")" ::: "memory")
; #define BAR __builtin_amdgcn_s_barrier()
; template <int EPI> ...
;     ...
;   WAIT_V(4); BAR;
;   STAGE(SB(1, 0), Bt, bcol, 1); STAGE(SA(1, 0), A, brow, 1); STAGE(SB(1, 1), Bt, bcol + HALF, 1);
;   WAIT_V(6); BAR;
;   for (int t = 0; t < nt - 2; t += 2) {
;     LDB(B0, 0, 0); SCHED; LDA(At, 0, 0); STAGE(SA(1, 1), A, brow + HALF, t + 1);
;     WAIT_L(8); BAR; WAIT_L(0); MMA(0, 0, At, B0); BAR; SCHED;
;     LDB(B1, 0, 1); STAGE(SB(0, 0), Bt, bcol, t + 2);
;     BAR; WAIT_L(0); MMA(0, 1, At, B1); BAR;
;     LDA(At, 0, 1); STAGE(SA(0, 0), A, brow, t + 2);
;     BAR; WAIT_L(0); MMA(1, 0, At, B0); BAR; SCHED;
;     STAGE(SB(0, 1), Bt, bcol + HALF, t + 2);
;     WAIT_V(6); BAR; MMA(1, 1, At, B1); BAR;
;     LDB(B0, 1, 0); SCHED; LDA(At, 1, 0); STAGE(SA(0, 1), A, brow + HALF, t + 2);
;     WAIT_L(8); BAR; WAIT_L(0); MMA(0, 0, At, B0); BAR; SCHED;
;     LDB(B1, 1, 1); STAGE(SB(1, 0), Bt, bcol, t + 3);
;     BAR; WAIT_L(0); MMA(0, 1, At, B1); BAR;
;     LDA(At, 1, 1); STAGE(SA(1, 0), A, brow, t + 3);
;     BAR; WAIT_L(0); MMA(1, 0, At, B0); BAR; SCHED;
;     STAGE(SB(1, 1), Bt, bcol + HALF, t + 3);
;     WAIT_V(6); BAR; MMA(1, 1, At, B1); BAR;
;   }
;   { LDB(B0, 0, 0); LDA(At, 0, 0); STAGE(SA(1, 1), A, brow + HALF, nt - 1);
;     BAR; WAIT_L(0); MMA(0, 0, At, B0); BAR;
;     LDB(B1, 0, 1); BAR; WAIT_L(0); MMA(0, 1, At, B1); BAR;
;     LDA(At, 0, 1); WAIT_V(4); BAR; WAIT_L(0); MMA(1, 0, At, B0); MMA(1, 1, At, B1); BAR; }
.LBB0_834:
	s_or_b64 exec, exec, s[22:23]
	v_readfirstlane_b32 s17, v141
	v_lshl_add_u64 v[6:7], v[0:1], 0, s[10:11]
	s_mov_b32 m0, s17
	s_waitcnt vmcnt(4)
	s_barrier
	global_load_lds_dwordx4 v[6:7], off
	v_add_u32_e32 v6, 0x2000, v141
	v_lshl_add_u64 v[0:1], v[0:1], 0, s[12:13]
	v_readfirstlane_b32 s17, v6
	v_add_u32_e32 v6, 0x8000, v135
	s_mov_b32 m0, s17
	v_readfirstlane_b32 s17, v6
	global_load_lds_dwordx4 v[0:1], off
	v_lshl_add_u64 v[0:1], v[2:3], 0, s[10:11]
	s_mov_b32 m0, s17
	v_readfirstlane_b32 s17, v144
	global_load_lds_dwordx4 v[0:1], off
	v_lshl_add_u64 v[0:1], v[2:3], 0, s[12:13]
	s_mov_b32 m0, s17
	v_readfirstlane_b32 s17, v145
	global_load_lds_dwordx4 v[0:1], off
	v_lshl_add_u64 v[0:1], v[4:5], 0, s[10:11]
	s_mov_b32 m0, s17
	v_readfirstlane_b32 s17, v146
	s_add_u32 s20, s27, s20
	global_load_lds_dwordx4 v[0:1], off
	v_lshl_add_u64 v[0:1], v[4:5], 0, s[12:13]
	s_mov_b32 m0, s17
	s_addc_u32 s21, s28, s21
	v_readfirstlane_b32 s17, v148
	global_load_lds_dwordx4 v[0:1], off
	v_lshl_add_u64 v[48:49], s[20:21], 0, v[128:129]
	s_mov_b32 m0, s17
	v_readfirstlane_b32 s17, v149
	s_waitcnt vmcnt(6)
	s_barrier
	ds_read_b128 v[0:3], v154
	ds_read_b128 v[4:7], v154 offset:256
	ds_read_b128 v[8:11], v155
	ds_read_b128 v[12:15], v155 offset:256
	ds_read_b128 v[16:19], v147
	ds_read_b128 v[20:23], v147 offset:1024
	ds_read_b128 v[24:27], v147 offset:2048
	ds_read_b128 v[28:31], v147 offset:3072
	ds_read_b128 v[32:35], v147 offset:4096
	ds_read_b128 v[36:39], v147 offset:5120
	ds_read_b128 v[40:43], v147 offset:6144
	ds_read_b128 v[44:47], v147 offset:7168
	global_load_lds_dwordx4 v[48:49], off
	v_lshl_add_u64 v[48:49], v[48:49], 0, s[8:9]
	s_mov_b32 m0, s17
	s_nop 0
	global_load_lds_dwordx4 v[48:49], off
	s_waitcnt lgkmcnt(0)
	s_setprio 1
	s_barrier
	v_mfma_f32_16x16x32_bf16 v[48:51], v[0:3], v[16:19], 0
	v_mfma_f32_16x16x32_bf16 v[52:55], v[4:7], v[16:19], 0
	v_mfma_f32_16x16x32_bf16 v[56:59], v[0:3], v[24:27], 0
	v_mfma_f32_16x16x32_bf16 v[60:63], v[4:7], v[24:27], 0
	v_mfma_f32_16x16x32_bf16 v[64:67], v[0:3], v[32:35], 0
	v_mfma_f32_16x16x32_bf16 v[68:71], v[4:7], v[32:35], 0
	v_mfma_f32_16x16x32_bf16 v[72:75], v[0:3], v[40:43], 0
	v_mfma_f32_16x16x32_bf16 v[76:79], v[4:7], v[40:43], 0
	v_mfma_f32_16x16x32_bf16 v[48:51], v[8:11], v[20:23], v[48:51]
	v_mfma_f32_16x16x32_bf16 v[52:55], v[12:15], v[20:23], v[52:55]
	v_mfma_f32_16x16x32_bf16 v[56:59], v[8:11], v[28:31], v[56:59]
	v_mfma_f32_16x16x32_bf16 v[60:63], v[12:15], v[28:31], v[60:63]
	v_mfma_f32_16x16x32_bf16 v[64:67], v[8:11], v[36:39], v[64:67]
	v_mfma_f32_16x16x32_bf16 v[68:71], v[12:15], v[36:39], v[68:71]
	v_mfma_f32_16x16x32_bf16 v[72:75], v[8:11], v[44:47], v[72:75]
	v_mfma_f32_16x16x32_bf16 v[76:79], v[12:15], v[44:47], v[76:79]
	s_barrier
	s_setprio 0
	ds_read_b128 v[80:83], v156
	ds_read_b128 v[84:87], v156 offset:256
	ds_read_b128 v[88:91], v157
	ds_read_b128 v[92:95], v157 offset:256
	s_waitcnt lgkmcnt(0)
	s_setprio 1
	s_barrier
	v_mfma_f32_16x16x32_bf16 v[96:99], v[80:83], v[16:19], 0
	v_mfma_f32_16x16x32_bf16 v[16:19], v[84:87], v[16:19], 0
	v_mfma_f32_16x16x32_bf16 v[96:99], v[88:91], v[20:23], v[96:99]
	v_mfma_f32_16x16x32_bf16 v[16:19], v[92:95], v[20:23], v[16:19]
	v_mfma_f32_16x16x32_bf16 v[20:23], v[80:83], v[24:27], 0
	v_mfma_f32_16x16x32_bf16 v[24:27], v[84:87], v[24:27], 0
	v_mfma_f32_16x16x32_bf16 v[20:23], v[88:91], v[28:31], v[20:23]
	v_mfma_f32_16x16x32_bf16 v[24:27], v[92:95], v[28:31], v[24:27]
	v_mfma_f32_16x16x32_bf16 v[28:31], v[80:83], v[32:35], 0
	v_mfma_f32_16x16x32_bf16 v[32:35], v[84:87], v[32:35], 0
	v_mfma_f32_16x16x32_bf16 v[28:31], v[88:91], v[36:39], v[28:31]
	v_mfma_f32_16x16x32_bf16 v[32:35], v[92:95], v[36:39], v[32:35]
	v_mfma_f32_16x16x32_bf16 v[36:39], v[80:83], v[40:43], 0
	v_mfma_f32_16x16x32_bf16 v[40:43], v[84:87], v[40:43], 0
	v_mfma_f32_16x16x32_bf16 v[36:39], v[88:91], v[44:47], v[36:39]
	v_mfma_f32_16x16x32_bf16 v[40:43], v[92:95], v[44:47], v[40:43]
	s_barrier
	s_setprio 0
	ds_read_b128 v[44:47], v147 offset:16384
	ds_read_b128 v[100:103], v147 offset:17408
	ds_read_b128 v[104:107], v147 offset:18432
	ds_read_b128 v[108:111], v147 offset:19456
	ds_read_b128 v[112:115], v147 offset:20480
	ds_read_b128 v[116:119], v147 offset:21504
	ds_read_b128 v[120:123], v147 offset:22528
	ds_read_b128 v[124:127], v147 offset:23552
	s_waitcnt vmcnt(4)
	s_waitcnt lgkmcnt(0)
	s_setprio 1
	s_barrier
	v_mfma_f32_16x16x32_bf16 v[158:161], v[0:3], v[44:47], 0
	v_mfma_f32_16x16x32_bf16 v[162:165], v[4:7], v[44:47], 0
	v_mfma_f32_16x16x32_bf16 v[166:169], v[0:3], v[104:107], 0
	v_mfma_f32_16x16x32_bf16 v[170:173], v[4:7], v[104:107], 0
	v_mfma_f32_16x16x32_bf16 v[174:177], v[0:3], v[112:115], 0
	v_mfma_f32_16x16x32_bf16 v[178:181], v[4:7], v[112:115], 0
	v_mfma_f32_16x16x32_bf16 v[0:3], v[0:3], v[120:123], 0
	v_mfma_f32_16x16x32_bf16 v[4:7], v[4:7], v[120:123], 0
	v_mfma_f32_16x16x32_bf16 v[0:3], v[8:11], v[124:127], v[0:3]
	v_mfma_f32_16x16x32_bf16 v[4:7], v[12:15], v[124:127], v[4:7]
	v_mfma_f32_16x16x32_bf16 v[158:161], v[8:11], v[100:103], v[158:161]
	v_mfma_f32_16x16x32_bf16 v[162:165], v[12:15], v[100:103], v[162:165]
	v_mfma_f32_16x16x32_bf16 v[166:169], v[8:11], v[108:111], v[166:169]
	v_mfma_f32_16x16x32_bf16 v[170:173], v[12:15], v[108:111], v[170:173]
	v_mfma_f32_16x16x32_bf16 v[174:177], v[8:11], v[116:119], v[174:177]
	v_mfma_f32_16x16x32_bf16 v[178:181], v[12:15], v[116:119], v[178:181]
	v_mfma_f32_16x16x32_bf16 v[8:11], v[80:83], v[44:47], 0
	v_mfma_f32_16x16x32_bf16 v[12:15], v[84:87], v[44:47], 0
	v_mfma_f32_16x16x32_bf16 v[44:47], v[80:83], v[104:107], 0
	v_mfma_f32_16x16x32_bf16 v[182:185], v[88:91], v[108:111], v[44:47]
	v_mfma_f32_16x16x32_bf16 v[44:47], v[84:87], v[104:107], 0
	v_mfma_f32_16x16x32_bf16 v[186:189], v[92:95], v[108:111], v[44:47]
	v_mfma_f32_16x16x32_bf16 v[44:47], v[80:83], v[112:115], 0
	v_mfma_f32_16x16x32_bf16 v[190:193], v[88:91], v[116:119], v[44:47]
	v_mfma_f32_16x16x32_bf16 v[44:47], v[84:87], v[112:115], 0
	v_mfma_f32_16x16x32_bf16 v[194:197], v[92:95], v[116:119], v[44:47]
	v_mfma_f32_16x16x32_bf16 v[44:47], v[80:83], v[120:123], 0
	v_mfma_f32_16x16x32_bf16 v[8:11], v[88:91], v[100:103], v[8:11]
	v_mfma_f32_16x16x32_bf16 v[12:15], v[92:95], v[100:103], v[12:15]
	v_mfma_f32_16x16x32_bf16 v[198:201], v[88:91], v[124:127], v[44:47]
	v_mfma_f32_16x16x32_bf16 v[44:47], v[84:87], v[120:123], 0
	v_mfma_f32_16x16x32_bf16 v[202:205], v[92:95], v[124:127], v[44:47]
	s_barrier
; #define LDA(dst, b, h) for (int m = 0; m < 4; ++m) { \
;     dst[m][0] = *reinterpret_cast<const bf16x8*>((char*)SA(b, h) + aoff0 + m * 2048); \
;     dst[m][1] = *reinterpret_cast<const bf16x8*>((char*)SA(b, h) + aoff1 + m * 2048); }
; #define LDB(dst, b, h) for (int n = 0; n < 2; ++n) { \
;     dst[n][0] = *reinterpret_cast<const bf16x8*>((char*)SB(b, h) + boff0 + n * 256); \
;     dst[n][1] = *reinterpret_cast<const bf16x8*>((char*)SB(b, h) + boff1 + n * 256); }
; #define MMA(ai, bj, At, Btf) do { __builtin_amdgcn_s_setprio(1); \
;     for (int m = 0; m < 4; ++m) for (int n = 0; n < 2; ++n) for (int k = 0; k < 2; ++k) \
;       acc[ai][bj][m][n] = __builtin_amdgcn_mfma_f32_16x16x32_bf16(Btf[n][k], At[m][k], acc[ai][bj][m][n], 0, 0, 0); \
;     __builtin_amdgcn_s_setprio(0); } while (0)
; #define WAIT_V(n) asm volatile("s_waitcnt vmcnt(" #n ")" ::: "memory")
; #define WAIT_L(n) asm volatile("s_waitcnt lgkmcnt(" #n ")" ::: "memory")
; #define BAR __builtin_amdgcn_s_barrier()
; template <int EPI> ...
;     ...
;   { LDB(B0, 1, 0); LDA(At, 1, 0); WAIT_V(2); BAR; WAIT_L(0); MMA(0, 0, At, B0); BAR;
;     LDB(B1, 1, 1); WAIT_V(0); BAR; WAIT_L(0); MMA(0, 1, At, B1); BAR;
;     LDA(At, 1, 1); BAR; WAIT_L(0); MMA(1, 0, At, B0); MMA(1, 1, At, B1); BAR; }
;   if (wr == 0) BAR;
	s_setprio 0
	ds_read_b128 v[206:209], v150
	ds_read_b128 v[210:213], v150 offset:256
	ds_read_b128 v[214:217], v151
	ds_read_b128 v[218:221], v151 offset:256
	s_nop 0
	ds_read_b128 v[44:47], v147 offset:32768
	ds_read_b128 v[88:91], v147 offset:33792
	ds_read_b128 v[92:95], v147 offset:34816
	ds_read_b128 v[222:225], v147 offset:35840
	ds_read_b128 v[226:229], v147 offset:36864
	ds_read_b128 v[230:233], v147 offset:37888
	ds_read_b128 v[234:237], v147 offset:38912
	ds_read_b128 v[238:241], v147 offset:39936
	s_waitcnt vmcnt(2)
	s_waitcnt lgkmcnt(0)
	s_setprio 1
	s_barrier
	v_mfma_f32_16x16x32_bf16 v[48:51], v[206:209], v[44:47], v[48:51]
	v_mfma_f32_16x16x32_bf16 v[120:123], v[214:217], v[88:91], v[48:51]
	v_mfma_f32_16x16x32_bf16 v[48:51], v[210:213], v[44:47], v[52:55]
	v_mfma_f32_16x16x32_bf16 v[124:127], v[218:221], v[88:91], v[48:51]
	v_mfma_f32_16x16x32_bf16 v[48:51], v[206:209], v[92:95], v[56:59]
	v_mfma_f32_16x16x32_bf16 v[112:115], v[214:217], v[222:225], v[48:51]
	v_mfma_f32_16x16x32_bf16 v[48:51], v[210:213], v[92:95], v[60:63]
	v_mfma_f32_16x16x32_bf16 v[116:119], v[218:221], v[222:225], v[48:51]
	v_mfma_f32_16x16x32_bf16 v[48:51], v[206:209], v[226:229], v[64:67]
	v_mfma_f32_16x16x32_bf16 v[104:107], v[214:217], v[230:233], v[48:51]
	v_mfma_f32_16x16x32_bf16 v[48:51], v[210:213], v[226:229], v[68:71]
	v_mfma_f32_16x16x32_bf16 v[108:111], v[218:221], v[230:233], v[48:51]
	v_mfma_f32_16x16x32_bf16 v[48:51], v[206:209], v[234:237], v[72:75]
	v_mfma_f32_16x16x32_bf16 v[80:83], v[214:217], v[238:241], v[48:51]
	v_mfma_f32_16x16x32_bf16 v[48:51], v[210:213], v[234:237], v[76:79]
	v_mfma_f32_16x16x32_bf16 v[84:87], v[218:221], v[238:241], v[48:51]
	s_barrier
	s_setprio 0
	ds_read_b128 v[242:245], v152
	ds_read_b128 v[246:249], v152 offset:256
	ds_read_b128 v[250:253], v153
	ds_read_b128 v[130:133], v153 offset:256
	s_waitcnt vmcnt(0)
	s_waitcnt lgkmcnt(0)
	s_setprio 1
	s_barrier
	v_mfma_f32_16x16x32_bf16 v[16:19], v[246:249], v[44:47], v[16:19]
	v_mfma_f32_16x16x32_bf16 v[48:51], v[242:245], v[44:47], v[96:99]
	v_mfma_f32_16x16x32_bf16 v[100:103], v[130:133], v[88:91], v[16:19]
	v_mfma_f32_16x16x32_bf16 v[16:19], v[242:245], v[92:95], v[20:23]
	v_mfma_f32_16x16x32_bf16 v[96:99], v[250:253], v[88:91], v[48:51]
	v_mfma_f32_16x16x32_bf16 v[88:91], v[250:253], v[222:225], v[16:19]
	v_mfma_f32_16x16x32_bf16 v[16:19], v[246:249], v[92:95], v[24:27]
	v_mfma_f32_16x16x32_bf16 v[92:95], v[130:133], v[222:225], v[16:19]
	v_mfma_f32_16x16x32_bf16 v[16:19], v[242:245], v[226:229], v[28:31]
	v_mfma_f32_16x16x32_bf16 v[64:67], v[250:253], v[230:233], v[16:19]
	v_mfma_f32_16x16x32_bf16 v[16:19], v[246:249], v[226:229], v[32:35]
	v_mfma_f32_16x16x32_bf16 v[68:71], v[130:133], v[230:233], v[16:19]
	v_mfma_f32_16x16x32_bf16 v[16:19], v[242:245], v[234:237], v[36:39]
	v_mfma_f32_16x16x32_bf16 v[48:51], v[250:253], v[238:241], v[16:19]
	v_mfma_f32_16x16x32_bf16 v[16:19], v[246:249], v[234:237], v[40:43]
	v_mfma_f32_16x16x32_bf16 v[52:55], v[130:133], v[238:241], v[16:19]
	s_barrier
	s_setprio 0
	s_nop 4
	ds_read_b128 v[16:19], v147 offset:49152
	ds_read_b128 v[20:23], v147 offset:50176
	ds_read_b128 v[222:225], v147 offset:51200
	ds_read_b128 v[226:229], v147 offset:52224
	ds_read_b128 v[230:233], v147 offset:53248
	ds_read_b128 v[234:237], v147 offset:54272
	ds_read_b128 v[238:241], v147 offset:55296
	ds_read_b128 v[136:139], v147 offset:56320
	s_waitcnt lgkmcnt(0)
	s_setprio 1
	s_barrier
	v_mfma_f32_16x16x32_bf16 v[24:27], v[206:209], v[16:19], v[158:161]
	v_mfma_f32_16x16x32_bf16 v[72:75], v[214:217], v[20:23], v[24:27]
	v_mfma_f32_16x16x32_bf16 v[24:27], v[210:213], v[16:19], v[162:165]
	v_mfma_f32_16x16x32_bf16 v[76:79], v[218:221], v[20:23], v[24:27]
	v_mfma_f32_16x16x32_bf16 v[24:27], v[206:209], v[222:225], v[166:169]
	v_mfma_f32_16x16x32_bf16 v[56:59], v[214:217], v[226:229], v[24:27]
	v_mfma_f32_16x16x32_bf16 v[24:27], v[210:213], v[222:225], v[170:173]
	v_mfma_f32_16x16x32_bf16 v[60:63], v[218:221], v[226:229], v[24:27]
	v_mfma_f32_16x16x32_bf16 v[24:27], v[206:209], v[230:233], v[174:177]
	v_mfma_f32_16x16x32_bf16 v[0:3], v[206:209], v[238:241], v[0:3]
	v_mfma_f32_16x16x32_bf16 v[40:43], v[214:217], v[234:237], v[24:27]
	v_mfma_f32_16x16x32_bf16 v[24:27], v[210:213], v[230:233], v[178:181]
	v_mfma_f32_16x16x32_bf16 v[32:35], v[214:217], v[136:139], v[0:3]
	v_mfma_f32_16x16x32_bf16 v[0:3], v[210:213], v[238:241], v[4:7]
	v_mfma_f32_16x16x32_bf16 v[44:47], v[218:221], v[234:237], v[24:27]
	v_mfma_f32_16x16x32_bf16 v[36:39], v[218:221], v[136:139], v[0:3]
	v_mfma_f32_16x16x32_bf16 v[0:3], v[242:245], v[16:19], v[8:11]
	v_mfma_f32_16x16x32_bf16 v[24:27], v[250:253], v[20:23], v[0:3]
	v_mfma_f32_16x16x32_bf16 v[0:3], v[246:249], v[16:19], v[12:15]
	v_mfma_f32_16x16x32_bf16 v[28:31], v[130:133], v[20:23], v[0:3]
	v_mfma_f32_16x16x32_bf16 v[0:3], v[242:245], v[222:225], v[182:185]
	v_mfma_f32_16x16x32_bf16 v[16:19], v[250:253], v[226:229], v[0:3]
	v_mfma_f32_16x16x32_bf16 v[0:3], v[246:249], v[222:225], v[186:189]
	v_mfma_f32_16x16x32_bf16 v[20:23], v[130:133], v[226:229], v[0:3]
	v_mfma_f32_16x16x32_bf16 v[0:3], v[242:245], v[230:233], v[190:193]
	v_mfma_f32_16x16x32_bf16 v[8:11], v[250:253], v[234:237], v[0:3]
	v_mfma_f32_16x16x32_bf16 v[0:3], v[246:249], v[230:233], v[194:197]
	v_mfma_f32_16x16x32_bf16 v[12:15], v[130:133], v[234:237], v[0:3]
	v_mfma_f32_16x16x32_bf16 v[0:3], v[242:245], v[238:241], v[198:201]
	v_mfma_f32_16x16x32_bf16 v[4:7], v[246:249], v[238:241], v[202:205]
	v_mfma_f32_16x16x32_bf16 v[0:3], v[250:253], v[136:139], v[0:3]
	v_mfma_f32_16x16x32_bf16 v[4:7], v[130:133], v[136:139], v[4:7]
	s_barrier
	s_setprio 0
	s_and_saveexec_b64 s[20:21], s[2:3]
	s_cbranch_execz .LBB0_829
	s_barrier
	s_branch .LBB0_829

; #define STAGE(P, BASE, br, kt) do { const char* _gb = (const char*)(BASE) + ((size_t)(br) * K + (size_t)(kt) * BK) * 2; \
;     __builtin_amdgcn_global_load_lds((const unsigned*)(_gb + loff0), (unsigned*)((char*)(P) + tid * 16), 16, 0, 0); \
;     __builtin_amdgcn_global_load_lds((const unsigned*)(_gb + (size_t)K * 128 + loff0), (unsigned*)((char*)(P) + tid * 16 + 8192), 16, 0, 0); } while (0)
; #define LDA(dst, b, h) for (int m = 0; m < 4; ++m) { \
;     dst[m][0] = *reinterpret_cast<const bf16x8*>((char*)SA(b, h) + aoff0 + m * 2048); \
;     dst[m][1] = *reinterpret_cast<const bf16x8*>((char*)SA(b, h) + aoff1 + m * 2048); }
; #define LDB(dst, b, h) for (int n = 0; n < 2; ++n) { \
;     dst[n][0] = *reinterpret_cast<const bf16x8*>((char*)SB(b, h) + boff0 + n * 256); \
;     dst[n][1] = *reinterpret_cast<const bf16x8*>((char*)SB(b, h) + boff1 + n * 256); }
; #define MMA(ai, bj, At, Btf) do { __builtin_amdgcn_s_setprio(1); \
;     for (int m = 0; m < 4; ++m) for (int n = 0; n < 2; ++n) for (int k = 0; k < 2; ++k) \
;       acc[ai][bj][m][n] = __builtin_amdgcn_mfma_f32_16x16x32_bf16(Btf[n][k], At[m][k], acc[ai][bj][m][n], 0, 0, 0); \
;     __builtin_amdgcn_s_setprio(0); } while (0)
; #define WAIT_V(n) asm volatile("s_waitcnt vmcnt(" #n ")" ::: "memory")
; #define WAIT_L(n) asm volatile("s_waitcnt lgkmcnt(" #n ")" ::: "memory")
; #define BAR __builtin_amdgcn_s_barrier()
; #define SCHED __builtin_amdgcn_sched_barrier(0)
; template <int EPI> ...
;     ...
;   WAIT_V(4); BAR;
;   STAGE(SB(1, 0), Bt, bcol, 1); STAGE(SA(1, 0), A, brow, 1); STAGE(SB(1, 1), Bt, bcol + HALF, 1);
;   WAIT_V(6); BAR;
;   for (int t = 0; t < nt - 2; t += 2) {
;     LDB(B0, 0, 0); SCHED; LDA(At, 0, 0); STAGE(SA(1, 1), A, brow + HALF, t + 1);
;     WAIT_L(8); BAR; WAIT_L(0); MMA(0, 0, At, B0); BAR; SCHED;
;     LDB(B1, 0, 1); STAGE(SB(0, 0), Bt, bcol, t + 2);
;     BAR; WAIT_L(0); MMA(0, 1, At, B1); BAR;
;     LDA(At, 0, 1); STAGE(SA(0, 0), A, brow, t + 2);
;     BAR; WAIT_L(0); MMA(1, 0, At, B0); BAR; SCHED;
.LBB0_850:
	s_or_b64 exec, exec, s[28:29]
	v_readfirstlane_b32 s50, v144
	v_add_u32_e32 v10, 0x2000, v144
	v_lshl_add_u64 v[8:9], v[4:5], 0, s[8:9]
	s_mov_b32 m0, s50
	v_readfirstlane_b32 s49, v10
	v_add_u32_e32 v10, 0x8000, v135
	s_waitcnt vmcnt(4)
	s_barrier
	global_load_lds_dwordx4 v[8:9], off
	v_lshl_add_u64 v[8:9], v[4:5], 0, s[10:11]
	s_mov_b32 m0, s49
	v_readfirstlane_b32 s48, v10
	v_add_u32_e32 v10, 0xa000, v135
	global_load_lds_dwordx4 v[8:9], off
	v_lshl_add_u64 v[8:9], v[2:3], 0, s[8:9]
	s_mov_b32 m0, s48
	v_readfirstlane_b32 s47, v10
	global_load_lds_dwordx4 v[8:9], off
	v_lshl_add_u64 v[8:9], v[2:3], 0, s[10:11]
	s_mov_b32 m0, s47
	v_readfirstlane_b32 s46, v145
	global_load_lds_dwordx4 v[8:9], off
	v_lshl_add_u64 v[8:9], v[0:1], 0, s[8:9]
	s_mov_b32 m0, s46
	v_readfirstlane_b32 s29, v146
	global_load_lds_dwordx4 v[8:9], off
	v_lshl_add_u64 v[8:9], v[0:1], 0, s[10:11]
	s_mov_b32 m0, s29
	s_nop 0
	global_load_lds_dwordx4 v[8:9], off
	s_waitcnt vmcnt(6)
	s_barrier
	ds_read_b128 v[8:11], v154
	ds_read_b128 v[12:15], v154 offset:256
	ds_read_b128 v[16:19], v155
	ds_read_b128 v[20:23], v155 offset:256
	v_readfirstlane_b32 s28, v148
	v_lshl_add_u64 v[56:57], v[6:7], 0, s[8:9]
	s_mov_b32 m0, s28
	v_readfirstlane_b32 s23, v149
	ds_read_b128 v[24:27], v147
	ds_read_b128 v[28:31], v147 offset:1024
	ds_read_b128 v[32:35], v147 offset:2048
	ds_read_b128 v[36:39], v147 offset:3072
	ds_read_b128 v[40:43], v147 offset:4096
	ds_read_b128 v[44:47], v147 offset:5120
	ds_read_b128 v[48:51], v147 offset:6144
	ds_read_b128 v[52:55], v147 offset:7168
	global_load_lds_dwordx4 v[56:57], off
	v_lshl_add_u64 v[56:57], v[6:7], 0, s[10:11]
	s_mov_b32 m0, s23
	s_nop 0
	global_load_lds_dwordx4 v[56:57], off
	s_waitcnt lgkmcnt(8)
	s_waitcnt lgkmcnt(0)
	s_setprio 1
	s_barrier
	v_mfma_f32_16x16x32_bf16 v[56:59], v[8:11], v[24:27], 0
	v_mfma_f32_16x16x32_bf16 v[60:63], v[12:15], v[24:27], 0
	v_mfma_f32_16x16x32_bf16 v[64:67], v[8:11], v[32:35], 0
	v_mfma_f32_16x16x32_bf16 v[68:71], v[12:15], v[32:35], 0
	v_mfma_f32_16x16x32_bf16 v[72:75], v[8:11], v[40:43], 0
	v_mfma_f32_16x16x32_bf16 v[76:79], v[12:15], v[40:43], 0
	v_mfma_f32_16x16x32_bf16 v[80:83], v[8:11], v[48:51], 0
	v_mfma_f32_16x16x32_bf16 v[84:87], v[12:15], v[48:51], 0
	v_mfma_f32_16x16x32_bf16 v[56:59], v[16:19], v[28:31], v[56:59]
	v_mfma_f32_16x16x32_bf16 v[60:63], v[20:23], v[28:31], v[60:63]
	v_mfma_f32_16x16x32_bf16 v[64:67], v[16:19], v[36:39], v[64:67]
	v_mfma_f32_16x16x32_bf16 v[68:71], v[20:23], v[36:39], v[68:71]
	v_mfma_f32_16x16x32_bf16 v[72:75], v[16:19], v[44:47], v[72:75]
	v_mfma_f32_16x16x32_bf16 v[76:79], v[20:23], v[44:47], v[76:79]
	v_mfma_f32_16x16x32_bf16 v[80:83], v[16:19], v[52:55], v[80:83]
	v_mfma_f32_16x16x32_bf16 v[84:87], v[20:23], v[52:55], v[84:87]
	s_barrier
	s_setprio 0
	v_readfirstlane_b32 s51, v133
	v_lshl_add_u64 v[104:105], v[4:5], 0, s[12:13]
	s_mov_b32 m0, s51
	v_readfirstlane_b32 s51, v134
	ds_read_b128 v[88:91], v156
	ds_read_b128 v[92:95], v156 offset:256
	ds_read_b128 v[96:99], v157
	ds_read_b128 v[100:103], v157 offset:256
	global_load_lds_dwordx4 v[104:105], off
	v_lshl_add_u64 v[104:105], v[4:5], 0, s[16:17]
	s_mov_b32 m0, s51
	s_nop 0
	global_load_lds_dwordx4 v[104:105], off
	s_barrier
	s_waitcnt lgkmcnt(0)
	s_setprio 1
	s_waitcnt lgkmcnt(0)
	v_mfma_f32_16x16x32_bf16 v[104:107], v[88:91], v[24:27], 0
	v_mfma_f32_16x16x32_bf16 v[24:27], v[92:95], v[24:27], 0
	v_mfma_f32_16x16x32_bf16 v[104:107], v[96:99], v[28:31], v[104:107]
	v_mfma_f32_16x16x32_bf16 v[24:27], v[100:103], v[28:31], v[24:27]
	v_mfma_f32_16x16x32_bf16 v[28:31], v[88:91], v[32:35], 0
	v_mfma_f32_16x16x32_bf16 v[32:35], v[92:95], v[32:35], 0
	v_mfma_f32_16x16x32_bf16 v[28:31], v[96:99], v[36:39], v[28:31]
	v_mfma_f32_16x16x32_bf16 v[32:35], v[100:103], v[36:39], v[32:35]
	v_mfma_f32_16x16x32_bf16 v[36:39], v[88:91], v[40:43], 0
	v_mfma_f32_16x16x32_bf16 v[40:43], v[92:95], v[40:43], 0
	v_mfma_f32_16x16x32_bf16 v[36:39], v[96:99], v[44:47], v[36:39]
	v_mfma_f32_16x16x32_bf16 v[40:43], v[100:103], v[44:47], v[40:43]
	v_mfma_f32_16x16x32_bf16 v[44:47], v[88:91], v[48:51], 0
	v_mfma_f32_16x16x32_bf16 v[48:51], v[92:95], v[48:51], 0
	v_mfma_f32_16x16x32_bf16 v[44:47], v[96:99], v[52:55], v[44:47]
	v_mfma_f32_16x16x32_bf16 v[48:51], v[100:103], v[52:55], v[48:51]
	s_setprio 0
	v_readfirstlane_b32 s51, v135
	v_lshl_add_u64 v[138:139], v[2:3], 0, s[12:13]
	s_mov_b32 m0, s51
	v_readfirstlane_b32 s51, v136
	s_barrier
	ds_read_b128 v[52:55], v147 offset:16384
	ds_read_b128 v[108:111], v147 offset:17408
	ds_read_b128 v[112:115], v147 offset:18432
	ds_read_b128 v[116:119], v147 offset:19456
	ds_read_b128 v[120:123], v147 offset:20480
	ds_read_b128 v[124:127], v147 offset:21504
	ds_read_b128 v[158:161], v147 offset:22528
	ds_read_b128 v[162:165], v147 offset:23552
	global_load_lds_dwordx4 v[138:139], off
	v_lshl_add_u64 v[138:139], v[2:3], 0, s[16:17]
	s_mov_b32 m0, s51
	s_nop 0
	global_load_lds_dwordx4 v[138:139], off
	s_waitcnt lgkmcnt(0)
	s_setprio 1
	s_barrier
	v_mfma_f32_16x16x32_bf16 v[166:169], v[8:11], v[52:55], 0
	v_mfma_f32_16x16x32_bf16 v[170:173], v[12:15], v[52:55], 0
	v_mfma_f32_16x16x32_bf16 v[174:177], v[8:11], v[112:115], 0
	v_mfma_f32_16x16x32_bf16 v[178:181], v[12:15], v[112:115], 0
	v_mfma_f32_16x16x32_bf16 v[182:185], v[8:11], v[120:123], 0
	v_mfma_f32_16x16x32_bf16 v[186:189], v[12:15], v[120:123], 0
	v_mfma_f32_16x16x32_bf16 v[8:11], v[8:11], v[158:161], 0
	v_mfma_f32_16x16x32_bf16 v[12:15], v[12:15], v[158:161], 0
	v_mfma_f32_16x16x32_bf16 v[8:11], v[16:19], v[162:165], v[8:11]
	v_mfma_f32_16x16x32_bf16 v[12:15], v[20:23], v[162:165], v[12:15]
	v_mfma_f32_16x16x32_bf16 v[166:169], v[16:19], v[108:111], v[166:169]
	v_mfma_f32_16x16x32_bf16 v[170:173], v[20:23], v[108:111], v[170:173]
	v_mfma_f32_16x16x32_bf16 v[174:177], v[16:19], v[116:119], v[174:177]
	v_mfma_f32_16x16x32_bf16 v[178:181], v[20:23], v[116:119], v[178:181]
	v_mfma_f32_16x16x32_bf16 v[182:185], v[16:19], v[124:127], v[182:185]
	v_mfma_f32_16x16x32_bf16 v[186:189], v[20:23], v[124:127], v[186:189]
	s_barrier
; #define STAGE(P, BASE, br, kt) do { const char* _gb = (const char*)(BASE) + ((size_t)(br) * K + (size_t)(kt) * BK) * 2; \
;     __builtin_amdgcn_global_load_lds((const unsigned*)(_gb + loff0), (unsigned*)((char*)(P) + tid * 16), 16, 0, 0); \
;     __builtin_amdgcn_global_load_lds((const unsigned*)(_gb + (size_t)K * 128 + loff0), (unsigned*)((char*)(P) + tid * 16 + 8192), 16, 0, 0); } while (0)
; #define LDA(dst, b, h) for (int m = 0; m < 4; ++m) { \
;     dst[m][0] = *reinterpret_cast<const bf16x8*>((char*)SA(b, h) + aoff0 + m * 2048); \
;     dst[m][1] = *reinterpret_cast<const bf16x8*>((char*)SA(b, h) + aoff1 + m * 2048); }
; #define LDB(dst, b, h) for (int n = 0; n < 2; ++n) { \
;     dst[n][0] = *reinterpret_cast<const bf16x8*>((char*)SB(b, h) + boff0 + n * 256); \
;     dst[n][1] = *reinterpret_cast<const bf16x8*>((char*)SB(b, h) + boff1 + n * 256); }
; #define MMA(ai, bj, At, Btf) do { __builtin_amdgcn_s_setprio(1); \
;     for (int m = 0; m < 4; ++m) for (int n = 0; n < 2; ++n) for (int k = 0; k < 2; ++k) \
;       acc[ai][bj][m][n] = __builtin_amdgcn_mfma_f32_16x16x32_bf16(Btf[n][k], At[m][k], acc[ai][bj][m][n], 0, 0, 0); \
;     __builtin_amdgcn_s_setprio(0); } while (0)
; #define WAIT_V(n) asm volatile("s_waitcnt vmcnt(" #n ")" ::: "memory")
; #define WAIT_L(n) asm volatile("s_waitcnt lgkmcnt(" #n ")" ::: "memory")
; #define BAR __builtin_amdgcn_s_barrier()
; #define SCHED __builtin_amdgcn_sched_barrier(0)
; template <int EPI> ...
;     ...
;     STAGE(SB(0, 1), Bt, bcol + HALF, t + 2);
;     WAIT_V(6); BAR; MMA(1, 1, At, B1); BAR;
;     LDB(B0, 1, 0); SCHED; LDA(At, 1, 0); STAGE(SA(0, 1), A, brow + HALF, t + 2);
;     WAIT_L(8); BAR; WAIT_L(0); MMA(0, 0, At, B0); BAR; SCHED;
;     LDB(B1, 1, 1); STAGE(SB(1, 0), Bt, bcol, t + 3);
;     BAR; WAIT_L(0); MMA(0, 1, At, B1); BAR;
;     LDA(At, 1, 1); STAGE(SA(1, 0), A, brow, t + 3);
;     BAR; WAIT_L(0); MMA(1, 0, At, B0); BAR; SCHED;
	s_setprio 0
	v_readfirstlane_b32 s51, v137
	v_lshl_add_u64 v[16:17], v[0:1], 0, s[12:13]
	s_mov_b32 m0, s51
	v_readfirstlane_b32 s51, v254
	global_load_lds_dwordx4 v[16:17], off
	v_lshl_add_u64 v[16:17], v[0:1], 0, s[16:17]
	s_mov_b32 m0, s51
	s_nop 0
	global_load_lds_dwordx4 v[16:17], off
	s_waitcnt vmcnt(6)
	s_barrier
	s_setprio 1
	v_mfma_f32_16x16x32_bf16 v[16:19], v[88:91], v[52:55], 0
	v_mfma_f32_16x16x32_bf16 v[20:23], v[92:95], v[52:55], 0
	v_mfma_f32_16x16x32_bf16 v[16:19], v[96:99], v[108:111], v[16:19]
	v_mfma_f32_16x16x32_bf16 v[20:23], v[100:103], v[108:111], v[20:23]
	v_mfma_f32_16x16x32_bf16 v[52:55], v[88:91], v[112:115], 0
	v_mfma_f32_16x16x32_bf16 v[108:111], v[92:95], v[112:115], 0
	v_mfma_f32_16x16x32_bf16 v[52:55], v[96:99], v[116:119], v[52:55]
	v_mfma_f32_16x16x32_bf16 v[108:111], v[100:103], v[116:119], v[108:111]
	v_mfma_f32_16x16x32_bf16 v[112:115], v[88:91], v[120:123], 0
	v_mfma_f32_16x16x32_bf16 v[116:119], v[92:95], v[120:123], 0
	v_mfma_f32_16x16x32_bf16 v[88:91], v[88:91], v[158:161], 0
	v_mfma_f32_16x16x32_bf16 v[92:95], v[92:95], v[158:161], 0
	v_mfma_f32_16x16x32_bf16 v[112:115], v[96:99], v[124:127], v[112:115]
	v_mfma_f32_16x16x32_bf16 v[116:119], v[100:103], v[124:127], v[116:119]
	v_mfma_f32_16x16x32_bf16 v[88:91], v[96:99], v[162:165], v[88:91]
	v_mfma_f32_16x16x32_bf16 v[92:95], v[100:103], v[162:165], v[92:95]
	s_setprio 0
	s_barrier
	ds_read_b128 v[96:99], v150
	ds_read_b128 v[100:103], v150 offset:256
	ds_read_b128 v[120:123], v151
	ds_read_b128 v[124:127], v151 offset:256
	v_readfirstlane_b32 s51, v142
	v_lshl_add_u64 v[138:139], v[6:7], 0, s[12:13]
	s_mov_b32 m0, s51
	v_readfirstlane_b32 s51, v143
	ds_read_b128 v[158:161], v147 offset:32768
	ds_read_b128 v[162:165], v147 offset:33792
	ds_read_b128 v[190:193], v147 offset:34816
	ds_read_b128 v[194:197], v147 offset:35840
	ds_read_b128 v[198:201], v147 offset:36864
	ds_read_b128 v[202:205], v147 offset:37888
	ds_read_b128 v[206:209], v147 offset:38912
	ds_read_b128 v[210:213], v147 offset:39936
	global_load_lds_dwordx4 v[138:139], off
	v_lshl_add_u64 v[6:7], v[6:7], 0, s[16:17]
	s_mov_b32 m0, s51
	s_nop 0
	global_load_lds_dwordx4 v[6:7], off
	s_waitcnt lgkmcnt(8)
	s_waitcnt lgkmcnt(0)
	s_setprio 1
	s_barrier
	v_mfma_f32_16x16x32_bf16 v[56:59], v[96:99], v[158:161], v[56:59]
	v_mfma_f32_16x16x32_bf16 v[60:63], v[100:103], v[158:161], v[60:63]
	v_mfma_f32_16x16x32_bf16 v[64:67], v[96:99], v[190:193], v[64:67]
	v_mfma_f32_16x16x32_bf16 v[68:71], v[100:103], v[190:193], v[68:71]
	v_mfma_f32_16x16x32_bf16 v[72:75], v[96:99], v[198:201], v[72:75]
	v_mfma_f32_16x16x32_bf16 v[76:79], v[100:103], v[198:201], v[76:79]
	v_mfma_f32_16x16x32_bf16 v[80:83], v[96:99], v[206:209], v[80:83]
	v_mfma_f32_16x16x32_bf16 v[84:87], v[100:103], v[206:209], v[84:87]
	v_mfma_f32_16x16x32_bf16 v[56:59], v[120:123], v[162:165], v[56:59]
	v_mfma_f32_16x16x32_bf16 v[60:63], v[124:127], v[162:165], v[60:63]
	v_mfma_f32_16x16x32_bf16 v[64:67], v[120:123], v[194:197], v[64:67]
	v_mfma_f32_16x16x32_bf16 v[68:71], v[124:127], v[194:197], v[68:71]
	v_mfma_f32_16x16x32_bf16 v[72:75], v[120:123], v[202:205], v[72:75]
	v_mfma_f32_16x16x32_bf16 v[76:79], v[124:127], v[202:205], v[76:79]
	v_mfma_f32_16x16x32_bf16 v[80:83], v[120:123], v[210:213], v[80:83]
	v_mfma_f32_16x16x32_bf16 v[84:87], v[124:127], v[210:213], v[84:87]
	s_barrier
	s_setprio 0
	s_mov_b32 m0, s50
	v_lshl_add_u64 v[6:7], v[4:5], 0, s[18:19]
	ds_read_b128 v[214:217], v152
	ds_read_b128 v[218:221], v152 offset:256
	ds_read_b128 v[222:225], v153
	ds_read_b128 v[226:229], v153 offset:256
	global_load_lds_dwordx4 v[6:7], off
	v_lshl_add_u64 v[4:5], v[4:5], 0, s[20:21]
	s_mov_b32 m0, s49
	s_nop 0
	global_load_lds_dwordx4 v[4:5], off
	s_barrier
	s_waitcnt lgkmcnt(0)
	s_setprio 1
	s_waitcnt lgkmcnt(0)
	v_mfma_f32_16x16x32_bf16 v[4:7], v[214:217], v[158:161], v[104:107]
	v_mfma_f32_16x16x32_bf16 v[24:27], v[218:221], v[158:161], v[24:27]
	v_mfma_f32_16x16x32_bf16 v[28:31], v[214:217], v[190:193], v[28:31]
	v_mfma_f32_16x16x32_bf16 v[32:35], v[218:221], v[190:193], v[32:35]
	v_mfma_f32_16x16x32_bf16 v[36:39], v[214:217], v[198:201], v[36:39]
	v_mfma_f32_16x16x32_bf16 v[40:43], v[218:221], v[198:201], v[40:43]
	v_mfma_f32_16x16x32_bf16 v[44:47], v[214:217], v[206:209], v[44:47]
	v_mfma_f32_16x16x32_bf16 v[48:51], v[218:221], v[206:209], v[48:51]
	v_mfma_f32_16x16x32_bf16 v[4:7], v[222:225], v[162:165], v[4:7]
	v_mfma_f32_16x16x32_bf16 v[24:27], v[226:229], v[162:165], v[24:27]
	v_mfma_f32_16x16x32_bf16 v[28:31], v[222:225], v[194:197], v[28:31]
	v_mfma_f32_16x16x32_bf16 v[32:35], v[226:229], v[194:197], v[32:35]
	v_mfma_f32_16x16x32_bf16 v[36:39], v[222:225], v[202:205], v[36:39]
	v_mfma_f32_16x16x32_bf16 v[40:43], v[226:229], v[202:205], v[40:43]
	v_mfma_f32_16x16x32_bf16 v[44:47], v[222:225], v[210:213], v[44:47]
	v_mfma_f32_16x16x32_bf16 v[48:51], v[226:229], v[210:213], v[48:51]
	s_setprio 0
	s_mov_b32 m0, s48
	v_lshl_add_u64 v[138:139], v[2:3], 0, s[18:19]
	s_barrier
	ds_read_b128 v[104:107], v147 offset:49152
	ds_read_b128 v[158:161], v147 offset:50176
	ds_read_b128 v[162:165], v147 offset:51200
	ds_read_b128 v[190:193], v147 offset:52224
	ds_read_b128 v[194:197], v147 offset:53248
	ds_read_b128 v[198:201], v147 offset:54272
	ds_read_b128 v[202:205], v147 offset:55296
	ds_read_b128 v[206:209], v147 offset:56320
	global_load_lds_dwordx4 v[138:139], off
	v_lshl_add_u64 v[2:3], v[2:3], 0, s[20:21]
	s_mov_b32 m0, s47
	s_nop 0
	global_load_lds_dwordx4 v[2:3], off
	s_waitcnt lgkmcnt(0)
	s_setprio 1
	s_barrier
; #define STAGE(P, BASE, br, kt) do { const char* _gb = (const char*)(BASE) + ((size_t)(br) * K + (size_t)(kt) * BK) * 2; \
;     __builtin_amdgcn_global_load_lds((const unsigned*)(_gb + loff0), (unsigned*)((char*)(P) + tid * 16), 16, 0, 0); \
;     __builtin_amdgcn_global_load_lds((const unsigned*)(_gb + (size_t)K * 128 + loff0), (unsigned*)((char*)(P) + tid * 16 + 8192), 16, 0, 0); } while (0)
; #define LDA(dst, b, h) for (int m = 0; m < 4; ++m) { \
;     dst[m][0] = *reinterpret_cast<const bf16x8*>((char*)SA(b, h) + aoff0 + m * 2048); \
;     dst[m][1] = *reinterpret_cast<const bf16x8*>((char*)SA(b, h) + aoff1 + m * 2048); }
; #define LDB(dst, b, h) for (int n = 0; n < 2; ++n) { \
;     dst[n][0] = *reinterpret_cast<const bf16x8*>((char*)SB(b, h) + boff0 + n * 256); \
;     dst[n][1] = *reinterpret_cast<const bf16x8*>((char*)SB(b, h) + boff1 + n * 256); }
; #define MMA(ai, bj, At, Btf) do { __builtin_amdgcn_s_setprio(1); \
;     for (int m = 0; m < 4; ++m) for (int n = 0; n < 2; ++n) for (int k = 0; k < 2; ++k) \
;       acc[ai][bj][m][n] = __builtin_amdgcn_mfma_f32_16x16x32_bf16(Btf[n][k], At[m][k], acc[ai][bj][m][n], 0, 0, 0); \
;     __builtin_amdgcn_s_setprio(0); } while (0)
; #define WAIT_V(n) asm volatile("s_waitcnt vmcnt(" #n ")" ::: "memory")
; #define WAIT_L(n) asm volatile("s_waitcnt lgkmcnt(" #n ")" ::: "memory")
; #define BAR __builtin_amdgcn_s_barrier()
; #define SCHED __builtin_amdgcn_sched_barrier(0)
; template <int EPI> ...
;     ...
;     BAR; WAIT_L(0); MMA(1, 0, At, B0); BAR; SCHED;
;     STAGE(SB(1, 1), Bt, bcol + HALF, t + 3);
;     WAIT_V(6); BAR; MMA(1, 1, At, B1); BAR;
;   }
;   { LDB(B0, 0, 0); LDA(At, 0, 0); STAGE(SA(1, 1), A, brow + HALF, nt - 1);
;     BAR; WAIT_L(0); MMA(0, 0, At, B0); BAR;
;     LDB(B1, 0, 1); BAR; WAIT_L(0); MMA(0, 1, At, B1); BAR;
	v_mfma_f32_16x16x32_bf16 v[8:11], v[96:99], v[202:205], v[8:11]
	v_mfma_f32_16x16x32_bf16 v[12:15], v[100:103], v[202:205], v[12:15]
	v_mfma_f32_16x16x32_bf16 v[166:169], v[96:99], v[104:107], v[166:169]
	v_mfma_f32_16x16x32_bf16 v[170:173], v[100:103], v[104:107], v[170:173]
	v_mfma_f32_16x16x32_bf16 v[174:177], v[96:99], v[162:165], v[174:177]
	v_mfma_f32_16x16x32_bf16 v[178:181], v[100:103], v[162:165], v[178:181]
	v_mfma_f32_16x16x32_bf16 v[182:185], v[96:99], v[194:197], v[182:185]
	v_mfma_f32_16x16x32_bf16 v[186:189], v[100:103], v[194:197], v[186:189]
	v_mfma_f32_16x16x32_bf16 v[8:11], v[120:123], v[206:209], v[8:11]
	v_mfma_f32_16x16x32_bf16 v[12:15], v[124:127], v[206:209], v[12:15]
	v_mfma_f32_16x16x32_bf16 v[166:169], v[120:123], v[158:161], v[166:169]
	v_mfma_f32_16x16x32_bf16 v[170:173], v[124:127], v[158:161], v[170:173]
	v_mfma_f32_16x16x32_bf16 v[174:177], v[120:123], v[190:193], v[174:177]
	v_mfma_f32_16x16x32_bf16 v[178:181], v[124:127], v[190:193], v[178:181]
	v_mfma_f32_16x16x32_bf16 v[182:185], v[120:123], v[198:201], v[182:185]
	v_mfma_f32_16x16x32_bf16 v[186:189], v[124:127], v[198:201], v[186:189]
	s_barrier
	s_setprio 0
	s_mov_b32 m0, s46
	v_lshl_add_u64 v[2:3], v[0:1], 0, s[18:19]
	global_load_lds_dwordx4 v[2:3], off
	v_lshl_add_u64 v[0:1], v[0:1], 0, s[20:21]
	s_mov_b32 m0, s29
	s_nop 0
	global_load_lds_dwordx4 v[0:1], off
	s_waitcnt vmcnt(6)
	s_barrier
	s_setprio 1
	v_mfma_f32_16x16x32_bf16 v[0:3], v[214:217], v[104:107], v[16:19]
	v_mfma_f32_16x16x32_bf16 v[16:19], v[218:221], v[104:107], v[20:23]
	v_mfma_f32_16x16x32_bf16 v[20:23], v[214:217], v[162:165], v[52:55]
	v_mfma_f32_16x16x32_bf16 v[52:55], v[218:221], v[162:165], v[108:111]
	v_mfma_f32_16x16x32_bf16 v[96:99], v[214:217], v[194:197], v[112:115]
	v_mfma_f32_16x16x32_bf16 v[100:103], v[218:221], v[194:197], v[116:119]
	v_mfma_f32_16x16x32_bf16 v[88:91], v[214:217], v[202:205], v[88:91]
	v_mfma_f32_16x16x32_bf16 v[92:95], v[218:221], v[202:205], v[92:95]
	v_mfma_f32_16x16x32_bf16 v[0:3], v[222:225], v[158:161], v[0:3]
	v_mfma_f32_16x16x32_bf16 v[16:19], v[226:229], v[158:161], v[16:19]
	v_mfma_f32_16x16x32_bf16 v[20:23], v[222:225], v[190:193], v[20:23]
	v_mfma_f32_16x16x32_bf16 v[52:55], v[226:229], v[190:193], v[52:55]
	v_mfma_f32_16x16x32_bf16 v[96:99], v[222:225], v[198:201], v[96:99]
	v_mfma_f32_16x16x32_bf16 v[100:103], v[226:229], v[198:201], v[100:103]
	v_mfma_f32_16x16x32_bf16 v[88:91], v[222:225], v[206:209], v[88:91]
	v_mfma_f32_16x16x32_bf16 v[92:95], v[226:229], v[206:209], v[92:95]
	s_setprio 0
	s_add_u32 s26, s37, s26
	s_addc_u32 s27, s38, s27
	s_mov_b32 m0, s28
	v_lshl_add_u64 v[138:139], s[26:27], 0, v[128:129]
	s_barrier
	ds_read_b128 v[104:107], v154
	ds_read_b128 v[108:111], v154 offset:256
	ds_read_b128 v[112:115], v155
	ds_read_b128 v[116:119], v155 offset:256
	ds_read_b128 v[120:123], v147
	ds_read_b128 v[124:127], v147 offset:1024
	ds_read_b128 v[158:161], v147 offset:2048
	ds_read_b128 v[162:165], v147 offset:3072
	ds_read_b128 v[190:193], v147 offset:4096
	ds_read_b128 v[194:197], v147 offset:5120
	ds_read_b128 v[198:201], v147 offset:6144
	ds_read_b128 v[202:205], v147 offset:7168
	global_load_lds_dwordx4 v[138:139], off
	v_lshl_add_u64 v[138:139], v[138:139], 0, s[6:7]
	s_mov_b32 m0, s23
	s_nop 0
	global_load_lds_dwordx4 v[138:139], off
	s_waitcnt lgkmcnt(0)
	s_setprio 1
	s_barrier
	v_mfma_f32_16x16x32_bf16 v[56:59], v[104:107], v[120:123], v[56:59]
	v_mfma_f32_16x16x32_bf16 v[60:63], v[108:111], v[120:123], v[60:63]
	v_mfma_f32_16x16x32_bf16 v[64:67], v[104:107], v[158:161], v[64:67]
	v_mfma_f32_16x16x32_bf16 v[68:71], v[108:111], v[158:161], v[68:71]
	v_mfma_f32_16x16x32_bf16 v[72:75], v[104:107], v[190:193], v[72:75]
	v_mfma_f32_16x16x32_bf16 v[76:79], v[108:111], v[190:193], v[76:79]
	v_mfma_f32_16x16x32_bf16 v[80:83], v[104:107], v[198:201], v[80:83]
	v_mfma_f32_16x16x32_bf16 v[84:87], v[108:111], v[198:201], v[84:87]
	v_mfma_f32_16x16x32_bf16 v[56:59], v[112:115], v[124:127], v[56:59]
	v_mfma_f32_16x16x32_bf16 v[60:63], v[116:119], v[124:127], v[60:63]
	v_mfma_f32_16x16x32_bf16 v[64:67], v[112:115], v[162:165], v[64:67]
	v_mfma_f32_16x16x32_bf16 v[68:71], v[116:119], v[162:165], v[68:71]
	v_mfma_f32_16x16x32_bf16 v[72:75], v[112:115], v[194:197], v[72:75]
	v_mfma_f32_16x16x32_bf16 v[76:79], v[116:119], v[194:197], v[76:79]
	v_mfma_f32_16x16x32_bf16 v[80:83], v[112:115], v[202:205], v[80:83]
	v_mfma_f32_16x16x32_bf16 v[84:87], v[116:119], v[202:205], v[84:87]
	s_barrier
	s_setprio 0
	ds_read_b128 v[206:209], v156
	ds_read_b128 v[210:213], v156 offset:256
	ds_read_b128 v[214:217], v157
	ds_read_b128 v[218:221], v157 offset:256
	s_waitcnt lgkmcnt(0)
	s_setprio 1
	s_barrier
	v_mfma_f32_16x16x32_bf16 v[4:7], v[206:209], v[120:123], v[4:7]
	v_mfma_f32_16x16x32_bf16 v[24:27], v[210:213], v[120:123], v[24:27]
	v_mfma_f32_16x16x32_bf16 v[28:31], v[206:209], v[158:161], v[28:31]
	v_mfma_f32_16x16x32_bf16 v[32:35], v[210:213], v[158:161], v[32:35]
	v_mfma_f32_16x16x32_bf16 v[36:39], v[206:209], v[190:193], v[36:39]
	v_mfma_f32_16x16x32_bf16 v[40:43], v[210:213], v[190:193], v[40:43]
	v_mfma_f32_16x16x32_bf16 v[44:47], v[206:209], v[198:201], v[44:47]
	v_mfma_f32_16x16x32_bf16 v[4:7], v[214:217], v[124:127], v[4:7]
	v_mfma_f32_16x16x32_bf16 v[24:27], v[218:221], v[124:127], v[24:27]
	v_mfma_f32_16x16x32_bf16 v[28:31], v[214:217], v[162:165], v[28:31]
	v_mfma_f32_16x16x32_bf16 v[32:35], v[218:221], v[162:165], v[32:35]
	v_mfma_f32_16x16x32_bf16 v[36:39], v[214:217], v[194:197], v[36:39]
	v_mfma_f32_16x16x32_bf16 v[40:43], v[218:221], v[194:197], v[40:43]
	v_mfma_f32_16x16x32_bf16 v[44:47], v[214:217], v[202:205], v[44:47]
	v_mfma_f32_16x16x32_bf16 v[48:51], v[210:213], v[198:201], v[48:51]
	v_mfma_f32_16x16x32_bf16 v[158:161], v[218:221], v[202:205], v[48:51]
	s_barrier
; #define LDA(dst, b, h) for (int m = 0; m < 4; ++m) { \
;     dst[m][0] = *reinterpret_cast<const bf16x8*>((char*)SA(b, h) + aoff0 + m * 2048); \
;     dst[m][1] = *reinterpret_cast<const bf16x8*>((char*)SA(b, h) + aoff1 + m * 2048); }
; #define LDB(dst, b, h) for (int n = 0; n < 2; ++n) { \
;     dst[n][0] = *reinterpret_cast<const bf16x8*>((char*)SB(b, h) + boff0 + n * 256); \
;     dst[n][1] = *reinterpret_cast<const bf16x8*>((char*)SB(b, h) + boff1 + n * 256); }
; #define MMA(ai, bj, At, Btf) do { __builtin_amdgcn_s_setprio(1); \
;     for (int m = 0; m < 4; ++m) for (int n = 0; n < 2; ++n) for (int k = 0; k < 2; ++k) \
;       acc[ai][bj][m][n] = __builtin_amdgcn_mfma_f32_16x16x32_bf16(Btf[n][k], At[m][k], acc[ai][bj][m][n], 0, 0, 0); \
;     __builtin_amdgcn_s_setprio(0); } while (0)
; #define WAIT_V(n) asm volatile("s_waitcnt vmcnt(" #n ")" ::: "memory")
; #define WAIT_L(n) asm volatile("s_waitcnt lgkmcnt(" #n ")" ::: "memory")
; #define BAR __builtin_amdgcn_s_barrier()
; template <int EPI> ...
;     ...
;     LDA(At, 0, 1); WAIT_V(4); BAR; WAIT_L(0); MMA(1, 0, At, B0); MMA(1, 1, At, B1); BAR; }
;   { LDB(B0, 1, 0); LDA(At, 1, 0); WAIT_V(2); BAR; WAIT_L(0); MMA(0, 0, At, B0); BAR;
	s_setprio 0
	s_nop 4
	ds_read_b128 v[48:51], v147 offset:16384
	ds_read_b128 v[120:123], v147 offset:17408
	ds_read_b128 v[124:127], v147 offset:18432
	ds_read_b128 v[162:165], v147 offset:19456
	ds_read_b128 v[190:193], v147 offset:20480
	ds_read_b128 v[194:197], v147 offset:21504
	ds_read_b128 v[198:201], v147 offset:22528
	ds_read_b128 v[202:205], v147 offset:23552
	s_waitcnt vmcnt(4)
	s_waitcnt lgkmcnt(0)
	s_setprio 1
	s_barrier
	v_mfma_f32_16x16x32_bf16 v[8:11], v[104:107], v[198:201], v[8:11]
	v_mfma_f32_16x16x32_bf16 v[12:15], v[108:111], v[198:201], v[12:15]
	v_mfma_f32_16x16x32_bf16 v[166:169], v[104:107], v[48:51], v[166:169]
	v_mfma_f32_16x16x32_bf16 v[170:173], v[108:111], v[48:51], v[170:173]
	v_mfma_f32_16x16x32_bf16 v[174:177], v[104:107], v[124:127], v[174:177]
	v_mfma_f32_16x16x32_bf16 v[178:181], v[108:111], v[124:127], v[178:181]
	v_mfma_f32_16x16x32_bf16 v[182:185], v[104:107], v[190:193], v[182:185]
	v_mfma_f32_16x16x32_bf16 v[186:189], v[108:111], v[190:193], v[186:189]
	v_mfma_f32_16x16x32_bf16 v[8:11], v[112:115], v[202:205], v[8:11]
	v_mfma_f32_16x16x32_bf16 v[12:15], v[116:119], v[202:205], v[12:15]
	v_mfma_f32_16x16x32_bf16 v[166:169], v[112:115], v[120:123], v[166:169]
	v_mfma_f32_16x16x32_bf16 v[170:173], v[116:119], v[120:123], v[170:173]
	v_mfma_f32_16x16x32_bf16 v[174:177], v[112:115], v[162:165], v[174:177]
	v_mfma_f32_16x16x32_bf16 v[178:181], v[116:119], v[162:165], v[178:181]
	v_mfma_f32_16x16x32_bf16 v[182:185], v[112:115], v[194:197], v[182:185]
	v_mfma_f32_16x16x32_bf16 v[186:189], v[116:119], v[194:197], v[186:189]
	v_mfma_f32_16x16x32_bf16 v[0:3], v[206:209], v[48:51], v[0:3]
	v_mfma_f32_16x16x32_bf16 v[16:19], v[210:213], v[48:51], v[16:19]
	v_mfma_f32_16x16x32_bf16 v[20:23], v[206:209], v[124:127], v[20:23]
	v_mfma_f32_16x16x32_bf16 v[48:51], v[210:213], v[124:127], v[52:55]
	v_mfma_f32_16x16x32_bf16 v[20:23], v[214:217], v[162:165], v[20:23]
	v_mfma_f32_16x16x32_bf16 v[162:165], v[218:221], v[162:165], v[48:51]
	v_mfma_f32_16x16x32_bf16 v[48:51], v[206:209], v[190:193], v[96:99]
	v_mfma_f32_16x16x32_bf16 v[222:225], v[214:217], v[194:197], v[48:51]
	v_mfma_f32_16x16x32_bf16 v[48:51], v[210:213], v[190:193], v[100:103]
	v_mfma_f32_16x16x32_bf16 v[190:193], v[218:221], v[194:197], v[48:51]
	v_mfma_f32_16x16x32_bf16 v[48:51], v[206:209], v[198:201], v[88:91]
	v_mfma_f32_16x16x32_bf16 v[0:3], v[214:217], v[120:123], v[0:3]
	v_mfma_f32_16x16x32_bf16 v[16:19], v[218:221], v[120:123], v[16:19]
	v_mfma_f32_16x16x32_bf16 v[194:197], v[214:217], v[202:205], v[48:51]
	v_mfma_f32_16x16x32_bf16 v[48:51], v[210:213], v[198:201], v[92:95]
	v_mfma_f32_16x16x32_bf16 v[198:201], v[218:221], v[202:205], v[48:51]
	s_barrier
	s_setprio 0
	ds_read_b128 v[202:205], v150
	ds_read_b128 v[206:209], v150 offset:256
	ds_read_b128 v[210:213], v151
	ds_read_b128 v[214:217], v151 offset:256
	s_nop 0
	ds_read_b128 v[48:51], v147 offset:32768
	ds_read_b128 v[52:55], v147 offset:33792
	ds_read_b128 v[92:95], v147 offset:34816
	ds_read_b128 v[218:221], v147 offset:35840
	ds_read_b128 v[226:229], v147 offset:36864
	ds_read_b128 v[230:233], v147 offset:37888
	ds_read_b128 v[234:237], v147 offset:38912
	ds_read_b128 v[238:241], v147 offset:39936
	s_waitcnt vmcnt(2)
	s_waitcnt lgkmcnt(0)
	s_setprio 1
	s_barrier
	v_mfma_f32_16x16x32_bf16 v[56:59], v[202:205], v[48:51], v[56:59]
	v_mfma_f32_16x16x32_bf16 v[120:123], v[210:213], v[52:55], v[56:59]
	v_mfma_f32_16x16x32_bf16 v[56:59], v[206:209], v[48:51], v[60:63]
	v_mfma_f32_16x16x32_bf16 v[124:127], v[214:217], v[52:55], v[56:59]
	v_mfma_f32_16x16x32_bf16 v[56:59], v[202:205], v[92:95], v[64:67]
	v_mfma_f32_16x16x32_bf16 v[112:115], v[210:213], v[218:221], v[56:59]
	v_mfma_f32_16x16x32_bf16 v[56:59], v[206:209], v[92:95], v[68:71]
	v_mfma_f32_16x16x32_bf16 v[116:119], v[214:217], v[218:221], v[56:59]
	v_mfma_f32_16x16x32_bf16 v[56:59], v[202:205], v[226:229], v[72:75]
	v_mfma_f32_16x16x32_bf16 v[104:107], v[210:213], v[230:233], v[56:59]
	v_mfma_f32_16x16x32_bf16 v[56:59], v[206:209], v[226:229], v[76:79]
	v_mfma_f32_16x16x32_bf16 v[108:111], v[214:217], v[230:233], v[56:59]
	v_mfma_f32_16x16x32_bf16 v[56:59], v[202:205], v[234:237], v[80:83]
	v_mfma_f32_16x16x32_bf16 v[80:83], v[210:213], v[238:241], v[56:59]
	v_mfma_f32_16x16x32_bf16 v[56:59], v[206:209], v[234:237], v[84:87]
	v_mfma_f32_16x16x32_bf16 v[84:87], v[214:217], v[238:241], v[56:59]
	s_barrier
; #define LDA(dst, b, h) for (int m = 0; m < 4; ++m) { \
;     dst[m][0] = *reinterpret_cast<const bf16x8*>((char*)SA(b, h) + aoff0 + m * 2048); \
;     dst[m][1] = *reinterpret_cast<const bf16x8*>((char*)SA(b, h) + aoff1 + m * 2048); }
; #define LDB(dst, b, h) for (int n = 0; n < 2; ++n) { \
;     dst[n][0] = *reinterpret_cast<const bf16x8*>((char*)SB(b, h) + boff0 + n * 256); \
;     dst[n][1] = *reinterpret_cast<const bf16x8*>((char*)SB(b, h) + boff1 + n * 256); }
; #define MMA(ai, bj, At, Btf) do { __builtin_amdgcn_s_setprio(1); \
;     for (int m = 0; m < 4; ++m) for (int n = 0; n < 2; ++n) for (int k = 0; k < 2; ++k) \
;       acc[ai][bj][m][n] = __builtin_amdgcn_mfma_f32_16x16x32_bf16(Btf[n][k], At[m][k], acc[ai][bj][m][n], 0, 0, 0); \
;     __builtin_amdgcn_s_setprio(0); } while (0)
; #define WAIT_V(n) asm volatile("s_waitcnt vmcnt(" #n ")" ::: "memory")
; #define WAIT_L(n) asm volatile("s_waitcnt lgkmcnt(" #n ")" ::: "memory")
; #define BAR __builtin_amdgcn_s_barrier()
; template <int EPI> ...
;     ...
;     LDB(B1, 1, 1); WAIT_V(0); BAR; WAIT_L(0); MMA(0, 1, At, B1); BAR;
;     LDA(At, 1, 1); BAR; WAIT_L(0); MMA(1, 0, At, B0); MMA(1, 1, At, B1); BAR; }
;   if (wr == 0) BAR;
	s_setprio 0
	ds_read_b128 v[242:245], v152
	ds_read_b128 v[246:249], v152 offset:256
	ds_read_b128 v[250:253], v153
	ds_read_b128 v[138:141], v153 offset:256
	s_waitcnt vmcnt(0)
	s_waitcnt lgkmcnt(0)
	s_setprio 1
	s_barrier
	v_mfma_f32_16x16x32_bf16 v[4:7], v[242:245], v[48:51], v[4:7]
	v_mfma_f32_16x16x32_bf16 v[96:99], v[250:253], v[52:55], v[4:7]
	v_mfma_f32_16x16x32_bf16 v[4:7], v[246:249], v[48:51], v[24:27]
	v_mfma_f32_16x16x32_bf16 v[100:103], v[138:141], v[52:55], v[4:7]
	v_mfma_f32_16x16x32_bf16 v[4:7], v[242:245], v[92:95], v[28:31]
	v_mfma_f32_16x16x32_bf16 v[88:91], v[250:253], v[218:221], v[4:7]
	v_mfma_f32_16x16x32_bf16 v[4:7], v[246:249], v[92:95], v[32:35]
	v_mfma_f32_16x16x32_bf16 v[92:95], v[138:141], v[218:221], v[4:7]
	v_mfma_f32_16x16x32_bf16 v[4:7], v[242:245], v[226:229], v[36:39]
	v_mfma_f32_16x16x32_bf16 v[64:67], v[250:253], v[230:233], v[4:7]
	v_mfma_f32_16x16x32_bf16 v[4:7], v[246:249], v[226:229], v[40:43]
	v_mfma_f32_16x16x32_bf16 v[68:71], v[138:141], v[230:233], v[4:7]
	v_mfma_f32_16x16x32_bf16 v[4:7], v[242:245], v[234:237], v[44:47]
	v_mfma_f32_16x16x32_bf16 v[48:51], v[250:253], v[238:241], v[4:7]
	v_mfma_f32_16x16x32_bf16 v[4:7], v[246:249], v[234:237], v[158:161]
	v_mfma_f32_16x16x32_bf16 v[52:55], v[138:141], v[238:241], v[4:7]
	s_barrier
	s_setprio 0
	s_nop 4
	ds_read_b128 v[4:7], v147 offset:49152
	ds_read_b128 v[28:31], v147 offset:50176
	ds_read_b128 v[158:161], v147 offset:51200
	ds_read_b128 v[218:221], v147 offset:52224
	ds_read_b128 v[226:229], v147 offset:53248
	ds_read_b128 v[230:233], v147 offset:54272
	ds_read_b128 v[234:237], v147 offset:55296
	ds_read_b128 v[238:241], v147 offset:56320
	s_waitcnt lgkmcnt(0)
	s_setprio 1
	s_barrier
	v_mfma_f32_16x16x32_bf16 v[24:27], v[202:205], v[4:7], v[166:169]
	v_mfma_f32_16x16x32_bf16 v[72:75], v[210:213], v[28:31], v[24:27]
	v_mfma_f32_16x16x32_bf16 v[24:27], v[206:209], v[4:7], v[170:173]
	v_mfma_f32_16x16x32_bf16 v[76:79], v[214:217], v[28:31], v[24:27]
	v_mfma_f32_16x16x32_bf16 v[24:27], v[202:205], v[158:161], v[174:177]
	v_mfma_f32_16x16x32_bf16 v[56:59], v[210:213], v[218:221], v[24:27]
	v_mfma_f32_16x16x32_bf16 v[24:27], v[206:209], v[158:161], v[178:181]
	v_mfma_f32_16x16x32_bf16 v[60:63], v[214:217], v[218:221], v[24:27]
	v_mfma_f32_16x16x32_bf16 v[24:27], v[202:205], v[226:229], v[182:185]
	v_mfma_f32_16x16x32_bf16 v[8:11], v[202:205], v[234:237], v[8:11]
	v_mfma_f32_16x16x32_bf16 v[40:43], v[210:213], v[230:233], v[24:27]
	v_mfma_f32_16x16x32_bf16 v[24:27], v[206:209], v[226:229], v[186:189]
	v_mfma_f32_16x16x32_bf16 v[32:35], v[210:213], v[238:241], v[8:11]
	v_mfma_f32_16x16x32_bf16 v[8:11], v[206:209], v[234:237], v[12:15]
	v_mfma_f32_16x16x32_bf16 v[44:47], v[214:217], v[230:233], v[24:27]
	v_mfma_f32_16x16x32_bf16 v[36:39], v[214:217], v[238:241], v[8:11]
	v_mfma_f32_16x16x32_bf16 v[0:3], v[242:245], v[4:7], v[0:3]
	v_mfma_f32_16x16x32_bf16 v[24:27], v[250:253], v[28:31], v[0:3]
	v_mfma_f32_16x16x32_bf16 v[0:3], v[246:249], v[4:7], v[16:19]
	v_mfma_f32_16x16x32_bf16 v[28:31], v[138:141], v[28:31], v[0:3]
	v_mfma_f32_16x16x32_bf16 v[0:3], v[242:245], v[158:161], v[20:23]
	v_mfma_f32_16x16x32_bf16 v[16:19], v[250:253], v[218:221], v[0:3]
	v_mfma_f32_16x16x32_bf16 v[0:3], v[246:249], v[158:161], v[162:165]
	v_mfma_f32_16x16x32_bf16 v[20:23], v[138:141], v[218:221], v[0:3]
	v_mfma_f32_16x16x32_bf16 v[0:3], v[242:245], v[226:229], v[222:225]
	v_mfma_f32_16x16x32_bf16 v[8:11], v[250:253], v[230:233], v[0:3]
	v_mfma_f32_16x16x32_bf16 v[0:3], v[246:249], v[226:229], v[190:193]
	v_mfma_f32_16x16x32_bf16 v[12:15], v[138:141], v[230:233], v[0:3]
	v_mfma_f32_16x16x32_bf16 v[0:3], v[242:245], v[234:237], v[194:197]
	v_mfma_f32_16x16x32_bf16 v[4:7], v[246:249], v[234:237], v[198:201]
	v_mfma_f32_16x16x32_bf16 v[0:3], v[250:253], v[238:241], v[0:3]
	v_mfma_f32_16x16x32_bf16 v[4:7], v[138:141], v[238:241], v[4:7]
	s_barrier
	s_setprio 0
	s_and_saveexec_b64 s[26:27], s[2:3]
	s_cbranch_execz .LBB0_845
	s_barrier
	s_branch .LBB0_845

; #define STAGE(P, BASE, br, kt) do { const char* _gb = (const char*)(BASE) + ((size_t)(br) * K + (size_t)(kt) * BK) * 2; \
;     __builtin_amdgcn_global_load_lds((const unsigned*)(_gb + loff0), (unsigned*)((char*)(P) + tid * 16), 16, 0, 0); \
;     __builtin_amdgcn_global_load_lds((const unsigned*)(_gb + (size_t)K * 128 + loff0), (unsigned*)((char*)(P) + tid * 16 + 8192), 16, 0, 0); } while (0)
; #define LDA(dst, b, h) for (int m = 0; m < 4; ++m) { \
;     dst[m][0] = *reinterpret_cast<const bf16x8*>((char*)SA(b, h) + aoff0 + m * 2048); \
;     dst[m][1] = *reinterpret_cast<const bf16x8*>((char*)SA(b, h) + aoff1 + m * 2048); }
; #define LDB(dst, b, h) for (int n = 0; n < 2; ++n) { \
;     dst[n][0] = *reinterpret_cast<const bf16x8*>((char*)SB(b, h) + boff0 + n * 256); \
;     dst[n][1] = *reinterpret_cast<const bf16x8*>((char*)SB(b, h) + boff1 + n * 256); }
; #define MMA(ai, bj, At, Btf) do { __builtin_amdgcn_s_setprio(1); \
;     for (int m = 0; m < 4; ++m) for (int n = 0; n < 2; ++n) for (int k = 0; k < 2; ++k) \
;       acc[ai][bj][m][n] = __builtin_amdgcn_mfma_f32_16x16x32_bf16(Btf[n][k], At[m][k], acc[ai][bj][m][n], 0, 0, 0); \
;     __builtin_amdgcn_s_setprio(0); } while (0)
; #define WAIT_V(n) asm volatile("s_waitcnt vmcnt(" #n ")" ::: "memory")
; #define WAIT_L(n) asm volatile("s_waitcnt lgkmcnt(" #n ")" ::: "memory")
; #define BAR __builtin_amdgcn_s_barrier()
; #define SCHED __builtin_amdgcn_sched_barrier(0)
; template <int EPI> ...
;     ...
;   WAIT_V(4); BAR;
;   STAGE(SB(1, 0), Bt, bcol, 1); STAGE(SA(1, 0), A, brow, 1); STAGE(SB(1, 1), Bt, bcol + HALF, 1);
;   WAIT_V(6); BAR;
;   for (int t = 0; t < nt - 2; t += 2) {
;     LDB(B0, 0, 0); SCHED; LDA(At, 0, 0); STAGE(SA(1, 1), A, brow + HALF, t + 1);
;     WAIT_L(8); BAR; WAIT_L(0); MMA(0, 0, At, B0); BAR; SCHED;
;     LDB(B1, 0, 1); STAGE(SB(0, 0), Bt, bcol, t + 2);
;     BAR; WAIT_L(0); MMA(0, 1, At, B1); BAR;
;     LDA(At, 0, 1); STAGE(SA(0, 0), A, brow, t + 2);
;     BAR; WAIT_L(0); MMA(1, 0, At, B0); BAR; SCHED;
.LBB0_972:
	s_or_b64 exec, exec, s[52:53]
	v_readfirstlane_b32 s52, v164
	v_add_u32_e32 v10, 0x2000, v164
	v_lshl_add_u64 v[8:9], v[6:7], 0, s[8:9]
	s_mov_b32 m0, s52
	v_readfirstlane_b32 s49, v10
	s_waitcnt vmcnt(4)
	s_barrier
	global_load_lds_dwordx4 v[8:9], off
	v_lshl_add_u64 v[8:9], v[6:7], 0, s[10:11]
	s_mov_b32 m0, s49
	v_readfirstlane_b32 s72, v254
	global_load_lds_dwordx4 v[8:9], off
	v_lshl_add_u64 v[8:9], v[4:5], 0, s[8:9]
	s_mov_b32 m0, s72
	v_readfirstlane_b32 s71, v165
	global_load_lds_dwordx4 v[8:9], off
	v_lshl_add_u64 v[8:9], v[4:5], 0, s[10:11]
	s_mov_b32 m0, s71
	v_readfirstlane_b32 s70, v168
	global_load_lds_dwordx4 v[8:9], off
	v_lshl_add_u64 v[8:9], v[2:3], 0, s[8:9]
	s_mov_b32 m0, s70
	v_readfirstlane_b32 s69, v169
	global_load_lds_dwordx4 v[8:9], off
	v_lshl_add_u64 v[8:9], v[2:3], 0, s[10:11]
	s_mov_b32 m0, s69
	s_nop 0
	global_load_lds_dwordx4 v[8:9], off
	s_waitcnt vmcnt(6)
	s_barrier
	ds_read_b128 v[8:11], v176
	ds_read_b128 v[12:15], v176 offset:256
	ds_read_b128 v[16:19], v177
	s_waitcnt vmcnt(0)
	ds_read_b128 v[20:23], v177 offset:256
	v_readfirstlane_b32 s66, v170
	v_lshl_add_u64 v[56:57], v[0:1], 0, s[8:9]
	s_mov_b32 m0, s66
	v_readfirstlane_b32 s53, v171
	ds_read_b128 v[24:27], v154
	ds_read_b128 v[28:31], v154 offset:1024
	ds_read_b128 v[32:35], v154 offset:2048
	ds_read_b128 v[36:39], v154 offset:3072
	ds_read_b128 v[40:43], v154 offset:4096
	ds_read_b128 v[44:47], v154 offset:5120
	ds_read_b128 v[48:51], v154 offset:6144
	ds_read_b128 v[52:55], v154 offset:7168
	global_load_lds_dwordx4 v[56:57], off
	v_lshl_add_u64 v[56:57], v[0:1], 0, s[10:11]
	s_mov_b32 m0, s53
	s_nop 0
	global_load_lds_dwordx4 v[56:57], off
	s_waitcnt lgkmcnt(8)
	s_waitcnt lgkmcnt(0)
	s_setprio 1
	s_barrier
	v_mfma_f32_16x16x32_bf16 v[56:59], v[8:11], v[24:27], 0
	v_mfma_f32_16x16x32_bf16 v[60:63], v[12:15], v[24:27], 0
	v_mfma_f32_16x16x32_bf16 v[64:67], v[8:11], v[32:35], 0
	v_mfma_f32_16x16x32_bf16 v[68:71], v[12:15], v[32:35], 0
	v_mfma_f32_16x16x32_bf16 v[72:75], v[8:11], v[40:43], 0
	v_mfma_f32_16x16x32_bf16 v[76:79], v[12:15], v[40:43], 0
	v_mfma_f32_16x16x32_bf16 v[80:83], v[8:11], v[48:51], 0
	v_mfma_f32_16x16x32_bf16 v[84:87], v[12:15], v[48:51], 0
	v_mfma_f32_16x16x32_bf16 v[56:59], v[16:19], v[28:31], v[56:59]
	v_mfma_f32_16x16x32_bf16 v[60:63], v[20:23], v[28:31], v[60:63]
	v_mfma_f32_16x16x32_bf16 v[64:67], v[16:19], v[36:39], v[64:67]
	v_mfma_f32_16x16x32_bf16 v[68:71], v[20:23], v[36:39], v[68:71]
	v_mfma_f32_16x16x32_bf16 v[72:75], v[16:19], v[44:47], v[72:75]
	v_mfma_f32_16x16x32_bf16 v[76:79], v[20:23], v[44:47], v[76:79]
	v_mfma_f32_16x16x32_bf16 v[80:83], v[16:19], v[52:55], v[80:83]
	v_mfma_f32_16x16x32_bf16 v[84:87], v[20:23], v[52:55], v[84:87]
	s_barrier
	s_setprio 0
	v_readfirstlane_b32 s65, v156
	v_lshl_add_u64 v[104:105], v[6:7], 0, s[12:13]
	s_mov_b32 m0, s65
	v_readfirstlane_b32 s60, v157
	ds_read_b128 v[88:91], v178
	ds_read_b128 v[92:95], v178 offset:256
	ds_read_b128 v[96:99], v179
	ds_read_b128 v[100:103], v179 offset:256
	global_load_lds_dwordx4 v[104:105], off
	v_lshl_add_u64 v[104:105], v[6:7], 0, s[16:17]
	s_mov_b32 m0, s60
	s_nop 0
	global_load_lds_dwordx4 v[104:105], off
	s_barrier
	s_waitcnt lgkmcnt(0)
	s_setprio 1
	s_waitcnt lgkmcnt(0)
	v_mfma_f32_16x16x32_bf16 v[104:107], v[88:91], v[24:27], 0
	v_mfma_f32_16x16x32_bf16 v[24:27], v[92:95], v[24:27], 0
	v_mfma_f32_16x16x32_bf16 v[104:107], v[96:99], v[28:31], v[104:107]
	v_mfma_f32_16x16x32_bf16 v[24:27], v[100:103], v[28:31], v[24:27]
	v_mfma_f32_16x16x32_bf16 v[28:31], v[88:91], v[32:35], 0
	v_mfma_f32_16x16x32_bf16 v[32:35], v[92:95], v[32:35], 0
	v_mfma_f32_16x16x32_bf16 v[28:31], v[96:99], v[36:39], v[28:31]
	v_mfma_f32_16x16x32_bf16 v[32:35], v[100:103], v[36:39], v[32:35]
	v_mfma_f32_16x16x32_bf16 v[36:39], v[88:91], v[40:43], 0
	v_mfma_f32_16x16x32_bf16 v[40:43], v[92:95], v[40:43], 0
	v_mfma_f32_16x16x32_bf16 v[36:39], v[96:99], v[44:47], v[36:39]
	v_mfma_f32_16x16x32_bf16 v[40:43], v[100:103], v[44:47], v[40:43]
	v_mfma_f32_16x16x32_bf16 v[44:47], v[88:91], v[48:51], 0
	v_mfma_f32_16x16x32_bf16 v[48:51], v[92:95], v[48:51], 0
	v_mfma_f32_16x16x32_bf16 v[44:47], v[96:99], v[52:55], v[44:47]
	v_mfma_f32_16x16x32_bf16 v[48:51], v[100:103], v[52:55], v[48:51]
	s_setprio 0
	v_readfirstlane_b32 s67, v158
	v_lshl_add_u64 v[138:139], v[4:5], 0, s[12:13]
	s_mov_b32 m0, s67
	v_readfirstlane_b32 s61, v159
	s_barrier
	ds_read_b128 v[52:55], v154 offset:16384
	ds_read_b128 v[108:111], v154 offset:17408
	ds_read_b128 v[112:115], v154 offset:18432
	ds_read_b128 v[116:119], v154 offset:19456
	ds_read_b128 v[120:123], v154 offset:20480
	ds_read_b128 v[124:127], v154 offset:21504
	ds_read_b128 v[128:131], v154 offset:22528
	ds_read_b128 v[132:135], v154 offset:23552
	global_load_lds_dwordx4 v[138:139], off
	v_lshl_add_u64 v[138:139], v[4:5], 0, s[16:17]
	s_mov_b32 m0, s61
	s_nop 0
	global_load_lds_dwordx4 v[138:139], off
	s_waitcnt lgkmcnt(0)
	s_setprio 1
	s_barrier
	v_mfma_f32_16x16x32_bf16 v[142:145], v[8:11], v[52:55], 0
	v_mfma_f32_16x16x32_bf16 v[146:149], v[12:15], v[52:55], 0
	v_mfma_f32_16x16x32_bf16 v[150:153], v[8:11], v[112:115], 0
	v_mfma_f32_16x16x32_bf16 v[180:183], v[12:15], v[112:115], 0
	v_mfma_f32_16x16x32_bf16 v[184:187], v[8:11], v[120:123], 0
	v_mfma_f32_16x16x32_bf16 v[188:191], v[12:15], v[120:123], 0
	v_mfma_f32_16x16x32_bf16 v[8:11], v[8:11], v[128:131], 0
	v_mfma_f32_16x16x32_bf16 v[12:15], v[12:15], v[128:131], 0
	v_mfma_f32_16x16x32_bf16 v[8:11], v[16:19], v[132:135], v[8:11]
	v_mfma_f32_16x16x32_bf16 v[12:15], v[20:23], v[132:135], v[12:15]
	v_mfma_f32_16x16x32_bf16 v[142:145], v[16:19], v[108:111], v[142:145]
	v_mfma_f32_16x16x32_bf16 v[146:149], v[20:23], v[108:111], v[146:149]
	v_mfma_f32_16x16x32_bf16 v[150:153], v[16:19], v[116:119], v[150:153]
	v_mfma_f32_16x16x32_bf16 v[180:183], v[20:23], v[116:119], v[180:183]
	v_mfma_f32_16x16x32_bf16 v[184:187], v[16:19], v[124:127], v[184:187]
	v_mfma_f32_16x16x32_bf16 v[188:191], v[20:23], v[124:127], v[188:191]
	s_barrier
; #define STAGE(P, BASE, br, kt) do { const char* _gb = (const char*)(BASE) + ((size_t)(br) * K + (size_t)(kt) * BK) * 2; \
;     __builtin_amdgcn_global_load_lds((const unsigned*)(_gb + loff0), (unsigned*)((char*)(P) + tid * 16), 16, 0, 0); \
;     __builtin_amdgcn_global_load_lds((const unsigned*)(_gb + (size_t)K * 128 + loff0), (unsigned*)((char*)(P) + tid * 16 + 8192), 16, 0, 0); } while (0)
; #define LDA(dst, b, h) for (int m = 0; m < 4; ++m) { \
;     dst[m][0] = *reinterpret_cast<const bf16x8*>((char*)SA(b, h) + aoff0 + m * 2048); \
;     dst[m][1] = *reinterpret_cast<const bf16x8*>((char*)SA(b, h) + aoff1 + m * 2048); }
; #define LDB(dst, b, h) for (int n = 0; n < 2; ++n) { \
;     dst[n][0] = *reinterpret_cast<const bf16x8*>((char*)SB(b, h) + boff0 + n * 256); \
;     dst[n][1] = *reinterpret_cast<const bf16x8*>((char*)SB(b, h) + boff1 + n * 256); }
; #define MMA(ai, bj, At, Btf) do { __builtin_amdgcn_s_setprio(1); \
;     for (int m = 0; m < 4; ++m) for (int n = 0; n < 2; ++n) for (int k = 0; k < 2; ++k) \
;       acc[ai][bj][m][n] = __builtin_amdgcn_mfma_f32_16x16x32_bf16(Btf[n][k], At[m][k], acc[ai][bj][m][n], 0, 0, 0); \
;     __builtin_amdgcn_s_setprio(0); } while (0)
; #define WAIT_V(n) asm volatile("s_waitcnt vmcnt(" #n ")" ::: "memory")
; #define WAIT_L(n) asm volatile("s_waitcnt lgkmcnt(" #n ")" ::: "memory")
; #define BAR __builtin_amdgcn_s_barrier()
; #define SCHED __builtin_amdgcn_sched_barrier(0)
; template <int EPI> ...
;     ...
;     STAGE(SB(0, 1), Bt, bcol + HALF, t + 2);
;     WAIT_V(6); BAR; MMA(1, 1, At, B1); BAR;
;     LDB(B0, 1, 0); SCHED; LDA(At, 1, 0); STAGE(SA(0, 1), A, brow + HALF, t + 2);
;     WAIT_L(8); BAR; WAIT_L(0); MMA(0, 0, At, B0); BAR; SCHED;
;     LDB(B1, 1, 1); STAGE(SB(1, 0), Bt, bcol, t + 3);
;     BAR; WAIT_L(0); MMA(0, 1, At, B1); BAR;
;     LDA(At, 1, 1); STAGE(SA(1, 0), A, brow, t + 3);
;     BAR; WAIT_L(0); MMA(1, 0, At, B0); BAR; SCHED;
	s_setprio 0
	v_readfirstlane_b32 s64, v160
	v_lshl_add_u64 v[16:17], v[2:3], 0, s[12:13]
	s_mov_b32 m0, s64
	v_readfirstlane_b32 s62, v161
	global_load_lds_dwordx4 v[16:17], off
	v_lshl_add_u64 v[16:17], v[2:3], 0, s[16:17]
	s_mov_b32 m0, s62
	s_nop 0
	global_load_lds_dwordx4 v[16:17], off
	s_waitcnt vmcnt(6)
	s_barrier
	s_setprio 1
	v_mfma_f32_16x16x32_bf16 v[16:19], v[88:91], v[52:55], 0
	v_mfma_f32_16x16x32_bf16 v[20:23], v[92:95], v[52:55], 0
	v_mfma_f32_16x16x32_bf16 v[16:19], v[96:99], v[108:111], v[16:19]
	v_mfma_f32_16x16x32_bf16 v[20:23], v[100:103], v[108:111], v[20:23]
	v_mfma_f32_16x16x32_bf16 v[52:55], v[88:91], v[112:115], 0
	v_mfma_f32_16x16x32_bf16 v[108:111], v[92:95], v[112:115], 0
	v_mfma_f32_16x16x32_bf16 v[52:55], v[96:99], v[116:119], v[52:55]
	v_mfma_f32_16x16x32_bf16 v[108:111], v[100:103], v[116:119], v[108:111]
	v_mfma_f32_16x16x32_bf16 v[112:115], v[88:91], v[120:123], 0
	v_mfma_f32_16x16x32_bf16 v[116:119], v[92:95], v[120:123], 0
	v_mfma_f32_16x16x32_bf16 v[88:91], v[88:91], v[128:131], 0
	v_mfma_f32_16x16x32_bf16 v[92:95], v[92:95], v[128:131], 0
	v_mfma_f32_16x16x32_bf16 v[112:115], v[96:99], v[124:127], v[112:115]
	v_mfma_f32_16x16x32_bf16 v[116:119], v[100:103], v[124:127], v[116:119]
	v_mfma_f32_16x16x32_bf16 v[88:91], v[96:99], v[132:135], v[88:91]
	v_mfma_f32_16x16x32_bf16 v[92:95], v[100:103], v[132:135], v[92:95]
	s_setprio 0
	s_barrier
	ds_read_b128 v[96:99], v172
	ds_read_b128 v[100:103], v172 offset:256
	ds_read_b128 v[120:123], v173
	ds_read_b128 v[124:127], v173 offset:256
	v_readfirstlane_b32 s68, v162
	v_lshl_add_u64 v[138:139], v[0:1], 0, s[12:13]
	s_mov_b32 m0, s68
	v_readfirstlane_b32 s63, v163
	ds_read_b128 v[128:131], v154 offset:32768
	ds_read_b128 v[132:135], v154 offset:33792
	ds_read_b128 v[192:195], v154 offset:34816
	ds_read_b128 v[196:199], v154 offset:35840
	ds_read_b128 v[200:203], v154 offset:36864
	ds_read_b128 v[204:207], v154 offset:37888
	ds_read_b128 v[208:211], v154 offset:38912
	ds_read_b128 v[212:215], v154 offset:39936
	global_load_lds_dwordx4 v[138:139], off
	v_lshl_add_u64 v[138:139], v[0:1], 0, s[16:17]
	s_mov_b32 m0, s63
	s_nop 0
	global_load_lds_dwordx4 v[138:139], off
	s_waitcnt lgkmcnt(8)
	s_waitcnt lgkmcnt(0)
	s_setprio 1
	s_barrier
	v_mfma_f32_16x16x32_bf16 v[56:59], v[96:99], v[128:131], v[56:59]
	v_mfma_f32_16x16x32_bf16 v[60:63], v[100:103], v[128:131], v[60:63]
	v_mfma_f32_16x16x32_bf16 v[64:67], v[96:99], v[192:195], v[64:67]
	v_mfma_f32_16x16x32_bf16 v[68:71], v[100:103], v[192:195], v[68:71]
	v_mfma_f32_16x16x32_bf16 v[72:75], v[96:99], v[200:203], v[72:75]
	v_mfma_f32_16x16x32_bf16 v[76:79], v[100:103], v[200:203], v[76:79]
	v_mfma_f32_16x16x32_bf16 v[80:83], v[96:99], v[208:211], v[80:83]
	v_mfma_f32_16x16x32_bf16 v[84:87], v[100:103], v[208:211], v[84:87]
	v_mfma_f32_16x16x32_bf16 v[56:59], v[120:123], v[132:135], v[56:59]
	v_mfma_f32_16x16x32_bf16 v[60:63], v[124:127], v[132:135], v[60:63]
	v_mfma_f32_16x16x32_bf16 v[64:67], v[120:123], v[196:199], v[64:67]
	v_mfma_f32_16x16x32_bf16 v[68:71], v[124:127], v[196:199], v[68:71]
	v_mfma_f32_16x16x32_bf16 v[72:75], v[120:123], v[204:207], v[72:75]
	v_mfma_f32_16x16x32_bf16 v[76:79], v[124:127], v[204:207], v[76:79]
	v_mfma_f32_16x16x32_bf16 v[80:83], v[120:123], v[212:215], v[80:83]
	v_mfma_f32_16x16x32_bf16 v[84:87], v[124:127], v[212:215], v[84:87]
	s_barrier
	s_setprio 0
	s_mov_b32 m0, s52
	v_lshl_add_u64 v[138:139], v[6:7], 0, s[18:19]
	ds_read_b128 v[216:219], v174
	ds_read_b128 v[220:223], v174 offset:256
	ds_read_b128 v[224:227], v175
	ds_read_b128 v[228:231], v175 offset:256
	global_load_lds_dwordx4 v[138:139], off
	v_lshl_add_u64 v[138:139], v[6:7], 0, s[20:21]
	s_mov_b32 m0, s49
	s_nop 0
	global_load_lds_dwordx4 v[138:139], off
	s_barrier
	s_waitcnt lgkmcnt(0)
	s_setprio 1
	s_waitcnt lgkmcnt(0)
	v_mfma_f32_16x16x32_bf16 v[104:107], v[216:219], v[128:131], v[104:107]
	v_mfma_f32_16x16x32_bf16 v[24:27], v[220:223], v[128:131], v[24:27]
	v_mfma_f32_16x16x32_bf16 v[28:31], v[216:219], v[192:195], v[28:31]
	v_mfma_f32_16x16x32_bf16 v[32:35], v[220:223], v[192:195], v[32:35]
	v_mfma_f32_16x16x32_bf16 v[36:39], v[216:219], v[200:203], v[36:39]
	v_mfma_f32_16x16x32_bf16 v[40:43], v[220:223], v[200:203], v[40:43]
	v_mfma_f32_16x16x32_bf16 v[44:47], v[216:219], v[208:211], v[44:47]
	v_mfma_f32_16x16x32_bf16 v[48:51], v[220:223], v[208:211], v[48:51]
	v_mfma_f32_16x16x32_bf16 v[104:107], v[224:227], v[132:135], v[104:107]
	v_mfma_f32_16x16x32_bf16 v[24:27], v[228:231], v[132:135], v[24:27]
	v_mfma_f32_16x16x32_bf16 v[28:31], v[224:227], v[196:199], v[28:31]
	v_mfma_f32_16x16x32_bf16 v[32:35], v[228:231], v[196:199], v[32:35]
	v_mfma_f32_16x16x32_bf16 v[36:39], v[224:227], v[204:207], v[36:39]
	v_mfma_f32_16x16x32_bf16 v[40:43], v[228:231], v[204:207], v[40:43]
	v_mfma_f32_16x16x32_bf16 v[44:47], v[224:227], v[212:215], v[44:47]
	v_mfma_f32_16x16x32_bf16 v[48:51], v[228:231], v[212:215], v[48:51]
	s_setprio 0
	s_mov_b32 m0, s72
	v_lshl_add_u64 v[138:139], v[4:5], 0, s[18:19]
	s_barrier
	ds_read_b128 v[128:131], v154 offset:49152
	ds_read_b128 v[132:135], v154 offset:50176
	ds_read_b128 v[192:195], v154 offset:51200
	ds_read_b128 v[196:199], v154 offset:52224
	ds_read_b128 v[200:203], v154 offset:53248
	ds_read_b128 v[204:207], v154 offset:54272
	ds_read_b128 v[208:211], v154 offset:55296
	ds_read_b128 v[212:215], v154 offset:56320
	global_load_lds_dwordx4 v[138:139], off
	v_lshl_add_u64 v[138:139], v[4:5], 0, s[20:21]
	s_mov_b32 m0, s71
	s_nop 0
	global_load_lds_dwordx4 v[138:139], off
	s_waitcnt lgkmcnt(0)
	s_setprio 1
	s_barrier
; #define STAGE(P, BASE, br, kt) do { const char* _gb = (const char*)(BASE) + ((size_t)(br) * K + (size_t)(kt) * BK) * 2; \
;     __builtin_amdgcn_global_load_lds((const unsigned*)(_gb + loff0), (unsigned*)((char*)(P) + tid * 16), 16, 0, 0); \
;     __builtin_amdgcn_global_load_lds((const unsigned*)(_gb + (size_t)K * 128 + loff0), (unsigned*)((char*)(P) + tid * 16 + 8192), 16, 0, 0); } while (0)
; #define LDA(dst, b, h) for (int m = 0; m < 4; ++m) { \
;     dst[m][0] = *reinterpret_cast<const bf16x8*>((char*)SA(b, h) + aoff0 + m * 2048); \
;     dst[m][1] = *reinterpret_cast<const bf16x8*>((char*)SA(b, h) + aoff1 + m * 2048); }
; #define LDB(dst, b, h) for (int n = 0; n < 2; ++n) { \
;     dst[n][0] = *reinterpret_cast<const bf16x8*>((char*)SB(b, h) + boff0 + n * 256); \
;     dst[n][1] = *reinterpret_cast<const bf16x8*>((char*)SB(b, h) + boff1 + n * 256); }
; #define MMA(ai, bj, At, Btf) do { __builtin_amdgcn_s_setprio(1); \
;     for (int m = 0; m < 4; ++m) for (int n = 0; n < 2; ++n) for (int k = 0; k < 2; ++k) \
;       acc[ai][bj][m][n] = __builtin_amdgcn_mfma_f32_16x16x32_bf16(Btf[n][k], At[m][k], acc[ai][bj][m][n], 0, 0, 0); \
;     __builtin_amdgcn_s_setprio(0); } while (0)
; #define WAIT_V(n) asm volatile("s_waitcnt vmcnt(" #n ")" ::: "memory")
; #define WAIT_L(n) asm volatile("s_waitcnt lgkmcnt(" #n ")" ::: "memory")
; #define BAR __builtin_amdgcn_s_barrier()
; #define SCHED __builtin_amdgcn_sched_barrier(0)
; template <int EPI> ...
;     ...
;     LDB(B0, 0, 0); SCHED; LDA(At, 0, 0); STAGE(SA(1, 1), A, brow + HALF, t + 1);
;     WAIT_L(8); BAR; WAIT_L(0); MMA(0, 0, At, B0); BAR; SCHED;
;     LDB(B1, 0, 1); STAGE(SB(0, 0), Bt, bcol, t + 2);
;     BAR; WAIT_L(0); MMA(0, 1, At, B1); BAR;
;     LDA(At, 0, 1); STAGE(SA(0, 0), A, brow, t + 2);
;     ...
;     BAR; WAIT_L(0); MMA(1, 0, At, B0); BAR; SCHED;
;     STAGE(SB(1, 1), Bt, bcol + HALF, t + 3);
;     WAIT_V(6); BAR; MMA(1, 1, At, B1); BAR;
	v_mfma_f32_16x16x32_bf16 v[8:11], v[96:99], v[208:211], v[8:11]
	v_mfma_f32_16x16x32_bf16 v[12:15], v[100:103], v[208:211], v[12:15]
	v_mfma_f32_16x16x32_bf16 v[142:145], v[96:99], v[128:131], v[142:145]
	v_mfma_f32_16x16x32_bf16 v[146:149], v[100:103], v[128:131], v[146:149]
	v_mfma_f32_16x16x32_bf16 v[150:153], v[96:99], v[192:195], v[150:153]
	v_mfma_f32_16x16x32_bf16 v[180:183], v[100:103], v[192:195], v[180:183]
	v_mfma_f32_16x16x32_bf16 v[184:187], v[96:99], v[200:203], v[184:187]
	v_mfma_f32_16x16x32_bf16 v[188:191], v[100:103], v[200:203], v[188:191]
	v_mfma_f32_16x16x32_bf16 v[8:11], v[120:123], v[212:215], v[8:11]
	v_mfma_f32_16x16x32_bf16 v[12:15], v[124:127], v[212:215], v[12:15]
	v_mfma_f32_16x16x32_bf16 v[142:145], v[120:123], v[132:135], v[142:145]
	v_mfma_f32_16x16x32_bf16 v[146:149], v[124:127], v[132:135], v[146:149]
	v_mfma_f32_16x16x32_bf16 v[150:153], v[120:123], v[196:199], v[150:153]
	v_mfma_f32_16x16x32_bf16 v[180:183], v[124:127], v[196:199], v[180:183]
	v_mfma_f32_16x16x32_bf16 v[184:187], v[120:123], v[204:207], v[184:187]
	v_mfma_f32_16x16x32_bf16 v[188:191], v[124:127], v[204:207], v[188:191]
	s_barrier
	s_setprio 0
	s_mov_b32 m0, s70
	v_lshl_add_u64 v[96:97], v[2:3], 0, s[18:19]
	global_load_lds_dwordx4 v[96:97], off
	v_lshl_add_u64 v[96:97], v[2:3], 0, s[20:21]
	s_mov_b32 m0, s69
	s_nop 0
	global_load_lds_dwordx4 v[96:97], off
	s_waitcnt vmcnt(6)
	s_barrier
	s_setprio 1
	v_mfma_f32_16x16x32_bf16 v[16:19], v[216:219], v[128:131], v[16:19]
	v_mfma_f32_16x16x32_bf16 v[20:23], v[220:223], v[128:131], v[20:23]
	v_mfma_f32_16x16x32_bf16 v[52:55], v[216:219], v[192:195], v[52:55]
	v_mfma_f32_16x16x32_bf16 v[96:99], v[220:223], v[192:195], v[108:111]
	v_mfma_f32_16x16x32_bf16 v[108:111], v[220:223], v[200:203], v[116:119]
	v_mfma_f32_16x16x32_bf16 v[88:91], v[216:219], v[208:211], v[88:91]
	v_mfma_f32_16x16x32_bf16 v[92:95], v[220:223], v[208:211], v[92:95]
	v_mfma_f32_16x16x32_bf16 v[16:19], v[224:227], v[132:135], v[16:19]
	v_mfma_f32_16x16x32_bf16 v[20:23], v[228:231], v[132:135], v[20:23]
	v_mfma_f32_16x16x32_bf16 v[52:55], v[224:227], v[196:199], v[52:55]
	v_mfma_f32_16x16x32_bf16 v[100:103], v[216:219], v[200:203], v[112:115]
	v_mfma_f32_16x16x32_bf16 v[108:111], v[228:231], v[204:207], v[108:111]
	v_mfma_f32_16x16x32_bf16 v[88:91], v[224:227], v[212:215], v[88:91]
	v_mfma_f32_16x16x32_bf16 v[92:95], v[228:231], v[212:215], v[92:95]
	v_mfma_f32_16x16x32_bf16 v[96:99], v[228:231], v[196:199], v[96:99]
	v_mfma_f32_16x16x32_bf16 v[100:103], v[224:227], v[204:207], v[100:103]
	s_setprio 0
	s_barrier
	ds_read_b128 v[112:115], v176
	ds_read_b128 v[116:119], v176 offset:256
	ds_read_b128 v[120:123], v177
	ds_read_b128 v[124:127], v177 offset:256
	s_mov_b32 m0, s66
	v_lshl_add_u64 v[138:139], v[0:1], 0, s[18:19]
	ds_read_b128 v[128:131], v154
	ds_read_b128 v[132:135], v154 offset:1024
	ds_read_b128 v[192:195], v154 offset:2048
	ds_read_b128 v[196:199], v154 offset:3072
	ds_read_b128 v[200:203], v154 offset:4096
	ds_read_b128 v[204:207], v154 offset:5120
	ds_read_b128 v[208:211], v154 offset:6144
	ds_read_b128 v[212:215], v154 offset:7168
	global_load_lds_dwordx4 v[138:139], off
	v_lshl_add_u64 v[138:139], v[0:1], 0, s[20:21]
	s_mov_b32 m0, s53
	s_nop 0
	global_load_lds_dwordx4 v[138:139], off
	s_waitcnt lgkmcnt(8)
	s_waitcnt lgkmcnt(0)
	s_setprio 1
	s_barrier
	v_mfma_f32_16x16x32_bf16 v[56:59], v[112:115], v[128:131], v[56:59]
	v_mfma_f32_16x16x32_bf16 v[60:63], v[116:119], v[128:131], v[60:63]
	v_mfma_f32_16x16x32_bf16 v[64:67], v[112:115], v[192:195], v[64:67]
	v_mfma_f32_16x16x32_bf16 v[68:71], v[116:119], v[192:195], v[68:71]
	v_mfma_f32_16x16x32_bf16 v[72:75], v[112:115], v[200:203], v[72:75]
	v_mfma_f32_16x16x32_bf16 v[76:79], v[116:119], v[200:203], v[76:79]
	v_mfma_f32_16x16x32_bf16 v[80:83], v[112:115], v[208:211], v[80:83]
	v_mfma_f32_16x16x32_bf16 v[84:87], v[116:119], v[208:211], v[84:87]
	v_mfma_f32_16x16x32_bf16 v[56:59], v[120:123], v[132:135], v[56:59]
	v_mfma_f32_16x16x32_bf16 v[60:63], v[124:127], v[132:135], v[60:63]
	v_mfma_f32_16x16x32_bf16 v[64:67], v[120:123], v[196:199], v[64:67]
	v_mfma_f32_16x16x32_bf16 v[68:71], v[124:127], v[196:199], v[68:71]
	v_mfma_f32_16x16x32_bf16 v[72:75], v[120:123], v[204:207], v[72:75]
	v_mfma_f32_16x16x32_bf16 v[76:79], v[124:127], v[204:207], v[76:79]
	v_mfma_f32_16x16x32_bf16 v[80:83], v[120:123], v[212:215], v[80:83]
	v_mfma_f32_16x16x32_bf16 v[84:87], v[124:127], v[212:215], v[84:87]
	s_barrier
	s_setprio 0
	s_mov_b32 m0, s65
	v_lshl_add_u64 v[138:139], v[6:7], 0, s[22:23]
	ds_read_b128 v[216:219], v178
	ds_read_b128 v[220:223], v178 offset:256
	ds_read_b128 v[224:227], v179
	ds_read_b128 v[228:231], v179 offset:256
	global_load_lds_dwordx4 v[138:139], off
	v_lshl_add_u64 v[138:139], v[6:7], 0, s[24:25]
	s_mov_b32 m0, s60
	s_nop 0
	global_load_lds_dwordx4 v[138:139], off
	s_barrier
	s_waitcnt lgkmcnt(0)
	s_setprio 1
	s_waitcnt lgkmcnt(0)
	v_mfma_f32_16x16x32_bf16 v[104:107], v[216:219], v[128:131], v[104:107]
	v_mfma_f32_16x16x32_bf16 v[24:27], v[220:223], v[128:131], v[24:27]
	v_mfma_f32_16x16x32_bf16 v[28:31], v[216:219], v[192:195], v[28:31]
	v_mfma_f32_16x16x32_bf16 v[32:35], v[220:223], v[192:195], v[32:35]
	v_mfma_f32_16x16x32_bf16 v[36:39], v[216:219], v[200:203], v[36:39]
	v_mfma_f32_16x16x32_bf16 v[40:43], v[220:223], v[200:203], v[40:43]
	v_mfma_f32_16x16x32_bf16 v[44:47], v[216:219], v[208:211], v[44:47]
	v_mfma_f32_16x16x32_bf16 v[48:51], v[220:223], v[208:211], v[48:51]
	v_mfma_f32_16x16x32_bf16 v[104:107], v[224:227], v[132:135], v[104:107]
	v_mfma_f32_16x16x32_bf16 v[24:27], v[228:231], v[132:135], v[24:27]
	v_mfma_f32_16x16x32_bf16 v[28:31], v[224:227], v[196:199], v[28:31]
	v_mfma_f32_16x16x32_bf16 v[32:35], v[228:231], v[196:199], v[32:35]
	v_mfma_f32_16x16x32_bf16 v[36:39], v[224:227], v[204:207], v[36:39]
	v_mfma_f32_16x16x32_bf16 v[40:43], v[228:231], v[204:207], v[40:43]
	v_mfma_f32_16x16x32_bf16 v[44:47], v[224:227], v[212:215], v[44:47]
	v_mfma_f32_16x16x32_bf16 v[48:51], v[228:231], v[212:215], v[48:51]
	s_setprio 0
	s_mov_b32 m0, s67
	v_lshl_add_u64 v[138:139], v[4:5], 0, s[22:23]
	s_barrier
; #define STAGE(P, BASE, br, kt) do { const char* _gb = (const char*)(BASE) + ((size_t)(br) * K + (size_t)(kt) * BK) * 2; \
;     __builtin_amdgcn_global_load_lds((const unsigned*)(_gb + loff0), (unsigned*)((char*)(P) + tid * 16), 16, 0, 0); \
;     __builtin_amdgcn_global_load_lds((const unsigned*)(_gb + (size_t)K * 128 + loff0), (unsigned*)((char*)(P) + tid * 16 + 8192), 16, 0, 0); } while (0)
; #define LDA(dst, b, h) for (int m = 0; m < 4; ++m) { \
;     dst[m][0] = *reinterpret_cast<const bf16x8*>((char*)SA(b, h) + aoff0 + m * 2048); \
;     dst[m][1] = *reinterpret_cast<const bf16x8*>((char*)SA(b, h) + aoff1 + m * 2048); }
; #define LDB(dst, b, h) for (int n = 0; n < 2; ++n) { \
;     dst[n][0] = *reinterpret_cast<const bf16x8*>((char*)SB(b, h) + boff0 + n * 256); \
;     dst[n][1] = *reinterpret_cast<const bf16x8*>((char*)SB(b, h) + boff1 + n * 256); }
; #define MMA(ai, bj, At, Btf) do { __builtin_amdgcn_s_setprio(1); \
;     for (int m = 0; m < 4; ++m) for (int n = 0; n < 2; ++n) for (int k = 0; k < 2; ++k) \
;       acc[ai][bj][m][n] = __builtin_amdgcn_mfma_f32_16x16x32_bf16(Btf[n][k], At[m][k], acc[ai][bj][m][n], 0, 0, 0); \
;     __builtin_amdgcn_s_setprio(0); } while (0)
; #define WAIT_V(n) asm volatile("s_waitcnt vmcnt(" #n ")" ::: "memory")
; #define WAIT_L(n) asm volatile("s_waitcnt lgkmcnt(" #n ")" ::: "memory")
; #define BAR __builtin_amdgcn_s_barrier()
; #define SCHED __builtin_amdgcn_sched_barrier(0)
; template <int EPI> ...
;     ...
;     LDA(At, 0, 1); STAGE(SA(0, 0), A, brow, t + 2);
;     BAR; WAIT_L(0); MMA(1, 0, At, B0); BAR; SCHED;
;     STAGE(SB(0, 1), Bt, bcol + HALF, t + 2);
;     WAIT_V(6); BAR; MMA(1, 1, At, B1); BAR;
;     LDB(B0, 1, 0); SCHED; LDA(At, 1, 0); STAGE(SA(0, 1), A, brow + HALF, t + 2);
;     WAIT_L(8); BAR; WAIT_L(0); MMA(0, 0, At, B0); BAR; SCHED;
;     LDB(B1, 1, 1); STAGE(SB(1, 0), Bt, bcol, t + 3);
	ds_read_b128 v[128:131], v154 offset:16384
	ds_read_b128 v[132:135], v154 offset:17408
	ds_read_b128 v[192:195], v154 offset:18432
	ds_read_b128 v[196:199], v154 offset:19456
	ds_read_b128 v[200:203], v154 offset:20480
	ds_read_b128 v[204:207], v154 offset:21504
	ds_read_b128 v[208:211], v154 offset:22528
	ds_read_b128 v[212:215], v154 offset:23552
	global_load_lds_dwordx4 v[138:139], off
	v_lshl_add_u64 v[138:139], v[4:5], 0, s[24:25]
	s_mov_b32 m0, s61
	s_nop 0
	global_load_lds_dwordx4 v[138:139], off
	s_waitcnt lgkmcnt(0)
	s_setprio 1
	s_barrier
	v_mfma_f32_16x16x32_bf16 v[8:11], v[112:115], v[208:211], v[8:11]
	v_mfma_f32_16x16x32_bf16 v[12:15], v[116:119], v[208:211], v[12:15]
	v_mfma_f32_16x16x32_bf16 v[142:145], v[112:115], v[128:131], v[142:145]
	v_mfma_f32_16x16x32_bf16 v[146:149], v[116:119], v[128:131], v[146:149]
	v_mfma_f32_16x16x32_bf16 v[150:153], v[112:115], v[192:195], v[150:153]
	v_mfma_f32_16x16x32_bf16 v[180:183], v[116:119], v[192:195], v[180:183]
	v_mfma_f32_16x16x32_bf16 v[184:187], v[112:115], v[200:203], v[184:187]
	v_mfma_f32_16x16x32_bf16 v[188:191], v[116:119], v[200:203], v[188:191]
	v_mfma_f32_16x16x32_bf16 v[8:11], v[120:123], v[212:215], v[8:11]
	v_mfma_f32_16x16x32_bf16 v[12:15], v[124:127], v[212:215], v[12:15]
	v_mfma_f32_16x16x32_bf16 v[142:145], v[120:123], v[132:135], v[142:145]
	v_mfma_f32_16x16x32_bf16 v[146:149], v[124:127], v[132:135], v[146:149]
	v_mfma_f32_16x16x32_bf16 v[150:153], v[120:123], v[196:199], v[150:153]
	v_mfma_f32_16x16x32_bf16 v[180:183], v[124:127], v[196:199], v[180:183]
	v_mfma_f32_16x16x32_bf16 v[184:187], v[120:123], v[204:207], v[184:187]
	v_mfma_f32_16x16x32_bf16 v[188:191], v[124:127], v[204:207], v[188:191]
	s_barrier
	s_setprio 0
	s_mov_b32 m0, s64
	v_lshl_add_u64 v[112:113], v[2:3], 0, s[22:23]
	global_load_lds_dwordx4 v[112:113], off
	v_lshl_add_u64 v[112:113], v[2:3], 0, s[24:25]
	s_mov_b32 m0, s62
	s_nop 0
	global_load_lds_dwordx4 v[112:113], off
	s_waitcnt vmcnt(6)
	s_barrier
	s_setprio 1
	v_mfma_f32_16x16x32_bf16 v[16:19], v[216:219], v[128:131], v[16:19]
	v_mfma_f32_16x16x32_bf16 v[20:23], v[220:223], v[128:131], v[20:23]
	v_mfma_f32_16x16x32_bf16 v[52:55], v[216:219], v[192:195], v[52:55]
	v_mfma_f32_16x16x32_bf16 v[108:111], v[220:223], v[200:203], v[108:111]
	v_mfma_f32_16x16x32_bf16 v[88:91], v[216:219], v[208:211], v[88:91]
	v_mfma_f32_16x16x32_bf16 v[92:95], v[220:223], v[208:211], v[92:95]
	v_mfma_f32_16x16x32_bf16 v[16:19], v[224:227], v[132:135], v[16:19]
	v_mfma_f32_16x16x32_bf16 v[20:23], v[228:231], v[132:135], v[20:23]
	v_mfma_f32_16x16x32_bf16 v[52:55], v[224:227], v[196:199], v[52:55]
	v_mfma_f32_16x16x32_bf16 v[96:99], v[220:223], v[192:195], v[96:99]
	v_mfma_f32_16x16x32_bf16 v[100:103], v[216:219], v[200:203], v[100:103]
	v_mfma_f32_16x16x32_bf16 v[108:111], v[228:231], v[204:207], v[108:111]
	v_mfma_f32_16x16x32_bf16 v[88:91], v[224:227], v[212:215], v[88:91]
	v_mfma_f32_16x16x32_bf16 v[92:95], v[228:231], v[212:215], v[92:95]
	v_mfma_f32_16x16x32_bf16 v[96:99], v[228:231], v[196:199], v[96:99]
	v_mfma_f32_16x16x32_bf16 v[100:103], v[224:227], v[204:207], v[100:103]
	s_setprio 0
	s_barrier
	ds_read_b128 v[112:115], v172
	ds_read_b128 v[116:119], v172 offset:256
	ds_read_b128 v[120:123], v173
	ds_read_b128 v[124:127], v173 offset:256
	s_mov_b32 m0, s68
	v_lshl_add_u64 v[138:139], v[0:1], 0, s[22:23]
	ds_read_b128 v[128:131], v154 offset:32768
	ds_read_b128 v[132:135], v154 offset:33792
	ds_read_b128 v[192:195], v154 offset:34816
	ds_read_b128 v[196:199], v154 offset:35840
	ds_read_b128 v[200:203], v154 offset:36864
	ds_read_b128 v[204:207], v154 offset:37888
	ds_read_b128 v[208:211], v154 offset:38912
	ds_read_b128 v[212:215], v154 offset:39936
	global_load_lds_dwordx4 v[138:139], off
	v_lshl_add_u64 v[138:139], v[0:1], 0, s[24:25]
	s_mov_b32 m0, s63
	s_nop 0
	global_load_lds_dwordx4 v[138:139], off
	s_waitcnt lgkmcnt(8)
	s_waitcnt lgkmcnt(0)
	s_setprio 1
	s_barrier
	v_mfma_f32_16x16x32_bf16 v[56:59], v[112:115], v[128:131], v[56:59]
	v_mfma_f32_16x16x32_bf16 v[60:63], v[116:119], v[128:131], v[60:63]
	v_mfma_f32_16x16x32_bf16 v[64:67], v[112:115], v[192:195], v[64:67]
	v_mfma_f32_16x16x32_bf16 v[68:71], v[116:119], v[192:195], v[68:71]
	v_mfma_f32_16x16x32_bf16 v[72:75], v[112:115], v[200:203], v[72:75]
	v_mfma_f32_16x16x32_bf16 v[76:79], v[116:119], v[200:203], v[76:79]
	v_mfma_f32_16x16x32_bf16 v[80:83], v[112:115], v[208:211], v[80:83]
	v_mfma_f32_16x16x32_bf16 v[84:87], v[116:119], v[208:211], v[84:87]
	v_mfma_f32_16x16x32_bf16 v[56:59], v[120:123], v[132:135], v[56:59]
	v_mfma_f32_16x16x32_bf16 v[60:63], v[124:127], v[132:135], v[60:63]
	v_mfma_f32_16x16x32_bf16 v[64:67], v[120:123], v[196:199], v[64:67]
	v_mfma_f32_16x16x32_bf16 v[68:71], v[124:127], v[196:199], v[68:71]
	v_mfma_f32_16x16x32_bf16 v[72:75], v[120:123], v[204:207], v[72:75]
	v_mfma_f32_16x16x32_bf16 v[76:79], v[124:127], v[204:207], v[76:79]
	v_mfma_f32_16x16x32_bf16 v[80:83], v[120:123], v[212:215], v[80:83]
	v_mfma_f32_16x16x32_bf16 v[84:87], v[124:127], v[212:215], v[84:87]
	s_barrier
	s_setprio 0
	s_mov_b32 m0, s52
	v_lshl_add_u64 v[138:139], v[6:7], 0, s[26:27]
	ds_read_b128 v[216:219], v174
	ds_read_b128 v[220:223], v174 offset:256
	ds_read_b128 v[224:227], v175
	ds_read_b128 v[228:231], v175 offset:256
	global_load_lds_dwordx4 v[138:139], off
	v_lshl_add_u64 v[138:139], v[6:7], 0, s[28:29]
	s_mov_b32 m0, s49
	s_nop 0
	global_load_lds_dwordx4 v[138:139], off
	s_barrier
; #define STAGE(P, BASE, br, kt) do { const char* _gb = (const char*)(BASE) + ((size_t)(br) * K + (size_t)(kt) * BK) * 2; \
;     __builtin_amdgcn_global_load_lds((const unsigned*)(_gb + loff0), (unsigned*)((char*)(P) + tid * 16), 16, 0, 0); \
;     __builtin_amdgcn_global_load_lds((const unsigned*)(_gb + (size_t)K * 128 + loff0), (unsigned*)((char*)(P) + tid * 16 + 8192), 16, 0, 0); } while (0)
; #define LDA(dst, b, h) for (int m = 0; m < 4; ++m) { \
;     dst[m][0] = *reinterpret_cast<const bf16x8*>((char*)SA(b, h) + aoff0 + m * 2048); \
;     dst[m][1] = *reinterpret_cast<const bf16x8*>((char*)SA(b, h) + aoff1 + m * 2048); }
; #define LDB(dst, b, h) for (int n = 0; n < 2; ++n) { \
;     dst[n][0] = *reinterpret_cast<const bf16x8*>((char*)SB(b, h) + boff0 + n * 256); \
;     dst[n][1] = *reinterpret_cast<const bf16x8*>((char*)SB(b, h) + boff1 + n * 256); }
; #define MMA(ai, bj, At, Btf) do { __builtin_amdgcn_s_setprio(1); \
;     for (int m = 0; m < 4; ++m) for (int n = 0; n < 2; ++n) for (int k = 0; k < 2; ++k) \
;       acc[ai][bj][m][n] = __builtin_amdgcn_mfma_f32_16x16x32_bf16(Btf[n][k], At[m][k], acc[ai][bj][m][n], 0, 0, 0); \
;     __builtin_amdgcn_s_setprio(0); } while (0)
; #define WAIT_V(n) asm volatile("s_waitcnt vmcnt(" #n ")" ::: "memory")
; #define WAIT_L(n) asm volatile("s_waitcnt lgkmcnt(" #n ")" ::: "memory")
; #define BAR __builtin_amdgcn_s_barrier()
; #define SCHED __builtin_amdgcn_sched_barrier(0)
; template <int EPI> ...
;     ...
;     LDB(B0, 0, 0); SCHED; LDA(At, 0, 0); STAGE(SA(1, 1), A, brow + HALF, t + 1);
;     WAIT_L(8); BAR; WAIT_L(0); MMA(0, 0, At, B0); BAR; SCHED;
;     LDB(B1, 0, 1); STAGE(SB(0, 0), Bt, bcol, t + 2);
;     BAR; WAIT_L(0); MMA(0, 1, At, B1); BAR;
;     LDA(At, 0, 1); STAGE(SA(0, 0), A, brow, t + 2);
;     BAR; WAIT_L(0); MMA(1, 0, At, B0); BAR; SCHED;
;     STAGE(SB(0, 1), Bt, bcol + HALF, t + 2);
;     WAIT_V(6); BAR; MMA(1, 1, At, B1); BAR;
;     LDB(B0, 1, 0); SCHED; LDA(At, 1, 0); STAGE(SA(0, 1), A, brow + HALF, t + 2);
;     WAIT_L(8); BAR; WAIT_L(0); MMA(0, 0, At, B0); BAR; SCHED;
;     LDB(B1, 1, 1); STAGE(SB(1, 0), Bt, bcol, t + 3);
;     BAR; WAIT_L(0); MMA(0, 1, At, B1); BAR;
;     LDA(At, 1, 1); STAGE(SA(1, 0), A, brow, t + 3);
;     BAR; WAIT_L(0); MMA(1, 0, At, B0); BAR; SCHED;
;     STAGE(SB(1, 1), Bt, bcol + HALF, t + 3);
;     WAIT_V(6); BAR; MMA(1, 1, At, B1); BAR;
	s_waitcnt lgkmcnt(0)
	s_setprio 1
	s_waitcnt lgkmcnt(0)
	v_mfma_f32_16x16x32_bf16 v[104:107], v[216:219], v[128:131], v[104:107]
	v_mfma_f32_16x16x32_bf16 v[24:27], v[220:223], v[128:131], v[24:27]
	v_mfma_f32_16x16x32_bf16 v[28:31], v[216:219], v[192:195], v[28:31]
	v_mfma_f32_16x16x32_bf16 v[32:35], v[220:223], v[192:195], v[32:35]
	v_mfma_f32_16x16x32_bf16 v[36:39], v[216:219], v[200:203], v[36:39]
	v_mfma_f32_16x16x32_bf16 v[40:43], v[220:223], v[200:203], v[40:43]
	v_mfma_f32_16x16x32_bf16 v[44:47], v[216:219], v[208:211], v[44:47]
	v_mfma_f32_16x16x32_bf16 v[48:51], v[220:223], v[208:211], v[48:51]
	v_mfma_f32_16x16x32_bf16 v[104:107], v[224:227], v[132:135], v[104:107]
	v_mfma_f32_16x16x32_bf16 v[24:27], v[228:231], v[132:135], v[24:27]
	v_mfma_f32_16x16x32_bf16 v[28:31], v[224:227], v[196:199], v[28:31]
	v_mfma_f32_16x16x32_bf16 v[32:35], v[228:231], v[196:199], v[32:35]
	v_mfma_f32_16x16x32_bf16 v[36:39], v[224:227], v[204:207], v[36:39]
	v_mfma_f32_16x16x32_bf16 v[40:43], v[228:231], v[204:207], v[40:43]
	v_mfma_f32_16x16x32_bf16 v[44:47], v[224:227], v[212:215], v[44:47]
	v_mfma_f32_16x16x32_bf16 v[48:51], v[228:231], v[212:215], v[48:51]
	s_setprio 0
	v_readfirstlane_b32 s63, v254
	v_lshl_add_u64 v[138:139], v[4:5], 0, s[26:27]
	s_mov_b32 m0, s63
	v_readfirstlane_b32 s53, v165
	s_barrier
	ds_read_b128 v[128:131], v154 offset:49152
	ds_read_b128 v[132:135], v154 offset:50176
	ds_read_b128 v[192:195], v154 offset:51200
	ds_read_b128 v[196:199], v154 offset:52224
	ds_read_b128 v[200:203], v154 offset:53248
	ds_read_b128 v[204:207], v154 offset:54272
	ds_read_b128 v[208:211], v154 offset:55296
	ds_read_b128 v[212:215], v154 offset:56320
	global_load_lds_dwordx4 v[138:139], off
	v_lshl_add_u64 v[138:139], v[4:5], 0, s[28:29]
	s_mov_b32 m0, s53
	s_nop 0
	global_load_lds_dwordx4 v[138:139], off
	s_waitcnt lgkmcnt(0)
	s_setprio 1
	s_barrier
	v_mfma_f32_16x16x32_bf16 v[8:11], v[112:115], v[208:211], v[8:11]
	v_mfma_f32_16x16x32_bf16 v[12:15], v[116:119], v[208:211], v[12:15]
	v_mfma_f32_16x16x32_bf16 v[142:145], v[112:115], v[128:131], v[142:145]
	v_mfma_f32_16x16x32_bf16 v[146:149], v[116:119], v[128:131], v[146:149]
	v_mfma_f32_16x16x32_bf16 v[150:153], v[112:115], v[192:195], v[150:153]
	v_mfma_f32_16x16x32_bf16 v[180:183], v[116:119], v[192:195], v[180:183]
	v_mfma_f32_16x16x32_bf16 v[184:187], v[112:115], v[200:203], v[184:187]
	v_mfma_f32_16x16x32_bf16 v[188:191], v[116:119], v[200:203], v[188:191]
	v_mfma_f32_16x16x32_bf16 v[8:11], v[120:123], v[212:215], v[8:11]
	v_mfma_f32_16x16x32_bf16 v[12:15], v[124:127], v[212:215], v[12:15]
	v_mfma_f32_16x16x32_bf16 v[142:145], v[120:123], v[132:135], v[142:145]
	v_mfma_f32_16x16x32_bf16 v[146:149], v[124:127], v[132:135], v[146:149]
	v_mfma_f32_16x16x32_bf16 v[150:153], v[120:123], v[196:199], v[150:153]
	v_mfma_f32_16x16x32_bf16 v[180:183], v[124:127], v[196:199], v[180:183]
	v_mfma_f32_16x16x32_bf16 v[184:187], v[120:123], v[204:207], v[184:187]
	v_mfma_f32_16x16x32_bf16 v[188:191], v[124:127], v[204:207], v[188:191]
	s_barrier
	s_setprio 0
	v_readfirstlane_b32 s61, v168
	v_lshl_add_u64 v[112:113], v[2:3], 0, s[26:27]
	s_mov_b32 m0, s61
	v_readfirstlane_b32 s60, v169
	global_load_lds_dwordx4 v[112:113], off
	v_lshl_add_u64 v[112:113], v[2:3], 0, s[28:29]
	s_mov_b32 m0, s60
	s_nop 0
	global_load_lds_dwordx4 v[112:113], off
	s_waitcnt vmcnt(6)
	s_barrier
	s_setprio 1
	v_mfma_f32_16x16x32_bf16 v[16:19], v[216:219], v[128:131], v[16:19]
	v_mfma_f32_16x16x32_bf16 v[20:23], v[220:223], v[128:131], v[20:23]
	v_mfma_f32_16x16x32_bf16 v[52:55], v[216:219], v[192:195], v[52:55]
	v_mfma_f32_16x16x32_bf16 v[108:111], v[220:223], v[200:203], v[108:111]
	v_mfma_f32_16x16x32_bf16 v[88:91], v[216:219], v[208:211], v[88:91]
	v_mfma_f32_16x16x32_bf16 v[92:95], v[220:223], v[208:211], v[92:95]
	v_mfma_f32_16x16x32_bf16 v[16:19], v[224:227], v[132:135], v[16:19]
	v_mfma_f32_16x16x32_bf16 v[20:23], v[228:231], v[132:135], v[20:23]
	v_mfma_f32_16x16x32_bf16 v[52:55], v[224:227], v[196:199], v[52:55]
	v_mfma_f32_16x16x32_bf16 v[96:99], v[220:223], v[192:195], v[96:99]
	v_mfma_f32_16x16x32_bf16 v[100:103], v[216:219], v[200:203], v[100:103]
	v_mfma_f32_16x16x32_bf16 v[108:111], v[228:231], v[204:207], v[108:111]
	v_mfma_f32_16x16x32_bf16 v[88:91], v[224:227], v[212:215], v[88:91]
	v_mfma_f32_16x16x32_bf16 v[92:95], v[228:231], v[212:215], v[92:95]
	v_mfma_f32_16x16x32_bf16 v[96:99], v[228:231], v[196:199], v[96:99]
	v_mfma_f32_16x16x32_bf16 v[100:103], v[224:227], v[204:207], v[100:103]
	s_setprio 0
	s_barrier
	ds_read_b128 v[112:115], v176
	ds_read_b128 v[116:119], v176 offset:256
	ds_read_b128 v[120:123], v177
	ds_read_b128 v[124:127], v177 offset:256
	v_readfirstlane_b32 s64, v170
	v_lshl_add_u64 v[138:139], v[0:1], 0, s[26:27]
	s_mov_b32 m0, s64
	v_readfirstlane_b32 s62, v171
	ds_read_b128 v[128:131], v154
	ds_read_b128 v[132:135], v154 offset:1024
	ds_read_b128 v[192:195], v154 offset:2048
	ds_read_b128 v[196:199], v154 offset:3072
	ds_read_b128 v[200:203], v154 offset:4096
	ds_read_b128 v[204:207], v154 offset:5120
	ds_read_b128 v[208:211], v154 offset:6144
	ds_read_b128 v[212:215], v154 offset:7168
	global_load_lds_dwordx4 v[138:139], off
	v_lshl_add_u64 v[138:139], v[0:1], 0, s[28:29]
	s_mov_b32 m0, s62
	s_nop 0
	global_load_lds_dwordx4 v[138:139], off
	s_waitcnt lgkmcnt(8)
	s_waitcnt lgkmcnt(0)
	s_setprio 1
	s_barrier
; #define STAGE(P, BASE, br, kt) do { const char* _gb = (const char*)(BASE) + ((size_t)(br) * K + (size_t)(kt) * BK) * 2; \
;     __builtin_amdgcn_global_load_lds((const unsigned*)(_gb + loff0), (unsigned*)((char*)(P) + tid * 16), 16, 0, 0); \
;     __builtin_amdgcn_global_load_lds((const unsigned*)(_gb + (size_t)K * 128 + loff0), (unsigned*)((char*)(P) + tid * 16 + 8192), 16, 0, 0); } while (0)
; #define LDA(dst, b, h) for (int m = 0; m < 4; ++m) { \
;     dst[m][0] = *reinterpret_cast<const bf16x8*>((char*)SA(b, h) + aoff0 + m * 2048); \
;     dst[m][1] = *reinterpret_cast<const bf16x8*>((char*)SA(b, h) + aoff1 + m * 2048); }
; #define LDB(dst, b, h) for (int n = 0; n < 2; ++n) { \
;     dst[n][0] = *reinterpret_cast<const bf16x8*>((char*)SB(b, h) + boff0 + n * 256); \
;     dst[n][1] = *reinterpret_cast<const bf16x8*>((char*)SB(b, h) + boff1 + n * 256); }
; #define MMA(ai, bj, At, Btf) do { __builtin_amdgcn_s_setprio(1); \
;     for (int m = 0; m < 4; ++m) for (int n = 0; n < 2; ++n) for (int k = 0; k < 2; ++k) \
;       acc[ai][bj][m][n] = __builtin_amdgcn_mfma_f32_16x16x32_bf16(Btf[n][k], At[m][k], acc[ai][bj][m][n], 0, 0, 0); \
;     __builtin_amdgcn_s_setprio(0); } while (0)
; #define WAIT_V(n) asm volatile("s_waitcnt vmcnt(" #n ")" ::: "memory")
; #define WAIT_L(n) asm volatile("s_waitcnt lgkmcnt(" #n ")" ::: "memory")
; #define BAR __builtin_amdgcn_s_barrier()
; #define SCHED __builtin_amdgcn_sched_barrier(0)
; template <int EPI> ...
;     ...
;     WAIT_L(8); BAR; WAIT_L(0); MMA(0, 0, At, B0); BAR; SCHED;
;     LDB(B1, 0, 1); STAGE(SB(0, 0), Bt, bcol, t + 2);
;     BAR; WAIT_L(0); MMA(0, 1, At, B1); BAR;
;     LDA(At, 0, 1); STAGE(SA(0, 0), A, brow, t + 2);
;     BAR; WAIT_L(0); MMA(1, 0, At, B0); BAR; SCHED;
;     STAGE(SB(0, 1), Bt, bcol + HALF, t + 2);
;     WAIT_V(6); BAR; MMA(1, 1, At, B1); BAR;
	v_mfma_f32_16x16x32_bf16 v[56:59], v[112:115], v[128:131], v[56:59]
	v_mfma_f32_16x16x32_bf16 v[60:63], v[116:119], v[128:131], v[60:63]
	v_mfma_f32_16x16x32_bf16 v[64:67], v[112:115], v[192:195], v[64:67]
	v_mfma_f32_16x16x32_bf16 v[68:71], v[116:119], v[192:195], v[68:71]
	v_mfma_f32_16x16x32_bf16 v[72:75], v[112:115], v[200:203], v[72:75]
	v_mfma_f32_16x16x32_bf16 v[76:79], v[116:119], v[200:203], v[76:79]
	v_mfma_f32_16x16x32_bf16 v[80:83], v[112:115], v[208:211], v[80:83]
	v_mfma_f32_16x16x32_bf16 v[84:87], v[116:119], v[208:211], v[84:87]
	v_mfma_f32_16x16x32_bf16 v[56:59], v[120:123], v[132:135], v[56:59]
	v_mfma_f32_16x16x32_bf16 v[60:63], v[124:127], v[132:135], v[60:63]
	v_mfma_f32_16x16x32_bf16 v[64:67], v[120:123], v[196:199], v[64:67]
	v_mfma_f32_16x16x32_bf16 v[68:71], v[124:127], v[196:199], v[68:71]
	v_mfma_f32_16x16x32_bf16 v[72:75], v[120:123], v[204:207], v[72:75]
	v_mfma_f32_16x16x32_bf16 v[76:79], v[124:127], v[204:207], v[76:79]
	v_mfma_f32_16x16x32_bf16 v[80:83], v[120:123], v[212:215], v[80:83]
	v_mfma_f32_16x16x32_bf16 v[84:87], v[124:127], v[212:215], v[84:87]
	s_barrier
	s_setprio 0
	v_readfirstlane_b32 s65, v156
	v_lshl_add_u64 v[138:139], v[6:7], 0, s[30:31]
	s_mov_b32 m0, s65
	v_readfirstlane_b32 s65, v157
	ds_read_b128 v[216:219], v178
	ds_read_b128 v[220:223], v178 offset:256
	ds_read_b128 v[224:227], v179
	ds_read_b128 v[228:231], v179 offset:256
	global_load_lds_dwordx4 v[138:139], off
	v_lshl_add_u64 v[138:139], v[6:7], 0, s[36:37]
	s_mov_b32 m0, s65
	s_nop 0
	global_load_lds_dwordx4 v[138:139], off
	s_barrier
	s_waitcnt lgkmcnt(0)
	s_setprio 1
	s_waitcnt lgkmcnt(0)
	v_mfma_f32_16x16x32_bf16 v[104:107], v[216:219], v[128:131], v[104:107]
	v_mfma_f32_16x16x32_bf16 v[24:27], v[220:223], v[128:131], v[24:27]
	v_mfma_f32_16x16x32_bf16 v[28:31], v[216:219], v[192:195], v[28:31]
	v_mfma_f32_16x16x32_bf16 v[32:35], v[220:223], v[192:195], v[32:35]
	v_mfma_f32_16x16x32_bf16 v[36:39], v[216:219], v[200:203], v[36:39]
	v_mfma_f32_16x16x32_bf16 v[40:43], v[220:223], v[200:203], v[40:43]
	v_mfma_f32_16x16x32_bf16 v[44:47], v[216:219], v[208:211], v[44:47]
	v_mfma_f32_16x16x32_bf16 v[48:51], v[220:223], v[208:211], v[48:51]
	v_mfma_f32_16x16x32_bf16 v[104:107], v[224:227], v[132:135], v[104:107]
	v_mfma_f32_16x16x32_bf16 v[24:27], v[228:231], v[132:135], v[24:27]
	v_mfma_f32_16x16x32_bf16 v[28:31], v[224:227], v[196:199], v[28:31]
	v_mfma_f32_16x16x32_bf16 v[32:35], v[228:231], v[196:199], v[32:35]
	v_mfma_f32_16x16x32_bf16 v[36:39], v[224:227], v[204:207], v[36:39]
	v_mfma_f32_16x16x32_bf16 v[40:43], v[228:231], v[204:207], v[40:43]
	v_mfma_f32_16x16x32_bf16 v[44:47], v[224:227], v[212:215], v[44:47]
	v_mfma_f32_16x16x32_bf16 v[48:51], v[228:231], v[212:215], v[48:51]
	s_setprio 0
	v_readfirstlane_b32 s65, v158
	v_lshl_add_u64 v[138:139], v[4:5], 0, s[30:31]
	s_mov_b32 m0, s65
	v_readfirstlane_b32 s65, v159
	s_barrier
	ds_read_b128 v[128:131], v154 offset:16384
	ds_read_b128 v[132:135], v154 offset:17408
	ds_read_b128 v[192:195], v154 offset:18432
	ds_read_b128 v[196:199], v154 offset:19456
	ds_read_b128 v[200:203], v154 offset:20480
	ds_read_b128 v[204:207], v154 offset:21504
	ds_read_b128 v[208:211], v154 offset:22528
	ds_read_b128 v[212:215], v154 offset:23552
	global_load_lds_dwordx4 v[138:139], off
	v_lshl_add_u64 v[138:139], v[4:5], 0, s[36:37]
	s_mov_b32 m0, s65
	s_nop 0
	global_load_lds_dwordx4 v[138:139], off
	s_waitcnt lgkmcnt(0)
	s_setprio 1
	s_barrier
	v_mfma_f32_16x16x32_bf16 v[8:11], v[112:115], v[208:211], v[8:11]
	v_mfma_f32_16x16x32_bf16 v[12:15], v[116:119], v[208:211], v[12:15]
	v_mfma_f32_16x16x32_bf16 v[142:145], v[112:115], v[128:131], v[142:145]
	v_mfma_f32_16x16x32_bf16 v[146:149], v[116:119], v[128:131], v[146:149]
	v_mfma_f32_16x16x32_bf16 v[150:153], v[112:115], v[192:195], v[150:153]
	v_mfma_f32_16x16x32_bf16 v[180:183], v[116:119], v[192:195], v[180:183]
	v_mfma_f32_16x16x32_bf16 v[184:187], v[112:115], v[200:203], v[184:187]
	v_mfma_f32_16x16x32_bf16 v[188:191], v[116:119], v[200:203], v[188:191]
	v_mfma_f32_16x16x32_bf16 v[8:11], v[120:123], v[212:215], v[8:11]
	v_mfma_f32_16x16x32_bf16 v[12:15], v[124:127], v[212:215], v[12:15]
	v_mfma_f32_16x16x32_bf16 v[142:145], v[120:123], v[132:135], v[142:145]
	v_mfma_f32_16x16x32_bf16 v[146:149], v[124:127], v[132:135], v[146:149]
	v_mfma_f32_16x16x32_bf16 v[150:153], v[120:123], v[196:199], v[150:153]
	v_mfma_f32_16x16x32_bf16 v[180:183], v[124:127], v[196:199], v[180:183]
	v_mfma_f32_16x16x32_bf16 v[184:187], v[120:123], v[204:207], v[184:187]
	v_mfma_f32_16x16x32_bf16 v[188:191], v[124:127], v[204:207], v[188:191]
	s_barrier
	s_setprio 0
	v_readfirstlane_b32 s65, v160
	v_lshl_add_u64 v[112:113], v[2:3], 0, s[30:31]
	s_mov_b32 m0, s65
	v_readfirstlane_b32 s65, v161
	global_load_lds_dwordx4 v[112:113], off
	v_lshl_add_u64 v[112:113], v[2:3], 0, s[36:37]
	s_mov_b32 m0, s65
	s_nop 0
	global_load_lds_dwordx4 v[112:113], off
	s_waitcnt vmcnt(6)
	s_barrier
	s_setprio 1
	v_mfma_f32_16x16x32_bf16 v[16:19], v[216:219], v[128:131], v[16:19]
	v_mfma_f32_16x16x32_bf16 v[20:23], v[220:223], v[128:131], v[20:23]
	v_mfma_f32_16x16x32_bf16 v[52:55], v[216:219], v[192:195], v[52:55]
	v_mfma_f32_16x16x32_bf16 v[108:111], v[220:223], v[200:203], v[108:111]
	v_mfma_f32_16x16x32_bf16 v[88:91], v[216:219], v[208:211], v[88:91]
	v_mfma_f32_16x16x32_bf16 v[92:95], v[220:223], v[208:211], v[92:95]
	v_mfma_f32_16x16x32_bf16 v[16:19], v[224:227], v[132:135], v[16:19]
	v_mfma_f32_16x16x32_bf16 v[20:23], v[228:231], v[132:135], v[20:23]
	v_mfma_f32_16x16x32_bf16 v[52:55], v[224:227], v[196:199], v[52:55]
	v_mfma_f32_16x16x32_bf16 v[96:99], v[220:223], v[192:195], v[96:99]
	v_mfma_f32_16x16x32_bf16 v[100:103], v[216:219], v[200:203], v[100:103]
	v_mfma_f32_16x16x32_bf16 v[108:111], v[228:231], v[204:207], v[108:111]
	v_mfma_f32_16x16x32_bf16 v[88:91], v[224:227], v[212:215], v[88:91]
	v_mfma_f32_16x16x32_bf16 v[92:95], v[228:231], v[212:215], v[92:95]
	v_mfma_f32_16x16x32_bf16 v[96:99], v[228:231], v[196:199], v[96:99]
	v_mfma_f32_16x16x32_bf16 v[100:103], v[224:227], v[204:207], v[100:103]
	s_setprio 0
	s_barrier
; #define STAGE(P, BASE, br, kt) do { const char* _gb = (const char*)(BASE) + ((size_t)(br) * K + (size_t)(kt) * BK) * 2; \
;     __builtin_amdgcn_global_load_lds((const unsigned*)(_gb + loff0), (unsigned*)((char*)(P) + tid * 16), 16, 0, 0); \
;     __builtin_amdgcn_global_load_lds((const unsigned*)(_gb + (size_t)K * 128 + loff0), (unsigned*)((char*)(P) + tid * 16 + 8192), 16, 0, 0); } while (0)
; #define LDA(dst, b, h) for (int m = 0; m < 4; ++m) { \
;     dst[m][0] = *reinterpret_cast<const bf16x8*>((char*)SA(b, h) + aoff0 + m * 2048); \
;     dst[m][1] = *reinterpret_cast<const bf16x8*>((char*)SA(b, h) + aoff1 + m * 2048); }
; #define LDB(dst, b, h) for (int n = 0; n < 2; ++n) { \
;     dst[n][0] = *reinterpret_cast<const bf16x8*>((char*)SB(b, h) + boff0 + n * 256); \
;     dst[n][1] = *reinterpret_cast<const bf16x8*>((char*)SB(b, h) + boff1 + n * 256); }
; #define MMA(ai, bj, At, Btf) do { __builtin_amdgcn_s_setprio(1); \
;     for (int m = 0; m < 4; ++m) for (int n = 0; n < 2; ++n) for (int k = 0; k < 2; ++k) \
;       acc[ai][bj][m][n] = __builtin_amdgcn_mfma_f32_16x16x32_bf16(Btf[n][k], At[m][k], acc[ai][bj][m][n], 0, 0, 0); \
;     __builtin_amdgcn_s_setprio(0); } while (0)
; #define WAIT_V(n) asm volatile("s_waitcnt vmcnt(" #n ")" ::: "memory")
; #define WAIT_L(n) asm volatile("s_waitcnt lgkmcnt(" #n ")" ::: "memory")
; #define BAR __builtin_amdgcn_s_barrier()
; #define SCHED __builtin_amdgcn_sched_barrier(0)
; template <int EPI> ...
;     ...
;     LDB(B0, 1, 0); SCHED; LDA(At, 1, 0); STAGE(SA(0, 1), A, brow + HALF, t + 2);
;     WAIT_L(8); BAR; WAIT_L(0); MMA(0, 0, At, B0); BAR; SCHED;
;     LDB(B1, 1, 1); STAGE(SB(1, 0), Bt, bcol, t + 3);
;     BAR; WAIT_L(0); MMA(0, 1, At, B1); BAR;
;     LDA(At, 1, 1); STAGE(SA(1, 0), A, brow, t + 3);
;     BAR; WAIT_L(0); MMA(1, 0, At, B0); BAR; SCHED;
;     STAGE(SB(1, 1), Bt, bcol + HALF, t + 3);
;     WAIT_V(6); BAR; MMA(1, 1, At, B1); BAR;
	ds_read_b128 v[112:115], v172
	ds_read_b128 v[116:119], v172 offset:256
	ds_read_b128 v[120:123], v173
	ds_read_b128 v[124:127], v173 offset:256
	v_readfirstlane_b32 s65, v162
	v_lshl_add_u64 v[138:139], v[0:1], 0, s[30:31]
	s_mov_b32 m0, s65
	v_readfirstlane_b32 s65, v163
	ds_read_b128 v[128:131], v154 offset:32768
	ds_read_b128 v[132:135], v154 offset:33792
	ds_read_b128 v[192:195], v154 offset:34816
	ds_read_b128 v[196:199], v154 offset:35840
	ds_read_b128 v[200:203], v154 offset:36864
	ds_read_b128 v[204:207], v154 offset:37888
	ds_read_b128 v[208:211], v154 offset:38912
	ds_read_b128 v[212:215], v154 offset:39936
	global_load_lds_dwordx4 v[138:139], off
	v_lshl_add_u64 v[138:139], v[0:1], 0, s[36:37]
	s_mov_b32 m0, s65
	s_nop 0
	global_load_lds_dwordx4 v[138:139], off
	s_waitcnt lgkmcnt(8)
	s_waitcnt lgkmcnt(0)
	s_setprio 1
	s_barrier
	v_mfma_f32_16x16x32_bf16 v[56:59], v[112:115], v[128:131], v[56:59]
	v_mfma_f32_16x16x32_bf16 v[60:63], v[116:119], v[128:131], v[60:63]
	v_mfma_f32_16x16x32_bf16 v[64:67], v[112:115], v[192:195], v[64:67]
	v_mfma_f32_16x16x32_bf16 v[68:71], v[116:119], v[192:195], v[68:71]
	v_mfma_f32_16x16x32_bf16 v[72:75], v[112:115], v[200:203], v[72:75]
	v_mfma_f32_16x16x32_bf16 v[76:79], v[116:119], v[200:203], v[76:79]
	v_mfma_f32_16x16x32_bf16 v[80:83], v[112:115], v[208:211], v[80:83]
	v_mfma_f32_16x16x32_bf16 v[84:87], v[116:119], v[208:211], v[84:87]
	v_mfma_f32_16x16x32_bf16 v[56:59], v[120:123], v[132:135], v[56:59]
	v_mfma_f32_16x16x32_bf16 v[60:63], v[124:127], v[132:135], v[60:63]
	v_mfma_f32_16x16x32_bf16 v[64:67], v[120:123], v[196:199], v[64:67]
	v_mfma_f32_16x16x32_bf16 v[68:71], v[124:127], v[196:199], v[68:71]
	v_mfma_f32_16x16x32_bf16 v[72:75], v[120:123], v[204:207], v[72:75]
	v_mfma_f32_16x16x32_bf16 v[76:79], v[124:127], v[204:207], v[76:79]
	v_mfma_f32_16x16x32_bf16 v[80:83], v[120:123], v[212:215], v[80:83]
	v_mfma_f32_16x16x32_bf16 v[84:87], v[124:127], v[212:215], v[84:87]
	s_barrier
	s_setprio 0
	s_mov_b32 m0, s52
	v_lshl_add_u64 v[138:139], v[6:7], 0, s[38:39]
	ds_read_b128 v[216:219], v174
	ds_read_b128 v[220:223], v174 offset:256
	ds_read_b128 v[224:227], v175
	ds_read_b128 v[228:231], v175 offset:256
	global_load_lds_dwordx4 v[138:139], off
	v_lshl_add_u64 v[6:7], v[6:7], 0, s[46:47]
	s_mov_b32 m0, s49
	s_nop 0
	global_load_lds_dwordx4 v[6:7], off
	s_barrier
	s_waitcnt lgkmcnt(0)
	s_setprio 1
	s_waitcnt lgkmcnt(0)
	v_mfma_f32_16x16x32_bf16 v[104:107], v[216:219], v[128:131], v[104:107]
	v_mfma_f32_16x16x32_bf16 v[24:27], v[220:223], v[128:131], v[24:27]
	v_mfma_f32_16x16x32_bf16 v[28:31], v[216:219], v[192:195], v[28:31]
	v_mfma_f32_16x16x32_bf16 v[32:35], v[220:223], v[192:195], v[32:35]
	v_mfma_f32_16x16x32_bf16 v[36:39], v[216:219], v[200:203], v[36:39]
	v_mfma_f32_16x16x32_bf16 v[40:43], v[220:223], v[200:203], v[40:43]
	v_mfma_f32_16x16x32_bf16 v[44:47], v[216:219], v[208:211], v[44:47]
	v_mfma_f32_16x16x32_bf16 v[48:51], v[220:223], v[208:211], v[48:51]
	v_mfma_f32_16x16x32_bf16 v[104:107], v[224:227], v[132:135], v[104:107]
	v_mfma_f32_16x16x32_bf16 v[24:27], v[228:231], v[132:135], v[24:27]
	v_mfma_f32_16x16x32_bf16 v[28:31], v[224:227], v[196:199], v[28:31]
	v_mfma_f32_16x16x32_bf16 v[32:35], v[228:231], v[196:199], v[32:35]
	v_mfma_f32_16x16x32_bf16 v[36:39], v[224:227], v[204:207], v[36:39]
	v_mfma_f32_16x16x32_bf16 v[40:43], v[228:231], v[204:207], v[40:43]
	v_mfma_f32_16x16x32_bf16 v[44:47], v[224:227], v[212:215], v[44:47]
	v_mfma_f32_16x16x32_bf16 v[48:51], v[228:231], v[212:215], v[48:51]
	s_setprio 0
	s_mov_b32 m0, s63
	v_lshl_add_u64 v[6:7], v[4:5], 0, s[38:39]
	s_barrier
	ds_read_b128 v[128:131], v154 offset:49152
	ds_read_b128 v[132:135], v154 offset:50176
	ds_read_b128 v[192:195], v154 offset:51200
	ds_read_b128 v[196:199], v154 offset:52224
	ds_read_b128 v[200:203], v154 offset:53248
	ds_read_b128 v[204:207], v154 offset:54272
	ds_read_b128 v[208:211], v154 offset:55296
	ds_read_b128 v[212:215], v154 offset:56320
	global_load_lds_dwordx4 v[6:7], off
	v_lshl_add_u64 v[4:5], v[4:5], 0, s[46:47]
	s_mov_b32 m0, s53
	s_nop 0
	global_load_lds_dwordx4 v[4:5], off
	s_waitcnt lgkmcnt(0)
	s_setprio 1
	s_barrier
	v_mfma_f32_16x16x32_bf16 v[4:7], v[112:115], v[128:131], v[142:145]
	v_mfma_f32_16x16x32_bf16 v[8:11], v[112:115], v[208:211], v[8:11]
	v_mfma_f32_16x16x32_bf16 v[12:15], v[116:119], v[208:211], v[12:15]
	v_mfma_f32_16x16x32_bf16 v[4:7], v[120:123], v[132:135], v[4:7]
	v_mfma_f32_16x16x32_bf16 v[142:145], v[116:119], v[128:131], v[146:149]
	v_mfma_f32_16x16x32_bf16 v[146:149], v[112:115], v[192:195], v[150:153]
	v_mfma_f32_16x16x32_bf16 v[150:153], v[116:119], v[192:195], v[180:183]
	v_mfma_f32_16x16x32_bf16 v[180:183], v[112:115], v[200:203], v[184:187]
	v_mfma_f32_16x16x32_bf16 v[184:187], v[116:119], v[200:203], v[188:191]
	v_mfma_f32_16x16x32_bf16 v[8:11], v[120:123], v[212:215], v[8:11]
	v_mfma_f32_16x16x32_bf16 v[12:15], v[124:127], v[212:215], v[12:15]
	v_mfma_f32_16x16x32_bf16 v[142:145], v[124:127], v[132:135], v[142:145]
	v_mfma_f32_16x16x32_bf16 v[146:149], v[120:123], v[196:199], v[146:149]
	v_mfma_f32_16x16x32_bf16 v[150:153], v[124:127], v[196:199], v[150:153]
	v_mfma_f32_16x16x32_bf16 v[180:183], v[120:123], v[204:207], v[180:183]
	v_mfma_f32_16x16x32_bf16 v[184:187], v[124:127], v[204:207], v[184:187]
	s_barrier
	s_setprio 0
	s_mov_b32 m0, s61
	v_lshl_add_u64 v[112:113], v[2:3], 0, s[38:39]
	global_load_lds_dwordx4 v[112:113], off
	v_lshl_add_u64 v[2:3], v[2:3], 0, s[46:47]
	s_mov_b32 m0, s60
	s_nop 0
	global_load_lds_dwordx4 v[2:3], off
	s_waitcnt vmcnt(6)
	s_barrier
; #define STAGE(P, BASE, br, kt) do { const char* _gb = (const char*)(BASE) + ((size_t)(br) * K + (size_t)(kt) * BK) * 2; \
;     __builtin_amdgcn_global_load_lds((const unsigned*)(_gb + loff0), (unsigned*)((char*)(P) + tid * 16), 16, 0, 0); \
;     __builtin_amdgcn_global_load_lds((const unsigned*)(_gb + (size_t)K * 128 + loff0), (unsigned*)((char*)(P) + tid * 16 + 8192), 16, 0, 0); } while (0)
; #define LDA(dst, b, h) for (int m = 0; m < 4; ++m) { \
;     dst[m][0] = *reinterpret_cast<const bf16x8*>((char*)SA(b, h) + aoff0 + m * 2048); \
;     dst[m][1] = *reinterpret_cast<const bf16x8*>((char*)SA(b, h) + aoff1 + m * 2048); }
; #define LDB(dst, b, h) for (int n = 0; n < 2; ++n) { \
;     dst[n][0] = *reinterpret_cast<const bf16x8*>((char*)SB(b, h) + boff0 + n * 256); \
;     dst[n][1] = *reinterpret_cast<const bf16x8*>((char*)SB(b, h) + boff1 + n * 256); }
; #define MMA(ai, bj, At, Btf) do { __builtin_amdgcn_s_setprio(1); \
;     for (int m = 0; m < 4; ++m) for (int n = 0; n < 2; ++n) for (int k = 0; k < 2; ++k) \
;       acc[ai][bj][m][n] = __builtin_amdgcn_mfma_f32_16x16x32_bf16(Btf[n][k], At[m][k], acc[ai][bj][m][n], 0, 0, 0); \
;     __builtin_amdgcn_s_setprio(0); } while (0)
; #define WAIT_V(n) asm volatile("s_waitcnt vmcnt(" #n ")" ::: "memory")
; #define WAIT_L(n) asm volatile("s_waitcnt lgkmcnt(" #n ")" ::: "memory")
; #define BAR __builtin_amdgcn_s_barrier()
; template <int EPI> ...
;     ...
;     WAIT_V(6); BAR; MMA(1, 1, At, B1); BAR;
;   }
;   { LDB(B0, 0, 0); LDA(At, 0, 0); STAGE(SA(1, 1), A, brow + HALF, nt - 1);
;     BAR; WAIT_L(0); MMA(0, 0, At, B0); BAR;
;     LDB(B1, 0, 1); BAR; WAIT_L(0); MMA(0, 1, At, B1); BAR;
;     LDA(At, 0, 1); WAIT_V(4); BAR; WAIT_L(0); MMA(1, 0, At, B0); MMA(1, 1, At, B1); BAR; }
	s_setprio 1
	v_mfma_f32_16x16x32_bf16 v[16:19], v[216:219], v[128:131], v[16:19]
	v_mfma_f32_16x16x32_bf16 v[20:23], v[220:223], v[128:131], v[20:23]
	v_mfma_f32_16x16x32_bf16 v[52:55], v[216:219], v[192:195], v[52:55]
	v_mfma_f32_16x16x32_bf16 v[108:111], v[220:223], v[200:203], v[108:111]
	v_mfma_f32_16x16x32_bf16 v[88:91], v[216:219], v[208:211], v[88:91]
	v_mfma_f32_16x16x32_bf16 v[92:95], v[220:223], v[208:211], v[92:95]
	v_mfma_f32_16x16x32_bf16 v[16:19], v[224:227], v[132:135], v[16:19]
	v_mfma_f32_16x16x32_bf16 v[20:23], v[228:231], v[132:135], v[20:23]
	v_mfma_f32_16x16x32_bf16 v[52:55], v[224:227], v[196:199], v[52:55]
	v_mfma_f32_16x16x32_bf16 v[96:99], v[220:223], v[192:195], v[96:99]
	v_mfma_f32_16x16x32_bf16 v[100:103], v[216:219], v[200:203], v[100:103]
	v_mfma_f32_16x16x32_bf16 v[108:111], v[228:231], v[204:207], v[108:111]
	v_mfma_f32_16x16x32_bf16 v[88:91], v[224:227], v[212:215], v[88:91]
	v_mfma_f32_16x16x32_bf16 v[92:95], v[228:231], v[212:215], v[92:95]
	v_mfma_f32_16x16x32_bf16 v[96:99], v[228:231], v[196:199], v[96:99]
	v_mfma_f32_16x16x32_bf16 v[100:103], v[224:227], v[204:207], v[100:103]
	s_setprio 0
	s_mov_b32 m0, s64
	v_lshl_add_u64 v[2:3], v[0:1], 0, s[38:39]
	s_barrier
	ds_read_b128 v[112:115], v176
	ds_read_b128 v[116:119], v176 offset:256
	ds_read_b128 v[120:123], v177
	ds_read_b128 v[124:127], v177 offset:256
	ds_read_b128 v[128:131], v154
	ds_read_b128 v[132:135], v154 offset:1024
	ds_read_b128 v[188:191], v154 offset:2048
	ds_read_b128 v[192:195], v154 offset:3072
	ds_read_b128 v[196:199], v154 offset:4096
	ds_read_b128 v[200:203], v154 offset:5120
	ds_read_b128 v[204:207], v154 offset:6144
	ds_read_b128 v[208:211], v154 offset:7168
	global_load_lds_dwordx4 v[2:3], off
	v_lshl_add_u64 v[0:1], v[0:1], 0, s[46:47]
	s_mov_b32 m0, s62
	s_nop 0
	global_load_lds_dwordx4 v[0:1], off
	s_waitcnt lgkmcnt(0)
	s_setprio 1
	s_barrier
	v_mfma_f32_16x16x32_bf16 v[0:3], v[112:115], v[128:131], v[56:59]
	v_mfma_f32_16x16x32_bf16 v[56:59], v[116:119], v[128:131], v[60:63]
	v_mfma_f32_16x16x32_bf16 v[60:63], v[112:115], v[188:191], v[64:67]
	v_mfma_f32_16x16x32_bf16 v[64:67], v[116:119], v[188:191], v[68:71]
	v_mfma_f32_16x16x32_bf16 v[68:71], v[112:115], v[196:199], v[72:75]
	v_mfma_f32_16x16x32_bf16 v[72:75], v[116:119], v[196:199], v[76:79]
	v_mfma_f32_16x16x32_bf16 v[76:79], v[112:115], v[204:207], v[80:83]
	v_mfma_f32_16x16x32_bf16 v[80:83], v[116:119], v[204:207], v[84:87]
	v_mfma_f32_16x16x32_bf16 v[0:3], v[120:123], v[132:135], v[0:3]
	v_mfma_f32_16x16x32_bf16 v[56:59], v[124:127], v[132:135], v[56:59]
	v_mfma_f32_16x16x32_bf16 v[60:63], v[120:123], v[192:195], v[60:63]
	v_mfma_f32_16x16x32_bf16 v[64:67], v[124:127], v[192:195], v[64:67]
	v_mfma_f32_16x16x32_bf16 v[68:71], v[120:123], v[200:203], v[68:71]
	v_mfma_f32_16x16x32_bf16 v[72:75], v[124:127], v[200:203], v[72:75]
	v_mfma_f32_16x16x32_bf16 v[76:79], v[120:123], v[208:211], v[76:79]
	v_mfma_f32_16x16x32_bf16 v[80:83], v[124:127], v[208:211], v[80:83]
	s_barrier
	s_setprio 0
	ds_read_b128 v[84:87], v178
	ds_read_b128 v[212:215], v178 offset:256
	ds_read_b128 v[216:219], v179
	ds_read_b128 v[220:223], v179 offset:256
	s_waitcnt lgkmcnt(0)
	s_setprio 1
	s_barrier
	v_mfma_f32_16x16x32_bf16 v[24:27], v[212:215], v[128:131], v[24:27]
	v_mfma_f32_16x16x32_bf16 v[28:31], v[84:87], v[188:191], v[28:31]
	v_mfma_f32_16x16x32_bf16 v[32:35], v[212:215], v[188:191], v[32:35]
	v_mfma_f32_16x16x32_bf16 v[36:39], v[84:87], v[196:199], v[36:39]
	v_mfma_f32_16x16x32_bf16 v[40:43], v[212:215], v[196:199], v[40:43]
	v_mfma_f32_16x16x32_bf16 v[44:47], v[84:87], v[204:207], v[44:47]
	v_mfma_f32_16x16x32_bf16 v[48:51], v[212:215], v[204:207], v[48:51]
	v_mfma_f32_16x16x32_bf16 v[104:107], v[84:87], v[128:131], v[104:107]
	v_mfma_f32_16x16x32_bf16 v[24:27], v[220:223], v[132:135], v[24:27]
	v_mfma_f32_16x16x32_bf16 v[28:31], v[216:219], v[192:195], v[28:31]
	v_mfma_f32_16x16x32_bf16 v[32:35], v[220:223], v[192:195], v[32:35]
	v_mfma_f32_16x16x32_bf16 v[36:39], v[216:219], v[200:203], v[36:39]
	v_mfma_f32_16x16x32_bf16 v[40:43], v[220:223], v[200:203], v[40:43]
	v_mfma_f32_16x16x32_bf16 v[44:47], v[216:219], v[208:211], v[44:47]
	v_mfma_f32_16x16x32_bf16 v[48:51], v[220:223], v[208:211], v[48:51]
	v_mfma_f32_16x16x32_bf16 v[224:227], v[216:219], v[132:135], v[104:107]
	s_barrier
	s_setprio 0
	s_nop 0
	ds_read_b128 v[104:107], v154 offset:16384
	ds_read_b128 v[128:131], v154 offset:17408
	ds_read_b128 v[132:135], v154 offset:18432
	ds_read_b128 v[188:191], v154 offset:19456
	ds_read_b128 v[192:195], v154 offset:20480
	ds_read_b128 v[196:199], v154 offset:21504
	ds_read_b128 v[200:203], v154 offset:22528
	ds_read_b128 v[204:207], v154 offset:23552
	s_waitcnt vmcnt(4)
	s_waitcnt lgkmcnt(0)
	s_setprio 1
	s_barrier
; #define LDA(dst, b, h) for (int m = 0; m < 4; ++m) { \
;     dst[m][0] = *reinterpret_cast<const bf16x8*>((char*)SA(b, h) + aoff0 + m * 2048); \
;     dst[m][1] = *reinterpret_cast<const bf16x8*>((char*)SA(b, h) + aoff1 + m * 2048); }
; #define LDB(dst, b, h) for (int n = 0; n < 2; ++n) { \
;     dst[n][0] = *reinterpret_cast<const bf16x8*>((char*)SB(b, h) + boff0 + n * 256); \
;     dst[n][1] = *reinterpret_cast<const bf16x8*>((char*)SB(b, h) + boff1 + n * 256); }
; #define MMA(ai, bj, At, Btf) do { __builtin_amdgcn_s_setprio(1); \
;     for (int m = 0; m < 4; ++m) for (int n = 0; n < 2; ++n) for (int k = 0; k < 2; ++k) \
;       acc[ai][bj][m][n] = __builtin_amdgcn_mfma_f32_16x16x32_bf16(Btf[n][k], At[m][k], acc[ai][bj][m][n], 0, 0, 0); \
;     __builtin_amdgcn_s_setprio(0); } while (0)
; #define WAIT_V(n) asm volatile("s_waitcnt vmcnt(" #n ")" ::: "memory")
; #define WAIT_L(n) asm volatile("s_waitcnt lgkmcnt(" #n ")" ::: "memory")
; #define BAR __builtin_amdgcn_s_barrier()
; template <int EPI> ...
;     ...
;     LDA(At, 0, 1); WAIT_V(4); BAR; WAIT_L(0); MMA(1, 0, At, B0); MMA(1, 1, At, B1); BAR; }
;   { LDB(B0, 1, 0); LDA(At, 1, 0); WAIT_V(2); BAR; WAIT_L(0); MMA(0, 0, At, B0); BAR;
	v_mfma_f32_16x16x32_bf16 v[4:7], v[112:115], v[104:107], v[4:7]
	v_mfma_f32_16x16x32_bf16 v[8:11], v[112:115], v[200:203], v[8:11]
	v_mfma_f32_16x16x32_bf16 v[4:7], v[120:123], v[128:131], v[4:7]
	v_mfma_f32_16x16x32_bf16 v[142:145], v[116:119], v[104:107], v[142:145]
	v_mfma_f32_16x16x32_bf16 v[146:149], v[112:115], v[132:135], v[146:149]
	v_mfma_f32_16x16x32_bf16 v[150:153], v[116:119], v[132:135], v[150:153]
	v_mfma_f32_16x16x32_bf16 v[180:183], v[112:115], v[192:195], v[180:183]
	v_mfma_f32_16x16x32_bf16 v[184:187], v[116:119], v[192:195], v[184:187]
	v_mfma_f32_16x16x32_bf16 v[8:11], v[120:123], v[204:207], v[8:11]
	v_mfma_f32_16x16x32_bf16 v[12:15], v[116:119], v[200:203], v[12:15]
	v_mfma_f32_16x16x32_bf16 v[142:145], v[124:127], v[128:131], v[142:145]
	v_mfma_f32_16x16x32_bf16 v[146:149], v[120:123], v[188:191], v[146:149]
	v_mfma_f32_16x16x32_bf16 v[150:153], v[124:127], v[188:191], v[150:153]
	v_mfma_f32_16x16x32_bf16 v[180:183], v[120:123], v[196:199], v[180:183]
	v_mfma_f32_16x16x32_bf16 v[184:187], v[124:127], v[196:199], v[184:187]
	v_mfma_f32_16x16x32_bf16 v[208:211], v[124:127], v[204:207], v[12:15]
	v_mfma_f32_16x16x32_bf16 v[12:15], v[84:87], v[104:107], v[16:19]
	v_mfma_f32_16x16x32_bf16 v[228:231], v[216:219], v[128:131], v[12:15]
	v_mfma_f32_16x16x32_bf16 v[12:15], v[212:215], v[104:107], v[20:23]
	v_mfma_f32_16x16x32_bf16 v[232:235], v[220:223], v[128:131], v[12:15]
	v_mfma_f32_16x16x32_bf16 v[12:15], v[84:87], v[132:135], v[52:55]
	v_mfma_f32_16x16x32_bf16 v[52:55], v[216:219], v[188:191], v[12:15]
	v_mfma_f32_16x16x32_bf16 v[12:15], v[212:215], v[132:135], v[96:99]
	v_mfma_f32_16x16x32_bf16 v[96:99], v[220:223], v[188:191], v[12:15]
	v_mfma_f32_16x16x32_bf16 v[12:15], v[84:87], v[192:195], v[100:103]
	v_mfma_f32_16x16x32_bf16 v[100:103], v[216:219], v[196:199], v[12:15]
	v_mfma_f32_16x16x32_bf16 v[12:15], v[212:215], v[192:195], v[108:111]
	v_mfma_f32_16x16x32_bf16 v[188:191], v[220:223], v[196:199], v[12:15]
	v_mfma_f32_16x16x32_bf16 v[12:15], v[84:87], v[200:203], v[88:91]
	v_mfma_f32_16x16x32_bf16 v[192:195], v[216:219], v[204:207], v[12:15]
	v_mfma_f32_16x16x32_bf16 v[12:15], v[212:215], v[200:203], v[92:95]
	v_mfma_f32_16x16x32_bf16 v[196:199], v[220:223], v[204:207], v[12:15]
	s_barrier
	s_setprio 0
	ds_read_b128 v[88:91], v172
	ds_read_b128 v[92:95], v172 offset:256
	ds_read_b128 v[200:203], v173
	ds_read_b128 v[204:207], v173 offset:256
	ds_read_b128 v[16:19], v154 offset:32768
	ds_read_b128 v[20:23], v154 offset:33792
	ds_read_b128 v[84:87], v154 offset:34816
	ds_read_b128 v[212:215], v154 offset:35840
	ds_read_b128 v[216:219], v154 offset:36864
	ds_read_b128 v[220:223], v154 offset:37888
	ds_read_b128 v[236:239], v154 offset:38912
	ds_read_b128 v[240:243], v154 offset:39936
	s_waitcnt vmcnt(2)
	s_waitcnt lgkmcnt(0)
	s_setprio 1
	s_barrier
	v_mfma_f32_16x16x32_bf16 v[0:3], v[88:91], v[16:19], v[0:3]
	v_mfma_f32_16x16x32_bf16 v[104:107], v[200:203], v[20:23], v[0:3]
	v_mfma_f32_16x16x32_bf16 v[0:3], v[92:95], v[16:19], v[56:59]
	v_mfma_f32_16x16x32_bf16 v[108:111], v[204:207], v[20:23], v[0:3]
	v_mfma_f32_16x16x32_bf16 v[0:3], v[88:91], v[84:87], v[60:63]
	v_mfma_f32_16x16x32_bf16 v[112:115], v[200:203], v[212:215], v[0:3]
	v_mfma_f32_16x16x32_bf16 v[0:3], v[92:95], v[84:87], v[64:67]
	v_mfma_f32_16x16x32_bf16 v[116:119], v[204:207], v[212:215], v[0:3]
	v_mfma_f32_16x16x32_bf16 v[0:3], v[88:91], v[216:219], v[68:71]
	v_mfma_f32_16x16x32_bf16 v[120:123], v[200:203], v[220:223], v[0:3]
	v_mfma_f32_16x16x32_bf16 v[0:3], v[92:95], v[216:219], v[72:75]
	v_mfma_f32_16x16x32_bf16 v[124:127], v[204:207], v[220:223], v[0:3]
	v_mfma_f32_16x16x32_bf16 v[0:3], v[88:91], v[236:239], v[76:79]
	v_mfma_f32_16x16x32_bf16 v[128:131], v[200:203], v[240:243], v[0:3]
	v_mfma_f32_16x16x32_bf16 v[0:3], v[92:95], v[236:239], v[80:83]
	v_mfma_f32_16x16x32_bf16 v[132:135], v[204:207], v[240:243], v[0:3]
	s_barrier
; #define LDA(dst, b, h) for (int m = 0; m < 4; ++m) { \
;     dst[m][0] = *reinterpret_cast<const bf16x8*>((char*)SA(b, h) + aoff0 + m * 2048); \
;     dst[m][1] = *reinterpret_cast<const bf16x8*>((char*)SA(b, h) + aoff1 + m * 2048); }
; #define LDB(dst, b, h) for (int n = 0; n < 2; ++n) { \
;     dst[n][0] = *reinterpret_cast<const bf16x8*>((char*)SB(b, h) + boff0 + n * 256); \
;     dst[n][1] = *reinterpret_cast<const bf16x8*>((char*)SB(b, h) + boff1 + n * 256); }
; #define MMA(ai, bj, At, Btf) do { __builtin_amdgcn_s_setprio(1); \
;     for (int m = 0; m < 4; ++m) for (int n = 0; n < 2; ++n) for (int k = 0; k < 2; ++k) \
;       acc[ai][bj][m][n] = __builtin_amdgcn_mfma_f32_16x16x32_bf16(Btf[n][k], At[m][k], acc[ai][bj][m][n], 0, 0, 0); \
;     __builtin_amdgcn_s_setprio(0); } while (0)
; #define WAIT_V(n) asm volatile("s_waitcnt vmcnt(" #n ")" ::: "memory")
; #define WAIT_L(n) asm volatile("s_waitcnt lgkmcnt(" #n ")" ::: "memory")
; #define BAR __builtin_amdgcn_s_barrier()
; template <int EPI> ...
;     ...
;     LDB(B1, 1, 1); WAIT_V(0); BAR; WAIT_L(0); MMA(0, 1, At, B1); BAR;
;     LDA(At, 1, 1); BAR; WAIT_L(0); MMA(1, 0, At, B0); MMA(1, 1, At, B1); BAR; }
;   if (wr == 0) BAR;
	s_setprio 0
	s_nop 4
	ds_read_b128 v[0:3], v174
	ds_read_b128 v[244:247], v174 offset:256
	ds_read_b128 v[248:251], v175
	ds_read_b128 v[138:141], v175 offset:256
	s_waitcnt vmcnt(0)
	s_waitcnt lgkmcnt(0)
	s_setprio 1
	s_barrier
	v_mfma_f32_16x16x32_bf16 v[12:15], v[0:3], v[16:19], v[224:227]
	v_mfma_f32_16x16x32_bf16 v[16:19], v[244:247], v[16:19], v[24:27]
	v_mfma_f32_16x16x32_bf16 v[12:15], v[248:251], v[20:23], v[12:15]
	v_mfma_f32_16x16x32_bf16 v[16:19], v[138:141], v[20:23], v[16:19]
	v_mfma_f32_16x16x32_bf16 v[20:23], v[0:3], v[84:87], v[28:31]
	v_mfma_f32_16x16x32_bf16 v[24:27], v[244:247], v[84:87], v[32:35]
	v_mfma_f32_16x16x32_bf16 v[28:31], v[0:3], v[216:219], v[36:39]
	v_mfma_f32_16x16x32_bf16 v[32:35], v[244:247], v[216:219], v[40:43]
	v_mfma_f32_16x16x32_bf16 v[36:39], v[0:3], v[236:239], v[44:47]
	v_mfma_f32_16x16x32_bf16 v[40:43], v[244:247], v[236:239], v[48:51]
	v_mfma_f32_16x16x32_bf16 v[20:23], v[248:251], v[212:215], v[20:23]
	v_mfma_f32_16x16x32_bf16 v[24:27], v[138:141], v[212:215], v[24:27]
	v_mfma_f32_16x16x32_bf16 v[28:31], v[248:251], v[220:223], v[28:31]
	v_mfma_f32_16x16x32_bf16 v[32:35], v[138:141], v[220:223], v[32:35]
	v_mfma_f32_16x16x32_bf16 v[36:39], v[248:251], v[240:243], v[36:39]
	v_mfma_f32_16x16x32_bf16 v[40:43], v[138:141], v[240:243], v[40:43]
	s_barrier
	s_setprio 0
	ds_read_b128 v[44:47], v154 offset:49152
	ds_read_b128 v[48:51], v154 offset:50176
	ds_read_b128 v[212:215], v154 offset:51200
	ds_read_b128 v[216:219], v154 offset:52224
	ds_read_b128 v[220:223], v154 offset:53248
	ds_read_b128 v[224:227], v154 offset:54272
	ds_read_b128 v[236:239], v154 offset:55296
	ds_read_b128 v[240:243], v154 offset:56320
	s_waitcnt lgkmcnt(0)
	s_setprio 1
	s_barrier
	v_mfma_f32_16x16x32_bf16 v[4:7], v[88:91], v[44:47], v[4:7]
	v_mfma_f32_16x16x32_bf16 v[64:67], v[200:203], v[48:51], v[4:7]
	v_mfma_f32_16x16x32_bf16 v[4:7], v[92:95], v[44:47], v[142:145]
	v_mfma_f32_16x16x32_bf16 v[68:71], v[204:207], v[48:51], v[4:7]
	v_mfma_f32_16x16x32_bf16 v[4:7], v[88:91], v[212:215], v[146:149]
	v_mfma_f32_16x16x32_bf16 v[72:75], v[200:203], v[216:219], v[4:7]
	v_mfma_f32_16x16x32_bf16 v[4:7], v[92:95], v[212:215], v[150:153]
	v_mfma_f32_16x16x32_bf16 v[76:79], v[204:207], v[216:219], v[4:7]
	v_mfma_f32_16x16x32_bf16 v[4:7], v[88:91], v[220:223], v[180:183]
	v_mfma_f32_16x16x32_bf16 v[80:83], v[200:203], v[224:227], v[4:7]
	v_mfma_f32_16x16x32_bf16 v[4:7], v[92:95], v[220:223], v[184:187]
	v_mfma_f32_16x16x32_bf16 v[84:87], v[204:207], v[224:227], v[4:7]
	v_mfma_f32_16x16x32_bf16 v[4:7], v[88:91], v[236:239], v[8:11]
	v_mfma_f32_16x16x32_bf16 v[88:91], v[200:203], v[240:243], v[4:7]
	v_mfma_f32_16x16x32_bf16 v[4:7], v[92:95], v[236:239], v[208:211]
	v_mfma_f32_16x16x32_bf16 v[92:95], v[204:207], v[240:243], v[4:7]
	v_mfma_f32_16x16x32_bf16 v[4:7], v[0:3], v[44:47], v[228:231]
	v_mfma_f32_16x16x32_bf16 v[60:63], v[248:251], v[48:51], v[4:7]
	v_mfma_f32_16x16x32_bf16 v[4:7], v[244:247], v[44:47], v[232:235]
	v_mfma_f32_16x16x32_bf16 v[56:59], v[138:141], v[48:51], v[4:7]
	v_mfma_f32_16x16x32_bf16 v[4:7], v[0:3], v[212:215], v[52:55]
	v_mfma_f32_16x16x32_bf16 v[52:55], v[248:251], v[216:219], v[4:7]
	v_mfma_f32_16x16x32_bf16 v[4:7], v[244:247], v[212:215], v[96:99]
	v_mfma_f32_16x16x32_bf16 v[48:51], v[138:141], v[216:219], v[4:7]
	v_mfma_f32_16x16x32_bf16 v[4:7], v[0:3], v[220:223], v[100:103]
	v_mfma_f32_16x16x32_bf16 v[44:47], v[248:251], v[224:227], v[4:7]
	v_mfma_f32_16x16x32_bf16 v[4:7], v[244:247], v[220:223], v[188:191]
	v_mfma_f32_16x16x32_bf16 v[0:3], v[0:3], v[236:239], v[192:195]
	v_mfma_f32_16x16x32_bf16 v[8:11], v[138:141], v[224:227], v[4:7]
	v_mfma_f32_16x16x32_bf16 v[4:7], v[248:251], v[240:243], v[0:3]
	v_mfma_f32_16x16x32_bf16 v[0:3], v[244:247], v[236:239], v[196:199]
	v_mfma_f32_16x16x32_bf16 v[0:3], v[138:141], v[240:243], v[0:3]
	s_barrier
	s_setprio 0
	s_and_saveexec_b64 s[52:53], s[2:3]
	s_cbranch_execz .LBB0_967
	s_barrier
	s_branch .LBB0_967

; #define STAGE(P, BASE, br, kt) do { const char* _gb = (const char*)(BASE) + ((size_t)(br) * K + (size_t)(kt) * BK) * 2; \
;     __builtin_amdgcn_global_load_lds((const unsigned*)(_gb + loff0), (unsigned*)((char*)(P) + tid * 16), 16, 0, 0); \
;     __builtin_amdgcn_global_load_lds((const unsigned*)(_gb + (size_t)K * 128 + loff0), (unsigned*)((char*)(P) + tid * 16 + 8192), 16, 0, 0); } while (0)
; #define LDA(dst, b, h) for (int m = 0; m < 4; ++m) { \
;     dst[m][0] = *reinterpret_cast<const bf16x8*>((char*)SA(b, h) + aoff0 + m * 2048); \
;     dst[m][1] = *reinterpret_cast<const bf16x8*>((char*)SA(b, h) + aoff1 + m * 2048); }
; #define LDB(dst, b, h) for (int n = 0; n < 2; ++n) { \
;     dst[n][0] = *reinterpret_cast<const bf16x8*>((char*)SB(b, h) + boff0 + n * 256); \
;     dst[n][1] = *reinterpret_cast<const bf16x8*>((char*)SB(b, h) + boff1 + n * 256); }
; #define MMA(ai, bj, At, Btf) do { __builtin_amdgcn_s_setprio(1); \
;     for (int m = 0; m < 4; ++m) for (int n = 0; n < 2; ++n) for (int k = 0; k < 2; ++k) \
;       acc[ai][bj][m][n] = __builtin_amdgcn_mfma_f32_16x16x32_bf16(Btf[n][k], At[m][k], acc[ai][bj][m][n], 0, 0, 0); \
;     __builtin_amdgcn_s_setprio(0); } while (0)
; #define WAIT_V(n) asm volatile("s_waitcnt vmcnt(" #n ")" ::: "memory")
; #define WAIT_L(n) asm volatile("s_waitcnt lgkmcnt(" #n ")" ::: "memory")
; #define BAR __builtin_amdgcn_s_barrier()
; #define SCHED __builtin_amdgcn_sched_barrier(0)
; template <int EPI> ...
;     ...
;     LDB(B0, 0, 0); SCHED; LDA(At, 0, 0); STAGE(SA(1, 1), A, brow + HALF, t + 1);
;     WAIT_L(8); BAR; WAIT_L(0); MMA(0, 0, At, B0); BAR; SCHED;
;     LDB(B1, 0, 1); STAGE(SB(0, 0), Bt, bcol, t + 2);
;     BAR; WAIT_L(0); MMA(0, 1, At, B1); BAR;
;     LDA(At, 0, 1); STAGE(SA(0, 0), A, brow, t + 2);
;     BAR; WAIT_L(0); MMA(1, 0, At, B0); BAR; SCHED;
;     STAGE(SB(0, 1), Bt, bcol + HALF, t + 2);
;     WAIT_V(6); BAR; MMA(1, 1, At, B1); BAR;
.LBB0_1018:
	ds_read_b128 v[160:163], v152
	ds_read_b128 v[164:167], v152 offset:256
	ds_read_b128 v[168:171], v153
	ds_read_b128 v[172:175], v153 offset:256
	v_lshl_add_u64 v[224:225], s[66:67], 0, v[132:133]
	v_readfirstlane_b32 s68, v150
	v_lshl_add_u64 v[208:209], v[224:225], 0, s[16:17]
	s_mov_b32 m0, s68
	v_readfirstlane_b32 s68, v151
	ds_read_b128 v[176:179], v149
	ds_read_b128 v[180:183], v149 offset:1024
	ds_read_b128 v[184:187], v149 offset:2048
	ds_read_b128 v[188:191], v149 offset:3072
	ds_read_b128 v[192:195], v149 offset:4096
	ds_read_b128 v[196:199], v149 offset:5120
	ds_read_b128 v[200:203], v149 offset:6144
	ds_read_b128 v[204:207], v149 offset:7168
	global_load_lds_dwordx4 v[208:209], off
	v_lshl_add_u64 v[208:209], v[224:225], 0, s[18:19]
	s_mov_b32 m0, s68
	s_nop 0
	global_load_lds_dwordx4 v[208:209], off
	s_waitcnt lgkmcnt(8)
	v_readfirstlane_b32 s68, v148
	v_lshl_add_u64 v[246:247], v[226:227], 0, s[56:57]
	s_mov_b32 m0, s68
	s_nop 0
	global_load_lds_dwordx4 v[246:247], off
	ds_read_b128 v[208:211], v154
	ds_read_b128 v[212:215], v154 offset:256
	ds_read_b128 v[216:219], v155
	ds_read_b128 v[220:223], v155 offset:256
	s_waitcnt lgkmcnt(0)
	s_setprio 1
	s_barrier
	v_mfma_f32_16x16x32_bf16 v[124:127], v[160:163], v[176:179], v[124:127]
	v_mfma_f32_16x16x32_bf16 v[120:123], v[164:167], v[176:179], v[120:123]
	v_mfma_f32_16x16x32_bf16 v[116:119], v[160:163], v[184:187], v[116:119]
	v_mfma_f32_16x16x32_bf16 v[112:115], v[164:167], v[184:187], v[112:115]
	v_mfma_f32_16x16x32_bf16 v[108:111], v[160:163], v[192:195], v[108:111]
	v_mfma_f32_16x16x32_bf16 v[104:107], v[164:167], v[192:195], v[104:107]
	v_mfma_f32_16x16x32_bf16 v[100:103], v[160:163], v[200:203], v[100:103]
	v_mfma_f32_16x16x32_bf16 v[96:99], v[164:167], v[200:203], v[96:99]
	v_mfma_f32_16x16x32_bf16 v[124:127], v[168:171], v[180:183], v[124:127]
	v_mfma_f32_16x16x32_bf16 v[120:123], v[172:175], v[180:183], v[120:123]
	v_mfma_f32_16x16x32_bf16 v[116:119], v[168:171], v[188:191], v[116:119]
	v_mfma_f32_16x16x32_bf16 v[112:115], v[172:175], v[188:191], v[112:115]
	v_mfma_f32_16x16x32_bf16 v[108:111], v[168:171], v[196:199], v[108:111]
	v_mfma_f32_16x16x32_bf16 v[104:107], v[172:175], v[196:199], v[104:107]
	v_mfma_f32_16x16x32_bf16 v[100:103], v[168:171], v[204:207], v[100:103]
	v_mfma_f32_16x16x32_bf16 v[96:99], v[172:175], v[204:207], v[96:99]
	v_mfma_f32_16x16x32_bf16 v[92:95], v[208:211], v[176:179], v[92:95]
	v_mfma_f32_16x16x32_bf16 v[88:91], v[212:215], v[176:179], v[88:91]
	v_mfma_f32_16x16x32_bf16 v[84:87], v[208:211], v[184:187], v[84:87]
	v_mfma_f32_16x16x32_bf16 v[80:83], v[212:215], v[184:187], v[80:83]
	v_mfma_f32_16x16x32_bf16 v[76:79], v[208:211], v[192:195], v[76:79]
	v_mfma_f32_16x16x32_bf16 v[72:75], v[212:215], v[192:195], v[72:75]
	v_mfma_f32_16x16x32_bf16 v[68:71], v[208:211], v[200:203], v[68:71]
	v_mfma_f32_16x16x32_bf16 v[64:67], v[212:215], v[200:203], v[64:67]
	v_mfma_f32_16x16x32_bf16 v[92:95], v[216:219], v[180:183], v[92:95]
	v_mfma_f32_16x16x32_bf16 v[88:91], v[220:223], v[180:183], v[88:91]
	v_mfma_f32_16x16x32_bf16 v[84:87], v[216:219], v[188:191], v[84:87]
	v_mfma_f32_16x16x32_bf16 v[80:83], v[220:223], v[188:191], v[80:83]
	v_mfma_f32_16x16x32_bf16 v[76:79], v[216:219], v[196:199], v[76:79]
	v_mfma_f32_16x16x32_bf16 v[72:75], v[220:223], v[196:199], v[72:75]
	v_mfma_f32_16x16x32_bf16 v[68:71], v[216:219], v[204:207], v[68:71]
	v_mfma_f32_16x16x32_bf16 v[64:67], v[220:223], v[204:207], v[64:67]
	s_barrier
	s_setprio 0
	v_lshl_add_u64 v[226:227], s[64:65], 0, v[132:133]
	v_readfirstlane_b32 s68, v135
	v_lshl_add_u64 v[228:229], v[226:227], 0, s[20:21]
	s_mov_b32 m0, s68
	v_readfirstlane_b32 s68, v136
	global_load_lds_dwordx4 v[228:229], off
	v_lshl_add_u64 v[228:229], v[226:227], 0, s[22:23]
	s_mov_b32 m0, s68
	s_nop 0
	global_load_lds_dwordx4 v[228:229], off
	v_readfirstlane_b32 s68, v137
	v_lshl_add_u64 v[228:229], v[224:225], 0, s[24:25]
	s_mov_b32 m0, s68
	v_readfirstlane_b32 s68, v138
	ds_read_b128 v[176:179], v149 offset:16384
	ds_read_b128 v[180:183], v149 offset:17408
	ds_read_b128 v[184:187], v149 offset:18432
	ds_read_b128 v[188:191], v149 offset:19456
	ds_read_b128 v[192:195], v149 offset:20480
	ds_read_b128 v[196:199], v149 offset:21504
	ds_read_b128 v[200:203], v149 offset:22528
	ds_read_b128 v[204:207], v149 offset:23552
	global_load_lds_dwordx4 v[228:229], off
	v_lshl_add_u64 v[228:229], v[224:225], 0, s[26:27]
	s_mov_b32 m0, s68
	s_nop 0
	global_load_lds_dwordx4 v[228:229], off
	v_readfirstlane_b32 s68, v139
	v_lshl_add_u64 v[246:247], v[226:227], 0, s[28:29]
	s_mov_b32 m0, s68
	v_readfirstlane_b32 s68, v140
	global_load_lds_dwordx4 v[246:247], off
	s_waitcnt vmcnt(5)
	s_waitcnt lgkmcnt(0)
	s_setprio 1
	s_barrier
; #define STAGE(P, BASE, br, kt) do { const char* _gb = (const char*)(BASE) + ((size_t)(br) * K + (size_t)(kt) * BK) * 2; \
;     __builtin_amdgcn_global_load_lds((const unsigned*)(_gb + loff0), (unsigned*)((char*)(P) + tid * 16), 16, 0, 0); \
;     __builtin_amdgcn_global_load_lds((const unsigned*)(_gb + (size_t)K * 128 + loff0), (unsigned*)((char*)(P) + tid * 16 + 8192), 16, 0, 0); } while (0)
; #define LDA(dst, b, h) for (int m = 0; m < 4; ++m) { \
;     dst[m][0] = *reinterpret_cast<const bf16x8*>((char*)SA(b, h) + aoff0 + m * 2048); \
;     dst[m][1] = *reinterpret_cast<const bf16x8*>((char*)SA(b, h) + aoff1 + m * 2048); }
; #define LDB(dst, b, h) for (int n = 0; n < 2; ++n) { \
;     dst[n][0] = *reinterpret_cast<const bf16x8*>((char*)SB(b, h) + boff0 + n * 256); \
;     dst[n][1] = *reinterpret_cast<const bf16x8*>((char*)SB(b, h) + boff1 + n * 256); }
; #define MMA(ai, bj, At, Btf) do { __builtin_amdgcn_s_setprio(1); \
;     for (int m = 0; m < 4; ++m) for (int n = 0; n < 2; ++n) for (int k = 0; k < 2; ++k) \
;       acc[ai][bj][m][n] = __builtin_amdgcn_mfma_f32_16x16x32_bf16(Btf[n][k], At[m][k], acc[ai][bj][m][n], 0, 0, 0); \
;     __builtin_amdgcn_s_setprio(0); } while (0)
; #define WAIT_V(n) asm volatile("s_waitcnt vmcnt(" #n ")" ::: "memory")
; #define WAIT_L(n) asm volatile("s_waitcnt lgkmcnt(" #n ")" ::: "memory")
; #define BAR __builtin_amdgcn_s_barrier()
; #define SCHED __builtin_amdgcn_sched_barrier(0)
; template <int EPI> ...
;     ...
;     BAR; WAIT_L(0); MMA(1, 0, At, B0); BAR; SCHED;
;     STAGE(SB(0, 1), Bt, bcol + HALF, t + 2);
;     WAIT_V(6); BAR; MMA(1, 1, At, B1); BAR;
;     LDB(B0, 1, 0); SCHED; LDA(At, 1, 0); STAGE(SA(0, 1), A, brow + HALF, t + 2);
;     WAIT_L(8); BAR; WAIT_L(0); MMA(0, 0, At, B0); BAR; SCHED;
;     LDB(B1, 1, 1); STAGE(SB(1, 0), Bt, bcol, t + 3);
;     BAR; WAIT_L(0); MMA(0, 1, At, B1); BAR;
	v_mfma_f32_16x16x32_bf16 v[60:63], v[160:163], v[176:179], v[60:63]
	v_mfma_f32_16x16x32_bf16 v[56:59], v[164:167], v[176:179], v[56:59]
	v_mfma_f32_16x16x32_bf16 v[52:55], v[160:163], v[184:187], v[52:55]
	v_mfma_f32_16x16x32_bf16 v[48:51], v[164:167], v[184:187], v[48:51]
	v_mfma_f32_16x16x32_bf16 v[44:47], v[160:163], v[192:195], v[44:47]
	v_mfma_f32_16x16x32_bf16 v[40:43], v[164:167], v[192:195], v[40:43]
	v_mfma_f32_16x16x32_bf16 v[36:39], v[160:163], v[200:203], v[36:39]
	v_mfma_f32_16x16x32_bf16 v[32:35], v[164:167], v[200:203], v[32:35]
	v_mfma_f32_16x16x32_bf16 v[60:63], v[168:171], v[180:183], v[60:63]
	v_mfma_f32_16x16x32_bf16 v[56:59], v[172:175], v[180:183], v[56:59]
	v_mfma_f32_16x16x32_bf16 v[52:55], v[168:171], v[188:191], v[52:55]
	v_mfma_f32_16x16x32_bf16 v[48:51], v[172:175], v[188:191], v[48:51]
	v_mfma_f32_16x16x32_bf16 v[44:47], v[168:171], v[196:199], v[44:47]
	v_mfma_f32_16x16x32_bf16 v[40:43], v[172:175], v[196:199], v[40:43]
	v_mfma_f32_16x16x32_bf16 v[36:39], v[168:171], v[204:207], v[36:39]
	v_mfma_f32_16x16x32_bf16 v[32:35], v[172:175], v[204:207], v[32:35]
	v_mfma_f32_16x16x32_bf16 v[28:31], v[208:211], v[176:179], v[28:31]
	v_mfma_f32_16x16x32_bf16 v[24:27], v[212:215], v[176:179], v[24:27]
	v_mfma_f32_16x16x32_bf16 v[20:23], v[208:211], v[184:187], v[20:23]
	v_mfma_f32_16x16x32_bf16 v[16:19], v[212:215], v[184:187], v[16:19]
	v_mfma_f32_16x16x32_bf16 v[12:15], v[208:211], v[192:195], v[12:15]
	v_mfma_f32_16x16x32_bf16 v[8:11], v[212:215], v[192:195], v[8:11]
	v_mfma_f32_16x16x32_bf16 v[4:7], v[208:211], v[200:203], v[4:7]
	v_mfma_f32_16x16x32_bf16 v[0:3], v[212:215], v[200:203], v[0:3]
	v_mfma_f32_16x16x32_bf16 v[28:31], v[216:219], v[180:183], v[28:31]
	v_mfma_f32_16x16x32_bf16 v[24:27], v[220:223], v[180:183], v[24:27]
	v_mfma_f32_16x16x32_bf16 v[20:23], v[216:219], v[188:191], v[20:23]
	v_mfma_f32_16x16x32_bf16 v[16:19], v[220:223], v[188:191], v[16:19]
	v_mfma_f32_16x16x32_bf16 v[12:15], v[216:219], v[196:199], v[12:15]
	v_mfma_f32_16x16x32_bf16 v[8:11], v[220:223], v[196:199], v[8:11]
	v_mfma_f32_16x16x32_bf16 v[4:7], v[216:219], v[204:207], v[4:7]
	v_mfma_f32_16x16x32_bf16 v[0:3], v[220:223], v[204:207], v[0:3]
	s_barrier
	s_setprio 0
	ds_read_b128 v[160:163], v156
	ds_read_b128 v[164:167], v156 offset:256
	ds_read_b128 v[168:171], v157
	ds_read_b128 v[172:175], v157 offset:256
	v_readfirstlane_b32 s68, v141
	v_lshl_add_u64 v[208:209], v[224:225], 0, s[36:37]
	s_mov_b32 m0, s68
	v_readfirstlane_b32 s68, v142
	ds_read_b128 v[176:179], v149 offset:32768
	ds_read_b128 v[180:183], v149 offset:33792
	ds_read_b128 v[184:187], v149 offset:34816
	ds_read_b128 v[188:191], v149 offset:35840
	ds_read_b128 v[192:195], v149 offset:36864
	ds_read_b128 v[196:199], v149 offset:37888
	ds_read_b128 v[200:203], v149 offset:38912
	ds_read_b128 v[204:207], v149 offset:39936
	global_load_lds_dwordx4 v[208:209], off
	v_lshl_add_u64 v[208:209], v[224:225], 0, s[38:39]
	s_mov_b32 m0, s68
	s_nop 0
	global_load_lds_dwordx4 v[208:209], off
	s_waitcnt lgkmcnt(8)
	v_readfirstlane_b32 s68, v140
	v_lshl_add_u64 v[246:247], v[226:227], 0, s[30:31]
	s_mov_b32 m0, s68
	s_nop 0
	global_load_lds_dwordx4 v[246:247], off
	ds_read_b128 v[208:211], v158
	ds_read_b128 v[212:215], v158 offset:256
	ds_read_b128 v[216:219], v159
	ds_read_b128 v[220:223], v159 offset:256
	s_waitcnt lgkmcnt(0)
	s_setprio 1
	s_barrier
	v_mfma_f32_16x16x32_bf16 v[124:127], v[160:163], v[176:179], v[124:127]
	v_mfma_f32_16x16x32_bf16 v[120:123], v[164:167], v[176:179], v[120:123]
	v_mfma_f32_16x16x32_bf16 v[116:119], v[160:163], v[184:187], v[116:119]
	v_mfma_f32_16x16x32_bf16 v[112:115], v[164:167], v[184:187], v[112:115]
	v_mfma_f32_16x16x32_bf16 v[108:111], v[160:163], v[192:195], v[108:111]
	v_mfma_f32_16x16x32_bf16 v[104:107], v[164:167], v[192:195], v[104:107]
	v_mfma_f32_16x16x32_bf16 v[100:103], v[160:163], v[200:203], v[100:103]
	v_mfma_f32_16x16x32_bf16 v[96:99], v[164:167], v[200:203], v[96:99]
	v_mfma_f32_16x16x32_bf16 v[124:127], v[168:171], v[180:183], v[124:127]
	v_mfma_f32_16x16x32_bf16 v[120:123], v[172:175], v[180:183], v[120:123]
	v_mfma_f32_16x16x32_bf16 v[116:119], v[168:171], v[188:191], v[116:119]
	v_mfma_f32_16x16x32_bf16 v[112:115], v[172:175], v[188:191], v[112:115]
	v_mfma_f32_16x16x32_bf16 v[108:111], v[168:171], v[196:199], v[108:111]
	v_mfma_f32_16x16x32_bf16 v[104:107], v[172:175], v[196:199], v[104:107]
	v_mfma_f32_16x16x32_bf16 v[100:103], v[168:171], v[204:207], v[100:103]
	v_mfma_f32_16x16x32_bf16 v[96:99], v[172:175], v[204:207], v[96:99]
	v_mfma_f32_16x16x32_bf16 v[92:95], v[208:211], v[176:179], v[92:95]
	v_mfma_f32_16x16x32_bf16 v[88:91], v[212:215], v[176:179], v[88:91]
	v_mfma_f32_16x16x32_bf16 v[84:87], v[208:211], v[184:187], v[84:87]
	v_mfma_f32_16x16x32_bf16 v[80:83], v[212:215], v[184:187], v[80:83]
	v_mfma_f32_16x16x32_bf16 v[76:79], v[208:211], v[192:195], v[76:79]
	v_mfma_f32_16x16x32_bf16 v[72:75], v[212:215], v[192:195], v[72:75]
	v_mfma_f32_16x16x32_bf16 v[68:71], v[208:211], v[200:203], v[68:71]
	v_mfma_f32_16x16x32_bf16 v[64:67], v[212:215], v[200:203], v[64:67]
	v_mfma_f32_16x16x32_bf16 v[92:95], v[216:219], v[180:183], v[92:95]
	v_mfma_f32_16x16x32_bf16 v[88:91], v[220:223], v[180:183], v[88:91]
	v_mfma_f32_16x16x32_bf16 v[84:87], v[216:219], v[188:191], v[84:87]
	v_mfma_f32_16x16x32_bf16 v[80:83], v[220:223], v[188:191], v[80:83]
	v_mfma_f32_16x16x32_bf16 v[76:79], v[216:219], v[196:199], v[76:79]
	v_mfma_f32_16x16x32_bf16 v[72:75], v[220:223], v[196:199], v[72:75]
	v_mfma_f32_16x16x32_bf16 v[68:71], v[216:219], v[204:207], v[68:71]
	v_mfma_f32_16x16x32_bf16 v[64:67], v[220:223], v[204:207], v[64:67]
	s_barrier
; #define STAGE(P, BASE, br, kt) do { const char* _gb = (const char*)(BASE) + ((size_t)(br) * K + (size_t)(kt) * BK) * 2; \
;     __builtin_amdgcn_global_load_lds((const unsigned*)(_gb + loff0), (unsigned*)((char*)(P) + tid * 16), 16, 0, 0); \
;     __builtin_amdgcn_global_load_lds((const unsigned*)(_gb + (size_t)K * 128 + loff0), (unsigned*)((char*)(P) + tid * 16 + 8192), 16, 0, 0); } while (0)
; #define LDA(dst, b, h) for (int m = 0; m < 4; ++m) { \
;     dst[m][0] = *reinterpret_cast<const bf16x8*>((char*)SA(b, h) + aoff0 + m * 2048); \
;     dst[m][1] = *reinterpret_cast<const bf16x8*>((char*)SA(b, h) + aoff1 + m * 2048); }
; #define LDB(dst, b, h) for (int n = 0; n < 2; ++n) { \
;     dst[n][0] = *reinterpret_cast<const bf16x8*>((char*)SB(b, h) + boff0 + n * 256); \
;     dst[n][1] = *reinterpret_cast<const bf16x8*>((char*)SB(b, h) + boff1 + n * 256); }
; #define MMA(ai, bj, At, Btf) do { __builtin_amdgcn_s_setprio(1); \
;     for (int m = 0; m < 4; ++m) for (int n = 0; n < 2; ++n) for (int k = 0; k < 2; ++k) \
;       acc[ai][bj][m][n] = __builtin_amdgcn_mfma_f32_16x16x32_bf16(Btf[n][k], At[m][k], acc[ai][bj][m][n], 0, 0, 0); \
;     __builtin_amdgcn_s_setprio(0); } while (0)
; #define WAIT_V(n) asm volatile("s_waitcnt vmcnt(" #n ")" ::: "memory")
; #define WAIT_L(n) asm volatile("s_waitcnt lgkmcnt(" #n ")" ::: "memory")
; #define BAR __builtin_amdgcn_s_barrier()
; #define SCHED __builtin_amdgcn_sched_barrier(0)
; template <int EPI> ...
;     ...
;     LDA(At, 1, 1); STAGE(SA(1, 0), A, brow, t + 3);
;     BAR; WAIT_L(0); MMA(1, 0, At, B0); BAR; SCHED;
;     STAGE(SB(1, 1), Bt, bcol + HALF, t + 3);
;     WAIT_V(6); BAR; MMA(1, 1, At, B1); BAR;
;   }
;   { LDB(B0, 0, 0); LDA(At, 0, 0); STAGE(SA(1, 1), A, brow + HALF, nt - 1);
;     BAR; WAIT_L(0); MMA(0, 0, At, B0); BAR;
	s_setprio 0
	v_readfirstlane_b32 s68, v143
	v_lshl_add_u64 v[228:229], v[226:227], 0, s[46:47]
	s_mov_b32 m0, s68
	v_readfirstlane_b32 s68, v144
	global_load_lds_dwordx4 v[228:229], off
	v_lshl_add_u64 v[228:229], v[226:227], 0, s[48:49]
	s_mov_b32 m0, s68
	s_nop 0
	global_load_lds_dwordx4 v[228:229], off
	v_readfirstlane_b32 s68, v145
	v_lshl_add_u64 v[228:229], v[224:225], 0, s[50:51]
	s_mov_b32 m0, s68
	v_readfirstlane_b32 s68, v146
	ds_read_b128 v[176:179], v149 offset:49152
	ds_read_b128 v[180:183], v149 offset:50176
	ds_read_b128 v[184:187], v149 offset:51200
	ds_read_b128 v[188:191], v149 offset:52224
	ds_read_b128 v[192:195], v149 offset:53248
	ds_read_b128 v[196:199], v149 offset:54272
	ds_read_b128 v[200:203], v149 offset:55296
	ds_read_b128 v[204:207], v149 offset:56320
	global_load_lds_dwordx4 v[228:229], off
	v_lshl_add_u64 v[224:225], v[224:225], 0, s[52:53]
	s_mov_b32 m0, s68
	s_nop 0
	global_load_lds_dwordx4 v[224:225], off
	v_readfirstlane_b32 s68, v147
	v_lshl_add_u64 v[246:247], v[226:227], 0, s[54:55]
	s_mov_b32 m0, s68
	v_readfirstlane_b32 s68, v148
	global_load_lds_dwordx4 v[246:247], off
	s_waitcnt vmcnt(5)
	s_barrier
	s_waitcnt lgkmcnt(0)
	s_setprio 1
	s_waitcnt lgkmcnt(0)
	v_mfma_f32_16x16x32_bf16 v[60:63], v[160:163], v[176:179], v[60:63]
	v_mfma_f32_16x16x32_bf16 v[56:59], v[164:167], v[176:179], v[56:59]
	v_mfma_f32_16x16x32_bf16 v[52:55], v[160:163], v[184:187], v[52:55]
	v_mfma_f32_16x16x32_bf16 v[48:51], v[164:167], v[184:187], v[48:51]
	v_mfma_f32_16x16x32_bf16 v[44:47], v[160:163], v[192:195], v[44:47]
	v_mfma_f32_16x16x32_bf16 v[40:43], v[164:167], v[192:195], v[40:43]
	v_mfma_f32_16x16x32_bf16 v[36:39], v[160:163], v[200:203], v[36:39]
	v_mfma_f32_16x16x32_bf16 v[32:35], v[164:167], v[200:203], v[32:35]
	v_mfma_f32_16x16x32_bf16 v[60:63], v[168:171], v[180:183], v[60:63]
	v_mfma_f32_16x16x32_bf16 v[56:59], v[172:175], v[180:183], v[56:59]
	v_mfma_f32_16x16x32_bf16 v[52:55], v[168:171], v[188:191], v[52:55]
	v_mfma_f32_16x16x32_bf16 v[48:51], v[172:175], v[188:191], v[48:51]
	v_mfma_f32_16x16x32_bf16 v[44:47], v[168:171], v[196:199], v[44:47]
	v_mfma_f32_16x16x32_bf16 v[40:43], v[172:175], v[196:199], v[40:43]
	v_mfma_f32_16x16x32_bf16 v[36:39], v[168:171], v[204:207], v[36:39]
	v_mfma_f32_16x16x32_bf16 v[32:35], v[172:175], v[204:207], v[32:35]
	s_setprio 0
	s_setprio 1
	v_mfma_f32_16x16x32_bf16 v[28:31], v[208:211], v[176:179], v[28:31]
	v_mfma_f32_16x16x32_bf16 v[24:27], v[212:215], v[176:179], v[24:27]
	v_mfma_f32_16x16x32_bf16 v[20:23], v[208:211], v[184:187], v[20:23]
	v_mfma_f32_16x16x32_bf16 v[16:19], v[212:215], v[184:187], v[16:19]
	v_mfma_f32_16x16x32_bf16 v[12:15], v[208:211], v[192:195], v[12:15]
	v_mfma_f32_16x16x32_bf16 v[8:11], v[212:215], v[192:195], v[8:11]
	v_mfma_f32_16x16x32_bf16 v[4:7], v[208:211], v[200:203], v[4:7]
	v_mfma_f32_16x16x32_bf16 v[0:3], v[212:215], v[200:203], v[0:3]
	v_mfma_f32_16x16x32_bf16 v[28:31], v[216:219], v[180:183], v[28:31]
	v_mfma_f32_16x16x32_bf16 v[24:27], v[220:223], v[180:183], v[24:27]
	v_mfma_f32_16x16x32_bf16 v[20:23], v[216:219], v[188:191], v[20:23]
	v_mfma_f32_16x16x32_bf16 v[16:19], v[220:223], v[188:191], v[16:19]
	v_mfma_f32_16x16x32_bf16 v[12:15], v[216:219], v[196:199], v[12:15]
	v_mfma_f32_16x16x32_bf16 v[8:11], v[220:223], v[196:199], v[8:11]
	v_mfma_f32_16x16x32_bf16 v[4:7], v[216:219], v[204:207], v[4:7]
	v_mfma_f32_16x16x32_bf16 v[0:3], v[220:223], v[204:207], v[0:3]
	s_setprio 0
	s_add_i32 s59, s59, 2
	s_add_u32 s64, s64, 0x100
	s_addc_u32 s65, s65, 0
	s_add_u32 s66, s66, 0x100
	s_addc_u32 s67, s67, 0
	s_cmp_lt_u32 s59, 28
	s_barrier
	s_cbranch_scc1 .LBB0_1018
	v_readfirstlane_b32 s68, v148
	v_lshl_add_u64 v[246:247], v[226:227], 0, s[56:57]
	s_mov_b32 m0, s68
	s_nop 0
	global_load_lds_dwordx4 v[246:247], off
	s_add_u32 s62, s72, s62
	s_addc_u32 s63, s73, s63
	v_readfirstlane_b32 s59, v150
	v_lshl_add_u64 v[208:209], s[62:63], 0, v[128:129]
	s_mov_b32 m0, s59
	v_readfirstlane_b32 s59, v151
	ds_read_b128 v[160:163], v152
	ds_read_b128 v[164:167], v152 offset:256
	ds_read_b128 v[168:171], v153
	ds_read_b128 v[172:175], v153 offset:256
	ds_read_b128 v[176:179], v149
	ds_read_b128 v[180:183], v149 offset:1024
	ds_read_b128 v[184:187], v149 offset:2048
	ds_read_b128 v[188:191], v149 offset:3072
	ds_read_b128 v[192:195], v149 offset:4096
	ds_read_b128 v[196:199], v149 offset:5120
	ds_read_b128 v[200:203], v149 offset:6144
	ds_read_b128 v[204:207], v149 offset:7168
	global_load_lds_dwordx4 v[208:209], off
	v_lshl_add_u64 v[208:209], v[208:209], 0, s[8:9]
	s_mov_b32 m0, s59
	s_nop 0
	global_load_lds_dwordx4 v[208:209], off
	s_waitcnt lgkmcnt(0)
	s_setprio 1
	s_barrier
	v_mfma_f32_16x16x32_bf16 v[124:127], v[160:163], v[176:179], v[124:127]
	v_mfma_f32_16x16x32_bf16 v[116:119], v[160:163], v[184:187], v[116:119]
	v_mfma_f32_16x16x32_bf16 v[108:111], v[160:163], v[192:195], v[108:111]
	v_mfma_f32_16x16x32_bf16 v[100:103], v[160:163], v[200:203], v[100:103]
	v_mfma_f32_16x16x32_bf16 v[96:99], v[164:167], v[200:203], v[96:99]
	v_mfma_f32_16x16x32_bf16 v[124:127], v[168:171], v[180:183], v[124:127]
	v_mfma_f32_16x16x32_bf16 v[120:123], v[164:167], v[176:179], v[120:123]
	v_mfma_f32_16x16x32_bf16 v[116:119], v[168:171], v[188:191], v[116:119]
	v_mfma_f32_16x16x32_bf16 v[112:115], v[164:167], v[184:187], v[112:115]
	v_mfma_f32_16x16x32_bf16 v[108:111], v[168:171], v[196:199], v[108:111]
	v_mfma_f32_16x16x32_bf16 v[104:107], v[164:167], v[192:195], v[104:107]
	v_mfma_f32_16x16x32_bf16 v[100:103], v[168:171], v[204:207], v[100:103]
	v_mfma_f32_16x16x32_bf16 v[96:99], v[172:175], v[204:207], v[96:99]
	v_mfma_f32_16x16x32_bf16 v[208:211], v[172:175], v[180:183], v[120:123]
	v_mfma_f32_16x16x32_bf16 v[212:215], v[172:175], v[188:191], v[112:115]
	v_mfma_f32_16x16x32_bf16 v[216:219], v[172:175], v[196:199], v[104:107]
	s_barrier
; #define LDA(dst, b, h) for (int m = 0; m < 4; ++m) { \
;     dst[m][0] = *reinterpret_cast<const bf16x8*>((char*)SA(b, h) + aoff0 + m * 2048); \
;     dst[m][1] = *reinterpret_cast<const bf16x8*>((char*)SA(b, h) + aoff1 + m * 2048); }
; #define LDB(dst, b, h) for (int n = 0; n < 2; ++n) { \
;     dst[n][0] = *reinterpret_cast<const bf16x8*>((char*)SB(b, h) + boff0 + n * 256); \
;     dst[n][1] = *reinterpret_cast<const bf16x8*>((char*)SB(b, h) + boff1 + n * 256); }
; #define MMA(ai, bj, At, Btf) do { __builtin_amdgcn_s_setprio(1); \
;     for (int m = 0; m < 4; ++m) for (int n = 0; n < 2; ++n) for (int k = 0; k < 2; ++k) \
;       acc[ai][bj][m][n] = __builtin_amdgcn_mfma_f32_16x16x32_bf16(Btf[n][k], At[m][k], acc[ai][bj][m][n], 0, 0, 0); \
;     __builtin_amdgcn_s_setprio(0); } while (0)
; #define WAIT_V(n) asm volatile("s_waitcnt vmcnt(" #n ")" ::: "memory")
; #define WAIT_L(n) asm volatile("s_waitcnt lgkmcnt(" #n ")" ::: "memory")
; #define BAR __builtin_amdgcn_s_barrier()
; template <int EPI> ...
;     ...
;     LDB(B1, 0, 1); BAR; WAIT_L(0); MMA(0, 1, At, B1); BAR;
;     LDA(At, 0, 1); WAIT_V(4); BAR; WAIT_L(0); MMA(1, 0, At, B0); MMA(1, 1, At, B1); BAR; }
;   { LDB(B0, 1, 0); LDA(At, 1, 0); WAIT_V(2); BAR; WAIT_L(0); MMA(0, 0, At, B0); BAR;
	s_setprio 0
	s_nop 0
	ds_read_b128 v[104:107], v154
	ds_read_b128 v[112:115], v154 offset:256
	ds_read_b128 v[120:123], v155
	ds_read_b128 v[220:223], v155 offset:256
	s_waitcnt lgkmcnt(0)
	s_setprio 1
	s_barrier
	v_mfma_f32_16x16x32_bf16 v[84:87], v[104:107], v[184:187], v[84:87]
	v_mfma_f32_16x16x32_bf16 v[76:79], v[104:107], v[192:195], v[76:79]
	v_mfma_f32_16x16x32_bf16 v[72:75], v[112:115], v[192:195], v[72:75]
	v_mfma_f32_16x16x32_bf16 v[92:95], v[104:107], v[176:179], v[92:95]
	v_mfma_f32_16x16x32_bf16 v[88:91], v[112:115], v[176:179], v[88:91]
	v_mfma_f32_16x16x32_bf16 v[84:87], v[120:123], v[188:191], v[84:87]
	v_mfma_f32_16x16x32_bf16 v[80:83], v[112:115], v[184:187], v[80:83]
	v_mfma_f32_16x16x32_bf16 v[76:79], v[120:123], v[196:199], v[76:79]
	v_mfma_f32_16x16x32_bf16 v[72:75], v[220:223], v[196:199], v[72:75]
	v_mfma_f32_16x16x32_bf16 v[68:71], v[104:107], v[200:203], v[68:71]
	v_mfma_f32_16x16x32_bf16 v[64:67], v[112:115], v[200:203], v[64:67]
	v_mfma_f32_16x16x32_bf16 v[224:227], v[120:123], v[180:183], v[92:95]
	v_mfma_f32_16x16x32_bf16 v[176:179], v[220:223], v[180:183], v[88:91]
	v_mfma_f32_16x16x32_bf16 v[180:183], v[220:223], v[188:191], v[80:83]
	v_mfma_f32_16x16x32_bf16 v[184:187], v[120:123], v[204:207], v[68:71]
	v_mfma_f32_16x16x32_bf16 v[188:191], v[220:223], v[204:207], v[64:67]
	s_barrier
	s_setprio 0
	s_nop 0
	ds_read_b128 v[64:67], v149 offset:16384
	ds_read_b128 v[68:71], v149 offset:17408
	ds_read_b128 v[80:83], v149 offset:18432
	ds_read_b128 v[88:91], v149 offset:19456
	ds_read_b128 v[92:95], v149 offset:20480
	ds_read_b128 v[192:195], v149 offset:21504
	ds_read_b128 v[196:199], v149 offset:22528
	ds_read_b128 v[200:203], v149 offset:23552
	s_waitcnt vmcnt(4)
	s_waitcnt lgkmcnt(0)
	s_setprio 1
	s_barrier
	v_mfma_f32_16x16x32_bf16 v[52:55], v[160:163], v[80:83], v[52:55]
	v_mfma_f32_16x16x32_bf16 v[44:47], v[160:163], v[92:95], v[44:47]
	v_mfma_f32_16x16x32_bf16 v[36:39], v[160:163], v[196:199], v[36:39]
	v_mfma_f32_16x16x32_bf16 v[60:63], v[160:163], v[64:67], v[60:63]
	v_mfma_f32_16x16x32_bf16 v[56:59], v[164:167], v[64:67], v[56:59]
	v_mfma_f32_16x16x32_bf16 v[52:55], v[168:171], v[88:91], v[52:55]
	v_mfma_f32_16x16x32_bf16 v[48:51], v[164:167], v[80:83], v[48:51]
	v_mfma_f32_16x16x32_bf16 v[44:47], v[168:171], v[192:195], v[44:47]
	v_mfma_f32_16x16x32_bf16 v[40:43], v[164:167], v[92:95], v[40:43]
	v_mfma_f32_16x16x32_bf16 v[36:39], v[168:171], v[200:203], v[36:39]
	v_mfma_f32_16x16x32_bf16 v[32:35], v[164:167], v[196:199], v[32:35]
	v_mfma_f32_16x16x32_bf16 v[204:207], v[168:171], v[68:71], v[60:63]
	v_mfma_f32_16x16x32_bf16 v[228:231], v[172:175], v[68:71], v[56:59]
	v_mfma_f32_16x16x32_bf16 v[232:235], v[172:175], v[88:91], v[48:51]
	v_mfma_f32_16x16x32_bf16 v[236:239], v[172:175], v[192:195], v[40:43]
	v_mfma_f32_16x16x32_bf16 v[160:163], v[172:175], v[200:203], v[32:35]
	v_mfma_f32_16x16x32_bf16 v[28:31], v[104:107], v[64:67], v[28:31]
	v_mfma_f32_16x16x32_bf16 v[20:23], v[104:107], v[80:83], v[20:23]
	v_mfma_f32_16x16x32_bf16 v[12:15], v[104:107], v[92:95], v[12:15]
	v_mfma_f32_16x16x32_bf16 v[4:7], v[104:107], v[196:199], v[4:7]
	v_mfma_f32_16x16x32_bf16 v[28:31], v[120:123], v[68:71], v[28:31]
	v_mfma_f32_16x16x32_bf16 v[24:27], v[112:115], v[64:67], v[24:27]
	v_mfma_f32_16x16x32_bf16 v[20:23], v[120:123], v[88:91], v[20:23]
	v_mfma_f32_16x16x32_bf16 v[16:19], v[112:115], v[80:83], v[16:19]
	v_mfma_f32_16x16x32_bf16 v[12:15], v[120:123], v[192:195], v[12:15]
	v_mfma_f32_16x16x32_bf16 v[8:11], v[112:115], v[92:95], v[8:11]
	v_mfma_f32_16x16x32_bf16 v[4:7], v[120:123], v[200:203], v[4:7]
	v_mfma_f32_16x16x32_bf16 v[0:3], v[112:115], v[196:199], v[0:3]
	v_mfma_f32_16x16x32_bf16 v[164:167], v[220:223], v[68:71], v[24:27]
	v_mfma_f32_16x16x32_bf16 v[168:171], v[220:223], v[88:91], v[16:19]
	v_mfma_f32_16x16x32_bf16 v[172:175], v[220:223], v[192:195], v[8:11]
	v_mfma_f32_16x16x32_bf16 v[192:195], v[220:223], v[200:203], v[0:3]
	s_barrier
	s_setprio 0
	s_nop 1
	ds_read_b128 v[0:3], v156
	ds_read_b128 v[8:11], v156 offset:256
	ds_read_b128 v[16:19], v157
	ds_read_b128 v[24:27], v157 offset:256
	ds_read_b128 v[32:35], v149 offset:32768
	ds_read_b128 v[40:43], v149 offset:33792
	ds_read_b128 v[48:51], v149 offset:34816
	ds_read_b128 v[56:59], v149 offset:35840
	ds_read_b128 v[60:63], v149 offset:36864
	ds_read_b128 v[68:71], v149 offset:37888
	ds_read_b128 v[196:199], v149 offset:38912
	ds_read_b128 v[200:203], v149 offset:39936
	s_waitcnt vmcnt(2)
	s_waitcnt lgkmcnt(0)
	s_setprio 1
	s_barrier
; #define LDA(dst, b, h) for (int m = 0; m < 4; ++m) { \
;     dst[m][0] = *reinterpret_cast<const bf16x8*>((char*)SA(b, h) + aoff0 + m * 2048); \
;     dst[m][1] = *reinterpret_cast<const bf16x8*>((char*)SA(b, h) + aoff1 + m * 2048); }
; #define LDB(dst, b, h) for (int n = 0; n < 2; ++n) { \
;     dst[n][0] = *reinterpret_cast<const bf16x8*>((char*)SB(b, h) + boff0 + n * 256); \
;     dst[n][1] = *reinterpret_cast<const bf16x8*>((char*)SB(b, h) + boff1 + n * 256); }
; #define MMA(ai, bj, At, Btf) do { __builtin_amdgcn_s_setprio(1); \
;     for (int m = 0; m < 4; ++m) for (int n = 0; n < 2; ++n) for (int k = 0; k < 2; ++k) \
;       acc[ai][bj][m][n] = __builtin_amdgcn_mfma_f32_16x16x32_bf16(Btf[n][k], At[m][k], acc[ai][bj][m][n], 0, 0, 0); \
;     __builtin_amdgcn_s_setprio(0); } while (0)
; #define WAIT_V(n) asm volatile("s_waitcnt vmcnt(" #n ")" ::: "memory")
; #define WAIT_L(n) asm volatile("s_waitcnt lgkmcnt(" #n ")" ::: "memory")
; #define BAR __builtin_amdgcn_s_barrier()
; template <int EPI> ...
;     ...
;   { LDB(B0, 1, 0); LDA(At, 1, 0); WAIT_V(2); BAR; WAIT_L(0); MMA(0, 0, At, B0); BAR;
;     LDB(B1, 1, 1); WAIT_V(0); BAR; WAIT_L(0); MMA(0, 1, At, B1); BAR;
;     LDA(At, 1, 1); BAR; WAIT_L(0); MMA(1, 0, At, B0); MMA(1, 1, At, B1); BAR; }
;   if (wr == 0) BAR;
	v_mfma_f32_16x16x32_bf16 v[64:67], v[0:3], v[32:35], v[124:127]
	v_mfma_f32_16x16x32_bf16 v[120:123], v[16:19], v[40:43], v[64:67]
	v_mfma_f32_16x16x32_bf16 v[64:67], v[8:11], v[32:35], v[208:211]
	v_mfma_f32_16x16x32_bf16 v[124:127], v[24:27], v[40:43], v[64:67]
	v_mfma_f32_16x16x32_bf16 v[64:67], v[0:3], v[48:51], v[116:119]
	v_mfma_f32_16x16x32_bf16 v[112:115], v[16:19], v[56:59], v[64:67]
	v_mfma_f32_16x16x32_bf16 v[64:67], v[8:11], v[48:51], v[212:215]
	v_mfma_f32_16x16x32_bf16 v[116:119], v[24:27], v[56:59], v[64:67]
	v_mfma_f32_16x16x32_bf16 v[64:67], v[0:3], v[60:63], v[108:111]
	v_mfma_f32_16x16x32_bf16 v[104:107], v[16:19], v[68:71], v[64:67]
	v_mfma_f32_16x16x32_bf16 v[64:67], v[8:11], v[60:63], v[216:219]
	v_mfma_f32_16x16x32_bf16 v[108:111], v[24:27], v[68:71], v[64:67]
	v_mfma_f32_16x16x32_bf16 v[64:67], v[0:3], v[196:199], v[100:103]
	v_mfma_f32_16x16x32_bf16 v[88:91], v[16:19], v[200:203], v[64:67]
	v_mfma_f32_16x16x32_bf16 v[64:67], v[8:11], v[196:199], v[96:99]
	v_mfma_f32_16x16x32_bf16 v[92:95], v[24:27], v[200:203], v[64:67]
	s_barrier
	s_setprio 0
	ds_read_b128 v[208:211], v158
	ds_read_b128 v[212:215], v158 offset:256
	ds_read_b128 v[216:219], v159
	ds_read_b128 v[220:223], v159 offset:256
	s_waitcnt vmcnt(0)
	s_waitcnt lgkmcnt(0)
	s_setprio 1
	s_barrier
	v_mfma_f32_16x16x32_bf16 v[64:67], v[208:211], v[32:35], v[224:227]
	v_mfma_f32_16x16x32_bf16 v[32:35], v[212:215], v[32:35], v[176:179]
	v_mfma_f32_16x16x32_bf16 v[100:103], v[220:223], v[40:43], v[32:35]
	v_mfma_f32_16x16x32_bf16 v[32:35], v[208:211], v[48:51], v[84:87]
	v_mfma_f32_16x16x32_bf16 v[80:83], v[216:219], v[56:59], v[32:35]
	v_mfma_f32_16x16x32_bf16 v[32:35], v[212:215], v[48:51], v[180:183]
	v_mfma_f32_16x16x32_bf16 v[84:87], v[220:223], v[56:59], v[32:35]
	v_mfma_f32_16x16x32_bf16 v[32:35], v[208:211], v[60:63], v[76:79]
	v_mfma_f32_16x16x32_bf16 v[96:99], v[216:219], v[40:43], v[64:67]
	v_mfma_f32_16x16x32_bf16 v[64:67], v[216:219], v[68:71], v[32:35]
	v_mfma_f32_16x16x32_bf16 v[32:35], v[212:215], v[60:63], v[72:75]
	v_mfma_f32_16x16x32_bf16 v[68:71], v[220:223], v[68:71], v[32:35]
	v_mfma_f32_16x16x32_bf16 v[32:35], v[208:211], v[196:199], v[184:187]
	v_mfma_f32_16x16x32_bf16 v[56:59], v[216:219], v[200:203], v[32:35]
	v_mfma_f32_16x16x32_bf16 v[32:35], v[212:215], v[196:199], v[188:191]
	v_mfma_f32_16x16x32_bf16 v[60:63], v[220:223], v[200:203], v[32:35]
	s_barrier
	s_setprio 0
	ds_read_b128 v[176:179], v149 offset:49152
	ds_read_b128 v[180:183], v149 offset:50176
	ds_read_b128 v[184:187], v149 offset:51200
	ds_read_b128 v[188:191], v149 offset:52224
	ds_read_b128 v[196:199], v149 offset:53248
	ds_read_b128 v[200:203], v149 offset:54272
	ds_read_b128 v[224:227], v149 offset:55296
	ds_read_b128 v[240:243], v149 offset:56320
	s_waitcnt lgkmcnt(0)
	s_setprio 1
	s_barrier
	v_mfma_f32_16x16x32_bf16 v[32:35], v[0:3], v[176:179], v[204:207]
	v_mfma_f32_16x16x32_bf16 v[72:75], v[16:19], v[180:183], v[32:35]
	v_mfma_f32_16x16x32_bf16 v[32:35], v[8:11], v[176:179], v[228:231]
	v_mfma_f32_16x16x32_bf16 v[76:79], v[24:27], v[180:183], v[32:35]
	v_mfma_f32_16x16x32_bf16 v[32:35], v[0:3], v[184:187], v[52:55]
	v_mfma_f32_16x16x32_bf16 v[48:51], v[16:19], v[188:191], v[32:35]
	v_mfma_f32_16x16x32_bf16 v[32:35], v[8:11], v[184:187], v[232:235]
	v_mfma_f32_16x16x32_bf16 v[52:55], v[24:27], v[188:191], v[32:35]
	v_mfma_f32_16x16x32_bf16 v[32:35], v[0:3], v[196:199], v[44:47]
	v_mfma_f32_16x16x32_bf16 v[40:43], v[16:19], v[200:203], v[32:35]
	v_mfma_f32_16x16x32_bf16 v[32:35], v[8:11], v[196:199], v[236:239]
	v_mfma_f32_16x16x32_bf16 v[0:3], v[0:3], v[224:227], v[36:39]
	v_mfma_f32_16x16x32_bf16 v[44:47], v[24:27], v[200:203], v[32:35]
	v_mfma_f32_16x16x32_bf16 v[32:35], v[16:19], v[240:243], v[0:3]
	v_mfma_f32_16x16x32_bf16 v[0:3], v[8:11], v[224:227], v[160:163]
	v_mfma_f32_16x16x32_bf16 v[36:39], v[24:27], v[240:243], v[0:3]
	v_mfma_f32_16x16x32_bf16 v[0:3], v[208:211], v[176:179], v[28:31]
	v_mfma_f32_16x16x32_bf16 v[24:27], v[216:219], v[180:183], v[0:3]
	v_mfma_f32_16x16x32_bf16 v[0:3], v[212:215], v[176:179], v[164:167]
	v_mfma_f32_16x16x32_bf16 v[28:31], v[220:223], v[180:183], v[0:3]
	v_mfma_f32_16x16x32_bf16 v[0:3], v[208:211], v[184:187], v[20:23]
	v_mfma_f32_16x16x32_bf16 v[16:19], v[216:219], v[188:191], v[0:3]
	v_mfma_f32_16x16x32_bf16 v[0:3], v[212:215], v[184:187], v[168:171]
	v_mfma_f32_16x16x32_bf16 v[20:23], v[220:223], v[188:191], v[0:3]
	v_mfma_f32_16x16x32_bf16 v[0:3], v[208:211], v[196:199], v[12:15]
	v_mfma_f32_16x16x32_bf16 v[8:11], v[216:219], v[200:203], v[0:3]
	v_mfma_f32_16x16x32_bf16 v[0:3], v[212:215], v[196:199], v[172:175]
	v_mfma_f32_16x16x32_bf16 v[12:15], v[220:223], v[200:203], v[0:3]
	v_mfma_f32_16x16x32_bf16 v[0:3], v[208:211], v[224:227], v[4:7]
	v_mfma_f32_16x16x32_bf16 v[4:7], v[212:215], v[224:227], v[192:195]
	v_mfma_f32_16x16x32_bf16 v[0:3], v[216:219], v[240:243], v[0:3]
	v_mfma_f32_16x16x32_bf16 v[4:7], v[220:223], v[240:243], v[4:7]
	s_barrier
	s_setprio 0
	s_and_saveexec_b64 s[62:63], s[2:3]
	s_cbranch_execz .LBB0_1012
	s_barrier
	s_branch .LBB0_1012

; #define STAGE(P, BASE, br, kt) do { const char* _gb = (const char*)(BASE) + ((size_t)(br) * K + (size_t)(kt) * BK) * 2; \
;     __builtin_amdgcn_global_load_lds((const unsigned*)(_gb + loff0), (unsigned*)((char*)(P) + tid * 16), 16, 0, 0); \
;     __builtin_amdgcn_global_load_lds((const unsigned*)(_gb + (size_t)K * 128 + loff0), (unsigned*)((char*)(P) + tid * 16 + 8192), 16, 0, 0); } while (0)
; #define LDA(dst, b, h) for (int m = 0; m < 4; ++m) { \
;     dst[m][0] = *reinterpret_cast<const bf16x8*>((char*)SA(b, h) + aoff0 + m * 2048); \
;     dst[m][1] = *reinterpret_cast<const bf16x8*>((char*)SA(b, h) + aoff1 + m * 2048); }
; #define LDB(dst, b, h) for (int n = 0; n < 2; ++n) { \
;     dst[n][0] = *reinterpret_cast<const bf16x8*>((char*)SB(b, h) + boff0 + n * 256); \
;     dst[n][1] = *reinterpret_cast<const bf16x8*>((char*)SB(b, h) + boff1 + n * 256); }
; #define MMA(ai, bj, At, Btf) do { __builtin_amdgcn_s_setprio(1); \
;     for (int m = 0; m < 4; ++m) for (int n = 0; n < 2; ++n) for (int k = 0; k < 2; ++k) \
;       acc[ai][bj][m][n] = __builtin_amdgcn_mfma_f32_16x16x32_bf16(Btf[n][k], At[m][k], acc[ai][bj][m][n], 0, 0, 0); \
;     __builtin_amdgcn_s_setprio(0); } while (0)
; #define WAIT_V(n) asm volatile("s_waitcnt vmcnt(" #n ")" ::: "memory")
; #define WAIT_L(n) asm volatile("s_waitcnt lgkmcnt(" #n ")" ::: "memory")
; #define BAR __builtin_amdgcn_s_barrier()
; #define SCHED __builtin_amdgcn_sched_barrier(0)
; template <int EPI> ...
;     ...
;     LDB(B0, 0, 0); SCHED; LDA(At, 0, 0); STAGE(SA(1, 1), A, brow + HALF, t + 1);
;     WAIT_L(8); BAR; WAIT_L(0); MMA(0, 0, At, B0); BAR; SCHED;
;     LDB(B1, 0, 1); STAGE(SB(0, 0), Bt, bcol, t + 2);
;     BAR; WAIT_L(0); MMA(0, 1, At, B1); BAR;
;     LDA(At, 0, 1); STAGE(SA(0, 0), A, brow, t + 2);
;     BAR; WAIT_L(0); MMA(1, 0, At, B0); BAR; SCHED;
;     STAGE(SB(0, 1), Bt, bcol + HALF, t + 2);
;     WAIT_V(6); BAR; MMA(1, 1, At, B1); BAR;
.LBB0_1105:
	ds_read_b128 v[162:165], v153
	ds_read_b128 v[166:169], v153 offset:256
	ds_read_b128 v[170:173], v154
	ds_read_b128 v[174:177], v154 offset:256
	v_lshl_add_u64 v[226:227], s[66:67], 0, v[130:131]
	v_readfirstlane_b32 s70, v151
	v_lshl_add_u64 v[210:211], v[226:227], 0, s[18:19]
	s_mov_b32 m0, s70
	v_readfirstlane_b32 s70, v152
	ds_read_b128 v[178:181], v150
	ds_read_b128 v[182:185], v150 offset:1024
	ds_read_b128 v[186:189], v150 offset:2048
	ds_read_b128 v[190:193], v150 offset:3072
	ds_read_b128 v[194:197], v150 offset:4096
	ds_read_b128 v[198:201], v150 offset:5120
	ds_read_b128 v[202:205], v150 offset:6144
	ds_read_b128 v[206:209], v150 offset:7168
	global_load_lds_dwordx4 v[210:211], off
	v_lshl_add_u64 v[210:211], v[226:227], 0, s[20:21]
	s_mov_b32 m0, s70
	s_nop 0
	global_load_lds_dwordx4 v[210:211], off
	s_waitcnt lgkmcnt(8)
	v_readfirstlane_b32 s70, v149
	v_lshl_add_u64 v[246:247], v[228:229], 0, s[58:59]
	s_mov_b32 m0, s70
	s_nop 0
	global_load_lds_dwordx4 v[246:247], off
	ds_read_b128 v[210:213], v155
	ds_read_b128 v[214:217], v155 offset:256
	ds_read_b128 v[218:221], v156
	ds_read_b128 v[222:225], v156 offset:256
	s_waitcnt lgkmcnt(0)
	s_setprio 1
	s_barrier
	v_mfma_f32_16x16x32_bf16 v[124:127], v[162:165], v[178:181], v[124:127]
	v_mfma_f32_16x16x32_bf16 v[120:123], v[166:169], v[178:181], v[120:123]
	v_mfma_f32_16x16x32_bf16 v[116:119], v[162:165], v[186:189], v[116:119]
	v_mfma_f32_16x16x32_bf16 v[112:115], v[166:169], v[186:189], v[112:115]
	v_mfma_f32_16x16x32_bf16 v[108:111], v[162:165], v[194:197], v[108:111]
	v_mfma_f32_16x16x32_bf16 v[104:107], v[166:169], v[194:197], v[104:107]
	v_mfma_f32_16x16x32_bf16 v[100:103], v[162:165], v[202:205], v[100:103]
	v_mfma_f32_16x16x32_bf16 v[96:99], v[166:169], v[202:205], v[96:99]
	v_mfma_f32_16x16x32_bf16 v[124:127], v[170:173], v[182:185], v[124:127]
	v_mfma_f32_16x16x32_bf16 v[120:123], v[174:177], v[182:185], v[120:123]
	v_mfma_f32_16x16x32_bf16 v[116:119], v[170:173], v[190:193], v[116:119]
	v_mfma_f32_16x16x32_bf16 v[112:115], v[174:177], v[190:193], v[112:115]
	v_mfma_f32_16x16x32_bf16 v[108:111], v[170:173], v[198:201], v[108:111]
	v_mfma_f32_16x16x32_bf16 v[104:107], v[174:177], v[198:201], v[104:107]
	v_mfma_f32_16x16x32_bf16 v[100:103], v[170:173], v[206:209], v[100:103]
	v_mfma_f32_16x16x32_bf16 v[96:99], v[174:177], v[206:209], v[96:99]
	v_mfma_f32_16x16x32_bf16 v[92:95], v[210:213], v[178:181], v[92:95]
	v_mfma_f32_16x16x32_bf16 v[88:91], v[214:217], v[178:181], v[88:91]
	v_mfma_f32_16x16x32_bf16 v[84:87], v[210:213], v[186:189], v[84:87]
	v_mfma_f32_16x16x32_bf16 v[80:83], v[214:217], v[186:189], v[80:83]
	v_mfma_f32_16x16x32_bf16 v[76:79], v[210:213], v[194:197], v[76:79]
	v_mfma_f32_16x16x32_bf16 v[72:75], v[214:217], v[194:197], v[72:75]
	v_mfma_f32_16x16x32_bf16 v[68:71], v[210:213], v[202:205], v[68:71]
	v_mfma_f32_16x16x32_bf16 v[64:67], v[214:217], v[202:205], v[64:67]
	v_mfma_f32_16x16x32_bf16 v[92:95], v[218:221], v[182:185], v[92:95]
	v_mfma_f32_16x16x32_bf16 v[88:91], v[222:225], v[182:185], v[88:91]
	v_mfma_f32_16x16x32_bf16 v[84:87], v[218:221], v[190:193], v[84:87]
	v_mfma_f32_16x16x32_bf16 v[80:83], v[222:225], v[190:193], v[80:83]
	v_mfma_f32_16x16x32_bf16 v[76:79], v[218:221], v[198:201], v[76:79]
	v_mfma_f32_16x16x32_bf16 v[72:75], v[222:225], v[198:201], v[72:75]
	v_mfma_f32_16x16x32_bf16 v[68:71], v[218:221], v[206:209], v[68:71]
	v_mfma_f32_16x16x32_bf16 v[64:67], v[222:225], v[206:209], v[64:67]
	s_barrier
	s_setprio 0
	v_lshl_add_u64 v[228:229], s[68:69], 0, v[130:131]
	v_readfirstlane_b32 s70, v136
	v_lshl_add_u64 v[230:231], v[228:229], 0, s[22:23]
	s_mov_b32 m0, s70
	v_readfirstlane_b32 s70, v137
	global_load_lds_dwordx4 v[230:231], off
	v_lshl_add_u64 v[230:231], v[228:229], 0, s[24:25]
	s_mov_b32 m0, s70
	s_nop 0
	global_load_lds_dwordx4 v[230:231], off
	v_readfirstlane_b32 s70, v138
	v_lshl_add_u64 v[230:231], v[226:227], 0, s[26:27]
	s_mov_b32 m0, s70
	v_readfirstlane_b32 s70, v139
	ds_read_b128 v[178:181], v150 offset:16384
	ds_read_b128 v[182:185], v150 offset:17408
	ds_read_b128 v[186:189], v150 offset:18432
	ds_read_b128 v[190:193], v150 offset:19456
	ds_read_b128 v[194:197], v150 offset:20480
	ds_read_b128 v[198:201], v150 offset:21504
	ds_read_b128 v[202:205], v150 offset:22528
	ds_read_b128 v[206:209], v150 offset:23552
	global_load_lds_dwordx4 v[230:231], off
	v_lshl_add_u64 v[230:231], v[226:227], 0, s[28:29]
	s_mov_b32 m0, s70
	s_nop 0
	global_load_lds_dwordx4 v[230:231], off
	v_readfirstlane_b32 s70, v140
	v_lshl_add_u64 v[246:247], v[228:229], 0, s[30:31]
	s_mov_b32 m0, s70
	v_readfirstlane_b32 s70, v141
	global_load_lds_dwordx4 v[246:247], off
	s_waitcnt vmcnt(5)
	s_waitcnt lgkmcnt(0)
	s_setprio 1
	s_barrier
; #define STAGE(P, BASE, br, kt) do { const char* _gb = (const char*)(BASE) + ((size_t)(br) * K + (size_t)(kt) * BK) * 2; \
;     __builtin_amdgcn_global_load_lds((const unsigned*)(_gb + loff0), (unsigned*)((char*)(P) + tid * 16), 16, 0, 0); \
;     __builtin_amdgcn_global_load_lds((const unsigned*)(_gb + (size_t)K * 128 + loff0), (unsigned*)((char*)(P) + tid * 16 + 8192), 16, 0, 0); } while (0)
; #define LDA(dst, b, h) for (int m = 0; m < 4; ++m) { \
;     dst[m][0] = *reinterpret_cast<const bf16x8*>((char*)SA(b, h) + aoff0 + m * 2048); \
;     dst[m][1] = *reinterpret_cast<const bf16x8*>((char*)SA(b, h) + aoff1 + m * 2048); }
; #define LDB(dst, b, h) for (int n = 0; n < 2; ++n) { \
;     dst[n][0] = *reinterpret_cast<const bf16x8*>((char*)SB(b, h) + boff0 + n * 256); \
;     dst[n][1] = *reinterpret_cast<const bf16x8*>((char*)SB(b, h) + boff1 + n * 256); }
; #define MMA(ai, bj, At, Btf) do { __builtin_amdgcn_s_setprio(1); \
;     for (int m = 0; m < 4; ++m) for (int n = 0; n < 2; ++n) for (int k = 0; k < 2; ++k) \
;       acc[ai][bj][m][n] = __builtin_amdgcn_mfma_f32_16x16x32_bf16(Btf[n][k], At[m][k], acc[ai][bj][m][n], 0, 0, 0); \
;     __builtin_amdgcn_s_setprio(0); } while (0)
; #define WAIT_V(n) asm volatile("s_waitcnt vmcnt(" #n ")" ::: "memory")
; #define WAIT_L(n) asm volatile("s_waitcnt lgkmcnt(" #n ")" ::: "memory")
; #define BAR __builtin_amdgcn_s_barrier()
; #define SCHED __builtin_amdgcn_sched_barrier(0)
; template <int EPI> ...
;     ...
;     BAR; WAIT_L(0); MMA(1, 0, At, B0); BAR; SCHED;
;     STAGE(SB(0, 1), Bt, bcol + HALF, t + 2);
;     WAIT_V(6); BAR; MMA(1, 1, At, B1); BAR;
;     LDB(B0, 1, 0); SCHED; LDA(At, 1, 0); STAGE(SA(0, 1), A, brow + HALF, t + 2);
;     WAIT_L(8); BAR; WAIT_L(0); MMA(0, 0, At, B0); BAR; SCHED;
;     LDB(B1, 1, 1); STAGE(SB(1, 0), Bt, bcol, t + 3);
;     BAR; WAIT_L(0); MMA(0, 1, At, B1); BAR;
	v_mfma_f32_16x16x32_bf16 v[60:63], v[162:165], v[178:181], v[60:63]
	v_mfma_f32_16x16x32_bf16 v[56:59], v[166:169], v[178:181], v[56:59]
	v_mfma_f32_16x16x32_bf16 v[52:55], v[162:165], v[186:189], v[52:55]
	v_mfma_f32_16x16x32_bf16 v[48:51], v[166:169], v[186:189], v[48:51]
	v_mfma_f32_16x16x32_bf16 v[44:47], v[162:165], v[194:197], v[44:47]
	v_mfma_f32_16x16x32_bf16 v[40:43], v[166:169], v[194:197], v[40:43]
	v_mfma_f32_16x16x32_bf16 v[36:39], v[162:165], v[202:205], v[36:39]
	v_mfma_f32_16x16x32_bf16 v[32:35], v[166:169], v[202:205], v[32:35]
	v_mfma_f32_16x16x32_bf16 v[60:63], v[170:173], v[182:185], v[60:63]
	v_mfma_f32_16x16x32_bf16 v[56:59], v[174:177], v[182:185], v[56:59]
	v_mfma_f32_16x16x32_bf16 v[52:55], v[170:173], v[190:193], v[52:55]
	v_mfma_f32_16x16x32_bf16 v[48:51], v[174:177], v[190:193], v[48:51]
	v_mfma_f32_16x16x32_bf16 v[44:47], v[170:173], v[198:201], v[44:47]
	v_mfma_f32_16x16x32_bf16 v[40:43], v[174:177], v[198:201], v[40:43]
	v_mfma_f32_16x16x32_bf16 v[36:39], v[170:173], v[206:209], v[36:39]
	v_mfma_f32_16x16x32_bf16 v[32:35], v[174:177], v[206:209], v[32:35]
	v_mfma_f32_16x16x32_bf16 v[28:31], v[210:213], v[178:181], v[28:31]
	v_mfma_f32_16x16x32_bf16 v[24:27], v[214:217], v[178:181], v[24:27]
	v_mfma_f32_16x16x32_bf16 v[20:23], v[210:213], v[186:189], v[20:23]
	v_mfma_f32_16x16x32_bf16 v[16:19], v[214:217], v[186:189], v[16:19]
	v_mfma_f32_16x16x32_bf16 v[12:15], v[210:213], v[194:197], v[12:15]
	v_mfma_f32_16x16x32_bf16 v[8:11], v[214:217], v[194:197], v[8:11]
	v_mfma_f32_16x16x32_bf16 v[4:7], v[210:213], v[202:205], v[4:7]
	v_mfma_f32_16x16x32_bf16 v[0:3], v[214:217], v[202:205], v[0:3]
	v_mfma_f32_16x16x32_bf16 v[28:31], v[218:221], v[182:185], v[28:31]
	v_mfma_f32_16x16x32_bf16 v[24:27], v[222:225], v[182:185], v[24:27]
	v_mfma_f32_16x16x32_bf16 v[20:23], v[218:221], v[190:193], v[20:23]
	v_mfma_f32_16x16x32_bf16 v[16:19], v[222:225], v[190:193], v[16:19]
	v_mfma_f32_16x16x32_bf16 v[12:15], v[218:221], v[198:201], v[12:15]
	v_mfma_f32_16x16x32_bf16 v[8:11], v[222:225], v[198:201], v[8:11]
	v_mfma_f32_16x16x32_bf16 v[4:7], v[218:221], v[206:209], v[4:7]
	v_mfma_f32_16x16x32_bf16 v[0:3], v[222:225], v[206:209], v[0:3]
	s_barrier
	s_setprio 0
	ds_read_b128 v[162:165], v157
	ds_read_b128 v[166:169], v157 offset:256
	ds_read_b128 v[170:173], v158
	ds_read_b128 v[174:177], v158 offset:256
	v_readfirstlane_b32 s70, v142
	v_lshl_add_u64 v[210:211], v[226:227], 0, s[38:39]
	s_mov_b32 m0, s70
	v_readfirstlane_b32 s70, v143
	ds_read_b128 v[178:181], v150 offset:32768
	ds_read_b128 v[182:185], v150 offset:33792
	ds_read_b128 v[186:189], v150 offset:34816
	ds_read_b128 v[190:193], v150 offset:35840
	ds_read_b128 v[194:197], v150 offset:36864
	ds_read_b128 v[198:201], v150 offset:37888
	ds_read_b128 v[202:205], v150 offset:38912
	ds_read_b128 v[206:209], v150 offset:39936
	global_load_lds_dwordx4 v[210:211], off
	v_lshl_add_u64 v[210:211], v[226:227], 0, s[46:47]
	s_mov_b32 m0, s70
	s_nop 0
	global_load_lds_dwordx4 v[210:211], off
	s_waitcnt lgkmcnt(8)
	v_readfirstlane_b32 s70, v141
	v_lshl_add_u64 v[246:247], v[228:229], 0, s[36:37]
	s_mov_b32 m0, s70
	s_nop 0
	global_load_lds_dwordx4 v[246:247], off
	ds_read_b128 v[210:213], v159
	ds_read_b128 v[214:217], v159 offset:256
	ds_read_b128 v[218:221], v160
	ds_read_b128 v[222:225], v160 offset:256
	s_waitcnt lgkmcnt(0)
	s_setprio 1
	s_barrier
	v_mfma_f32_16x16x32_bf16 v[124:127], v[162:165], v[178:181], v[124:127]
	v_mfma_f32_16x16x32_bf16 v[120:123], v[166:169], v[178:181], v[120:123]
	v_mfma_f32_16x16x32_bf16 v[116:119], v[162:165], v[186:189], v[116:119]
	v_mfma_f32_16x16x32_bf16 v[112:115], v[166:169], v[186:189], v[112:115]
	v_mfma_f32_16x16x32_bf16 v[108:111], v[162:165], v[194:197], v[108:111]
	v_mfma_f32_16x16x32_bf16 v[104:107], v[166:169], v[194:197], v[104:107]
	v_mfma_f32_16x16x32_bf16 v[100:103], v[162:165], v[202:205], v[100:103]
	v_mfma_f32_16x16x32_bf16 v[96:99], v[166:169], v[202:205], v[96:99]
	v_mfma_f32_16x16x32_bf16 v[124:127], v[170:173], v[182:185], v[124:127]
	v_mfma_f32_16x16x32_bf16 v[120:123], v[174:177], v[182:185], v[120:123]
	v_mfma_f32_16x16x32_bf16 v[116:119], v[170:173], v[190:193], v[116:119]
	v_mfma_f32_16x16x32_bf16 v[112:115], v[174:177], v[190:193], v[112:115]
	v_mfma_f32_16x16x32_bf16 v[108:111], v[170:173], v[198:201], v[108:111]
	v_mfma_f32_16x16x32_bf16 v[104:107], v[174:177], v[198:201], v[104:107]
	v_mfma_f32_16x16x32_bf16 v[100:103], v[170:173], v[206:209], v[100:103]
	v_mfma_f32_16x16x32_bf16 v[96:99], v[174:177], v[206:209], v[96:99]
	v_mfma_f32_16x16x32_bf16 v[92:95], v[210:213], v[178:181], v[92:95]
	v_mfma_f32_16x16x32_bf16 v[88:91], v[214:217], v[178:181], v[88:91]
	v_mfma_f32_16x16x32_bf16 v[84:87], v[210:213], v[186:189], v[84:87]
	v_mfma_f32_16x16x32_bf16 v[80:83], v[214:217], v[186:189], v[80:83]
	v_mfma_f32_16x16x32_bf16 v[76:79], v[210:213], v[194:197], v[76:79]
	v_mfma_f32_16x16x32_bf16 v[72:75], v[214:217], v[194:197], v[72:75]
	v_mfma_f32_16x16x32_bf16 v[68:71], v[210:213], v[202:205], v[68:71]
	v_mfma_f32_16x16x32_bf16 v[64:67], v[214:217], v[202:205], v[64:67]
	v_mfma_f32_16x16x32_bf16 v[92:95], v[218:221], v[182:185], v[92:95]
	v_mfma_f32_16x16x32_bf16 v[88:91], v[222:225], v[182:185], v[88:91]
	v_mfma_f32_16x16x32_bf16 v[84:87], v[218:221], v[190:193], v[84:87]
	v_mfma_f32_16x16x32_bf16 v[80:83], v[222:225], v[190:193], v[80:83]
	v_mfma_f32_16x16x32_bf16 v[76:79], v[218:221], v[198:201], v[76:79]
	v_mfma_f32_16x16x32_bf16 v[72:75], v[222:225], v[198:201], v[72:75]
	v_mfma_f32_16x16x32_bf16 v[68:71], v[218:221], v[206:209], v[68:71]
	v_mfma_f32_16x16x32_bf16 v[64:67], v[222:225], v[206:209], v[64:67]
	s_barrier
; #define STAGE(P, BASE, br, kt) do { const char* _gb = (const char*)(BASE) + ((size_t)(br) * K + (size_t)(kt) * BK) * 2; \
;     __builtin_amdgcn_global_load_lds((const unsigned*)(_gb + loff0), (unsigned*)((char*)(P) + tid * 16), 16, 0, 0); \
;     __builtin_amdgcn_global_load_lds((const unsigned*)(_gb + (size_t)K * 128 + loff0), (unsigned*)((char*)(P) + tid * 16 + 8192), 16, 0, 0); } while (0)
; #define LDA(dst, b, h) for (int m = 0; m < 4; ++m) { \
;     dst[m][0] = *reinterpret_cast<const bf16x8*>((char*)SA(b, h) + aoff0 + m * 2048); \
;     dst[m][1] = *reinterpret_cast<const bf16x8*>((char*)SA(b, h) + aoff1 + m * 2048); }
; #define LDB(dst, b, h) for (int n = 0; n < 2; ++n) { \
;     dst[n][0] = *reinterpret_cast<const bf16x8*>((char*)SB(b, h) + boff0 + n * 256); \
;     dst[n][1] = *reinterpret_cast<const bf16x8*>((char*)SB(b, h) + boff1 + n * 256); }
; #define MMA(ai, bj, At, Btf) do { __builtin_amdgcn_s_setprio(1); \
;     for (int m = 0; m < 4; ++m) for (int n = 0; n < 2; ++n) for (int k = 0; k < 2; ++k) \
;       acc[ai][bj][m][n] = __builtin_amdgcn_mfma_f32_16x16x32_bf16(Btf[n][k], At[m][k], acc[ai][bj][m][n], 0, 0, 0); \
;     __builtin_amdgcn_s_setprio(0); } while (0)
; #define WAIT_V(n) asm volatile("s_waitcnt vmcnt(" #n ")" ::: "memory")
; #define WAIT_L(n) asm volatile("s_waitcnt lgkmcnt(" #n ")" ::: "memory")
; #define BAR __builtin_amdgcn_s_barrier()
; #define SCHED __builtin_amdgcn_sched_barrier(0)
; template <int EPI> ...
;     ...
;     LDA(At, 1, 1); STAGE(SA(1, 0), A, brow, t + 3);
;     BAR; WAIT_L(0); MMA(1, 0, At, B0); BAR; SCHED;
;     STAGE(SB(1, 1), Bt, bcol + HALF, t + 3);
;     WAIT_V(6); BAR; MMA(1, 1, At, B1); BAR;
;   }
;   { LDB(B0, 0, 0); LDA(At, 0, 0); STAGE(SA(1, 1), A, brow + HALF, nt - 1);
;     BAR; WAIT_L(0); MMA(0, 0, At, B0); BAR;
	s_setprio 0
	v_readfirstlane_b32 s70, v144
	v_lshl_add_u64 v[230:231], v[228:229], 0, s[48:49]
	s_mov_b32 m0, s70
	v_readfirstlane_b32 s70, v145
	global_load_lds_dwordx4 v[230:231], off
	v_lshl_add_u64 v[230:231], v[228:229], 0, s[50:51]
	s_mov_b32 m0, s70
	s_nop 0
	global_load_lds_dwordx4 v[230:231], off
	v_readfirstlane_b32 s70, v146
	v_lshl_add_u64 v[230:231], v[226:227], 0, s[52:53]
	s_mov_b32 m0, s70
	v_readfirstlane_b32 s70, v147
	ds_read_b128 v[178:181], v150 offset:49152
	ds_read_b128 v[182:185], v150 offset:50176
	ds_read_b128 v[186:189], v150 offset:51200
	ds_read_b128 v[190:193], v150 offset:52224
	ds_read_b128 v[194:197], v150 offset:53248
	ds_read_b128 v[198:201], v150 offset:54272
	ds_read_b128 v[202:205], v150 offset:55296
	ds_read_b128 v[206:209], v150 offset:56320
	global_load_lds_dwordx4 v[230:231], off
	v_lshl_add_u64 v[226:227], v[226:227], 0, s[54:55]
	s_mov_b32 m0, s70
	s_nop 0
	global_load_lds_dwordx4 v[226:227], off
	v_readfirstlane_b32 s70, v148
	v_lshl_add_u64 v[246:247], v[228:229], 0, s[56:57]
	s_mov_b32 m0, s70
	v_readfirstlane_b32 s70, v149
	global_load_lds_dwordx4 v[246:247], off
	s_waitcnt vmcnt(5)
	s_barrier
	s_waitcnt lgkmcnt(0)
	s_setprio 1
	s_waitcnt lgkmcnt(0)
	v_mfma_f32_16x16x32_bf16 v[60:63], v[162:165], v[178:181], v[60:63]
	v_mfma_f32_16x16x32_bf16 v[56:59], v[166:169], v[178:181], v[56:59]
	v_mfma_f32_16x16x32_bf16 v[52:55], v[162:165], v[186:189], v[52:55]
	v_mfma_f32_16x16x32_bf16 v[48:51], v[166:169], v[186:189], v[48:51]
	v_mfma_f32_16x16x32_bf16 v[44:47], v[162:165], v[194:197], v[44:47]
	v_mfma_f32_16x16x32_bf16 v[40:43], v[166:169], v[194:197], v[40:43]
	v_mfma_f32_16x16x32_bf16 v[36:39], v[162:165], v[202:205], v[36:39]
	v_mfma_f32_16x16x32_bf16 v[32:35], v[166:169], v[202:205], v[32:35]
	v_mfma_f32_16x16x32_bf16 v[60:63], v[170:173], v[182:185], v[60:63]
	v_mfma_f32_16x16x32_bf16 v[56:59], v[174:177], v[182:185], v[56:59]
	v_mfma_f32_16x16x32_bf16 v[52:55], v[170:173], v[190:193], v[52:55]
	v_mfma_f32_16x16x32_bf16 v[48:51], v[174:177], v[190:193], v[48:51]
	v_mfma_f32_16x16x32_bf16 v[44:47], v[170:173], v[198:201], v[44:47]
	v_mfma_f32_16x16x32_bf16 v[40:43], v[174:177], v[198:201], v[40:43]
	v_mfma_f32_16x16x32_bf16 v[36:39], v[170:173], v[206:209], v[36:39]
	v_mfma_f32_16x16x32_bf16 v[32:35], v[174:177], v[206:209], v[32:35]
	s_setprio 0
	s_setprio 1
	v_mfma_f32_16x16x32_bf16 v[28:31], v[210:213], v[178:181], v[28:31]
	v_mfma_f32_16x16x32_bf16 v[24:27], v[214:217], v[178:181], v[24:27]
	v_mfma_f32_16x16x32_bf16 v[20:23], v[210:213], v[186:189], v[20:23]
	v_mfma_f32_16x16x32_bf16 v[16:19], v[214:217], v[186:189], v[16:19]
	v_mfma_f32_16x16x32_bf16 v[12:15], v[210:213], v[194:197], v[12:15]
	v_mfma_f32_16x16x32_bf16 v[8:11], v[214:217], v[194:197], v[8:11]
	v_mfma_f32_16x16x32_bf16 v[4:7], v[210:213], v[202:205], v[4:7]
	v_mfma_f32_16x16x32_bf16 v[0:3], v[214:217], v[202:205], v[0:3]
	v_mfma_f32_16x16x32_bf16 v[28:31], v[218:221], v[182:185], v[28:31]
	v_mfma_f32_16x16x32_bf16 v[24:27], v[222:225], v[182:185], v[24:27]
	v_mfma_f32_16x16x32_bf16 v[20:23], v[218:221], v[190:193], v[20:23]
	v_mfma_f32_16x16x32_bf16 v[16:19], v[222:225], v[190:193], v[16:19]
	v_mfma_f32_16x16x32_bf16 v[12:15], v[218:221], v[198:201], v[12:15]
	v_mfma_f32_16x16x32_bf16 v[8:11], v[222:225], v[198:201], v[8:11]
	v_mfma_f32_16x16x32_bf16 v[4:7], v[218:221], v[206:209], v[4:7]
	v_mfma_f32_16x16x32_bf16 v[0:3], v[222:225], v[206:209], v[0:3]
	s_setprio 0
	s_add_i32 s65, s65, 2
	s_add_u32 s66, s66, 0x100
	s_addc_u32 s67, s67, 0
	s_add_u32 s68, s68, 0x100
	s_addc_u32 s69, s69, 0
	s_cmp_lt_u32 s65, 28
	s_barrier
	s_cbranch_scc1 .LBB0_1105
	v_readfirstlane_b32 s70, v149
	v_lshl_add_u64 v[246:247], v[228:229], 0, s[58:59]
	s_mov_b32 m0, s70
	s_nop 0
	global_load_lds_dwordx4 v[246:247], off
	v_readfirstlane_b32 s65, v151
	v_lshl_add_u64 v[210:211], v[132:133], 0, s[60:61]
	s_mov_b32 m0, s65
	v_readfirstlane_b32 s65, v152
	ds_read_b128 v[162:165], v153
	ds_read_b128 v[166:169], v153 offset:256
	ds_read_b128 v[170:173], v154
	ds_read_b128 v[174:177], v154 offset:256
	ds_read_b128 v[178:181], v150
	ds_read_b128 v[182:185], v150 offset:1024
	ds_read_b128 v[186:189], v150 offset:2048
	ds_read_b128 v[190:193], v150 offset:3072
	ds_read_b128 v[194:197], v150 offset:4096
	ds_read_b128 v[198:201], v150 offset:5120
	ds_read_b128 v[202:205], v150 offset:6144
	ds_read_b128 v[206:209], v150 offset:7168
	global_load_lds_dwordx4 v[210:211], off
	v_lshl_add_u64 v[132:133], v[132:133], 0, s[62:63]
	s_mov_b32 m0, s65
	s_nop 0
	global_load_lds_dwordx4 v[132:133], off
	s_waitcnt lgkmcnt(0)
	s_setprio 1
	s_barrier
	v_mfma_f32_16x16x32_bf16 v[124:127], v[162:165], v[178:181], v[124:127]
	v_mfma_f32_16x16x32_bf16 v[116:119], v[162:165], v[186:189], v[116:119]
	v_mfma_f32_16x16x32_bf16 v[108:111], v[162:165], v[194:197], v[108:111]
	v_mfma_f32_16x16x32_bf16 v[100:103], v[162:165], v[202:205], v[100:103]
	v_mfma_f32_16x16x32_bf16 v[124:127], v[170:173], v[182:185], v[124:127]
	v_mfma_f32_16x16x32_bf16 v[120:123], v[166:169], v[178:181], v[120:123]
	v_mfma_f32_16x16x32_bf16 v[116:119], v[170:173], v[190:193], v[116:119]
	v_mfma_f32_16x16x32_bf16 v[112:115], v[166:169], v[186:189], v[112:115]
	v_mfma_f32_16x16x32_bf16 v[108:111], v[170:173], v[198:201], v[108:111]
	v_mfma_f32_16x16x32_bf16 v[104:107], v[166:169], v[194:197], v[104:107]
	v_mfma_f32_16x16x32_bf16 v[100:103], v[170:173], v[206:209], v[100:103]
	v_mfma_f32_16x16x32_bf16 v[96:99], v[166:169], v[202:205], v[96:99]
	v_mfma_f32_16x16x32_bf16 v[210:213], v[174:177], v[182:185], v[120:123]
	v_mfma_f32_16x16x32_bf16 v[214:217], v[174:177], v[190:193], v[112:115]
	v_mfma_f32_16x16x32_bf16 v[218:221], v[174:177], v[198:201], v[104:107]
	v_mfma_f32_16x16x32_bf16 v[222:225], v[174:177], v[206:209], v[96:99]
	s_barrier
; #define LDA(dst, b, h) for (int m = 0; m < 4; ++m) { \
;     dst[m][0] = *reinterpret_cast<const bf16x8*>((char*)SA(b, h) + aoff0 + m * 2048); \
;     dst[m][1] = *reinterpret_cast<const bf16x8*>((char*)SA(b, h) + aoff1 + m * 2048); }
; #define LDB(dst, b, h) for (int n = 0; n < 2; ++n) { \
;     dst[n][0] = *reinterpret_cast<const bf16x8*>((char*)SB(b, h) + boff0 + n * 256); \
;     dst[n][1] = *reinterpret_cast<const bf16x8*>((char*)SB(b, h) + boff1 + n * 256); }
; #define MMA(ai, bj, At, Btf) do { __builtin_amdgcn_s_setprio(1); \
;     for (int m = 0; m < 4; ++m) for (int n = 0; n < 2; ++n) for (int k = 0; k < 2; ++k) \
;       acc[ai][bj][m][n] = __builtin_amdgcn_mfma_f32_16x16x32_bf16(Btf[n][k], At[m][k], acc[ai][bj][m][n], 0, 0, 0); \
;     __builtin_amdgcn_s_setprio(0); } while (0)
; #define WAIT_V(n) asm volatile("s_waitcnt vmcnt(" #n ")" ::: "memory")
; #define WAIT_L(n) asm volatile("s_waitcnt lgkmcnt(" #n ")" ::: "memory")
; #define BAR __builtin_amdgcn_s_barrier()
; template <int EPI> ...
;     ...
;     LDB(B1, 0, 1); BAR; WAIT_L(0); MMA(0, 1, At, B1); BAR;
;     LDA(At, 0, 1); WAIT_V(4); BAR; WAIT_L(0); MMA(1, 0, At, B0); MMA(1, 1, At, B1); BAR; }
;   { LDB(B0, 1, 0); LDA(At, 1, 0); WAIT_V(2); BAR; WAIT_L(0); MMA(0, 0, At, B0); BAR;
	s_setprio 0
	s_nop 1
	ds_read_b128 v[96:99], v155
	ds_read_b128 v[104:107], v155 offset:256
	ds_read_b128 v[112:115], v156
	ds_read_b128 v[120:123], v156 offset:256
	s_waitcnt lgkmcnt(0)
	s_setprio 1
	s_barrier
	v_mfma_f32_16x16x32_bf16 v[92:95], v[96:99], v[178:181], v[92:95]
	v_mfma_f32_16x16x32_bf16 v[84:87], v[96:99], v[186:189], v[84:87]
	v_mfma_f32_16x16x32_bf16 v[76:79], v[96:99], v[194:197], v[76:79]
	v_mfma_f32_16x16x32_bf16 v[68:71], v[96:99], v[202:205], v[68:71]
	v_mfma_f32_16x16x32_bf16 v[92:95], v[112:115], v[182:185], v[92:95]
	v_mfma_f32_16x16x32_bf16 v[88:91], v[104:107], v[178:181], v[88:91]
	v_mfma_f32_16x16x32_bf16 v[84:87], v[112:115], v[190:193], v[84:87]
	v_mfma_f32_16x16x32_bf16 v[80:83], v[104:107], v[186:189], v[80:83]
	v_mfma_f32_16x16x32_bf16 v[76:79], v[112:115], v[198:201], v[76:79]
	v_mfma_f32_16x16x32_bf16 v[72:75], v[104:107], v[194:197], v[72:75]
	v_mfma_f32_16x16x32_bf16 v[68:71], v[112:115], v[206:209], v[68:71]
	v_mfma_f32_16x16x32_bf16 v[64:67], v[104:107], v[202:205], v[64:67]
	v_mfma_f32_16x16x32_bf16 v[178:181], v[120:123], v[182:185], v[88:91]
	v_mfma_f32_16x16x32_bf16 v[182:185], v[120:123], v[190:193], v[80:83]
	v_mfma_f32_16x16x32_bf16 v[186:189], v[120:123], v[198:201], v[72:75]
	v_mfma_f32_16x16x32_bf16 v[190:193], v[120:123], v[206:209], v[64:67]
	s_barrier
	s_setprio 0
	s_nop 1
	ds_read_b128 v[64:67], v150 offset:16384
	ds_read_b128 v[72:75], v150 offset:17408
	ds_read_b128 v[80:83], v150 offset:18432
	ds_read_b128 v[88:91], v150 offset:19456
	ds_read_b128 v[194:197], v150 offset:20480
	ds_read_b128 v[198:201], v150 offset:21504
	ds_read_b128 v[202:205], v150 offset:22528
	ds_read_b128 v[206:209], v150 offset:23552
	s_waitcnt vmcnt(4)
	s_waitcnt lgkmcnt(0)
	s_setprio 1
	s_barrier
	v_mfma_f32_16x16x32_bf16 v[60:63], v[162:165], v[64:67], v[60:63]
	v_mfma_f32_16x16x32_bf16 v[56:59], v[166:169], v[64:67], v[56:59]
	v_mfma_f32_16x16x32_bf16 v[52:55], v[162:165], v[80:83], v[52:55]
	v_mfma_f32_16x16x32_bf16 v[40:43], v[166:169], v[194:197], v[40:43]
	v_mfma_f32_16x16x32_bf16 v[36:39], v[162:165], v[202:205], v[36:39]
	v_mfma_f32_16x16x32_bf16 v[60:63], v[170:173], v[72:75], v[60:63]
	v_mfma_f32_16x16x32_bf16 v[56:59], v[174:177], v[72:75], v[56:59]
	v_mfma_f32_16x16x32_bf16 v[52:55], v[170:173], v[88:91], v[52:55]
	v_mfma_f32_16x16x32_bf16 v[48:51], v[166:169], v[80:83], v[48:51]
	v_mfma_f32_16x16x32_bf16 v[44:47], v[162:165], v[194:197], v[44:47]
	v_mfma_f32_16x16x32_bf16 v[40:43], v[174:177], v[198:201], v[40:43]
	v_mfma_f32_16x16x32_bf16 v[36:39], v[170:173], v[206:209], v[36:39]
	v_mfma_f32_16x16x32_bf16 v[32:35], v[166:169], v[202:205], v[32:35]
	v_mfma_f32_16x16x32_bf16 v[226:229], v[174:177], v[88:91], v[48:51]
	v_mfma_f32_16x16x32_bf16 v[230:233], v[170:173], v[198:201], v[44:47]
	v_mfma_f32_16x16x32_bf16 v[162:165], v[174:177], v[206:209], v[32:35]
	v_mfma_f32_16x16x32_bf16 v[24:27], v[104:107], v[64:67], v[24:27]
	v_mfma_f32_16x16x32_bf16 v[20:23], v[96:99], v[80:83], v[20:23]
	v_mfma_f32_16x16x32_bf16 v[8:11], v[104:107], v[194:197], v[8:11]
	v_mfma_f32_16x16x32_bf16 v[4:7], v[96:99], v[202:205], v[4:7]
	v_mfma_f32_16x16x32_bf16 v[28:31], v[96:99], v[64:67], v[28:31]
	v_mfma_f32_16x16x32_bf16 v[24:27], v[120:123], v[72:75], v[24:27]
	v_mfma_f32_16x16x32_bf16 v[20:23], v[112:115], v[88:91], v[20:23]
	v_mfma_f32_16x16x32_bf16 v[16:19], v[104:107], v[80:83], v[16:19]
	v_mfma_f32_16x16x32_bf16 v[12:15], v[96:99], v[194:197], v[12:15]
	v_mfma_f32_16x16x32_bf16 v[8:11], v[120:123], v[198:201], v[8:11]
	v_mfma_f32_16x16x32_bf16 v[4:7], v[112:115], v[206:209], v[4:7]
	v_mfma_f32_16x16x32_bf16 v[0:3], v[104:107], v[202:205], v[0:3]
	v_mfma_f32_16x16x32_bf16 v[166:169], v[112:115], v[72:75], v[28:31]
	v_mfma_f32_16x16x32_bf16 v[170:173], v[120:123], v[88:91], v[16:19]
	v_mfma_f32_16x16x32_bf16 v[174:177], v[112:115], v[198:201], v[12:15]
	v_mfma_f32_16x16x32_bf16 v[194:197], v[120:123], v[206:209], v[0:3]
	s_barrier
	s_setprio 0
	s_nop 1
	ds_read_b128 v[0:3], v157
	ds_read_b128 v[198:201], v157 offset:256
	ds_read_b128 v[12:15], v158
	ds_read_b128 v[202:205], v158 offset:256
	ds_read_b128 v[16:19], v150 offset:32768
	ds_read_b128 v[28:31], v150 offset:33792
	ds_read_b128 v[32:35], v150 offset:34816
	ds_read_b128 v[44:47], v150 offset:35840
	ds_read_b128 v[48:51], v150 offset:36864
	ds_read_b128 v[206:209], v150 offset:37888
	ds_read_b128 v[234:237], v150 offset:38912
	ds_read_b128 v[238:241], v150 offset:39936
	s_waitcnt vmcnt(2)
	s_waitcnt lgkmcnt(0)
	s_setprio 1
	s_barrier
; #define LDA(dst, b, h) for (int m = 0; m < 4; ++m) { \
;     dst[m][0] = *reinterpret_cast<const bf16x8*>((char*)SA(b, h) + aoff0 + m * 2048); \
;     dst[m][1] = *reinterpret_cast<const bf16x8*>((char*)SA(b, h) + aoff1 + m * 2048); }
; #define LDB(dst, b, h) for (int n = 0; n < 2; ++n) { \
;     dst[n][0] = *reinterpret_cast<const bf16x8*>((char*)SB(b, h) + boff0 + n * 256); \
;     dst[n][1] = *reinterpret_cast<const bf16x8*>((char*)SB(b, h) + boff1 + n * 256); }
; #define MMA(ai, bj, At, Btf) do { __builtin_amdgcn_s_setprio(1); \
;     for (int m = 0; m < 4; ++m) for (int n = 0; n < 2; ++n) for (int k = 0; k < 2; ++k) \
;       acc[ai][bj][m][n] = __builtin_amdgcn_mfma_f32_16x16x32_bf16(Btf[n][k], At[m][k], acc[ai][bj][m][n], 0, 0, 0); \
;     __builtin_amdgcn_s_setprio(0); } while (0)
; #define WAIT_V(n) asm volatile("s_waitcnt vmcnt(" #n ")" ::: "memory")
; #define WAIT_L(n) asm volatile("s_waitcnt lgkmcnt(" #n ")" ::: "memory")
; #define BAR __builtin_amdgcn_s_barrier()
; template <int EPI> ...
;     ...
;   { LDB(B0, 1, 0); LDA(At, 1, 0); WAIT_V(2); BAR; WAIT_L(0); MMA(0, 0, At, B0); BAR;
;     LDB(B1, 1, 1); WAIT_V(0); BAR; WAIT_L(0); MMA(0, 1, At, B1); BAR;
;     LDA(At, 1, 1); BAR; WAIT_L(0); MMA(1, 0, At, B0); MMA(1, 1, At, B1); BAR; }
;   if (wr == 0) BAR;
	v_mfma_f32_16x16x32_bf16 v[64:67], v[0:3], v[16:19], v[124:127]
	v_mfma_f32_16x16x32_bf16 v[120:123], v[12:15], v[28:31], v[64:67]
	v_mfma_f32_16x16x32_bf16 v[64:67], v[198:201], v[16:19], v[210:213]
	v_mfma_f32_16x16x32_bf16 v[112:115], v[202:205], v[28:31], v[64:67]
	v_mfma_f32_16x16x32_bf16 v[64:67], v[0:3], v[32:35], v[116:119]
	v_mfma_f32_16x16x32_bf16 v[104:107], v[12:15], v[44:47], v[64:67]
	v_mfma_f32_16x16x32_bf16 v[64:67], v[198:201], v[32:35], v[214:217]
	v_mfma_f32_16x16x32_bf16 v[96:99], v[202:205], v[44:47], v[64:67]
	v_mfma_f32_16x16x32_bf16 v[64:67], v[0:3], v[48:51], v[108:111]
	v_mfma_f32_16x16x32_bf16 v[88:91], v[12:15], v[206:209], v[64:67]
	v_mfma_f32_16x16x32_bf16 v[64:67], v[198:201], v[48:51], v[218:221]
	v_mfma_f32_16x16x32_bf16 v[80:83], v[202:205], v[206:209], v[64:67]
	v_mfma_f32_16x16x32_bf16 v[64:67], v[0:3], v[234:237], v[100:103]
	v_mfma_f32_16x16x32_bf16 v[72:75], v[12:15], v[238:241], v[64:67]
	v_mfma_f32_16x16x32_bf16 v[64:67], v[198:201], v[234:237], v[222:225]
	v_mfma_f32_16x16x32_bf16 v[64:67], v[202:205], v[238:241], v[64:67]
	s_barrier
	s_setprio 0
	ds_read_b128 v[210:213], v159
	ds_read_b128 v[214:217], v159 offset:256
	ds_read_b128 v[218:221], v160
	ds_read_b128 v[222:225], v160 offset:256
	s_waitcnt vmcnt(0)
	s_waitcnt lgkmcnt(0)
	s_setprio 1
	s_barrier
	v_mfma_f32_16x16x32_bf16 v[92:95], v[210:213], v[16:19], v[92:95]
	v_mfma_f32_16x16x32_bf16 v[16:19], v[214:217], v[16:19], v[178:181]
	v_mfma_f32_16x16x32_bf16 v[116:119], v[222:225], v[28:31], v[16:19]
	v_mfma_f32_16x16x32_bf16 v[16:19], v[210:213], v[32:35], v[84:87]
	v_mfma_f32_16x16x32_bf16 v[108:111], v[218:221], v[44:47], v[16:19]
	v_mfma_f32_16x16x32_bf16 v[16:19], v[214:217], v[32:35], v[182:185]
	v_mfma_f32_16x16x32_bf16 v[100:103], v[222:225], v[44:47], v[16:19]
	v_mfma_f32_16x16x32_bf16 v[16:19], v[210:213], v[48:51], v[76:79]
	v_mfma_f32_16x16x32_bf16 v[124:127], v[218:221], v[28:31], v[92:95]
	v_mfma_f32_16x16x32_bf16 v[92:95], v[218:221], v[206:209], v[16:19]
	v_mfma_f32_16x16x32_bf16 v[16:19], v[214:217], v[48:51], v[186:189]
	v_mfma_f32_16x16x32_bf16 v[84:87], v[222:225], v[206:209], v[16:19]
	v_mfma_f32_16x16x32_bf16 v[16:19], v[210:213], v[234:237], v[68:71]
	v_mfma_f32_16x16x32_bf16 v[76:79], v[218:221], v[238:241], v[16:19]
	v_mfma_f32_16x16x32_bf16 v[16:19], v[214:217], v[234:237], v[190:193]
	v_mfma_f32_16x16x32_bf16 v[68:71], v[222:225], v[238:241], v[16:19]
	s_barrier
	s_setprio 0
	ds_read_b128 v[178:181], v150 offset:49152
	ds_read_b128 v[182:185], v150 offset:50176
	ds_read_b128 v[186:189], v150 offset:51200
	ds_read_b128 v[190:193], v150 offset:52224
	ds_read_b128 v[206:209], v150 offset:53248
	ds_read_b128 v[234:237], v150 offset:54272
	ds_read_b128 v[238:241], v150 offset:55296
	ds_read_b128 v[242:245], v150 offset:56320
	s_waitcnt lgkmcnt(0)
	s_setprio 1
	s_barrier
	v_mfma_f32_16x16x32_bf16 v[16:19], v[0:3], v[178:181], v[60:63]
	v_mfma_f32_16x16x32_bf16 v[60:63], v[12:15], v[182:185], v[16:19]
	v_mfma_f32_16x16x32_bf16 v[16:19], v[198:201], v[178:181], v[56:59]
	v_mfma_f32_16x16x32_bf16 v[48:51], v[202:205], v[182:185], v[16:19]
	v_mfma_f32_16x16x32_bf16 v[16:19], v[0:3], v[186:189], v[52:55]
	v_mfma_f32_16x16x32_bf16 v[44:47], v[12:15], v[190:193], v[16:19]
	v_mfma_f32_16x16x32_bf16 v[16:19], v[198:201], v[186:189], v[226:229]
	v_mfma_f32_16x16x32_bf16 v[32:35], v[202:205], v[190:193], v[16:19]
	v_mfma_f32_16x16x32_bf16 v[16:19], v[0:3], v[206:209], v[230:233]
	v_mfma_f32_16x16x32_bf16 v[0:3], v[0:3], v[238:241], v[36:39]
	v_mfma_f32_16x16x32_bf16 v[28:31], v[12:15], v[234:237], v[16:19]
	v_mfma_f32_16x16x32_bf16 v[16:19], v[198:201], v[206:209], v[40:43]
	v_mfma_f32_16x16x32_bf16 v[12:15], v[12:15], v[242:245], v[0:3]
	v_mfma_f32_16x16x32_bf16 v[0:3], v[198:201], v[238:241], v[162:165]
	v_mfma_f32_16x16x32_bf16 v[16:19], v[202:205], v[234:237], v[16:19]
	v_mfma_f32_16x16x32_bf16 v[0:3], v[202:205], v[242:245], v[0:3]
	v_mfma_f32_16x16x32_bf16 v[20:23], v[210:213], v[186:189], v[20:23]
	v_mfma_f32_16x16x32_bf16 v[36:39], v[210:213], v[178:181], v[166:169]
	v_mfma_f32_16x16x32_bf16 v[40:43], v[218:221], v[190:193], v[20:23]
	v_mfma_f32_16x16x32_bf16 v[20:23], v[214:217], v[186:189], v[170:173]
	v_mfma_f32_16x16x32_bf16 v[56:59], v[218:221], v[182:185], v[36:39]
	v_mfma_f32_16x16x32_bf16 v[24:27], v[214:217], v[178:181], v[24:27]
	v_mfma_f32_16x16x32_bf16 v[36:39], v[222:225], v[190:193], v[20:23]
	v_mfma_f32_16x16x32_bf16 v[20:23], v[210:213], v[206:209], v[174:177]
	v_mfma_f32_16x16x32_bf16 v[8:11], v[214:217], v[206:209], v[8:11]
	v_mfma_f32_16x16x32_bf16 v[4:7], v[210:213], v[238:241], v[4:7]
	v_mfma_f32_16x16x32_bf16 v[52:55], v[222:225], v[182:185], v[24:27]
	v_mfma_f32_16x16x32_bf16 v[24:27], v[218:221], v[234:237], v[20:23]
	v_mfma_f32_16x16x32_bf16 v[20:23], v[222:225], v[234:237], v[8:11]
	v_mfma_f32_16x16x32_bf16 v[8:11], v[218:221], v[242:245], v[4:7]
	v_mfma_f32_16x16x32_bf16 v[4:7], v[214:217], v[238:241], v[194:197]
	v_mfma_f32_16x16x32_bf16 v[4:7], v[222:225], v[242:245], v[4:7]
	s_barrier
	s_setprio 0
	s_and_saveexec_b64 s[66:67], s[2:3]
	s_cbranch_execz .LBB0_1099
	s_barrier
	s_branch .LBB0_1099

; #define STAGE(P, BASE, br, kt) do { const char* _gb = (const char*)(BASE) + ((size_t)(br) * K + (size_t)(kt) * BK) * 2; \
;     __builtin_amdgcn_global_load_lds((const unsigned*)(_gb + loff0), (unsigned*)((char*)(P) + tid * 16), 16, 0, 0); \
;     __builtin_amdgcn_global_load_lds((const unsigned*)(_gb + (size_t)K * 128 + loff0), (unsigned*)((char*)(P) + tid * 16 + 8192), 16, 0, 0); } while (0)
; #define LDA(dst, b, h) for (int m = 0; m < 4; ++m) { \
;     dst[m][0] = *reinterpret_cast<const bf16x8*>((char*)SA(b, h) + aoff0 + m * 2048); \
;     dst[m][1] = *reinterpret_cast<const bf16x8*>((char*)SA(b, h) + aoff1 + m * 2048); }
; #define LDB(dst, b, h) for (int n = 0; n < 2; ++n) { \
;     dst[n][0] = *reinterpret_cast<const bf16x8*>((char*)SB(b, h) + boff0 + n * 256); \
;     dst[n][1] = *reinterpret_cast<const bf16x8*>((char*)SB(b, h) + boff1 + n * 256); }
; #define MMA(ai, bj, At, Btf) do { __builtin_amdgcn_s_setprio(1); \
;     for (int m = 0; m < 4; ++m) for (int n = 0; n < 2; ++n) for (int k = 0; k < 2; ++k) \
;       acc[ai][bj][m][n] = __builtin_amdgcn_mfma_f32_16x16x32_bf16(Btf[n][k], At[m][k], acc[ai][bj][m][n], 0, 0, 0); \
;     __builtin_amdgcn_s_setprio(0); } while (0)
; #define WAIT_V(n) asm volatile("s_waitcnt vmcnt(" #n ")" ::: "memory")
; #define WAIT_L(n) asm volatile("s_waitcnt lgkmcnt(" #n ")" ::: "memory")
; #define BAR __builtin_amdgcn_s_barrier()
; #define SCHED __builtin_amdgcn_sched_barrier(0)
; template <int EPI> ...
;     ...
;     LDB(B0, 0, 0); SCHED; LDA(At, 0, 0); STAGE(SA(1, 1), A, brow + HALF, t + 1);
;     WAIT_L(8); BAR; WAIT_L(0); MMA(0, 0, At, B0); BAR; SCHED;
;     LDB(B1, 0, 1); STAGE(SB(0, 0), Bt, bcol, t + 2);
;     BAR; WAIT_L(0); MMA(0, 1, At, B1); BAR;
;     LDA(At, 0, 1); STAGE(SA(0, 0), A, brow, t + 2);
;     BAR; WAIT_L(0); MMA(1, 0, At, B0); BAR; SCHED;
;     STAGE(SB(0, 1), Bt, bcol + HALF, t + 2);
;     WAIT_V(6); BAR; MMA(1, 1, At, B1); BAR;
.LBB0_1152:
	ds_read_b128 v[160:163], v152
	ds_read_b128 v[164:167], v152 offset:256
	ds_read_b128 v[168:171], v153
	ds_read_b128 v[172:175], v153 offset:256
	v_lshl_add_u64 v[224:225], s[62:63], 0, v[132:133]
	v_readfirstlane_b32 s75, v150
	v_lshl_add_u64 v[208:209], v[224:225], 0, s[16:17]
	s_mov_b32 m0, s75
	v_readfirstlane_b32 s75, v151
	ds_read_b128 v[176:179], v149
	ds_read_b128 v[180:183], v149 offset:1024
	ds_read_b128 v[184:187], v149 offset:2048
	ds_read_b128 v[188:191], v149 offset:3072
	ds_read_b128 v[192:195], v149 offset:4096
	ds_read_b128 v[196:199], v149 offset:5120
	ds_read_b128 v[200:203], v149 offset:6144
	ds_read_b128 v[204:207], v149 offset:7168
	global_load_lds_dwordx4 v[208:209], off
	v_lshl_add_u64 v[208:209], v[224:225], 0, s[18:19]
	s_mov_b32 m0, s75
	s_nop 0
	global_load_lds_dwordx4 v[208:209], off
	s_waitcnt lgkmcnt(8)
	v_readfirstlane_b32 s75, v148
	v_lshl_add_u64 v[246:247], v[228:229], 0, s[56:57]
	s_mov_b32 m0, s75
	s_nop 0
	global_load_lds_dwordx4 v[246:247], off
	ds_read_b128 v[208:211], v154
	ds_read_b128 v[212:215], v154 offset:256
	ds_read_b128 v[216:219], v155
	ds_read_b128 v[220:223], v155 offset:256
	s_waitcnt lgkmcnt(0)
	s_setprio 1
	s_barrier
	v_mfma_f32_16x16x32_bf16 v[124:127], v[160:163], v[176:179], v[124:127]
	v_mfma_f32_16x16x32_bf16 v[120:123], v[164:167], v[176:179], v[120:123]
	v_mfma_f32_16x16x32_bf16 v[116:119], v[160:163], v[184:187], v[116:119]
	v_mfma_f32_16x16x32_bf16 v[112:115], v[164:167], v[184:187], v[112:115]
	v_mfma_f32_16x16x32_bf16 v[108:111], v[160:163], v[192:195], v[108:111]
	v_mfma_f32_16x16x32_bf16 v[104:107], v[164:167], v[192:195], v[104:107]
	v_mfma_f32_16x16x32_bf16 v[100:103], v[160:163], v[200:203], v[100:103]
	v_mfma_f32_16x16x32_bf16 v[96:99], v[164:167], v[200:203], v[96:99]
	v_mfma_f32_16x16x32_bf16 v[124:127], v[168:171], v[180:183], v[124:127]
	v_mfma_f32_16x16x32_bf16 v[120:123], v[172:175], v[180:183], v[120:123]
	v_mfma_f32_16x16x32_bf16 v[116:119], v[168:171], v[188:191], v[116:119]
	v_mfma_f32_16x16x32_bf16 v[112:115], v[172:175], v[188:191], v[112:115]
	v_mfma_f32_16x16x32_bf16 v[108:111], v[168:171], v[196:199], v[108:111]
	v_mfma_f32_16x16x32_bf16 v[104:107], v[172:175], v[196:199], v[104:107]
	v_mfma_f32_16x16x32_bf16 v[100:103], v[168:171], v[204:207], v[100:103]
	v_mfma_f32_16x16x32_bf16 v[96:99], v[172:175], v[204:207], v[96:99]
	v_mfma_f32_16x16x32_bf16 v[92:95], v[208:211], v[176:179], v[92:95]
	v_mfma_f32_16x16x32_bf16 v[88:91], v[212:215], v[176:179], v[88:91]
	v_mfma_f32_16x16x32_bf16 v[84:87], v[208:211], v[184:187], v[84:87]
	v_mfma_f32_16x16x32_bf16 v[80:83], v[212:215], v[184:187], v[80:83]
	v_mfma_f32_16x16x32_bf16 v[76:79], v[208:211], v[192:195], v[76:79]
	v_mfma_f32_16x16x32_bf16 v[72:75], v[212:215], v[192:195], v[72:75]
	v_mfma_f32_16x16x32_bf16 v[68:71], v[208:211], v[200:203], v[68:71]
	v_mfma_f32_16x16x32_bf16 v[64:67], v[212:215], v[200:203], v[64:67]
	v_mfma_f32_16x16x32_bf16 v[92:95], v[216:219], v[180:183], v[92:95]
	v_mfma_f32_16x16x32_bf16 v[88:91], v[220:223], v[180:183], v[88:91]
	v_mfma_f32_16x16x32_bf16 v[84:87], v[216:219], v[188:191], v[84:87]
	v_mfma_f32_16x16x32_bf16 v[80:83], v[220:223], v[188:191], v[80:83]
	v_mfma_f32_16x16x32_bf16 v[76:79], v[216:219], v[196:199], v[76:79]
	v_mfma_f32_16x16x32_bf16 v[72:75], v[220:223], v[196:199], v[72:75]
	v_mfma_f32_16x16x32_bf16 v[68:71], v[216:219], v[204:207], v[68:71]
	v_mfma_f32_16x16x32_bf16 v[64:67], v[220:223], v[204:207], v[64:67]
	s_barrier
	s_setprio 0
	v_lshl_add_u64 v[226:227], s[64:65], 0, v[132:133]
	v_readfirstlane_b32 s75, v135
	v_lshl_add_u64 v[228:229], v[226:227], 0, s[20:21]
	s_mov_b32 m0, s75
	v_readfirstlane_b32 s75, v136
	global_load_lds_dwordx4 v[228:229], off
	v_lshl_add_u64 v[228:229], v[226:227], 0, s[22:23]
	s_mov_b32 m0, s75
	s_nop 0
	global_load_lds_dwordx4 v[228:229], off
	v_readfirstlane_b32 s75, v137
	v_lshl_add_u64 v[228:229], v[224:225], 0, s[24:25]
	s_mov_b32 m0, s75
	v_readfirstlane_b32 s75, v138
	ds_read_b128 v[176:179], v149 offset:16384
	ds_read_b128 v[180:183], v149 offset:17408
	ds_read_b128 v[184:187], v149 offset:18432
	ds_read_b128 v[188:191], v149 offset:19456
	ds_read_b128 v[192:195], v149 offset:20480
	ds_read_b128 v[196:199], v149 offset:21504
	ds_read_b128 v[200:203], v149 offset:22528
	ds_read_b128 v[204:207], v149 offset:23552
	global_load_lds_dwordx4 v[228:229], off
	v_lshl_add_u64 v[228:229], v[224:225], 0, s[26:27]
	s_mov_b32 m0, s75
	s_nop 0
	global_load_lds_dwordx4 v[228:229], off
	v_lshl_add_u64 v[228:229], s[60:61], 0, v[132:133]
	v_readfirstlane_b32 s75, v139
	v_lshl_add_u64 v[246:247], v[228:229], 0, s[28:29]
	s_mov_b32 m0, s75
	v_readfirstlane_b32 s75, v140
	global_load_lds_dwordx4 v[246:247], off
	s_waitcnt vmcnt(5)
	s_waitcnt lgkmcnt(0)
	s_setprio 1
	s_barrier
; #define STAGE(P, BASE, br, kt) do { const char* _gb = (const char*)(BASE) + ((size_t)(br) * K + (size_t)(kt) * BK) * 2; \
;     __builtin_amdgcn_global_load_lds((const unsigned*)(_gb + loff0), (unsigned*)((char*)(P) + tid * 16), 16, 0, 0); \
;     __builtin_amdgcn_global_load_lds((const unsigned*)(_gb + (size_t)K * 128 + loff0), (unsigned*)((char*)(P) + tid * 16 + 8192), 16, 0, 0); } while (0)
; #define LDA(dst, b, h) for (int m = 0; m < 4; ++m) { \
;     dst[m][0] = *reinterpret_cast<const bf16x8*>((char*)SA(b, h) + aoff0 + m * 2048); \
;     dst[m][1] = *reinterpret_cast<const bf16x8*>((char*)SA(b, h) + aoff1 + m * 2048); }
; #define LDB(dst, b, h) for (int n = 0; n < 2; ++n) { \
;     dst[n][0] = *reinterpret_cast<const bf16x8*>((char*)SB(b, h) + boff0 + n * 256); \
;     dst[n][1] = *reinterpret_cast<const bf16x8*>((char*)SB(b, h) + boff1 + n * 256); }
; #define MMA(ai, bj, At, Btf) do { __builtin_amdgcn_s_setprio(1); \
;     for (int m = 0; m < 4; ++m) for (int n = 0; n < 2; ++n) for (int k = 0; k < 2; ++k) \
;       acc[ai][bj][m][n] = __builtin_amdgcn_mfma_f32_16x16x32_bf16(Btf[n][k], At[m][k], acc[ai][bj][m][n], 0, 0, 0); \
;     __builtin_amdgcn_s_setprio(0); } while (0)
; #define WAIT_V(n) asm volatile("s_waitcnt vmcnt(" #n ")" ::: "memory")
; #define WAIT_L(n) asm volatile("s_waitcnt lgkmcnt(" #n ")" ::: "memory")
; #define BAR __builtin_amdgcn_s_barrier()
; #define SCHED __builtin_amdgcn_sched_barrier(0)
; template <int EPI> ...
;     ...
;     BAR; WAIT_L(0); MMA(1, 0, At, B0); BAR; SCHED;
;     STAGE(SB(0, 1), Bt, bcol + HALF, t + 2);
;     WAIT_V(6); BAR; MMA(1, 1, At, B1); BAR;
;     LDB(B0, 1, 0); SCHED; LDA(At, 1, 0); STAGE(SA(0, 1), A, brow + HALF, t + 2);
;     WAIT_L(8); BAR; WAIT_L(0); MMA(0, 0, At, B0); BAR; SCHED;
;     LDB(B1, 1, 1); STAGE(SB(1, 0), Bt, bcol, t + 3);
;     BAR; WAIT_L(0); MMA(0, 1, At, B1); BAR;
	v_mfma_f32_16x16x32_bf16 v[60:63], v[160:163], v[176:179], v[60:63]
	v_mfma_f32_16x16x32_bf16 v[56:59], v[164:167], v[176:179], v[56:59]
	v_mfma_f32_16x16x32_bf16 v[52:55], v[160:163], v[184:187], v[52:55]
	v_mfma_f32_16x16x32_bf16 v[48:51], v[164:167], v[184:187], v[48:51]
	v_mfma_f32_16x16x32_bf16 v[44:47], v[160:163], v[192:195], v[44:47]
	v_mfma_f32_16x16x32_bf16 v[40:43], v[164:167], v[192:195], v[40:43]
	v_mfma_f32_16x16x32_bf16 v[36:39], v[160:163], v[200:203], v[36:39]
	v_mfma_f32_16x16x32_bf16 v[32:35], v[164:167], v[200:203], v[32:35]
	v_mfma_f32_16x16x32_bf16 v[60:63], v[168:171], v[180:183], v[60:63]
	v_mfma_f32_16x16x32_bf16 v[56:59], v[172:175], v[180:183], v[56:59]
	v_mfma_f32_16x16x32_bf16 v[52:55], v[168:171], v[188:191], v[52:55]
	v_mfma_f32_16x16x32_bf16 v[48:51], v[172:175], v[188:191], v[48:51]
	v_mfma_f32_16x16x32_bf16 v[44:47], v[168:171], v[196:199], v[44:47]
	v_mfma_f32_16x16x32_bf16 v[40:43], v[172:175], v[196:199], v[40:43]
	v_mfma_f32_16x16x32_bf16 v[36:39], v[168:171], v[204:207], v[36:39]
	v_mfma_f32_16x16x32_bf16 v[32:35], v[172:175], v[204:207], v[32:35]
	v_mfma_f32_16x16x32_bf16 v[28:31], v[208:211], v[176:179], v[28:31]
	v_mfma_f32_16x16x32_bf16 v[24:27], v[212:215], v[176:179], v[24:27]
	v_mfma_f32_16x16x32_bf16 v[20:23], v[208:211], v[184:187], v[20:23]
	v_mfma_f32_16x16x32_bf16 v[16:19], v[212:215], v[184:187], v[16:19]
	v_mfma_f32_16x16x32_bf16 v[12:15], v[208:211], v[192:195], v[12:15]
	v_mfma_f32_16x16x32_bf16 v[8:11], v[212:215], v[192:195], v[8:11]
	v_mfma_f32_16x16x32_bf16 v[4:7], v[208:211], v[200:203], v[4:7]
	v_mfma_f32_16x16x32_bf16 v[0:3], v[212:215], v[200:203], v[0:3]
	v_mfma_f32_16x16x32_bf16 v[28:31], v[216:219], v[180:183], v[28:31]
	v_mfma_f32_16x16x32_bf16 v[24:27], v[220:223], v[180:183], v[24:27]
	v_mfma_f32_16x16x32_bf16 v[20:23], v[216:219], v[188:191], v[20:23]
	v_mfma_f32_16x16x32_bf16 v[16:19], v[220:223], v[188:191], v[16:19]
	v_mfma_f32_16x16x32_bf16 v[12:15], v[216:219], v[196:199], v[12:15]
	v_mfma_f32_16x16x32_bf16 v[8:11], v[220:223], v[196:199], v[8:11]
	v_mfma_f32_16x16x32_bf16 v[4:7], v[216:219], v[204:207], v[4:7]
	v_mfma_f32_16x16x32_bf16 v[0:3], v[220:223], v[204:207], v[0:3]
	s_barrier
	s_setprio 0
	ds_read_b128 v[160:163], v156
	ds_read_b128 v[164:167], v156 offset:256
	ds_read_b128 v[168:171], v157
	ds_read_b128 v[172:175], v157 offset:256
	v_readfirstlane_b32 s75, v141
	v_lshl_add_u64 v[208:209], v[224:225], 0, s[36:37]
	s_mov_b32 m0, s75
	v_readfirstlane_b32 s75, v142
	ds_read_b128 v[176:179], v149 offset:32768
	ds_read_b128 v[180:183], v149 offset:33792
	ds_read_b128 v[184:187], v149 offset:34816
	ds_read_b128 v[188:191], v149 offset:35840
	ds_read_b128 v[192:195], v149 offset:36864
	ds_read_b128 v[196:199], v149 offset:37888
	ds_read_b128 v[200:203], v149 offset:38912
	ds_read_b128 v[204:207], v149 offset:39936
	global_load_lds_dwordx4 v[208:209], off
	v_lshl_add_u64 v[208:209], v[224:225], 0, s[38:39]
	s_mov_b32 m0, s75
	s_nop 0
	global_load_lds_dwordx4 v[208:209], off
	s_waitcnt lgkmcnt(8)
	v_readfirstlane_b32 s75, v140
	v_lshl_add_u64 v[246:247], v[228:229], 0, s[30:31]
	s_mov_b32 m0, s75
	s_nop 0
	global_load_lds_dwordx4 v[246:247], off
	ds_read_b128 v[208:211], v158
	ds_read_b128 v[212:215], v158 offset:256
	ds_read_b128 v[216:219], v159
	ds_read_b128 v[220:223], v159 offset:256
	s_waitcnt lgkmcnt(0)
	s_setprio 1
	s_barrier
	v_mfma_f32_16x16x32_bf16 v[124:127], v[160:163], v[176:179], v[124:127]
	v_mfma_f32_16x16x32_bf16 v[120:123], v[164:167], v[176:179], v[120:123]
	v_mfma_f32_16x16x32_bf16 v[116:119], v[160:163], v[184:187], v[116:119]
	v_mfma_f32_16x16x32_bf16 v[112:115], v[164:167], v[184:187], v[112:115]
	v_mfma_f32_16x16x32_bf16 v[108:111], v[160:163], v[192:195], v[108:111]
	v_mfma_f32_16x16x32_bf16 v[104:107], v[164:167], v[192:195], v[104:107]
	v_mfma_f32_16x16x32_bf16 v[100:103], v[160:163], v[200:203], v[100:103]
	v_mfma_f32_16x16x32_bf16 v[96:99], v[164:167], v[200:203], v[96:99]
	v_mfma_f32_16x16x32_bf16 v[124:127], v[168:171], v[180:183], v[124:127]
	v_mfma_f32_16x16x32_bf16 v[120:123], v[172:175], v[180:183], v[120:123]
	v_mfma_f32_16x16x32_bf16 v[116:119], v[168:171], v[188:191], v[116:119]
	v_mfma_f32_16x16x32_bf16 v[112:115], v[172:175], v[188:191], v[112:115]
	v_mfma_f32_16x16x32_bf16 v[108:111], v[168:171], v[196:199], v[108:111]
	v_mfma_f32_16x16x32_bf16 v[104:107], v[172:175], v[196:199], v[104:107]
	v_mfma_f32_16x16x32_bf16 v[100:103], v[168:171], v[204:207], v[100:103]
	v_mfma_f32_16x16x32_bf16 v[96:99], v[172:175], v[204:207], v[96:99]
	v_mfma_f32_16x16x32_bf16 v[92:95], v[208:211], v[176:179], v[92:95]
	v_mfma_f32_16x16x32_bf16 v[88:91], v[212:215], v[176:179], v[88:91]
	v_mfma_f32_16x16x32_bf16 v[84:87], v[208:211], v[184:187], v[84:87]
	v_mfma_f32_16x16x32_bf16 v[80:83], v[212:215], v[184:187], v[80:83]
	v_mfma_f32_16x16x32_bf16 v[76:79], v[208:211], v[192:195], v[76:79]
	v_mfma_f32_16x16x32_bf16 v[72:75], v[212:215], v[192:195], v[72:75]
	v_mfma_f32_16x16x32_bf16 v[68:71], v[208:211], v[200:203], v[68:71]
	v_mfma_f32_16x16x32_bf16 v[64:67], v[212:215], v[200:203], v[64:67]
	v_mfma_f32_16x16x32_bf16 v[92:95], v[216:219], v[180:183], v[92:95]
	v_mfma_f32_16x16x32_bf16 v[88:91], v[220:223], v[180:183], v[88:91]
	v_mfma_f32_16x16x32_bf16 v[84:87], v[216:219], v[188:191], v[84:87]
	v_mfma_f32_16x16x32_bf16 v[80:83], v[220:223], v[188:191], v[80:83]
	v_mfma_f32_16x16x32_bf16 v[76:79], v[216:219], v[196:199], v[76:79]
	v_mfma_f32_16x16x32_bf16 v[72:75], v[220:223], v[196:199], v[72:75]
	v_mfma_f32_16x16x32_bf16 v[68:71], v[216:219], v[204:207], v[68:71]
	v_mfma_f32_16x16x32_bf16 v[64:67], v[220:223], v[204:207], v[64:67]
	s_barrier
; #define STAGE(P, BASE, br, kt) do { const char* _gb = (const char*)(BASE) + ((size_t)(br) * K + (size_t)(kt) * BK) * 2; \
;     __builtin_amdgcn_global_load_lds((const unsigned*)(_gb + loff0), (unsigned*)((char*)(P) + tid * 16), 16, 0, 0); \
;     __builtin_amdgcn_global_load_lds((const unsigned*)(_gb + (size_t)K * 128 + loff0), (unsigned*)((char*)(P) + tid * 16 + 8192), 16, 0, 0); } while (0)
; #define LDA(dst, b, h) for (int m = 0; m < 4; ++m) { \
;     dst[m][0] = *reinterpret_cast<const bf16x8*>((char*)SA(b, h) + aoff0 + m * 2048); \
;     dst[m][1] = *reinterpret_cast<const bf16x8*>((char*)SA(b, h) + aoff1 + m * 2048); }
; #define LDB(dst, b, h) for (int n = 0; n < 2; ++n) { \
;     dst[n][0] = *reinterpret_cast<const bf16x8*>((char*)SB(b, h) + boff0 + n * 256); \
;     dst[n][1] = *reinterpret_cast<const bf16x8*>((char*)SB(b, h) + boff1 + n * 256); }
; #define MMA(ai, bj, At, Btf) do { __builtin_amdgcn_s_setprio(1); \
;     for (int m = 0; m < 4; ++m) for (int n = 0; n < 2; ++n) for (int k = 0; k < 2; ++k) \
;       acc[ai][bj][m][n] = __builtin_amdgcn_mfma_f32_16x16x32_bf16(Btf[n][k], At[m][k], acc[ai][bj][m][n], 0, 0, 0); \
;     __builtin_amdgcn_s_setprio(0); } while (0)
; #define WAIT_V(n) asm volatile("s_waitcnt vmcnt(" #n ")" ::: "memory")
; #define WAIT_L(n) asm volatile("s_waitcnt lgkmcnt(" #n ")" ::: "memory")
; #define BAR __builtin_amdgcn_s_barrier()
; #define SCHED __builtin_amdgcn_sched_barrier(0)
; template <int EPI> ...
;     ...
;     LDA(At, 1, 1); STAGE(SA(1, 0), A, brow, t + 3);
;     BAR; WAIT_L(0); MMA(1, 0, At, B0); BAR; SCHED;
;     STAGE(SB(1, 1), Bt, bcol + HALF, t + 3);
;     WAIT_V(6); BAR; MMA(1, 1, At, B1); BAR;
;   }
;   { LDB(B0, 0, 0); LDA(At, 0, 0); STAGE(SA(1, 1), A, brow + HALF, nt - 1);
;     BAR; WAIT_L(0); MMA(0, 0, At, B0); BAR;
	s_setprio 0
	v_readfirstlane_b32 s75, v143
	v_lshl_add_u64 v[230:231], v[226:227], 0, s[46:47]
	s_mov_b32 m0, s75
	v_readfirstlane_b32 s75, v144
	global_load_lds_dwordx4 v[230:231], off
	v_lshl_add_u64 v[226:227], v[226:227], 0, s[48:49]
	s_mov_b32 m0, s75
	s_nop 0
	global_load_lds_dwordx4 v[226:227], off
	v_readfirstlane_b32 s75, v145
	v_lshl_add_u64 v[226:227], v[224:225], 0, s[50:51]
	s_mov_b32 m0, s75
	v_readfirstlane_b32 s75, v146
	ds_read_b128 v[176:179], v149 offset:49152
	ds_read_b128 v[180:183], v149 offset:50176
	ds_read_b128 v[184:187], v149 offset:51200
	ds_read_b128 v[188:191], v149 offset:52224
	ds_read_b128 v[192:195], v149 offset:53248
	ds_read_b128 v[196:199], v149 offset:54272
	ds_read_b128 v[200:203], v149 offset:55296
	ds_read_b128 v[204:207], v149 offset:56320
	global_load_lds_dwordx4 v[226:227], off
	v_lshl_add_u64 v[224:225], v[224:225], 0, s[52:53]
	s_mov_b32 m0, s75
	s_nop 0
	global_load_lds_dwordx4 v[224:225], off
	v_readfirstlane_b32 s75, v147
	v_lshl_add_u64 v[246:247], v[228:229], 0, s[54:55]
	s_mov_b32 m0, s75
	v_readfirstlane_b32 s75, v148
	global_load_lds_dwordx4 v[246:247], off
	s_waitcnt vmcnt(5)
	s_barrier
	s_waitcnt lgkmcnt(0)
	s_setprio 1
	s_waitcnt lgkmcnt(0)
	v_mfma_f32_16x16x32_bf16 v[60:63], v[160:163], v[176:179], v[60:63]
	v_mfma_f32_16x16x32_bf16 v[56:59], v[164:167], v[176:179], v[56:59]
	v_mfma_f32_16x16x32_bf16 v[52:55], v[160:163], v[184:187], v[52:55]
	v_mfma_f32_16x16x32_bf16 v[48:51], v[164:167], v[184:187], v[48:51]
	v_mfma_f32_16x16x32_bf16 v[44:47], v[160:163], v[192:195], v[44:47]
	v_mfma_f32_16x16x32_bf16 v[40:43], v[164:167], v[192:195], v[40:43]
	v_mfma_f32_16x16x32_bf16 v[36:39], v[160:163], v[200:203], v[36:39]
	v_mfma_f32_16x16x32_bf16 v[32:35], v[164:167], v[200:203], v[32:35]
	v_mfma_f32_16x16x32_bf16 v[60:63], v[168:171], v[180:183], v[60:63]
	v_mfma_f32_16x16x32_bf16 v[56:59], v[172:175], v[180:183], v[56:59]
	v_mfma_f32_16x16x32_bf16 v[52:55], v[168:171], v[188:191], v[52:55]
	v_mfma_f32_16x16x32_bf16 v[48:51], v[172:175], v[188:191], v[48:51]
	v_mfma_f32_16x16x32_bf16 v[44:47], v[168:171], v[196:199], v[44:47]
	v_mfma_f32_16x16x32_bf16 v[40:43], v[172:175], v[196:199], v[40:43]
	v_mfma_f32_16x16x32_bf16 v[36:39], v[168:171], v[204:207], v[36:39]
	v_mfma_f32_16x16x32_bf16 v[32:35], v[172:175], v[204:207], v[32:35]
	s_setprio 0
	s_setprio 1
	v_mfma_f32_16x16x32_bf16 v[28:31], v[208:211], v[176:179], v[28:31]
	v_mfma_f32_16x16x32_bf16 v[24:27], v[212:215], v[176:179], v[24:27]
	v_mfma_f32_16x16x32_bf16 v[20:23], v[208:211], v[184:187], v[20:23]
	v_mfma_f32_16x16x32_bf16 v[16:19], v[212:215], v[184:187], v[16:19]
	v_mfma_f32_16x16x32_bf16 v[12:15], v[208:211], v[192:195], v[12:15]
	v_mfma_f32_16x16x32_bf16 v[8:11], v[212:215], v[192:195], v[8:11]
	v_mfma_f32_16x16x32_bf16 v[4:7], v[208:211], v[200:203], v[4:7]
	v_mfma_f32_16x16x32_bf16 v[0:3], v[212:215], v[200:203], v[0:3]
	v_mfma_f32_16x16x32_bf16 v[28:31], v[216:219], v[180:183], v[28:31]
	v_mfma_f32_16x16x32_bf16 v[24:27], v[220:223], v[180:183], v[24:27]
	v_mfma_f32_16x16x32_bf16 v[20:23], v[216:219], v[188:191], v[20:23]
	v_mfma_f32_16x16x32_bf16 v[16:19], v[220:223], v[188:191], v[16:19]
	v_mfma_f32_16x16x32_bf16 v[12:15], v[216:219], v[196:199], v[12:15]
	v_mfma_f32_16x16x32_bf16 v[8:11], v[220:223], v[196:199], v[8:11]
	v_mfma_f32_16x16x32_bf16 v[4:7], v[216:219], v[204:207], v[4:7]
	v_mfma_f32_16x16x32_bf16 v[0:3], v[220:223], v[204:207], v[0:3]
	s_setprio 0
	s_add_i32 s74, s74, 2
	s_add_u32 s60, s60, 0x100
	s_addc_u32 s61, s61, 0
	s_add_u32 s62, s62, 0x100
	s_addc_u32 s63, s63, 0
	s_add_u32 s64, s64, 0x100
	s_addc_u32 s65, s65, 0
	s_cmpk_lt_u32 s74, 0x54
	s_barrier
	s_cbranch_scc1 .LBB0_1152
	v_readfirstlane_b32 s75, v148
	v_lshl_add_u64 v[246:247], v[228:229], 0, s[56:57]
	s_mov_b32 m0, s75
	s_nop 0
	global_load_lds_dwordx4 v[246:247], off
	s_add_u32 s60, s68, s73
	s_addc_u32 s61, s69, s72
	v_lshl_add_u64 v[208:209], s[60:61], 0, v[128:129]
	v_readfirstlane_b32 s60, v150
	s_mov_b32 m0, s60
	v_readfirstlane_b32 s60, v151
	ds_read_b128 v[160:163], v152
	ds_read_b128 v[164:167], v152 offset:256
	ds_read_b128 v[168:171], v153
	ds_read_b128 v[172:175], v153 offset:256
	ds_read_b128 v[176:179], v149
	ds_read_b128 v[180:183], v149 offset:1024
	ds_read_b128 v[184:187], v149 offset:2048
	ds_read_b128 v[188:191], v149 offset:3072
	ds_read_b128 v[192:195], v149 offset:4096
	ds_read_b128 v[196:199], v149 offset:5120
	ds_read_b128 v[200:203], v149 offset:6144
	ds_read_b128 v[204:207], v149 offset:7168
	global_load_lds_dwordx4 v[208:209], off
	v_lshl_add_u64 v[208:209], v[208:209], 0, s[8:9]
	s_mov_b32 m0, s60
	s_nop 0
	global_load_lds_dwordx4 v[208:209], off
	s_waitcnt lgkmcnt(0)
	s_setprio 1
	s_barrier
	v_mfma_f32_16x16x32_bf16 v[124:127], v[160:163], v[176:179], v[124:127]
	v_mfma_f32_16x16x32_bf16 v[116:119], v[160:163], v[184:187], v[116:119]
	v_mfma_f32_16x16x32_bf16 v[108:111], v[160:163], v[192:195], v[108:111]
	v_mfma_f32_16x16x32_bf16 v[100:103], v[160:163], v[200:203], v[100:103]
	v_mfma_f32_16x16x32_bf16 v[96:99], v[164:167], v[200:203], v[96:99]
	v_mfma_f32_16x16x32_bf16 v[124:127], v[168:171], v[180:183], v[124:127]
	v_mfma_f32_16x16x32_bf16 v[120:123], v[164:167], v[176:179], v[120:123]
	v_mfma_f32_16x16x32_bf16 v[116:119], v[168:171], v[188:191], v[116:119]
	v_mfma_f32_16x16x32_bf16 v[112:115], v[164:167], v[184:187], v[112:115]
	v_mfma_f32_16x16x32_bf16 v[108:111], v[168:171], v[196:199], v[108:111]
	v_mfma_f32_16x16x32_bf16 v[104:107], v[164:167], v[192:195], v[104:107]
	v_mfma_f32_16x16x32_bf16 v[100:103], v[168:171], v[204:207], v[100:103]
	v_mfma_f32_16x16x32_bf16 v[96:99], v[172:175], v[204:207], v[96:99]
	v_mfma_f32_16x16x32_bf16 v[208:211], v[172:175], v[180:183], v[120:123]
	v_mfma_f32_16x16x32_bf16 v[212:215], v[172:175], v[188:191], v[112:115]
	v_mfma_f32_16x16x32_bf16 v[216:219], v[172:175], v[196:199], v[104:107]
	s_barrier
; #define LDA(dst, b, h) for (int m = 0; m < 4; ++m) { \
;     dst[m][0] = *reinterpret_cast<const bf16x8*>((char*)SA(b, h) + aoff0 + m * 2048); \
;     dst[m][1] = *reinterpret_cast<const bf16x8*>((char*)SA(b, h) + aoff1 + m * 2048); }
; #define LDB(dst, b, h) for (int n = 0; n < 2; ++n) { \
;     dst[n][0] = *reinterpret_cast<const bf16x8*>((char*)SB(b, h) + boff0 + n * 256); \
;     dst[n][1] = *reinterpret_cast<const bf16x8*>((char*)SB(b, h) + boff1 + n * 256); }
; #define MMA(ai, bj, At, Btf) do { __builtin_amdgcn_s_setprio(1); \
;     for (int m = 0; m < 4; ++m) for (int n = 0; n < 2; ++n) for (int k = 0; k < 2; ++k) \
;       acc[ai][bj][m][n] = __builtin_amdgcn_mfma_f32_16x16x32_bf16(Btf[n][k], At[m][k], acc[ai][bj][m][n], 0, 0, 0); \
;     __builtin_amdgcn_s_setprio(0); } while (0)
; #define WAIT_V(n) asm volatile("s_waitcnt vmcnt(" #n ")" ::: "memory")
; #define WAIT_L(n) asm volatile("s_waitcnt lgkmcnt(" #n ")" ::: "memory")
; #define BAR __builtin_amdgcn_s_barrier()
; template <int EPI> ...
;     ...
;     LDB(B1, 0, 1); BAR; WAIT_L(0); MMA(0, 1, At, B1); BAR;
;     LDA(At, 0, 1); WAIT_V(4); BAR; WAIT_L(0); MMA(1, 0, At, B0); MMA(1, 1, At, B1); BAR; }
;   { LDB(B0, 1, 0); LDA(At, 1, 0); WAIT_V(2); BAR; WAIT_L(0); MMA(0, 0, At, B0); BAR;
	s_setprio 0
	s_nop 0
	ds_read_b128 v[104:107], v154
	ds_read_b128 v[112:115], v154 offset:256
	ds_read_b128 v[120:123], v155
	ds_read_b128 v[220:223], v155 offset:256
	s_waitcnt lgkmcnt(0)
	s_setprio 1
	s_barrier
	v_mfma_f32_16x16x32_bf16 v[84:87], v[104:107], v[184:187], v[84:87]
	v_mfma_f32_16x16x32_bf16 v[76:79], v[104:107], v[192:195], v[76:79]
	v_mfma_f32_16x16x32_bf16 v[72:75], v[112:115], v[192:195], v[72:75]
	v_mfma_f32_16x16x32_bf16 v[92:95], v[104:107], v[176:179], v[92:95]
	v_mfma_f32_16x16x32_bf16 v[88:91], v[112:115], v[176:179], v[88:91]
	v_mfma_f32_16x16x32_bf16 v[84:87], v[120:123], v[188:191], v[84:87]
	v_mfma_f32_16x16x32_bf16 v[80:83], v[112:115], v[184:187], v[80:83]
	v_mfma_f32_16x16x32_bf16 v[76:79], v[120:123], v[196:199], v[76:79]
	v_mfma_f32_16x16x32_bf16 v[72:75], v[220:223], v[196:199], v[72:75]
	v_mfma_f32_16x16x32_bf16 v[68:71], v[104:107], v[200:203], v[68:71]
	v_mfma_f32_16x16x32_bf16 v[64:67], v[112:115], v[200:203], v[64:67]
	v_mfma_f32_16x16x32_bf16 v[224:227], v[120:123], v[180:183], v[92:95]
	v_mfma_f32_16x16x32_bf16 v[176:179], v[220:223], v[180:183], v[88:91]
	v_mfma_f32_16x16x32_bf16 v[180:183], v[220:223], v[188:191], v[80:83]
	v_mfma_f32_16x16x32_bf16 v[184:187], v[120:123], v[204:207], v[68:71]
	v_mfma_f32_16x16x32_bf16 v[188:191], v[220:223], v[204:207], v[64:67]
	s_barrier
	s_setprio 0
	s_nop 0
	ds_read_b128 v[64:67], v149 offset:16384
	ds_read_b128 v[68:71], v149 offset:17408
	ds_read_b128 v[80:83], v149 offset:18432
	ds_read_b128 v[88:91], v149 offset:19456
	ds_read_b128 v[92:95], v149 offset:20480
	ds_read_b128 v[192:195], v149 offset:21504
	ds_read_b128 v[196:199], v149 offset:22528
	ds_read_b128 v[200:203], v149 offset:23552
	s_waitcnt vmcnt(4)
	s_waitcnt lgkmcnt(0)
	s_setprio 1
	s_barrier
	v_mfma_f32_16x16x32_bf16 v[52:55], v[160:163], v[80:83], v[52:55]
	v_mfma_f32_16x16x32_bf16 v[44:47], v[160:163], v[92:95], v[44:47]
	v_mfma_f32_16x16x32_bf16 v[36:39], v[160:163], v[196:199], v[36:39]
	v_mfma_f32_16x16x32_bf16 v[60:63], v[160:163], v[64:67], v[60:63]
	v_mfma_f32_16x16x32_bf16 v[56:59], v[164:167], v[64:67], v[56:59]
	v_mfma_f32_16x16x32_bf16 v[52:55], v[168:171], v[88:91], v[52:55]
	v_mfma_f32_16x16x32_bf16 v[48:51], v[164:167], v[80:83], v[48:51]
	v_mfma_f32_16x16x32_bf16 v[44:47], v[168:171], v[192:195], v[44:47]
	v_mfma_f32_16x16x32_bf16 v[40:43], v[164:167], v[92:95], v[40:43]
	v_mfma_f32_16x16x32_bf16 v[36:39], v[168:171], v[200:203], v[36:39]
	v_mfma_f32_16x16x32_bf16 v[32:35], v[164:167], v[196:199], v[32:35]
	v_mfma_f32_16x16x32_bf16 v[204:207], v[168:171], v[68:71], v[60:63]
	v_mfma_f32_16x16x32_bf16 v[228:231], v[172:175], v[68:71], v[56:59]
	v_mfma_f32_16x16x32_bf16 v[232:235], v[172:175], v[88:91], v[48:51]
	v_mfma_f32_16x16x32_bf16 v[236:239], v[172:175], v[192:195], v[40:43]
	v_mfma_f32_16x16x32_bf16 v[160:163], v[172:175], v[200:203], v[32:35]
	v_mfma_f32_16x16x32_bf16 v[28:31], v[104:107], v[64:67], v[28:31]
	v_mfma_f32_16x16x32_bf16 v[20:23], v[104:107], v[80:83], v[20:23]
	v_mfma_f32_16x16x32_bf16 v[12:15], v[104:107], v[92:95], v[12:15]
	v_mfma_f32_16x16x32_bf16 v[4:7], v[104:107], v[196:199], v[4:7]
	v_mfma_f32_16x16x32_bf16 v[28:31], v[120:123], v[68:71], v[28:31]
	v_mfma_f32_16x16x32_bf16 v[24:27], v[112:115], v[64:67], v[24:27]
	v_mfma_f32_16x16x32_bf16 v[20:23], v[120:123], v[88:91], v[20:23]
	v_mfma_f32_16x16x32_bf16 v[16:19], v[112:115], v[80:83], v[16:19]
	v_mfma_f32_16x16x32_bf16 v[12:15], v[120:123], v[192:195], v[12:15]
	v_mfma_f32_16x16x32_bf16 v[8:11], v[112:115], v[92:95], v[8:11]
	v_mfma_f32_16x16x32_bf16 v[4:7], v[120:123], v[200:203], v[4:7]
	v_mfma_f32_16x16x32_bf16 v[0:3], v[112:115], v[196:199], v[0:3]
	v_mfma_f32_16x16x32_bf16 v[164:167], v[220:223], v[68:71], v[24:27]
	v_mfma_f32_16x16x32_bf16 v[168:171], v[220:223], v[88:91], v[16:19]
	v_mfma_f32_16x16x32_bf16 v[172:175], v[220:223], v[192:195], v[8:11]
	v_mfma_f32_16x16x32_bf16 v[192:195], v[220:223], v[200:203], v[0:3]
	s_barrier
	s_setprio 0
	s_nop 1
	ds_read_b128 v[0:3], v156
	ds_read_b128 v[8:11], v156 offset:256
	ds_read_b128 v[16:19], v157
	ds_read_b128 v[24:27], v157 offset:256
	ds_read_b128 v[32:35], v149 offset:32768
	ds_read_b128 v[40:43], v149 offset:33792
	ds_read_b128 v[48:51], v149 offset:34816
	ds_read_b128 v[56:59], v149 offset:35840
	ds_read_b128 v[60:63], v149 offset:36864
	ds_read_b128 v[68:71], v149 offset:37888
	ds_read_b128 v[196:199], v149 offset:38912
	ds_read_b128 v[200:203], v149 offset:39936
	s_waitcnt vmcnt(2)
	s_waitcnt lgkmcnt(0)
	s_setprio 1
	s_barrier
; #define LDA(dst, b, h) for (int m = 0; m < 4; ++m) { \
;     dst[m][0] = *reinterpret_cast<const bf16x8*>((char*)SA(b, h) + aoff0 + m * 2048); \
;     dst[m][1] = *reinterpret_cast<const bf16x8*>((char*)SA(b, h) + aoff1 + m * 2048); }
; #define LDB(dst, b, h) for (int n = 0; n < 2; ++n) { \
;     dst[n][0] = *reinterpret_cast<const bf16x8*>((char*)SB(b, h) + boff0 + n * 256); \
;     dst[n][1] = *reinterpret_cast<const bf16x8*>((char*)SB(b, h) + boff1 + n * 256); }
; #define MMA(ai, bj, At, Btf) do { __builtin_amdgcn_s_setprio(1); \
;     for (int m = 0; m < 4; ++m) for (int n = 0; n < 2; ++n) for (int k = 0; k < 2; ++k) \
;       acc[ai][bj][m][n] = __builtin_amdgcn_mfma_f32_16x16x32_bf16(Btf[n][k], At[m][k], acc[ai][bj][m][n], 0, 0, 0); \
;     __builtin_amdgcn_s_setprio(0); } while (0)
; #define WAIT_V(n) asm volatile("s_waitcnt vmcnt(" #n ")" ::: "memory")
; #define WAIT_L(n) asm volatile("s_waitcnt lgkmcnt(" #n ")" ::: "memory")
; #define BAR __builtin_amdgcn_s_barrier()
; template <int EPI> ...
;     ...
;   { LDB(B0, 1, 0); LDA(At, 1, 0); WAIT_V(2); BAR; WAIT_L(0); MMA(0, 0, At, B0); BAR;
;     LDB(B1, 1, 1); WAIT_V(0); BAR; WAIT_L(0); MMA(0, 1, At, B1); BAR;
;     LDA(At, 1, 1); BAR; WAIT_L(0); MMA(1, 0, At, B0); MMA(1, 1, At, B1); BAR; }
;   if (wr == 0) BAR;
	v_mfma_f32_16x16x32_bf16 v[64:67], v[0:3], v[32:35], v[124:127]
	v_mfma_f32_16x16x32_bf16 v[120:123], v[16:19], v[40:43], v[64:67]
	v_mfma_f32_16x16x32_bf16 v[64:67], v[8:11], v[32:35], v[208:211]
	v_mfma_f32_16x16x32_bf16 v[124:127], v[24:27], v[40:43], v[64:67]
	v_mfma_f32_16x16x32_bf16 v[64:67], v[0:3], v[48:51], v[116:119]
	v_mfma_f32_16x16x32_bf16 v[112:115], v[16:19], v[56:59], v[64:67]
	v_mfma_f32_16x16x32_bf16 v[64:67], v[8:11], v[48:51], v[212:215]
	v_mfma_f32_16x16x32_bf16 v[116:119], v[24:27], v[56:59], v[64:67]
	v_mfma_f32_16x16x32_bf16 v[64:67], v[0:3], v[60:63], v[108:111]
	v_mfma_f32_16x16x32_bf16 v[104:107], v[16:19], v[68:71], v[64:67]
	v_mfma_f32_16x16x32_bf16 v[64:67], v[8:11], v[60:63], v[216:219]
	v_mfma_f32_16x16x32_bf16 v[108:111], v[24:27], v[68:71], v[64:67]
	v_mfma_f32_16x16x32_bf16 v[64:67], v[0:3], v[196:199], v[100:103]
	v_mfma_f32_16x16x32_bf16 v[88:91], v[16:19], v[200:203], v[64:67]
	v_mfma_f32_16x16x32_bf16 v[64:67], v[8:11], v[196:199], v[96:99]
	v_mfma_f32_16x16x32_bf16 v[92:95], v[24:27], v[200:203], v[64:67]
	s_barrier
	s_setprio 0
	ds_read_b128 v[208:211], v158
	ds_read_b128 v[212:215], v158 offset:256
	ds_read_b128 v[216:219], v159
	ds_read_b128 v[220:223], v159 offset:256
	s_waitcnt vmcnt(0)
	s_waitcnt lgkmcnt(0)
	s_setprio 1
	s_barrier
	v_mfma_f32_16x16x32_bf16 v[64:67], v[208:211], v[32:35], v[224:227]
	v_mfma_f32_16x16x32_bf16 v[32:35], v[212:215], v[32:35], v[176:179]
	v_mfma_f32_16x16x32_bf16 v[100:103], v[220:223], v[40:43], v[32:35]
	v_mfma_f32_16x16x32_bf16 v[32:35], v[208:211], v[48:51], v[84:87]
	v_mfma_f32_16x16x32_bf16 v[80:83], v[216:219], v[56:59], v[32:35]
	v_mfma_f32_16x16x32_bf16 v[32:35], v[212:215], v[48:51], v[180:183]
	v_mfma_f32_16x16x32_bf16 v[84:87], v[220:223], v[56:59], v[32:35]
	v_mfma_f32_16x16x32_bf16 v[32:35], v[208:211], v[60:63], v[76:79]
	v_mfma_f32_16x16x32_bf16 v[96:99], v[216:219], v[40:43], v[64:67]
	v_mfma_f32_16x16x32_bf16 v[64:67], v[216:219], v[68:71], v[32:35]
	v_mfma_f32_16x16x32_bf16 v[32:35], v[212:215], v[60:63], v[72:75]
	v_mfma_f32_16x16x32_bf16 v[68:71], v[220:223], v[68:71], v[32:35]
	v_mfma_f32_16x16x32_bf16 v[32:35], v[208:211], v[196:199], v[184:187]
	v_mfma_f32_16x16x32_bf16 v[56:59], v[216:219], v[200:203], v[32:35]
	v_mfma_f32_16x16x32_bf16 v[32:35], v[212:215], v[196:199], v[188:191]
	v_mfma_f32_16x16x32_bf16 v[60:63], v[220:223], v[200:203], v[32:35]
	s_barrier
	s_setprio 0
	ds_read_b128 v[176:179], v149 offset:49152
	ds_read_b128 v[180:183], v149 offset:50176
	ds_read_b128 v[184:187], v149 offset:51200
	ds_read_b128 v[188:191], v149 offset:52224
	ds_read_b128 v[196:199], v149 offset:53248
	ds_read_b128 v[200:203], v149 offset:54272
	ds_read_b128 v[224:227], v149 offset:55296
	ds_read_b128 v[240:243], v149 offset:56320
	s_waitcnt lgkmcnt(0)
	s_setprio 1
	s_barrier
	v_mfma_f32_16x16x32_bf16 v[32:35], v[0:3], v[176:179], v[204:207]
	v_mfma_f32_16x16x32_bf16 v[72:75], v[16:19], v[180:183], v[32:35]
	v_mfma_f32_16x16x32_bf16 v[32:35], v[8:11], v[176:179], v[228:231]
	v_mfma_f32_16x16x32_bf16 v[76:79], v[24:27], v[180:183], v[32:35]
	v_mfma_f32_16x16x32_bf16 v[32:35], v[0:3], v[184:187], v[52:55]
	v_mfma_f32_16x16x32_bf16 v[48:51], v[16:19], v[188:191], v[32:35]
	v_mfma_f32_16x16x32_bf16 v[32:35], v[8:11], v[184:187], v[232:235]
	v_mfma_f32_16x16x32_bf16 v[52:55], v[24:27], v[188:191], v[32:35]
	v_mfma_f32_16x16x32_bf16 v[32:35], v[0:3], v[196:199], v[44:47]
	v_mfma_f32_16x16x32_bf16 v[40:43], v[16:19], v[200:203], v[32:35]
	v_mfma_f32_16x16x32_bf16 v[32:35], v[8:11], v[196:199], v[236:239]
	v_mfma_f32_16x16x32_bf16 v[0:3], v[0:3], v[224:227], v[36:39]
	v_mfma_f32_16x16x32_bf16 v[44:47], v[24:27], v[200:203], v[32:35]
	v_mfma_f32_16x16x32_bf16 v[32:35], v[16:19], v[240:243], v[0:3]
	v_mfma_f32_16x16x32_bf16 v[0:3], v[8:11], v[224:227], v[160:163]
	v_mfma_f32_16x16x32_bf16 v[36:39], v[24:27], v[240:243], v[0:3]
	v_mfma_f32_16x16x32_bf16 v[0:3], v[208:211], v[176:179], v[28:31]
	v_mfma_f32_16x16x32_bf16 v[24:27], v[216:219], v[180:183], v[0:3]
	v_mfma_f32_16x16x32_bf16 v[0:3], v[212:215], v[176:179], v[164:167]
	v_mfma_f32_16x16x32_bf16 v[28:31], v[220:223], v[180:183], v[0:3]
	v_mfma_f32_16x16x32_bf16 v[0:3], v[208:211], v[184:187], v[20:23]
	v_mfma_f32_16x16x32_bf16 v[16:19], v[216:219], v[188:191], v[0:3]
	v_mfma_f32_16x16x32_bf16 v[0:3], v[212:215], v[184:187], v[168:171]
	v_mfma_f32_16x16x32_bf16 v[20:23], v[220:223], v[188:191], v[0:3]
	v_mfma_f32_16x16x32_bf16 v[0:3], v[208:211], v[196:199], v[12:15]
	v_mfma_f32_16x16x32_bf16 v[8:11], v[216:219], v[200:203], v[0:3]
	v_mfma_f32_16x16x32_bf16 v[0:3], v[212:215], v[196:199], v[172:175]
	v_mfma_f32_16x16x32_bf16 v[12:15], v[220:223], v[200:203], v[0:3]
	v_mfma_f32_16x16x32_bf16 v[0:3], v[208:211], v[224:227], v[4:7]
	v_mfma_f32_16x16x32_bf16 v[4:7], v[212:215], v[224:227], v[192:195]
	v_mfma_f32_16x16x32_bf16 v[0:3], v[216:219], v[240:243], v[0:3]
	v_mfma_f32_16x16x32_bf16 v[4:7], v[220:223], v[240:243], v[4:7]
	s_barrier
	s_setprio 0
	s_and_saveexec_b64 s[60:61], s[2:3]
	s_cbranch_execz .LBB0_1146
	s_barrier
	s_branch .LBB0_1146
